# attention: waves 4-7 run half a KV tile behind waves 0-3 (stagger: one wave of each SIMD in QK^T while its partner is in PV), V staging shifted one tile later
# speedup vs baseline: 1.0072x; 1.0072x over previous
; #define QF(d, e) __uint_as_float(((unsigned)(unsigned short)qr[d][e]) << 16)
; template <typename TQ> ...
;     ...
;   const int tid = tid_, wid = __builtin_amdgcn_readfirstlane(tid >> 6), lane = tid & 63, r32 = lane & 31, hi = lane >> 5;
;   bf16* V_lds = (bf16*)lds; bf16* K_lds = (bf16*)(lds + 2 * SHM_V);
;   float* ws = (float*)(lds + 2 * SHM_V + 2 * SHM_K) + wid * 64; float* li_l = ws;
;   float l_reg = 0; f32x16 o[4] = {}; bf16x8 qr[8];
;   const TQ* Qw = Qb + (long)(wid * QBLK + r32) * LDQ + hi * 8;
; #pragma unroll
;   for (int d0 = 0; d0 < 8; ++d0) qr[d0] = SQ::tobf(SQ::ld8(Qw + d0 * 16));
;   const int sr = tid >> 4, sc = (tid & 15) * 8, vst0 = v_st(sr, sc), vst1 = v_st(32 + sr, sc);
;   const int vb0 = (int)(uintptr_t)V_lds + v_rd_base(lane);
;   struct { typename St::T vs0, vs1, ks0, ks1; } sr_[SDEPTH];
;     ...
;   constexpr int SE = 0, SO = SDEPTH - 1;
;   SLOAD(SE, 0);
;   {
;     float ss = 0.f;
;     ...
; #pragma unroll
;     for (int d0 = 0; d0 < 8; ++d0)
; #pragma unroll
;       for (int e = 0; e < 8; ++e) { const float x = QF(d0, e); ss += x * x; }
;     ss += __shfl_xor(ss, 32);
;     const float rn = (SCALE * 1.4426950408889634f) / sqrtf(ss * (1.0f / 128.0f) + 1e-6f);
;     const int t = trow0 + wid * QBLK + r32; const int prow = t >> 6, pcol = t & 63;
; #pragma unroll
;     for (int hf = 0; hf < 2; ++hf)
; #pragma unroll
;       for (int dd = 0; dd < 2; ++dd) {
;         const int dl = 4 * hf + dd, du = dl + 2;
;         const int f0 = 16 * dd + 8 * hi;
;         const float* cp = rc + (hf ? pcol : prow) * 32 + f0; const float* sp = rsn + (hf ? pcol : prow) * 32 + f0;
;         const float* gl = gq + 16 * dl + 8 * hi; const float* gu = gq + 16 * du + 8 * hi;
; __global__ void __launch_bounds__(NTHR, 2) fwd_megakernel(KArgs a) {
;     ...
;         for (int i = 0; i < upb; ++i) {
;             const int unit = vcu * upb + i; if (unit >= 512) break;
;             const int grp = unit >> 7, rem = unit & 127, gq = rem >> 5, qb = rem & 31, b = grp >> 1, kvh = grp & 1, h = kvh * 4 + gq;
;             const size_t qoff = ((size_t)(b * SEQ + qb * 256)) * DM + h * 128, koff = (size_t)b * SKV * 256 + kvh * 128;
;             att::attn_dense_body<att::bf16>(Q + qoff, Kb + koff, Vb + koff, O + qoff, SKV, (char*)lds_raw, mC, a.g_q, (const float*)(ws + WS_ROPE), (const float*)(ws + WS_ROPE) + 4096, qb * 256);
.LBB0_819:
	s_add_i32 s12, s74, s73
	s_cmpk_gt_i32 s12, 0x1ff
	s_mov_b64 s[0:1], -1
	s_cbranch_scc1 .LBB0_818
	s_lshl_b32 s0, s94, 1
	s_ashr_i32 s96, s12, 8
	s_lshl_b32 s1, s12, 8
	s_and_b32 s95, s0, 0x100
	s_lshl_b32 s0, s96, 13
	s_and_b32 s33, s1, 0x1f00
	s_bfe_u32 s15, s12, 0x10007
	s_or_b32 s0, s0, s33
	s_lshl_b32 s12, s12, 2
	s_ashr_i32 s1, s0, 31
	s_lshl_b32 s13, s15, 9
	s_and_b32 s12, s12, 0x180
	s_lshl_b64 s[0:1], s[0:1], 10
	s_or_b32 s12, s13, s12
	s_or_b32 s0, s0, s12
	s_mul_i32 s12, s96, 0x210000
	s_lshl_b32 s15, s15, 7
	s_or_b32 s12, s12, s15
	s_lshl_b64 s[48:49], s[0:1], 1
	s_mul_hi_i32 s13, s96, 0x210000
	s_add_u32 s0, s20, s48
	s_addc_u32 s1, s21, s49
	s_lshl_b64 s[12:13], s[12:13], 1
	s_add_u32 s54, s69, s12
	s_addc_u32 s55, s70, s13
	v_mov_b32_e32 v114, v0
	s_add_u32 s64, s67, s12
	s_addc_u32 s65, s68, s13
	v_readfirstlane_b32 s53, v114
	s_lshr_b32 s15, s53, 6
	s_lshl_b32 s80, s15, 11
	s_add_u32 s79, s80, 0x10000
	s_lshl_b32 s52, s15, 5
	s_lshl_b32 s12, s15, 3
	v_and_b32_e32 v1, 63, v0
	v_and_b32_e32 v16, 15, v1
	v_lshrrev_b32_e32 v17, 4, v1
	v_add_u32_e32 v12, s12, v17
	v_and_b32_e32 v6, 15, v12
	v_xor_b32_e32 v6, v6, v16
	v_lshlrev_b32_e32 v6, 4, v6
	v_lshl_or_b32 v246, v12, 9, v6
	v_and_b32_e32 v6, 7, v12
	v_lshrrev_b32_e32 v7, 1, v16
	v_xor_b32_e32 v6, v6, v7
	v_and_b32_e32 v7, 1, v16
	v_lshl_or_b32 v6, v6, 1, v7
	v_lshlrev_b32_e32 v6, 4, v6
	v_lshl_or_b32 v248, v12, 9, v6
	v_add_u32_e32 v12, s12, v17
	v_add_u32_e32 v12, 4, v12
	v_and_b32_e32 v6, 15, v12
	v_xor_b32_e32 v6, v6, v16
	v_lshlrev_b32_e32 v6, 4, v6
	v_lshl_or_b32 v247, v12, 9, v6
	v_and_b32_e32 v6, 7, v12
	v_lshrrev_b32_e32 v7, 1, v16
	v_xor_b32_e32 v6, v6, v7
	v_and_b32_e32 v7, 1, v16
	v_lshl_or_b32 v6, v6, 1, v7
	v_lshlrev_b32_e32 v6, 4, v6
	v_lshl_or_b32 v249, v12, 9, v6
	v_add_u32_e32 v6, s52, v16
	v_lshlrev_b32_e32 v6, 11, v6
	v_lshl_or_b32 v13, v17, 4, v6
	v_add_u32_e32 v14, 0x8000, v13
	global_load_dwordx4 v[146:149], v13, s[0:1] offset:0
	global_load_dwordx4 v[150:153], v13, s[0:1] offset:64
	global_load_dwordx4 v[154:157], v13, s[0:1] offset:128
	global_load_dwordx4 v[158:161], v13, s[0:1] offset:192
	global_load_dwordx4 v[162:165], v14, s[0:1] offset:0
	global_load_dwordx4 v[166:169], v14, s[0:1] offset:64
	global_load_dwordx4 v[170:173], v14, s[0:1] offset:128
	global_load_dwordx4 v[174:177], v14, s[0:1] offset:192
	v_lshlrev_b32_e32 v15, 5, v17
	global_load_dwordx4 v[18:21], v15, s[26:27] offset:0
	global_load_dwordx4 v[22:25], v15, s[26:27] offset:16
	global_load_dwordx4 v[26:29], v15, s[26:27] offset:128
	global_load_dwordx4 v[30:33], v15, s[26:27] offset:144
	global_load_dwordx4 v[34:37], v15, s[26:27] offset:256
	global_load_dwordx4 v[38:41], v15, s[26:27] offset:272
	global_load_dwordx4 v[42:45], v15, s[26:27] offset:384
	global_load_dwordx4 v[46:49], v15, s[26:27] offset:400
	s_add_u32 s13, s33, s52
	s_lshr_b32 s13, s13, 6
	s_lshl_b32 s13, s13, 7
	v_add_u32_e32 v200, s13, v15
	global_load_dwordx4 v[82:85], v200, s[4:5] offset:0
	global_load_dwordx4 v[90:93], v200, s[6:7] offset:0
	global_load_dwordx4 v[86:89], v200, s[4:5] offset:16
	global_load_dwordx4 v[94:97], v200, s[6:7] offset:16
	v_add_u32_e32 v6, s52, v16
	v_and_b32_e32 v6, 63, v6
	v_lshl_or_b32 v200, v6, 7, v15
	global_load_dwordx4 v[98:101], v200, s[4:5] offset:0
	global_load_dwordx4 v[106:109], v200, s[6:7] offset:0
	global_load_dwordx4 v[102:105], v200, s[4:5] offset:16
	global_load_dwordx4 v[110:113], v200, s[6:7] offset:16
	v_add_u32_e32 v6, s52, v16
	v_add_u32_e32 v6, 16, v6
	v_and_b32_e32 v6, 63, v6
	v_lshl_or_b32 v200, v6, 7, v15
	global_load_dwordx4 v[114:117], v200, s[4:5] offset:0
	global_load_dwordx4 v[122:125], v200, s[6:7] offset:0
	global_load_dwordx4 v[118:121], v200, s[4:5] offset:16
	global_load_dwordx4 v[126:129], v200, s[6:7] offset:16
	s_mov_b32 s98, s54
	s_mov_b32 s99, s55
	s_mov_b32 s100, s64
	s_mov_b32 s101, s65
	s_add_u32 m0, s79, 0
	s_nop 0
	global_load_lds_dwordx4 v246, s[98:99]
	s_add_u32 m0, s79, 1024
	s_nop 0
	global_load_lds_dwordx4 v247, s[98:99]
	s_add_u32 m0, s80, 0
	s_nop 0
	global_load_lds_dwordx4 v248, s[100:101]
	s_add_u32 m0, s80, 1024
	s_nop 0
	global_load_lds_dwordx4 v249, s[100:101]
	s_add_u32 s98, s98, 0x8000
	s_addc_u32 s99, s99, 0
	s_add_u32 s100, s100, 0x8000
	s_addc_u32 s101, s101, 0
	s_add_u32 m0, s79, 16384
	s_nop 0
	global_load_lds_dwordx4 v246, s[98:99]
	s_add_u32 m0, s79, 17408
	s_nop 0
	global_load_lds_dwordx4 v247, s[98:99]
	s_add_u32 m0, s80, 16384
	s_nop 0
	global_load_lds_dwordx4 v248, s[100:101]
	s_add_u32 m0, s80, 17408
	s_nop 0
	global_load_lds_dwordx4 v249, s[100:101]
	s_add_u32 s98, s98, 0x8000
	s_addc_u32 s99, s99, 0
	s_add_u32 m0, s79, 32768
	s_nop 0
	global_load_lds_dwordx4 v246, s[98:99]
	s_add_u32 m0, s79, 33792
	s_nop 0
	global_load_lds_dwordx4 v247, s[98:99]
	s_add_u32 s98, s98, 0x8000
	s_addc_u32 s99, s99, 0
	s_add_u32 m0, s79, 49152
	s_nop 0
	global_load_lds_dwordx4 v246, s[98:99]
	s_add_u32 m0, s79, 50176
	s_nop 0
	global_load_lds_dwordx4 v247, s[98:99]
	v_lshlrev_b32_e32 v7, 8, v16
	v_or_b32_e32 v6, 0, v17
	v_xor_b32_e32 v6, v6, v16
	v_lshl_or_b32 v6, v6, 4, v7
	v_add_u32_e32 v234, 0x10000, v6
	v_or_b32_e32 v6, 4, v17
	v_xor_b32_e32 v6, v6, v16
	v_lshl_or_b32 v6, v6, 4, v7
	v_add_u32_e32 v235, 0x10000, v6
	v_or_b32_e32 v6, 8, v17
	v_xor_b32_e32 v6, v6, v16
	v_lshl_or_b32 v6, v6, 4, v7
	v_add_u32_e32 v236, 0x10000, v6
	v_or_b32_e32 v6, 12, v17
	v_xor_b32_e32 v6, v6, v16
	v_lshl_or_b32 v6, v6, 4, v7
	v_add_u32_e32 v237, 0x10000, v6
	v_bfe_u32 v6, v1, 2, 2
	v_lshl_or_b32 v6, v17, 2, v6
	v_and_b32_e32 v201, 7, v6
	v_and_b32_e32 v7, 3, v1
	v_lshlrev_b32_e32 v7, 3, v7
	v_lshl_or_b32 v7, v6, 8, v7
	v_xor_b32_e32 v12, 0, v201
	v_lshl_or_b32 v238, v12, 5, v7
	v_xor_b32_e32 v12, 1, v201
	v_lshl_or_b32 v239, v12, 5, v7
	v_xor_b32_e32 v12, 2, v201
	v_lshl_or_b32 v240, v12, 5, v7
	v_xor_b32_e32 v12, 3, v201
	v_lshl_or_b32 v241, v12, 5, v7
	v_xor_b32_e32 v12, 4, v201
	v_lshl_or_b32 v242, v12, 5, v7
	v_xor_b32_e32 v12, 5, v201
	v_lshl_or_b32 v243, v12, 5, v7
	v_xor_b32_e32 v12, 6, v201
	v_lshl_or_b32 v244, v12, 5, v7
	v_xor_b32_e32 v12, 7, v201
	v_lshl_or_b32 v245, v12, 5, v7
	s_waitcnt vmcnt(12)
; #define QF(d, e) __uint_as_float(((unsigned)(unsigned short)qr[d][e]) << 16)
; template <typename TQ> ...
;     ...
;     float ss = 0.f;
;     ...
; #pragma unroll
;     for (int d0 = 0; d0 < 8; ++d0)
; #pragma unroll
;       for (int e = 0; e < 8; ++e) { const float x = QF(d0, e); ss += x * x; }
;     ss += __shfl_xor(ss, 32);
;     const float rn = (SCALE * 1.4426950408889634f) / sqrtf(ss * (1.0f / 128.0f) + 1e-6f);
;     const int t = trow0 + wid * QBLK + r32; const int prow = t >> 6, pcol = t & 63;
; #pragma unroll
;     for (int hf = 0; hf < 2; ++hf)
; #pragma unroll
;       for (int dd = 0; dd < 2; ++dd) {
;         const int dl = 4 * hf + dd, du = dl + 2;
;         const int f0 = 16 * dd + 8 * hi;
;         const float* cp = rc + (hf ? pcol : prow) * 32 + f0; const float* sp = rsn + (hf ? pcol : prow) * 32 + f0;
;         const float* gl = gq + 16 * dl + 8 * hi; const float* gu = gq + 16 * du + 8 * hi;
;         unsigned wl[4], wu[4];
; #pragma unroll
;         for (int e = 0; e < 8; e += 2) {
;           float o1[2], o2[2];
; #pragma unroll
;           for (int k = 0; k < 2; ++k) { const float x1 = QF(dl, e + k) * rn * gl[e + k], x2 = QF(du, e + k) * rn * gu[e + k]; const float c = cp[e + k], sn = sp[e + k];
;             o1[k] = x1 * c - x2 * sn; o2[k] = x2 * c + x1 * sn; }
;           wl[e >> 1] = cvtpk(o1[0], o1[1]); wu[e >> 1] = cvtpk(o2[0], o2[1]);
	v_lshlrev_b32_e32 v50, 16, v146
	v_and_b32_e32 v51, 0xffff0000, v146
	v_lshlrev_b32_e32 v52, 16, v147
	v_and_b32_e32 v53, 0xffff0000, v147
	v_lshlrev_b32_e32 v54, 16, v148
	v_and_b32_e32 v55, 0xffff0000, v148
	v_lshlrev_b32_e32 v56, 16, v149
	v_and_b32_e32 v57, 0xffff0000, v149
	v_lshlrev_b32_e32 v58, 16, v150
	v_and_b32_e32 v59, 0xffff0000, v150
	v_lshlrev_b32_e32 v60, 16, v151
	v_and_b32_e32 v61, 0xffff0000, v151
	v_lshlrev_b32_e32 v62, 16, v152
	v_and_b32_e32 v63, 0xffff0000, v152
	v_lshlrev_b32_e32 v64, 16, v153
	v_and_b32_e32 v65, 0xffff0000, v153
	v_lshlrev_b32_e32 v66, 16, v154
	v_and_b32_e32 v67, 0xffff0000, v154
	v_lshlrev_b32_e32 v68, 16, v155
	v_and_b32_e32 v69, 0xffff0000, v155
	v_lshlrev_b32_e32 v70, 16, v156
	v_and_b32_e32 v71, 0xffff0000, v156
	v_lshlrev_b32_e32 v72, 16, v157
	v_and_b32_e32 v73, 0xffff0000, v157
	v_lshlrev_b32_e32 v74, 16, v158
	v_and_b32_e32 v75, 0xffff0000, v158
	v_lshlrev_b32_e32 v76, 16, v159
	v_and_b32_e32 v77, 0xffff0000, v159
	v_lshlrev_b32_e32 v78, 16, v160
	v_and_b32_e32 v79, 0xffff0000, v160
	v_lshlrev_b32_e32 v80, 16, v161
	v_and_b32_e32 v81, 0xffff0000, v161
	v_mul_f32_e32 v130, v50, v50
	v_fmac_f32_e32 v130, v51, v51
	v_fmac_f32_e32 v130, v52, v52
	v_fmac_f32_e32 v130, v53, v53
	v_fmac_f32_e32 v130, v54, v54
	v_fmac_f32_e32 v130, v55, v55
	v_fmac_f32_e32 v130, v56, v56
	v_fmac_f32_e32 v130, v57, v57
	v_fmac_f32_e32 v130, v58, v58
	v_fmac_f32_e32 v130, v59, v59
	v_fmac_f32_e32 v130, v60, v60
	v_fmac_f32_e32 v130, v61, v61
	v_fmac_f32_e32 v130, v62, v62
	v_fmac_f32_e32 v130, v63, v63
	v_fmac_f32_e32 v130, v64, v64
	v_fmac_f32_e32 v130, v65, v65
	v_fmac_f32_e32 v130, v66, v66
	v_fmac_f32_e32 v130, v67, v67
	v_fmac_f32_e32 v130, v68, v68
	v_fmac_f32_e32 v130, v69, v69
	v_fmac_f32_e32 v130, v70, v70
	v_fmac_f32_e32 v130, v71, v71
	v_fmac_f32_e32 v130, v72, v72
	v_fmac_f32_e32 v130, v73, v73
	v_fmac_f32_e32 v130, v74, v74
	v_fmac_f32_e32 v130, v75, v75
	v_fmac_f32_e32 v130, v76, v76
	v_fmac_f32_e32 v130, v77, v77
	v_fmac_f32_e32 v130, v78, v78
	v_fmac_f32_e32 v130, v79, v79
	v_fmac_f32_e32 v130, v80, v80
	v_fmac_f32_e32 v130, v81, v81
	ds_swizzle_b32 v132, v130 offset:swizzle(SWAP,16)
	s_waitcnt lgkmcnt(0)
	v_add_f32_e32 v130, v130, v132
	v_mov_b32_e32 v132, v130
	s_nop 1
	v_permlane32_swap_b32_e32 v130, v132
	v_add_f32_e32 v130, v130, v132
	v_fmamk_f32 v130, v130, 0x3c000000, v199
	v_rsq_f32_e32 v130, v130
	s_nop 0
	v_mul_f32_e32 v131, s77, v130
	v_mul_f32_e32 v50, v50, v131
	v_mul_f32_e32 v50, v50, v18
	v_mul_f32_e32 v51, v51, v131
	v_mul_f32_e32 v51, v51, v19
	v_mul_f32_e32 v52, v52, v131
	v_mul_f32_e32 v52, v52, v20
	v_mul_f32_e32 v53, v53, v131
	v_mul_f32_e32 v53, v53, v21
	v_mul_f32_e32 v54, v54, v131
	v_mul_f32_e32 v54, v54, v22
	v_mul_f32_e32 v55, v55, v131
	v_mul_f32_e32 v55, v55, v23
	v_mul_f32_e32 v56, v56, v131
	v_mul_f32_e32 v56, v56, v24
	v_mul_f32_e32 v57, v57, v131
	v_mul_f32_e32 v57, v57, v25
	v_mul_f32_e32 v58, v58, v131
	v_mul_f32_e32 v58, v58, v26
	v_mul_f32_e32 v59, v59, v131
	v_mul_f32_e32 v59, v59, v27
	v_mul_f32_e32 v60, v60, v131
	v_mul_f32_e32 v60, v60, v28
	v_mul_f32_e32 v61, v61, v131
	v_mul_f32_e32 v61, v61, v29
	v_mul_f32_e32 v62, v62, v131
	v_mul_f32_e32 v62, v62, v30
	v_mul_f32_e32 v63, v63, v131
	v_mul_f32_e32 v63, v63, v31
	v_mul_f32_e32 v64, v64, v131
	v_mul_f32_e32 v64, v64, v32
	v_mul_f32_e32 v65, v65, v131
	v_mul_f32_e32 v65, v65, v33
	v_mul_f32_e32 v66, v66, v131
	v_mul_f32_e32 v66, v66, v34
	v_mul_f32_e32 v67, v67, v131
	v_mul_f32_e32 v67, v67, v35
	v_mul_f32_e32 v68, v68, v131
	v_mul_f32_e32 v68, v68, v36
	v_mul_f32_e32 v69, v69, v131
	v_mul_f32_e32 v69, v69, v37
	v_mul_f32_e32 v70, v70, v131
	v_mul_f32_e32 v70, v70, v38
	v_mul_f32_e32 v71, v71, v131
	v_mul_f32_e32 v71, v71, v39
	v_mul_f32_e32 v72, v72, v131
	v_mul_f32_e32 v72, v72, v40
	v_mul_f32_e32 v73, v73, v131
	v_mul_f32_e32 v73, v73, v41
	v_mul_f32_e32 v74, v74, v131
	v_mul_f32_e32 v74, v74, v42
	v_mul_f32_e32 v75, v75, v131
	v_mul_f32_e32 v75, v75, v43
	v_mul_f32_e32 v76, v76, v131
	v_mul_f32_e32 v76, v76, v44
	v_mul_f32_e32 v77, v77, v131
	v_mul_f32_e32 v77, v77, v45
	v_mul_f32_e32 v78, v78, v131
	v_mul_f32_e32 v78, v78, v46
	v_mul_f32_e32 v79, v79, v131
	v_mul_f32_e32 v79, v79, v47
	v_mul_f32_e32 v80, v80, v131
	v_mul_f32_e32 v80, v80, v48
	v_mul_f32_e32 v81, v81, v131
	v_mul_f32_e32 v81, v81, v49
	v_mul_f32_e32 v133, v58, v90
	v_mul_f32_e32 v134, v50, v90
	v_fma_f32 v50, v50, v82, -v133
	v_fma_f32 v58, v58, v82, v134
	v_mul_f32_e32 v133, v59, v91
	v_mul_f32_e32 v134, v51, v91
	v_fma_f32 v51, v51, v83, -v133
	v_fma_f32 v59, v59, v83, v134
	v_mul_f32_e32 v133, v60, v92
	v_mul_f32_e32 v134, v52, v92
	v_fma_f32 v52, v52, v84, -v133
	v_fma_f32 v60, v60, v84, v134
	v_mul_f32_e32 v133, v61, v93
	v_mul_f32_e32 v134, v53, v93
	v_fma_f32 v53, v53, v85, -v133
	v_fma_f32 v61, v61, v85, v134
	v_mul_f32_e32 v133, v62, v94
	v_mul_f32_e32 v134, v54, v94
	v_fma_f32 v54, v54, v86, -v133
	v_fma_f32 v62, v62, v86, v134
	v_mul_f32_e32 v133, v63, v95
	v_mul_f32_e32 v134, v55, v95
	v_fma_f32 v55, v55, v87, -v133
	v_fma_f32 v63, v63, v87, v134
	v_mul_f32_e32 v133, v64, v96
	v_mul_f32_e32 v134, v56, v96
	v_fma_f32 v56, v56, v88, -v133
	v_fma_f32 v64, v64, v88, v134
	v_mul_f32_e32 v133, v65, v97
	v_mul_f32_e32 v134, v57, v97
	v_fma_f32 v57, v57, v89, -v133
	v_fma_f32 v65, v65, v89, v134
	v_mul_f32_e32 v133, v74, v106
	v_mul_f32_e32 v134, v66, v106
	v_fma_f32 v66, v66, v98, -v133
	v_fma_f32 v74, v74, v98, v134
	v_mul_f32_e32 v133, v75, v107
	v_mul_f32_e32 v134, v67, v107
	v_fma_f32 v67, v67, v99, -v133
	v_fma_f32 v75, v75, v99, v134
	v_mul_f32_e32 v133, v76, v108
	v_mul_f32_e32 v134, v68, v108
	v_fma_f32 v68, v68, v100, -v133
; #define QF(d, e) __uint_as_float(((unsigned)(unsigned short)qr[d][e]) << 16)
; template <typename TQ> ...
;     ...
;         for (int e = 0; e < 8; e += 2) {
;           float o1[2], o2[2];
; #pragma unroll
;           for (int k = 0; k < 2; ++k) { const float x1 = QF(dl, e + k) * rn * gl[e + k], x2 = QF(du, e + k) * rn * gu[e + k]; const float c = cp[e + k], sn = sp[e + k];
;             o1[k] = x1 * c - x2 * sn; o2[k] = x2 * c + x1 * sn; }
;           wl[e >> 1] = cvtpk(o1[0], o1[1]); wu[e >> 1] = cvtpk(o2[0], o2[1]);
;         }
;         u32x4 vl = {wl[0], wl[1], wl[2], wl[3]}, vu = {wu[0], wu[1], wu[2], wu[3]};
;         qr[dl] = *reinterpret_cast<bf16x8*>(&vl); qr[du] = *reinterpret_cast<bf16x8*>(&vu);
	v_fma_f32 v76, v76, v100, v134
	v_mul_f32_e32 v133, v77, v109
	v_mul_f32_e32 v134, v69, v109
	v_fma_f32 v69, v69, v101, -v133
	v_fma_f32 v77, v77, v101, v134
	v_mul_f32_e32 v133, v78, v110
	v_mul_f32_e32 v134, v70, v110
	v_fma_f32 v70, v70, v102, -v133
	v_fma_f32 v78, v78, v102, v134
	v_mul_f32_e32 v133, v79, v111
	v_mul_f32_e32 v134, v71, v111
	v_fma_f32 v71, v71, v103, -v133
	v_fma_f32 v79, v79, v103, v134
	v_mul_f32_e32 v133, v80, v112
	v_mul_f32_e32 v134, v72, v112
	v_fma_f32 v72, v72, v104, -v133
	v_fma_f32 v80, v80, v104, v134
	v_mul_f32_e32 v133, v81, v113
	v_mul_f32_e32 v134, v73, v113
	v_fma_f32 v73, v73, v105, -v133
	v_fma_f32 v81, v81, v105, v134
	v_cvt_pk_bf16_f32 v146, v50, v51
	v_cvt_pk_bf16_f32 v147, v52, v53
	v_cvt_pk_bf16_f32 v148, v54, v55
	v_cvt_pk_bf16_f32 v149, v56, v57
	v_cvt_pk_bf16_f32 v150, v58, v59
	v_cvt_pk_bf16_f32 v151, v60, v61
	v_cvt_pk_bf16_f32 v152, v62, v63
	v_cvt_pk_bf16_f32 v153, v64, v65
	v_cvt_pk_bf16_f32 v154, v66, v67
	v_cvt_pk_bf16_f32 v155, v68, v69
	v_cvt_pk_bf16_f32 v156, v70, v71
	v_cvt_pk_bf16_f32 v157, v72, v73
	v_cvt_pk_bf16_f32 v158, v74, v75
	v_cvt_pk_bf16_f32 v159, v76, v77
	v_cvt_pk_bf16_f32 v160, v78, v79
	v_cvt_pk_bf16_f32 v161, v80, v81
	v_lshlrev_b32_e32 v50, 16, v162
	v_and_b32_e32 v51, 0xffff0000, v162
	v_lshlrev_b32_e32 v52, 16, v163
	v_and_b32_e32 v53, 0xffff0000, v163
	v_lshlrev_b32_e32 v54, 16, v164
	v_and_b32_e32 v55, 0xffff0000, v164
	v_lshlrev_b32_e32 v56, 16, v165
	v_and_b32_e32 v57, 0xffff0000, v165
	v_lshlrev_b32_e32 v58, 16, v166
	v_and_b32_e32 v59, 0xffff0000, v166
	v_lshlrev_b32_e32 v60, 16, v167
	v_and_b32_e32 v61, 0xffff0000, v167
	v_lshlrev_b32_e32 v62, 16, v168
	v_and_b32_e32 v63, 0xffff0000, v168
	v_lshlrev_b32_e32 v64, 16, v169
	v_and_b32_e32 v65, 0xffff0000, v169
	v_lshlrev_b32_e32 v66, 16, v170
	v_and_b32_e32 v67, 0xffff0000, v170
	v_lshlrev_b32_e32 v68, 16, v171
	v_and_b32_e32 v69, 0xffff0000, v171
	v_lshlrev_b32_e32 v70, 16, v172
	v_and_b32_e32 v71, 0xffff0000, v172
	v_lshlrev_b32_e32 v72, 16, v173
	v_and_b32_e32 v73, 0xffff0000, v173
	v_lshlrev_b32_e32 v74, 16, v174
	v_and_b32_e32 v75, 0xffff0000, v174
	v_lshlrev_b32_e32 v76, 16, v175
	v_and_b32_e32 v77, 0xffff0000, v175
	v_lshlrev_b32_e32 v78, 16, v176
	v_and_b32_e32 v79, 0xffff0000, v176
	v_lshlrev_b32_e32 v80, 16, v177
	v_and_b32_e32 v81, 0xffff0000, v177
	v_mul_f32_e32 v130, v50, v50
	v_fmac_f32_e32 v130, v51, v51
	v_fmac_f32_e32 v130, v52, v52
	v_fmac_f32_e32 v130, v53, v53
	v_fmac_f32_e32 v130, v54, v54
	v_fmac_f32_e32 v130, v55, v55
	v_fmac_f32_e32 v130, v56, v56
	v_fmac_f32_e32 v130, v57, v57
	v_fmac_f32_e32 v130, v58, v58
	v_fmac_f32_e32 v130, v59, v59
	v_fmac_f32_e32 v130, v60, v60
	v_fmac_f32_e32 v130, v61, v61
	v_fmac_f32_e32 v130, v62, v62
	v_fmac_f32_e32 v130, v63, v63
	v_fmac_f32_e32 v130, v64, v64
	v_fmac_f32_e32 v130, v65, v65
	v_fmac_f32_e32 v130, v66, v66
	v_fmac_f32_e32 v130, v67, v67
	v_fmac_f32_e32 v130, v68, v68
	v_fmac_f32_e32 v130, v69, v69
	v_fmac_f32_e32 v130, v70, v70
	v_fmac_f32_e32 v130, v71, v71
	v_fmac_f32_e32 v130, v72, v72
	v_fmac_f32_e32 v130, v73, v73
	v_fmac_f32_e32 v130, v74, v74
	v_fmac_f32_e32 v130, v75, v75
	v_fmac_f32_e32 v130, v76, v76
	v_fmac_f32_e32 v130, v77, v77
	v_fmac_f32_e32 v130, v78, v78
	v_fmac_f32_e32 v130, v79, v79
	v_fmac_f32_e32 v130, v80, v80
	v_fmac_f32_e32 v130, v81, v81
	ds_swizzle_b32 v132, v130 offset:swizzle(SWAP,16)
	s_waitcnt lgkmcnt(0)
	v_add_f32_e32 v130, v130, v132
	v_mov_b32_e32 v132, v130
	s_nop 1
	v_permlane32_swap_b32_e32 v130, v132
	v_add_f32_e32 v130, v130, v132
	v_fmamk_f32 v130, v130, 0x3c000000, v199
	v_rsq_f32_e32 v130, v130
	s_nop 0
	v_mul_f32_e32 v131, s77, v130
	v_mul_f32_e32 v50, v50, v131
	v_mul_f32_e32 v50, v50, v18
	v_mul_f32_e32 v51, v51, v131
	v_mul_f32_e32 v51, v51, v19
	v_mul_f32_e32 v52, v52, v131
	v_mul_f32_e32 v52, v52, v20
	v_mul_f32_e32 v53, v53, v131
	v_mul_f32_e32 v53, v53, v21
	v_mul_f32_e32 v54, v54, v131
	v_mul_f32_e32 v54, v54, v22
	v_mul_f32_e32 v55, v55, v131
	v_mul_f32_e32 v55, v55, v23
	v_mul_f32_e32 v56, v56, v131
	v_mul_f32_e32 v56, v56, v24
	v_mul_f32_e32 v57, v57, v131
	v_mul_f32_e32 v57, v57, v25
	v_mul_f32_e32 v58, v58, v131
	v_mul_f32_e32 v58, v58, v26
	v_mul_f32_e32 v59, v59, v131
	v_mul_f32_e32 v59, v59, v27
	v_mul_f32_e32 v60, v60, v131
	v_mul_f32_e32 v60, v60, v28
	v_mul_f32_e32 v61, v61, v131
	v_mul_f32_e32 v61, v61, v29
	v_mul_f32_e32 v62, v62, v131
	v_mul_f32_e32 v62, v62, v30
	v_mul_f32_e32 v63, v63, v131
	v_mul_f32_e32 v63, v63, v31
	v_mul_f32_e32 v64, v64, v131
	v_mul_f32_e32 v64, v64, v32
	v_mul_f32_e32 v65, v65, v131
	v_mul_f32_e32 v65, v65, v33
	v_mul_f32_e32 v66, v66, v131
	v_mul_f32_e32 v66, v66, v34
	v_mul_f32_e32 v67, v67, v131
	v_mul_f32_e32 v67, v67, v35
	v_mul_f32_e32 v68, v68, v131
	v_mul_f32_e32 v68, v68, v36
	v_mul_f32_e32 v69, v69, v131
	v_mul_f32_e32 v69, v69, v37
	v_mul_f32_e32 v70, v70, v131
	v_mul_f32_e32 v70, v70, v38
	v_mul_f32_e32 v71, v71, v131
	v_mul_f32_e32 v71, v71, v39
	v_mul_f32_e32 v72, v72, v131
	v_mul_f32_e32 v72, v72, v40
	v_mul_f32_e32 v73, v73, v131
	v_mul_f32_e32 v73, v73, v41
	v_mul_f32_e32 v74, v74, v131
	v_mul_f32_e32 v74, v74, v42
	v_mul_f32_e32 v75, v75, v131
	v_mul_f32_e32 v75, v75, v43
	v_mul_f32_e32 v76, v76, v131
	v_mul_f32_e32 v76, v76, v44
	v_mul_f32_e32 v77, v77, v131
	v_mul_f32_e32 v77, v77, v45
	v_mul_f32_e32 v78, v78, v131
	v_mul_f32_e32 v78, v78, v46
	v_mul_f32_e32 v79, v79, v131
	v_mul_f32_e32 v79, v79, v47
	v_mul_f32_e32 v80, v80, v131
	v_mul_f32_e32 v80, v80, v48
	v_mul_f32_e32 v81, v81, v131
	v_mul_f32_e32 v81, v81, v49
	v_mul_f32_e32 v133, v58, v90
	v_mul_f32_e32 v134, v50, v90
	v_fma_f32 v50, v50, v82, -v133
	v_fma_f32 v58, v58, v82, v134
; #define SBAR() __builtin_amdgcn_sched_barrier(0)
; #define QF(d, e) __uint_as_float(((unsigned)(unsigned short)qr[d][e]) << 16)
; __device__ __forceinline__ void qkt(f32x16& p0, f32x16& p1, const bf16* Ks, const bf16x8* qr, int r32, int hi, const f32x16& negm) {
; #pragma unroll
;   for (int d0 = 0; d0 < 8; ++d0) { int cb = (d0 * 16 + hi * 8) * 2;
;     bf16x8 b0 = *reinterpret_cast<const bf16x8*>((const char*)Ks + KSWZ(r32, cb));
;     bf16x8 b1 = *reinterpret_cast<const bf16x8*>((const char*)Ks + KSWZ(32 + r32, cb));
;     if (d0 == 0) { p0 = __builtin_amdgcn_mfma_f32_32x32x16_bf16(b0, qr[0], negm, 0, 0, 0); p1 = __builtin_amdgcn_mfma_f32_32x32x16_bf16(b1, qr[0], negm, 0, 0, 0); }
;     else { p0 = __builtin_amdgcn_mfma_f32_32x32x16_bf16(b0, qr[d0], p0, 0, 0, 0); p1 = __builtin_amdgcn_mfma_f32_32x32x16_bf16(b1, qr[d0], p1, 0, 0, 0); } }
; template <typename TQ> ...
;     ...
;           for (int k = 0; k < 2; ++k) { const float x1 = QF(dl, e + k) * rn * gl[e + k], x2 = QF(du, e + k) * rn * gu[e + k]; const float c = cp[e + k], sn = sp[e + k];
;             o1[k] = x1 * c - x2 * sn; o2[k] = x2 * c + x1 * sn; }
;           wl[e >> 1] = cvtpk(o1[0], o1[1]); wu[e >> 1] = cvtpk(o2[0], o2[1]);
;         }
;         u32x4 vl = {wl[0], wl[1], wl[2], wl[3]}, vu = {wu[0], wu[1], wu[2], wu[3]};
;         qr[dl] = *reinterpret_cast<bf16x8*>(&vl); qr[du] = *reinterpret_cast<bf16x8*>(&vu);
;       }
;   }
;     ...
;   SBAR();
;   f32x16 pA0, pA1, pB0, pB1; bf16x8 pa0, pa1, pa2, pa3; const int NT = seq / KVBLK;
;   f32x16 negm;
; #pragma unroll
;   for (int r = 0; r < 16; ++r) negm[r] = -mC;
;   asm volatile("" : "+v"(negm));
;   asm volatile("s_waitcnt vmcnt(0)" ::: "memory"); SWRITE(0, SE); __syncthreads();
;   qkt(pA0, pA1, K_lds, qr, r32, hi, negm); partialSM(pA0, pA1, mC);
	v_mul_f32_e32 v133, v59, v91
	v_mul_f32_e32 v134, v51, v91
	v_fma_f32 v51, v51, v83, -v133
	v_fma_f32 v59, v59, v83, v134
	v_mul_f32_e32 v133, v60, v92
	v_mul_f32_e32 v134, v52, v92
	v_fma_f32 v52, v52, v84, -v133
	v_fma_f32 v60, v60, v84, v134
	v_mul_f32_e32 v133, v61, v93
	v_mul_f32_e32 v134, v53, v93
	v_fma_f32 v53, v53, v85, -v133
	v_fma_f32 v61, v61, v85, v134
	v_mul_f32_e32 v133, v62, v94
	v_mul_f32_e32 v134, v54, v94
	v_fma_f32 v54, v54, v86, -v133
	v_fma_f32 v62, v62, v86, v134
	v_mul_f32_e32 v133, v63, v95
	v_mul_f32_e32 v134, v55, v95
	v_fma_f32 v55, v55, v87, -v133
	v_fma_f32 v63, v63, v87, v134
	v_mul_f32_e32 v133, v64, v96
	v_mul_f32_e32 v134, v56, v96
	v_fma_f32 v56, v56, v88, -v133
	v_fma_f32 v64, v64, v88, v134
	v_mul_f32_e32 v133, v65, v97
	v_mul_f32_e32 v134, v57, v97
	v_fma_f32 v57, v57, v89, -v133
	v_fma_f32 v65, v65, v89, v134
	v_mul_f32_e32 v133, v74, v122
	v_mul_f32_e32 v134, v66, v122
	v_fma_f32 v66, v66, v114, -v133
	v_fma_f32 v74, v74, v114, v134
	v_mul_f32_e32 v133, v75, v123
	v_mul_f32_e32 v134, v67, v123
	v_fma_f32 v67, v67, v115, -v133
	v_fma_f32 v75, v75, v115, v134
	v_mul_f32_e32 v133, v76, v124
	v_mul_f32_e32 v134, v68, v124
	v_fma_f32 v68, v68, v116, -v133
	v_fma_f32 v76, v76, v116, v134
	v_mul_f32_e32 v133, v77, v125
	v_mul_f32_e32 v134, v69, v125
	v_fma_f32 v69, v69, v117, -v133
	v_fma_f32 v77, v77, v117, v134
	v_mul_f32_e32 v133, v78, v126
	v_mul_f32_e32 v134, v70, v126
	v_fma_f32 v70, v70, v118, -v133
	v_fma_f32 v78, v78, v118, v134
	v_mul_f32_e32 v133, v79, v127
	v_mul_f32_e32 v134, v71, v127
	v_fma_f32 v71, v71, v119, -v133
	v_fma_f32 v79, v79, v119, v134
	v_mul_f32_e32 v133, v80, v128
	v_mul_f32_e32 v134, v72, v128
	v_fma_f32 v72, v72, v120, -v133
	v_fma_f32 v80, v80, v120, v134
	v_mul_f32_e32 v133, v81, v129
	v_mul_f32_e32 v134, v73, v129
	v_fma_f32 v73, v73, v121, -v133
	v_fma_f32 v81, v81, v121, v134
	v_cvt_pk_bf16_f32 v162, v50, v51
	v_cvt_pk_bf16_f32 v163, v52, v53
	v_cvt_pk_bf16_f32 v164, v54, v55
	v_cvt_pk_bf16_f32 v165, v56, v57
	v_cvt_pk_bf16_f32 v166, v58, v59
	v_cvt_pk_bf16_f32 v167, v60, v61
	v_cvt_pk_bf16_f32 v168, v62, v63
	v_cvt_pk_bf16_f32 v169, v64, v65
	v_cvt_pk_bf16_f32 v170, v66, v67
	v_cvt_pk_bf16_f32 v171, v68, v69
	v_cvt_pk_bf16_f32 v172, v70, v71
	v_cvt_pk_bf16_f32 v173, v72, v73
	v_cvt_pk_bf16_f32 v174, v74, v75
	v_cvt_pk_bf16_f32 v175, v76, v77
	v_cvt_pk_bf16_f32 v176, v78, v79
	v_cvt_pk_bf16_f32 v177, v80, v81
	v_mov_b32_e32 v18, 0
	v_mov_b32_e32 v19, 0
	v_mov_b32_e32 v20, 0
	v_mov_b32_e32 v21, 0
	v_mov_b32_e32 v22, 0
	v_mov_b32_e32 v23, 0
	v_mov_b32_e32 v24, 0
	v_mov_b32_e32 v25, 0
	v_mov_b32_e32 v26, 0
	v_mov_b32_e32 v27, 0
	v_mov_b32_e32 v28, 0
	v_mov_b32_e32 v29, 0
	v_mov_b32_e32 v30, 0
	v_mov_b32_e32 v31, 0
	v_mov_b32_e32 v32, 0
	v_mov_b32_e32 v33, 0
	v_mov_b32_e32 v34, 0
	v_mov_b32_e32 v35, 0
	v_mov_b32_e32 v36, 0
	v_mov_b32_e32 v37, 0
	v_mov_b32_e32 v38, 0
	v_mov_b32_e32 v39, 0
	v_mov_b32_e32 v40, 0
	v_mov_b32_e32 v41, 0
	v_mov_b32_e32 v42, 0
	v_mov_b32_e32 v43, 0
	v_mov_b32_e32 v44, 0
	v_mov_b32_e32 v45, 0
	v_mov_b32_e32 v46, 0
	v_mov_b32_e32 v47, 0
	v_mov_b32_e32 v48, 0
	v_mov_b32_e32 v49, 0
	v_mov_b32_e32 v50, 0
	v_mov_b32_e32 v51, 0
	v_mov_b32_e32 v52, 0
	v_mov_b32_e32 v53, 0
	v_mov_b32_e32 v54, 0
	v_mov_b32_e32 v55, 0
	v_mov_b32_e32 v56, 0
	v_mov_b32_e32 v57, 0
	v_mov_b32_e32 v58, 0
	v_mov_b32_e32 v59, 0
	v_mov_b32_e32 v60, 0
	v_mov_b32_e32 v61, 0
	v_mov_b32_e32 v62, 0
	v_mov_b32_e32 v63, 0
	v_mov_b32_e32 v64, 0
	v_mov_b32_e32 v65, 0
	v_mov_b32_e32 v66, 0
	v_mov_b32_e32 v67, 0
	v_mov_b32_e32 v68, 0
	v_mov_b32_e32 v69, 0
	v_mov_b32_e32 v70, 0
	v_mov_b32_e32 v71, 0
	v_mov_b32_e32 v72, 0
	v_mov_b32_e32 v73, 0
	v_mov_b32_e32 v74, 0
	v_mov_b32_e32 v75, 0
	v_mov_b32_e32 v76, 0
	v_mov_b32_e32 v77, 0
	v_mov_b32_e32 v78, 0
	v_mov_b32_e32 v79, 0
	v_mov_b32_e32 v80, 0
	v_mov_b32_e32 v81, 0
	v_mov_b32_e32 v250, 0
	v_mov_b32_e32 v251, 0
	s_waitcnt vmcnt(0)
	s_barrier
	ds_read_b128 v[178:181], v234 offset:0
	ds_read_b128 v[182:185], v234 offset:4096
	ds_read_b128 v[186:189], v234 offset:8192
	ds_read_b128 v[190:193], v234 offset:12288
	s_waitcnt lgkmcnt(3)
	v_mfma_f32_16x16x32_bf16 v[82:85], v[178:181], v[146:149], v[2:5]
	v_mfma_f32_16x16x32_bf16 v[86:89], v[178:181], v[162:165], v[2:5]
	ds_read_b128 v[178:181], v235 offset:0
	s_waitcnt lgkmcnt(3)
	v_mfma_f32_16x16x32_bf16 v[90:93], v[182:185], v[146:149], v[2:5]
	v_mfma_f32_16x16x32_bf16 v[94:97], v[182:185], v[162:165], v[2:5]
	ds_read_b128 v[182:185], v235 offset:4096
	s_waitcnt lgkmcnt(3)
	v_mfma_f32_16x16x32_bf16 v[98:101], v[186:189], v[146:149], v[2:5]
	v_mfma_f32_16x16x32_bf16 v[102:105], v[186:189], v[162:165], v[2:5]
	ds_read_b128 v[186:189], v235 offset:8192
	s_waitcnt lgkmcnt(3)
	v_mfma_f32_16x16x32_bf16 v[106:109], v[190:193], v[146:149], v[2:5]
	v_mfma_f32_16x16x32_bf16 v[110:113], v[190:193], v[162:165], v[2:5]
	ds_read_b128 v[190:193], v235 offset:12288
	s_waitcnt lgkmcnt(3)
	v_mfma_f32_16x16x32_bf16 v[82:85], v[178:181], v[150:153], v[82:85]
	v_mfma_f32_16x16x32_bf16 v[86:89], v[178:181], v[166:169], v[86:89]
	ds_read_b128 v[178:181], v236 offset:0
	s_waitcnt lgkmcnt(3)
	v_mfma_f32_16x16x32_bf16 v[90:93], v[182:185], v[150:153], v[90:93]
	v_mfma_f32_16x16x32_bf16 v[94:97], v[182:185], v[166:169], v[94:97]
	ds_read_b128 v[182:185], v236 offset:4096
	s_waitcnt lgkmcnt(3)
	v_mfma_f32_16x16x32_bf16 v[98:101], v[186:189], v[150:153], v[98:101]
	v_mfma_f32_16x16x32_bf16 v[102:105], v[186:189], v[166:169], v[102:105]
	ds_read_b128 v[186:189], v236 offset:8192
	s_waitcnt lgkmcnt(3)
	v_mfma_f32_16x16x32_bf16 v[106:109], v[190:193], v[150:153], v[106:109]
	v_mfma_f32_16x16x32_bf16 v[110:113], v[190:193], v[166:169], v[110:113]
	ds_read_b128 v[190:193], v236 offset:12288
	s_waitcnt lgkmcnt(3)
; #define SBAR() __builtin_amdgcn_sched_barrier(0)
; #define SLOAD(i, k0) do { sr_[i].vs0 = St::ld8(&Vh[(long)((k0) + sr) * LDK + sc]); sr_[i].vs1 = St::ld8(&Vh[(long)((k0) + 32 + sr) * LDK + sc]); \
;     sr_[i].ks0 = St::ld8(&Kh[(long)((k0) + sr) * LDK + sc]); sr_[i].ks1 = St::ld8(&Kh[(long)((k0) + 32 + sr) * LDK + sc]); } while (0)
; #define SWAIT() do { if constexpr (SDEPTH == 2) asm volatile("s_waitcnt vmcnt(4)" ::: "memory"); else asm volatile("s_waitcnt vmcnt(0)" ::: "memory"); } while (0)
; template <typename TQ> ...
;     ...
;   qkt(pA0, pA1, K_lds, qr, r32, hi, negm); partialSM(pA0, pA1, mC);
;   SLOAD(SO, KVBLK); if constexpr (SDEPTH == 2) { if (2 < NT) SLOAD(SE, 2 * KVBLK); }
;   SWAIT(); SWRITE(1, SO); __syncthreads();
;   for (int j = 1; j + 1 < NT; j += 2) {
;     SBAR(); SLOAD(SO, (j + SDEPTH) * KVBLK); SBAR();
;     qkt(pB0, pB1, (bf16*)((char*)K_lds + SHM_K), qr, r32, hi, negm);
;     finishSM(pA0, pA1, l_reg, pa0, pa1, pa2, pa3); SBAR();
;     pv_d0(o, vb0, pa0, pa1, pa2, pa3); partialSM(pB0, pB1, mC);
;     __syncthreads(); SWAIT(); SWRITE(0, SE);
;     __syncthreads();
;     SBAR(); if (SDEPTH == 1 || j + 3 < NT) SLOAD(SE, (j + 1 + SDEPTH) * KVBLK); SBAR();
;     qkt(pA0, pA1, K_lds, qr, r32, hi, negm);
;     finishSM(pB0, pB1, l_reg, pa0, pa1, pa2, pa3); SBAR();
;     pv_d0(o, vb0 + (int)SHM_V, pa0, pa1, pa2, pa3); partialSM(pA0, pA1, mC);
	v_mfma_f32_16x16x32_bf16 v[82:85], v[178:181], v[154:157], v[82:85]
	v_mfma_f32_16x16x32_bf16 v[86:89], v[178:181], v[170:173], v[86:89]
	ds_read_b128 v[178:181], v237 offset:0
	s_waitcnt lgkmcnt(3)
	v_mfma_f32_16x16x32_bf16 v[90:93], v[182:185], v[154:157], v[90:93]
	v_mfma_f32_16x16x32_bf16 v[94:97], v[182:185], v[170:173], v[94:97]
	ds_read_b128 v[182:185], v237 offset:4096
	s_waitcnt lgkmcnt(3)
	v_mfma_f32_16x16x32_bf16 v[98:101], v[186:189], v[154:157], v[98:101]
	v_mfma_f32_16x16x32_bf16 v[102:105], v[186:189], v[170:173], v[102:105]
	ds_read_b128 v[186:189], v237 offset:8192
	s_waitcnt lgkmcnt(3)
	v_mfma_f32_16x16x32_bf16 v[106:109], v[190:193], v[154:157], v[106:109]
	v_mfma_f32_16x16x32_bf16 v[110:113], v[190:193], v[170:173], v[110:113]
	ds_read_b128 v[190:193], v237 offset:12288
	s_waitcnt lgkmcnt(3)
	v_mfma_f32_16x16x32_bf16 v[82:85], v[178:181], v[158:161], v[82:85]
	v_mfma_f32_16x16x32_bf16 v[86:89], v[178:181], v[174:177], v[86:89]
	s_waitcnt lgkmcnt(2)
	v_mfma_f32_16x16x32_bf16 v[90:93], v[182:185], v[158:161], v[90:93]
	v_mfma_f32_16x16x32_bf16 v[94:97], v[182:185], v[174:177], v[94:97]
	s_waitcnt lgkmcnt(1)
	v_mfma_f32_16x16x32_bf16 v[98:101], v[186:189], v[158:161], v[98:101]
	v_mfma_f32_16x16x32_bf16 v[102:105], v[186:189], v[174:177], v[102:105]
	s_waitcnt lgkmcnt(0)
	v_mfma_f32_16x16x32_bf16 v[106:109], v[190:193], v[158:161], v[106:109]
	v_mfma_f32_16x16x32_bf16 v[110:113], v[190:193], v[174:177], v[110:113]
	s_nop 7
	v_exp_f32_e32 v82, v82
	v_exp_f32_e32 v83, v83
	v_exp_f32_e32 v84, v84
	v_exp_f32_e32 v85, v85
	v_exp_f32_e32 v86, v86
	v_exp_f32_e32 v87, v87
	v_exp_f32_e32 v88, v88
	v_exp_f32_e32 v89, v89
	v_exp_f32_e32 v90, v90
	v_exp_f32_e32 v91, v91
	v_exp_f32_e32 v92, v92
	v_exp_f32_e32 v93, v93
	v_exp_f32_e32 v94, v94
	v_exp_f32_e32 v95, v95
	v_exp_f32_e32 v96, v96
	v_exp_f32_e32 v97, v97
	v_exp_f32_e32 v98, v98
	v_exp_f32_e32 v99, v99
	v_exp_f32_e32 v100, v100
	v_exp_f32_e32 v101, v101
	v_exp_f32_e32 v102, v102
	v_exp_f32_e32 v103, v103
	v_exp_f32_e32 v104, v104
	v_exp_f32_e32 v105, v105
	v_exp_f32_e32 v106, v106
	v_exp_f32_e32 v107, v107
	v_exp_f32_e32 v108, v108
	v_exp_f32_e32 v109, v109
	v_exp_f32_e32 v110, v110
	v_exp_f32_e32 v111, v111
	v_exp_f32_e32 v112, v112
	v_exp_f32_e32 v113, v113
	ds_read_b128 v[178:181], v234 offset:16384
	ds_read_b128 v[182:185], v234 offset:20480
	ds_read_b128 v[186:189], v234 offset:24576
	ds_read_b128 v[190:193], v234 offset:28672
	s_mov_b32 s15, 0
	s_cmp_lt_u32 s53, 256
	s_cbranch_scc0 .Lattn_v2
.Lattn_loop1:
	s_barrier
	s_waitcnt lgkmcnt(3)
	v_mfma_f32_16x16x32_bf16 v[114:117], v[178:181], v[146:149], v[2:5]
	v_add_f32_e32 v250, v82, v250
	s_add_u32 s98, s98, 0x8000
	s_addc_u32 s99, s99, 0
	s_add_u32 s100, s100, 0x8000
	s_addc_u32 s101, s101, 0
	v_mfma_f32_16x16x32_bf16 v[118:121], v[178:181], v[162:165], v[2:5]
	ds_read_b128 v[178:181], v235 offset:16384
	v_add_f32_e32 v250, v83, v250
	v_add_f32_e32 v250, v84, v250
	s_waitcnt lgkmcnt(3)
	v_mfma_f32_16x16x32_bf16 v[122:125], v[182:185], v[146:149], v[2:5]
	v_add_f32_e32 v250, v85, v250
	s_add_u32 m0, s79, 0
	s_nop 0
	global_load_lds_dwordx4 v246, s[98:99]
	v_mfma_f32_16x16x32_bf16 v[126:129], v[182:185], v[162:165], v[2:5]
	ds_read_b128 v[182:185], v235 offset:20480
	v_add_f32_e32 v250, v90, v250
	v_add_f32_e32 v250, v91, v250
	s_waitcnt lgkmcnt(3)
	v_mfma_f32_16x16x32_bf16 v[130:133], v[186:189], v[146:149], v[2:5]
	v_add_f32_e32 v250, v92, v250
	v_mfma_f32_16x16x32_bf16 v[134:137], v[186:189], v[162:165], v[2:5]
	ds_read_b128 v[186:189], v235 offset:24576
	v_add_f32_e32 v250, v93, v250
	v_cvt_pk_bf16_f32 v82, v82, v83
	s_waitcnt lgkmcnt(3)
	v_mfma_f32_16x16x32_bf16 v[138:141], v[190:193], v[146:149], v[2:5]
	v_cvt_pk_bf16_f32 v83, v84, v85
	s_add_u32 m0, s79, 1024
	s_nop 0
	global_load_lds_dwordx4 v247, s[98:99]
	v_mfma_f32_16x16x32_bf16 v[142:145], v[190:193], v[162:165], v[2:5]
	ds_read_b128 v[190:193], v235 offset:28672
	v_cvt_pk_bf16_f32 v84, v90, v91
	v_cvt_pk_bf16_f32 v85, v92, v93
	s_waitcnt lgkmcnt(3)
	v_mfma_f32_16x16x32_bf16 v[114:117], v[178:181], v[150:153], v[114:117]
	v_add_f32_e32 v251, v86, v251
	v_mfma_f32_16x16x32_bf16 v[118:121], v[178:181], v[166:169], v[118:121]
	ds_read_b128 v[178:181], v236 offset:16384
	v_add_f32_e32 v251, v87, v251
	v_add_f32_e32 v251, v88, v251
	s_waitcnt lgkmcnt(3)
	v_mfma_f32_16x16x32_bf16 v[122:125], v[182:185], v[150:153], v[122:125]
	v_add_f32_e32 v251, v89, v251
	s_add_u32 m0, s80, 32768
	s_nop 0
	global_load_lds_dwordx4 v248, s[100:101]
	v_mfma_f32_16x16x32_bf16 v[126:129], v[182:185], v[166:169], v[126:129]
	ds_read_b128 v[182:185], v236 offset:20480
	v_add_f32_e32 v251, v94, v251
	v_add_f32_e32 v251, v95, v251
	s_waitcnt lgkmcnt(3)
	v_mfma_f32_16x16x32_bf16 v[130:133], v[186:189], v[150:153], v[130:133]
	v_add_f32_e32 v251, v96, v251
	v_mfma_f32_16x16x32_bf16 v[134:137], v[186:189], v[166:169], v[134:137]
	ds_read_b128 v[186:189], v236 offset:24576
	v_add_f32_e32 v251, v97, v251
	v_cvt_pk_bf16_f32 v86, v86, v87
	s_waitcnt lgkmcnt(3)
	v_mfma_f32_16x16x32_bf16 v[138:141], v[190:193], v[150:153], v[138:141]
	v_cvt_pk_bf16_f32 v87, v88, v89
	s_add_u32 m0, s80, 33792
	s_nop 0
	global_load_lds_dwordx4 v249, s[100:101]
	v_mfma_f32_16x16x32_bf16 v[142:145], v[190:193], v[166:169], v[142:145]
	ds_read_b128 v[190:193], v236 offset:28672
	v_cvt_pk_bf16_f32 v88, v94, v95
	v_cvt_pk_bf16_f32 v89, v96, v97
	s_waitcnt lgkmcnt(3)
	v_mfma_f32_16x16x32_bf16 v[114:117], v[178:181], v[154:157], v[114:117]
	v_add_f32_e32 v250, v98, v250
	v_mfma_f32_16x16x32_bf16 v[118:121], v[178:181], v[170:173], v[118:121]
	ds_read_b128 v[178:181], v237 offset:16384
	v_add_f32_e32 v250, v99, v250
	v_add_f32_e32 v250, v100, v250
	s_waitcnt lgkmcnt(3)
; #define SBAR() __builtin_amdgcn_sched_barrier(0)
; #define SLOAD(i, k0) do { sr_[i].vs0 = St::ld8(&Vh[(long)((k0) + sr) * LDK + sc]); sr_[i].vs1 = St::ld8(&Vh[(long)((k0) + 32 + sr) * LDK + sc]); \
;     sr_[i].ks0 = St::ld8(&Kh[(long)((k0) + sr) * LDK + sc]); sr_[i].ks1 = St::ld8(&Kh[(long)((k0) + 32 + sr) * LDK + sc]); } while (0)
; #define SWAIT() do { if constexpr (SDEPTH == 2) asm volatile("s_waitcnt vmcnt(4)" ::: "memory"); else asm volatile("s_waitcnt vmcnt(0)" ::: "memory"); } while (0)
; template <int D0> __device__ __forceinline__ void pv_one(f32x16& od, int vb, bf16x8 pa0, bf16x8 pa1, bf16x8 pa2, bf16x8 pa3) {
;   const s16x4 l0 = tr_read<v_rd_off(D0, 0, 0)>(vb), h0 = tr_read<v_rd_off(D0, 0, 1)>(vb), l1 = tr_read<v_rd_off(D0, 1, 0)>(vb), h1 = tr_read<v_rd_off(D0, 1, 1)>(vb);
;   const s16x4 l2 = tr_read<v_rd_off(D0, 2, 0)>(vb), h2 = tr_read<v_rd_off(D0, 2, 1)>(vb), l3 = tr_read<v_rd_off(D0, 3, 0)>(vb), h3 = tr_read<v_rd_off(D0, 3, 1)>(vb);
;   asm volatile("s_waitcnt lgkmcnt(0)" ::: "memory"); SBAR();
;     ...
;   od = __builtin_amdgcn_mfma_f32_32x32x16_bf16(pa0, PK(l0, h0), od, 0, 0, 0);
;   od = __builtin_amdgcn_mfma_f32_32x32x16_bf16(pa1, PK(l1, h1), od, 0, 0, 0);
;   od = __builtin_amdgcn_mfma_f32_32x32x16_bf16(pa2, PK(l2, h2), od, 0, 0, 0);
;   od = __builtin_amdgcn_mfma_f32_32x32x16_bf16(pa3, PK(l3, h3), od, 0, 0, 0);
; template <typename TQ> ...
;     ...
;   for (int j = 1; j + 1 < NT; j += 2) {
;     SBAR(); SLOAD(SO, (j + SDEPTH) * KVBLK); SBAR();
;     qkt(pB0, pB1, (bf16*)((char*)K_lds + SHM_K), qr, r32, hi, negm);
;     finishSM(pA0, pA1, l_reg, pa0, pa1, pa2, pa3); SBAR();
;     pv_d0(o, vb0, pa0, pa1, pa2, pa3); partialSM(pB0, pB1, mC);
;     __syncthreads(); SWAIT(); SWRITE(0, SE);
;     __syncthreads();
;     SBAR(); if (SDEPTH == 1 || j + 3 < NT) SLOAD(SE, (j + 1 + SDEPTH) * KVBLK); SBAR();
;     qkt(pA0, pA1, K_lds, qr, r32, hi, negm);
;     finishSM(pB0, pB1, l_reg, pa0, pa1, pa2, pa3); SBAR();
;     pv_d0(o, vb0 + (int)SHM_V, pa0, pa1, pa2, pa3); partialSM(pA0, pA1, mC);
	v_mfma_f32_16x16x32_bf16 v[122:125], v[182:185], v[154:157], v[122:125]
	v_add_f32_e32 v250, v101, v250
	v_mfma_f32_16x16x32_bf16 v[126:129], v[182:185], v[170:173], v[126:129]
	ds_read_b128 v[182:185], v237 offset:20480
	v_add_f32_e32 v250, v106, v250
	v_add_f32_e32 v250, v107, v250
	s_waitcnt lgkmcnt(3)
	v_mfma_f32_16x16x32_bf16 v[130:133], v[186:189], v[154:157], v[130:133]
	v_add_f32_e32 v250, v108, v250
	ds_read_b64_tr_b16 v[202:203], v238 offset:0
	ds_read_b64_tr_b16 v[204:205], v238 offset:4096
	v_mfma_f32_16x16x32_bf16 v[134:137], v[186:189], v[170:173], v[134:137]
	ds_read_b128 v[186:189], v237 offset:24576
	v_add_f32_e32 v250, v109, v250
	v_cvt_pk_bf16_f32 v98, v98, v99
	s_waitcnt lgkmcnt(5)
	v_mfma_f32_16x16x32_bf16 v[138:141], v[190:193], v[154:157], v[138:141]
	v_cvt_pk_bf16_f32 v99, v100, v101
	ds_read_b64_tr_b16 v[206:207], v239 offset:0
	ds_read_b64_tr_b16 v[208:209], v239 offset:4096
	v_mfma_f32_16x16x32_bf16 v[142:145], v[190:193], v[170:173], v[142:145]
	ds_read_b128 v[190:193], v237 offset:28672
	v_cvt_pk_bf16_f32 v100, v106, v107
	v_cvt_pk_bf16_f32 v101, v108, v109
	s_waitcnt lgkmcnt(7)
	v_mfma_f32_16x16x32_bf16 v[114:117], v[178:181], v[158:161], v[114:117]
	v_add_f32_e32 v251, v102, v251
	ds_read_b64_tr_b16 v[210:211], v240 offset:0
	ds_read_b64_tr_b16 v[212:213], v240 offset:4096
	v_mfma_f32_16x16x32_bf16 v[118:121], v[178:181], v[174:177], v[118:121]
	v_add_f32_e32 v251, v103, v251
	v_add_f32_e32 v251, v104, v251
	s_waitcnt lgkmcnt(8)
	v_mfma_f32_16x16x32_bf16 v[122:125], v[182:185], v[158:161], v[122:125]
	v_add_f32_e32 v251, v105, v251
	ds_read_b64_tr_b16 v[214:215], v241 offset:0
	ds_read_b64_tr_b16 v[216:217], v241 offset:4096
	v_mfma_f32_16x16x32_bf16 v[126:129], v[182:185], v[174:177], v[126:129]
	v_add_f32_e32 v251, v110, v251
	v_add_f32_e32 v251, v111, v251
	s_waitcnt lgkmcnt(7)
	v_mfma_f32_16x16x32_bf16 v[130:133], v[186:189], v[158:161], v[130:133]
	v_add_f32_e32 v251, v112, v251
	ds_read_b64_tr_b16 v[218:219], v242 offset:0
	ds_read_b64_tr_b16 v[220:221], v242 offset:4096
	v_mfma_f32_16x16x32_bf16 v[134:137], v[186:189], v[174:177], v[134:137]
	v_add_f32_e32 v251, v113, v251
	v_cvt_pk_bf16_f32 v102, v102, v103
	s_waitcnt lgkmcnt(6)
	v_mfma_f32_16x16x32_bf16 v[138:141], v[190:193], v[158:161], v[138:141]
	v_cvt_pk_bf16_f32 v103, v104, v105
	ds_read_b64_tr_b16 v[222:223], v243 offset:0
	ds_read_b64_tr_b16 v[224:225], v243 offset:4096
	v_mfma_f32_16x16x32_bf16 v[142:145], v[190:193], v[174:177], v[142:145]
	v_cvt_pk_bf16_f32 v104, v110, v111
	v_cvt_pk_bf16_f32 v105, v112, v113
	v_mfma_f32_16x16x32_bf16 v[18:21], v[202:205], v[82:85], v[18:21]
	v_exp_f32_e32 v114, v114
	v_mfma_f32_16x16x32_bf16 v[22:25], v[202:205], v[86:89], v[22:25]
	ds_read_b64_tr_b16 v[202:203], v244 offset:0
	ds_read_b64_tr_b16 v[204:205], v244 offset:4096
	v_exp_f32_e32 v115, v115
	v_mfma_f32_16x16x32_bf16 v[26:29], v[206:209], v[82:85], v[26:29]
	v_exp_f32_e32 v116, v116
	v_mfma_f32_16x16x32_bf16 v[30:33], v[206:209], v[86:89], v[30:33]
	ds_read_b64_tr_b16 v[206:207], v245 offset:0
	ds_read_b64_tr_b16 v[208:209], v245 offset:4096
	v_exp_f32_e32 v117, v117
	s_waitcnt lgkmcnt(10)
	v_mfma_f32_16x16x32_bf16 v[34:37], v[210:213], v[82:85], v[34:37]
	v_exp_f32_e32 v118, v118
	v_mfma_f32_16x16x32_bf16 v[38:41], v[210:213], v[86:89], v[38:41]
	ds_read_b64_tr_b16 v[210:211], v238 offset:8192
	ds_read_b64_tr_b16 v[212:213], v238 offset:12288
	v_exp_f32_e32 v119, v119
	s_waitcnt lgkmcnt(10)
	v_mfma_f32_16x16x32_bf16 v[42:45], v[214:217], v[82:85], v[42:45]
	v_exp_f32_e32 v120, v120
	v_mfma_f32_16x16x32_bf16 v[46:49], v[214:217], v[86:89], v[46:49]
	ds_read_b64_tr_b16 v[214:215], v239 offset:8192
	ds_read_b64_tr_b16 v[216:217], v239 offset:12288
	v_exp_f32_e32 v121, v121
	s_waitcnt lgkmcnt(10)
	v_mfma_f32_16x16x32_bf16 v[50:53], v[218:221], v[82:85], v[50:53]
	v_exp_f32_e32 v122, v122
	v_mfma_f32_16x16x32_bf16 v[54:57], v[218:221], v[86:89], v[54:57]
	ds_read_b64_tr_b16 v[218:219], v240 offset:8192
	ds_read_b64_tr_b16 v[220:221], v240 offset:12288
	v_exp_f32_e32 v123, v123
	s_waitcnt lgkmcnt(10)
	v_mfma_f32_16x16x32_bf16 v[58:61], v[222:225], v[82:85], v[58:61]
	v_exp_f32_e32 v124, v124
	v_mfma_f32_16x16x32_bf16 v[62:65], v[222:225], v[86:89], v[62:65]
	ds_read_b64_tr_b16 v[222:223], v241 offset:8192
	ds_read_b64_tr_b16 v[224:225], v241 offset:12288
	v_exp_f32_e32 v125, v125
	s_waitcnt lgkmcnt(10)
	v_mfma_f32_16x16x32_bf16 v[66:69], v[202:205], v[82:85], v[66:69]
	v_exp_f32_e32 v126, v126
	v_mfma_f32_16x16x32_bf16 v[70:73], v[202:205], v[86:89], v[70:73]
	ds_read_b64_tr_b16 v[202:203], v242 offset:8192
	ds_read_b64_tr_b16 v[204:205], v242 offset:12288
	v_exp_f32_e32 v127, v127
	s_waitcnt lgkmcnt(10)
	v_mfma_f32_16x16x32_bf16 v[74:77], v[206:209], v[82:85], v[74:77]
	v_exp_f32_e32 v128, v128
	v_mfma_f32_16x16x32_bf16 v[78:81], v[206:209], v[86:89], v[78:81]
	ds_read_b64_tr_b16 v[206:207], v243 offset:8192
	ds_read_b64_tr_b16 v[208:209], v243 offset:12288
	v_exp_f32_e32 v129, v129
	s_waitcnt lgkmcnt(10)
	v_mfma_f32_16x16x32_bf16 v[18:21], v[210:213], v[98:101], v[18:21]
	v_exp_f32_e32 v130, v130
	v_mfma_f32_16x16x32_bf16 v[22:25], v[210:213], v[102:105], v[22:25]
	ds_read_b64_tr_b16 v[210:211], v244 offset:8192
	ds_read_b64_tr_b16 v[212:213], v244 offset:12288
	v_exp_f32_e32 v131, v131
	s_waitcnt lgkmcnt(10)
	v_mfma_f32_16x16x32_bf16 v[26:29], v[214:217], v[98:101], v[26:29]
	v_exp_f32_e32 v132, v132
	v_mfma_f32_16x16x32_bf16 v[30:33], v[214:217], v[102:105], v[30:33]
	ds_read_b64_tr_b16 v[214:215], v245 offset:8192
	ds_read_b64_tr_b16 v[216:217], v245 offset:12288
	v_exp_f32_e32 v133, v133
	s_waitcnt lgkmcnt(10)
; #define SBAR() __builtin_amdgcn_sched_barrier(0)
; #define SLOAD(i, k0) do { sr_[i].vs0 = St::ld8(&Vh[(long)((k0) + sr) * LDK + sc]); sr_[i].vs1 = St::ld8(&Vh[(long)((k0) + 32 + sr) * LDK + sc]); \
;     sr_[i].ks0 = St::ld8(&Kh[(long)((k0) + sr) * LDK + sc]); sr_[i].ks1 = St::ld8(&Kh[(long)((k0) + 32 + sr) * LDK + sc]); } while (0)
; #define SWAIT() do { if constexpr (SDEPTH == 2) asm volatile("s_waitcnt vmcnt(4)" ::: "memory"); else asm volatile("s_waitcnt vmcnt(0)" ::: "memory"); } while (0)
; template <typename TQ> ...
;     ...
;   for (int j = 1; j + 1 < NT; j += 2) {
;     SBAR(); SLOAD(SO, (j + SDEPTH) * KVBLK); SBAR();
;     qkt(pB0, pB1, (bf16*)((char*)K_lds + SHM_K), qr, r32, hi, negm);
;     finishSM(pA0, pA1, l_reg, pa0, pa1, pa2, pa3); SBAR();
;     pv_d0(o, vb0, pa0, pa1, pa2, pa3); partialSM(pB0, pB1, mC);
;     __syncthreads(); SWAIT(); SWRITE(0, SE);
;     __syncthreads();
;     SBAR(); if (SDEPTH == 1 || j + 3 < NT) SLOAD(SE, (j + 1 + SDEPTH) * KVBLK); SBAR();
;     qkt(pA0, pA1, K_lds, qr, r32, hi, negm);
;     finishSM(pB0, pB1, l_reg, pa0, pa1, pa2, pa3); SBAR();
;     pv_d0(o, vb0 + (int)SHM_V, pa0, pa1, pa2, pa3); partialSM(pA0, pA1, mC);
;     __syncthreads(); SWAIT(); SWRITE(1, SO);
;     __syncthreads();
	v_mfma_f32_16x16x32_bf16 v[34:37], v[218:221], v[98:101], v[34:37]
	v_exp_f32_e32 v134, v134
	v_mfma_f32_16x16x32_bf16 v[38:41], v[218:221], v[102:105], v[38:41]
	v_exp_f32_e32 v135, v135
	s_waitcnt lgkmcnt(8)
	v_mfma_f32_16x16x32_bf16 v[42:45], v[222:225], v[98:101], v[42:45]
	v_exp_f32_e32 v136, v136
	v_mfma_f32_16x16x32_bf16 v[46:49], v[222:225], v[102:105], v[46:49]
	v_exp_f32_e32 v137, v137
	s_waitcnt lgkmcnt(6)
	v_mfma_f32_16x16x32_bf16 v[50:53], v[202:205], v[98:101], v[50:53]
	v_exp_f32_e32 v138, v138
	ds_read_b128 v[178:181], v234 offset:32768
	v_mfma_f32_16x16x32_bf16 v[54:57], v[202:205], v[102:105], v[54:57]
	v_exp_f32_e32 v139, v139
	s_waitcnt lgkmcnt(5)
	v_mfma_f32_16x16x32_bf16 v[58:61], v[206:209], v[98:101], v[58:61]
	v_exp_f32_e32 v140, v140
	ds_read_b128 v[182:185], v234 offset:36864
	v_mfma_f32_16x16x32_bf16 v[62:65], v[206:209], v[102:105], v[62:65]
	v_exp_f32_e32 v141, v141
	s_waitcnt lgkmcnt(4)
	v_mfma_f32_16x16x32_bf16 v[66:69], v[210:213], v[98:101], v[66:69]
	v_exp_f32_e32 v142, v142
	ds_read_b128 v[186:189], v234 offset:40960
	v_mfma_f32_16x16x32_bf16 v[70:73], v[210:213], v[102:105], v[70:73]
	v_exp_f32_e32 v143, v143
	s_waitcnt lgkmcnt(3)
	v_mfma_f32_16x16x32_bf16 v[74:77], v[214:217], v[98:101], v[74:77]
	v_exp_f32_e32 v144, v144
	ds_read_b128 v[190:193], v234 offset:45056
	v_mfma_f32_16x16x32_bf16 v[78:81], v[214:217], v[102:105], v[78:81]
	v_exp_f32_e32 v145, v145
	s_waitcnt vmcnt(4)
	s_barrier
	s_waitcnt lgkmcnt(3)
	v_mfma_f32_16x16x32_bf16 v[82:85], v[178:181], v[146:149], v[2:5]
	v_add_f32_e32 v250, v114, v250
	s_add_u32 s98, s98, 0x8000
	s_addc_u32 s99, s99, 0
	s_add_u32 s100, s100, 0x8000
	s_addc_u32 s101, s101, 0
	v_mfma_f32_16x16x32_bf16 v[86:89], v[178:181], v[162:165], v[2:5]
	ds_read_b128 v[178:181], v235 offset:32768
	v_add_f32_e32 v250, v115, v250
	v_add_f32_e32 v250, v116, v250
	s_waitcnt lgkmcnt(3)
	v_mfma_f32_16x16x32_bf16 v[90:93], v[182:185], v[146:149], v[2:5]
	v_add_f32_e32 v250, v117, v250
	s_add_u32 m0, s79, 16384
	s_nop 0
	global_load_lds_dwordx4 v246, s[98:99]
	v_mfma_f32_16x16x32_bf16 v[94:97], v[182:185], v[162:165], v[2:5]
	ds_read_b128 v[182:185], v235 offset:36864
	v_add_f32_e32 v250, v122, v250
	v_add_f32_e32 v250, v123, v250
	s_waitcnt lgkmcnt(3)
	v_mfma_f32_16x16x32_bf16 v[98:101], v[186:189], v[146:149], v[2:5]
	v_add_f32_e32 v250, v124, v250
	v_mfma_f32_16x16x32_bf16 v[102:105], v[186:189], v[162:165], v[2:5]
	ds_read_b128 v[186:189], v235 offset:40960
	v_add_f32_e32 v250, v125, v250
	v_cvt_pk_bf16_f32 v114, v114, v115
	s_waitcnt lgkmcnt(3)
	v_mfma_f32_16x16x32_bf16 v[106:109], v[190:193], v[146:149], v[2:5]
	v_cvt_pk_bf16_f32 v115, v116, v117
	s_add_u32 m0, s79, 17408
	s_nop 0
	global_load_lds_dwordx4 v247, s[98:99]
	v_mfma_f32_16x16x32_bf16 v[110:113], v[190:193], v[162:165], v[2:5]
	ds_read_b128 v[190:193], v235 offset:45056
	v_cvt_pk_bf16_f32 v116, v122, v123
	v_cvt_pk_bf16_f32 v117, v124, v125
	s_waitcnt lgkmcnt(3)
	v_mfma_f32_16x16x32_bf16 v[82:85], v[178:181], v[150:153], v[82:85]
	v_add_f32_e32 v251, v118, v251
	v_mfma_f32_16x16x32_bf16 v[86:89], v[178:181], v[166:169], v[86:89]
	ds_read_b128 v[178:181], v236 offset:32768
	v_add_f32_e32 v251, v119, v251
	v_add_f32_e32 v251, v120, v251
	s_waitcnt lgkmcnt(3)
	v_mfma_f32_16x16x32_bf16 v[90:93], v[182:185], v[150:153], v[90:93]
	v_add_f32_e32 v251, v121, v251
	s_add_u32 m0, s80, 49152
	s_nop 0
	global_load_lds_dwordx4 v248, s[100:101]
	v_mfma_f32_16x16x32_bf16 v[94:97], v[182:185], v[166:169], v[94:97]
	ds_read_b128 v[182:185], v236 offset:36864
	v_add_f32_e32 v251, v126, v251
	v_add_f32_e32 v251, v127, v251
	s_waitcnt lgkmcnt(3)
	v_mfma_f32_16x16x32_bf16 v[98:101], v[186:189], v[150:153], v[98:101]
	v_add_f32_e32 v251, v128, v251
	v_mfma_f32_16x16x32_bf16 v[102:105], v[186:189], v[166:169], v[102:105]
	ds_read_b128 v[186:189], v236 offset:40960
	v_add_f32_e32 v251, v129, v251
	v_cvt_pk_bf16_f32 v118, v118, v119
	s_waitcnt lgkmcnt(3)
	v_mfma_f32_16x16x32_bf16 v[106:109], v[190:193], v[150:153], v[106:109]
	v_cvt_pk_bf16_f32 v119, v120, v121
	s_add_u32 m0, s80, 50176
	s_nop 0
	global_load_lds_dwordx4 v249, s[100:101]
	v_mfma_f32_16x16x32_bf16 v[110:113], v[190:193], v[166:169], v[110:113]
	ds_read_b128 v[190:193], v236 offset:45056
	v_cvt_pk_bf16_f32 v120, v126, v127
	v_cvt_pk_bf16_f32 v121, v128, v129
	s_waitcnt lgkmcnt(3)
	v_mfma_f32_16x16x32_bf16 v[82:85], v[178:181], v[154:157], v[82:85]
	v_add_f32_e32 v250, v130, v250
	v_mfma_f32_16x16x32_bf16 v[86:89], v[178:181], v[170:173], v[86:89]
	ds_read_b128 v[178:181], v237 offset:32768
	v_add_f32_e32 v250, v131, v250
	v_add_f32_e32 v250, v132, v250
	s_waitcnt lgkmcnt(3)
	v_mfma_f32_16x16x32_bf16 v[90:93], v[182:185], v[154:157], v[90:93]
	v_add_f32_e32 v250, v133, v250
	v_mfma_f32_16x16x32_bf16 v[94:97], v[182:185], v[170:173], v[94:97]
	ds_read_b128 v[182:185], v237 offset:36864
	v_add_f32_e32 v250, v138, v250
	v_add_f32_e32 v250, v139, v250
	s_waitcnt lgkmcnt(3)
	v_mfma_f32_16x16x32_bf16 v[98:101], v[186:189], v[154:157], v[98:101]
	v_add_f32_e32 v250, v140, v250
	ds_read_b64_tr_b16 v[202:203], v238 offset:16384
	ds_read_b64_tr_b16 v[204:205], v238 offset:20480
	v_mfma_f32_16x16x32_bf16 v[102:105], v[186:189], v[170:173], v[102:105]
	ds_read_b128 v[186:189], v237 offset:40960
	v_add_f32_e32 v250, v141, v250
	v_cvt_pk_bf16_f32 v130, v130, v131
	s_waitcnt lgkmcnt(5)
	v_mfma_f32_16x16x32_bf16 v[106:109], v[190:193], v[154:157], v[106:109]
	v_cvt_pk_bf16_f32 v131, v132, v133
	ds_read_b64_tr_b16 v[206:207], v239 offset:16384
	ds_read_b64_tr_b16 v[208:209], v239 offset:20480
	v_mfma_f32_16x16x32_bf16 v[110:113], v[190:193], v[170:173], v[110:113]
	ds_read_b128 v[190:193], v237 offset:45056
	v_cvt_pk_bf16_f32 v132, v138, v139
	v_cvt_pk_bf16_f32 v133, v140, v141
	s_waitcnt lgkmcnt(7)
; #define SBAR() __builtin_amdgcn_sched_barrier(0)
; #define SLOAD(i, k0) do { sr_[i].vs0 = St::ld8(&Vh[(long)((k0) + sr) * LDK + sc]); sr_[i].vs1 = St::ld8(&Vh[(long)((k0) + 32 + sr) * LDK + sc]); \
;     sr_[i].ks0 = St::ld8(&Kh[(long)((k0) + sr) * LDK + sc]); sr_[i].ks1 = St::ld8(&Kh[(long)((k0) + 32 + sr) * LDK + sc]); } while (0)
; #define SWAIT() do { if constexpr (SDEPTH == 2) asm volatile("s_waitcnt vmcnt(4)" ::: "memory"); else asm volatile("s_waitcnt vmcnt(0)" ::: "memory"); } while (0)
; template <typename TQ> ...
;     ...
;   for (int j = 1; j + 1 < NT; j += 2) {
;     SBAR(); SLOAD(SO, (j + SDEPTH) * KVBLK); SBAR();
;     qkt(pB0, pB1, (bf16*)((char*)K_lds + SHM_K), qr, r32, hi, negm);
;     finishSM(pA0, pA1, l_reg, pa0, pa1, pa2, pa3); SBAR();
;     pv_d0(o, vb0, pa0, pa1, pa2, pa3); partialSM(pB0, pB1, mC);
;     __syncthreads(); SWAIT(); SWRITE(0, SE);
;     __syncthreads();
;     SBAR(); if (SDEPTH == 1 || j + 3 < NT) SLOAD(SE, (j + 1 + SDEPTH) * KVBLK); SBAR();
;     qkt(pA0, pA1, K_lds, qr, r32, hi, negm);
;     finishSM(pB0, pB1, l_reg, pa0, pa1, pa2, pa3); SBAR();
;     pv_d0(o, vb0 + (int)SHM_V, pa0, pa1, pa2, pa3); partialSM(pA0, pA1, mC);
;     __syncthreads(); SWAIT(); SWRITE(1, SO);
;     __syncthreads();
	v_mfma_f32_16x16x32_bf16 v[82:85], v[178:181], v[158:161], v[82:85]
	v_add_f32_e32 v251, v134, v251
	ds_read_b64_tr_b16 v[210:211], v240 offset:16384
	ds_read_b64_tr_b16 v[212:213], v240 offset:20480
	v_mfma_f32_16x16x32_bf16 v[86:89], v[178:181], v[174:177], v[86:89]
	v_add_f32_e32 v251, v135, v251
	v_add_f32_e32 v251, v136, v251
	s_waitcnt lgkmcnt(8)
	v_mfma_f32_16x16x32_bf16 v[90:93], v[182:185], v[158:161], v[90:93]
	v_add_f32_e32 v251, v137, v251
	ds_read_b64_tr_b16 v[214:215], v241 offset:16384
	ds_read_b64_tr_b16 v[216:217], v241 offset:20480
	v_mfma_f32_16x16x32_bf16 v[94:97], v[182:185], v[174:177], v[94:97]
	v_add_f32_e32 v251, v142, v251
	v_add_f32_e32 v251, v143, v251
	s_waitcnt lgkmcnt(7)
	v_mfma_f32_16x16x32_bf16 v[98:101], v[186:189], v[158:161], v[98:101]
	v_add_f32_e32 v251, v144, v251
	ds_read_b64_tr_b16 v[218:219], v242 offset:16384
	ds_read_b64_tr_b16 v[220:221], v242 offset:20480
	v_mfma_f32_16x16x32_bf16 v[102:105], v[186:189], v[174:177], v[102:105]
	v_add_f32_e32 v251, v145, v251
	v_cvt_pk_bf16_f32 v134, v134, v135
	s_waitcnt lgkmcnt(6)
	v_mfma_f32_16x16x32_bf16 v[106:109], v[190:193], v[158:161], v[106:109]
	v_cvt_pk_bf16_f32 v135, v136, v137
	ds_read_b64_tr_b16 v[222:223], v243 offset:16384
	ds_read_b64_tr_b16 v[224:225], v243 offset:20480
	v_mfma_f32_16x16x32_bf16 v[110:113], v[190:193], v[174:177], v[110:113]
	v_cvt_pk_bf16_f32 v136, v142, v143
	v_cvt_pk_bf16_f32 v137, v144, v145
	v_mfma_f32_16x16x32_bf16 v[18:21], v[202:205], v[114:117], v[18:21]
	v_exp_f32_e32 v82, v82
	v_mfma_f32_16x16x32_bf16 v[22:25], v[202:205], v[118:121], v[22:25]
	ds_read_b64_tr_b16 v[202:203], v244 offset:16384
	ds_read_b64_tr_b16 v[204:205], v244 offset:20480
	v_exp_f32_e32 v83, v83
	v_mfma_f32_16x16x32_bf16 v[26:29], v[206:209], v[114:117], v[26:29]
	v_exp_f32_e32 v84, v84
	v_mfma_f32_16x16x32_bf16 v[30:33], v[206:209], v[118:121], v[30:33]
	ds_read_b64_tr_b16 v[206:207], v245 offset:16384
	ds_read_b64_tr_b16 v[208:209], v245 offset:20480
	v_exp_f32_e32 v85, v85
	s_waitcnt lgkmcnt(10)
	v_mfma_f32_16x16x32_bf16 v[34:37], v[210:213], v[114:117], v[34:37]
	v_exp_f32_e32 v86, v86
	v_mfma_f32_16x16x32_bf16 v[38:41], v[210:213], v[118:121], v[38:41]
	ds_read_b64_tr_b16 v[210:211], v238 offset:24576
	ds_read_b64_tr_b16 v[212:213], v238 offset:28672
	v_exp_f32_e32 v87, v87
	s_waitcnt lgkmcnt(10)
	v_mfma_f32_16x16x32_bf16 v[42:45], v[214:217], v[114:117], v[42:45]
	v_exp_f32_e32 v88, v88
	v_mfma_f32_16x16x32_bf16 v[46:49], v[214:217], v[118:121], v[46:49]
	ds_read_b64_tr_b16 v[214:215], v239 offset:24576
	ds_read_b64_tr_b16 v[216:217], v239 offset:28672
	v_exp_f32_e32 v89, v89
	s_waitcnt lgkmcnt(10)
	v_mfma_f32_16x16x32_bf16 v[50:53], v[218:221], v[114:117], v[50:53]
	v_exp_f32_e32 v90, v90
	v_mfma_f32_16x16x32_bf16 v[54:57], v[218:221], v[118:121], v[54:57]
	ds_read_b64_tr_b16 v[218:219], v240 offset:24576
	ds_read_b64_tr_b16 v[220:221], v240 offset:28672
	v_exp_f32_e32 v91, v91
	s_waitcnt lgkmcnt(10)
	v_mfma_f32_16x16x32_bf16 v[58:61], v[222:225], v[114:117], v[58:61]
	v_exp_f32_e32 v92, v92
	v_mfma_f32_16x16x32_bf16 v[62:65], v[222:225], v[118:121], v[62:65]
	ds_read_b64_tr_b16 v[222:223], v241 offset:24576
	ds_read_b64_tr_b16 v[224:225], v241 offset:28672
	v_exp_f32_e32 v93, v93
	s_waitcnt lgkmcnt(10)
	v_mfma_f32_16x16x32_bf16 v[66:69], v[202:205], v[114:117], v[66:69]
	v_exp_f32_e32 v94, v94
	v_mfma_f32_16x16x32_bf16 v[70:73], v[202:205], v[118:121], v[70:73]
	ds_read_b64_tr_b16 v[202:203], v242 offset:24576
	ds_read_b64_tr_b16 v[204:205], v242 offset:28672
	v_exp_f32_e32 v95, v95
	s_waitcnt lgkmcnt(10)
	v_mfma_f32_16x16x32_bf16 v[74:77], v[206:209], v[114:117], v[74:77]
	v_exp_f32_e32 v96, v96
	v_mfma_f32_16x16x32_bf16 v[78:81], v[206:209], v[118:121], v[78:81]
	ds_read_b64_tr_b16 v[206:207], v243 offset:24576
	ds_read_b64_tr_b16 v[208:209], v243 offset:28672
	v_exp_f32_e32 v97, v97
	s_waitcnt lgkmcnt(10)
	v_mfma_f32_16x16x32_bf16 v[18:21], v[210:213], v[130:133], v[18:21]
	v_exp_f32_e32 v98, v98
	v_mfma_f32_16x16x32_bf16 v[22:25], v[210:213], v[134:137], v[22:25]
	ds_read_b64_tr_b16 v[210:211], v244 offset:24576
	ds_read_b64_tr_b16 v[212:213], v244 offset:28672
	v_exp_f32_e32 v99, v99
	s_waitcnt lgkmcnt(10)
	v_mfma_f32_16x16x32_bf16 v[26:29], v[214:217], v[130:133], v[26:29]
	v_exp_f32_e32 v100, v100
	v_mfma_f32_16x16x32_bf16 v[30:33], v[214:217], v[134:137], v[30:33]
	ds_read_b64_tr_b16 v[214:215], v245 offset:24576
	ds_read_b64_tr_b16 v[216:217], v245 offset:28672
	v_exp_f32_e32 v101, v101
	s_waitcnt lgkmcnt(10)
	v_mfma_f32_16x16x32_bf16 v[34:37], v[218:221], v[130:133], v[34:37]
	v_exp_f32_e32 v102, v102
	v_mfma_f32_16x16x32_bf16 v[38:41], v[218:221], v[134:137], v[38:41]
	v_exp_f32_e32 v103, v103
	s_waitcnt lgkmcnt(8)
	v_mfma_f32_16x16x32_bf16 v[42:45], v[222:225], v[130:133], v[42:45]
	v_exp_f32_e32 v104, v104
	v_mfma_f32_16x16x32_bf16 v[46:49], v[222:225], v[134:137], v[46:49]
	v_exp_f32_e32 v105, v105
	s_waitcnt lgkmcnt(6)
	v_mfma_f32_16x16x32_bf16 v[50:53], v[202:205], v[130:133], v[50:53]
	v_exp_f32_e32 v106, v106
	ds_read_b128 v[178:181], v234 offset:49152
	v_mfma_f32_16x16x32_bf16 v[54:57], v[202:205], v[134:137], v[54:57]
	v_exp_f32_e32 v107, v107
	s_waitcnt lgkmcnt(5)
	v_mfma_f32_16x16x32_bf16 v[58:61], v[206:209], v[130:133], v[58:61]
	v_exp_f32_e32 v108, v108
	ds_read_b128 v[182:185], v234 offset:53248
	v_mfma_f32_16x16x32_bf16 v[62:65], v[206:209], v[134:137], v[62:65]
	v_exp_f32_e32 v109, v109
	s_waitcnt lgkmcnt(4)
	v_mfma_f32_16x16x32_bf16 v[66:69], v[210:213], v[130:133], v[66:69]
	v_exp_f32_e32 v110, v110
	ds_read_b128 v[186:189], v234 offset:57344
	v_mfma_f32_16x16x32_bf16 v[70:73], v[210:213], v[134:137], v[70:73]
	v_exp_f32_e32 v111, v111
	s_waitcnt lgkmcnt(3)
	v_mfma_f32_16x16x32_bf16 v[74:77], v[214:217], v[130:133], v[74:77]
	v_exp_f32_e32 v112, v112
	ds_read_b128 v[190:193], v234 offset:61440
	v_mfma_f32_16x16x32_bf16 v[78:81], v[214:217], v[134:137], v[78:81]
	v_exp_f32_e32 v113, v113
	s_waitcnt vmcnt(4)
	s_barrier
; #define SBAR() __builtin_amdgcn_sched_barrier(0)
; #define SLOAD(i, k0) do { sr_[i].vs0 = St::ld8(&Vh[(long)((k0) + sr) * LDK + sc]); sr_[i].vs1 = St::ld8(&Vh[(long)((k0) + 32 + sr) * LDK + sc]); \
;     sr_[i].ks0 = St::ld8(&Kh[(long)((k0) + sr) * LDK + sc]); sr_[i].ks1 = St::ld8(&Kh[(long)((k0) + 32 + sr) * LDK + sc]); } while (0)
; #define SWAIT() do { if constexpr (SDEPTH == 2) asm volatile("s_waitcnt vmcnt(4)" ::: "memory"); else asm volatile("s_waitcnt vmcnt(0)" ::: "memory"); } while (0)
; template <typename TQ> ...
;     ...
;   for (int j = 1; j + 1 < NT; j += 2) {
;     SBAR(); SLOAD(SO, (j + SDEPTH) * KVBLK); SBAR();
;     qkt(pB0, pB1, (bf16*)((char*)K_lds + SHM_K), qr, r32, hi, negm);
;     finishSM(pA0, pA1, l_reg, pa0, pa1, pa2, pa3); SBAR();
;     pv_d0(o, vb0, pa0, pa1, pa2, pa3); partialSM(pB0, pB1, mC);
;     __syncthreads(); SWAIT(); SWRITE(0, SE);
;     __syncthreads();
;     SBAR(); if (SDEPTH == 1 || j + 3 < NT) SLOAD(SE, (j + 1 + SDEPTH) * KVBLK); SBAR();
;     qkt(pA0, pA1, K_lds, qr, r32, hi, negm);
;     finishSM(pB0, pB1, l_reg, pa0, pa1, pa2, pa3); SBAR();
;     pv_d0(o, vb0 + (int)SHM_V, pa0, pa1, pa2, pa3); partialSM(pA0, pA1, mC);
;     __syncthreads(); SWAIT(); SWRITE(1, SO);
;     __syncthreads();
	s_waitcnt lgkmcnt(3)
	v_mfma_f32_16x16x32_bf16 v[114:117], v[178:181], v[146:149], v[2:5]
	v_add_f32_e32 v250, v82, v250
	s_add_u32 s98, s98, 0x8000
	s_addc_u32 s99, s99, 0
	s_add_u32 s100, s100, 0x8000
	s_addc_u32 s101, s101, 0
	v_mfma_f32_16x16x32_bf16 v[118:121], v[178:181], v[162:165], v[2:5]
	ds_read_b128 v[178:181], v235 offset:49152
	v_add_f32_e32 v250, v83, v250
	v_add_f32_e32 v250, v84, v250
	s_waitcnt lgkmcnt(3)
	v_mfma_f32_16x16x32_bf16 v[122:125], v[182:185], v[146:149], v[2:5]
	v_add_f32_e32 v250, v85, v250
	s_add_u32 m0, s79, 32768
	s_nop 0
	global_load_lds_dwordx4 v246, s[98:99]
	v_mfma_f32_16x16x32_bf16 v[126:129], v[182:185], v[162:165], v[2:5]
	ds_read_b128 v[182:185], v235 offset:53248
	v_add_f32_e32 v250, v90, v250
	v_add_f32_e32 v250, v91, v250
	s_waitcnt lgkmcnt(3)
	v_mfma_f32_16x16x32_bf16 v[130:133], v[186:189], v[146:149], v[2:5]
	v_add_f32_e32 v250, v92, v250
	v_mfma_f32_16x16x32_bf16 v[134:137], v[186:189], v[162:165], v[2:5]
	ds_read_b128 v[186:189], v235 offset:57344
	v_add_f32_e32 v250, v93, v250
	v_cvt_pk_bf16_f32 v82, v82, v83
	s_waitcnt lgkmcnt(3)
	v_mfma_f32_16x16x32_bf16 v[138:141], v[190:193], v[146:149], v[2:5]
	v_cvt_pk_bf16_f32 v83, v84, v85
	s_add_u32 m0, s79, 33792
	s_nop 0
	global_load_lds_dwordx4 v247, s[98:99]
	v_mfma_f32_16x16x32_bf16 v[142:145], v[190:193], v[162:165], v[2:5]
	ds_read_b128 v[190:193], v235 offset:61440
	v_cvt_pk_bf16_f32 v84, v90, v91
	v_cvt_pk_bf16_f32 v85, v92, v93
	s_waitcnt lgkmcnt(3)
	v_mfma_f32_16x16x32_bf16 v[114:117], v[178:181], v[150:153], v[114:117]
	v_add_f32_e32 v251, v86, v251
	v_mfma_f32_16x16x32_bf16 v[118:121], v[178:181], v[166:169], v[118:121]
	ds_read_b128 v[178:181], v236 offset:49152
	v_add_f32_e32 v251, v87, v251
	v_add_f32_e32 v251, v88, v251
	s_waitcnt lgkmcnt(3)
	v_mfma_f32_16x16x32_bf16 v[122:125], v[182:185], v[150:153], v[122:125]
	v_add_f32_e32 v251, v89, v251
	s_add_u32 m0, s80, 0
	s_nop 0
	global_load_lds_dwordx4 v248, s[100:101]
	v_mfma_f32_16x16x32_bf16 v[126:129], v[182:185], v[166:169], v[126:129]
	ds_read_b128 v[182:185], v236 offset:53248
	v_add_f32_e32 v251, v94, v251
	v_add_f32_e32 v251, v95, v251
	s_waitcnt lgkmcnt(3)
	v_mfma_f32_16x16x32_bf16 v[130:133], v[186:189], v[150:153], v[130:133]
	v_add_f32_e32 v251, v96, v251
	v_mfma_f32_16x16x32_bf16 v[134:137], v[186:189], v[166:169], v[134:137]
	ds_read_b128 v[186:189], v236 offset:57344
	v_add_f32_e32 v251, v97, v251
	v_cvt_pk_bf16_f32 v86, v86, v87
	s_waitcnt lgkmcnt(3)
	v_mfma_f32_16x16x32_bf16 v[138:141], v[190:193], v[150:153], v[138:141]
	v_cvt_pk_bf16_f32 v87, v88, v89
	s_add_u32 m0, s80, 1024
	s_nop 0
	global_load_lds_dwordx4 v249, s[100:101]
	v_mfma_f32_16x16x32_bf16 v[142:145], v[190:193], v[166:169], v[142:145]
	ds_read_b128 v[190:193], v236 offset:61440
	v_cvt_pk_bf16_f32 v88, v94, v95
	v_cvt_pk_bf16_f32 v89, v96, v97
	s_waitcnt lgkmcnt(3)
	v_mfma_f32_16x16x32_bf16 v[114:117], v[178:181], v[154:157], v[114:117]
	v_add_f32_e32 v250, v98, v250
	v_mfma_f32_16x16x32_bf16 v[118:121], v[178:181], v[170:173], v[118:121]
	ds_read_b128 v[178:181], v237 offset:49152
	v_add_f32_e32 v250, v99, v250
	v_add_f32_e32 v250, v100, v250
	s_waitcnt lgkmcnt(3)
	v_mfma_f32_16x16x32_bf16 v[122:125], v[182:185], v[154:157], v[122:125]
	v_add_f32_e32 v250, v101, v250
	v_mfma_f32_16x16x32_bf16 v[126:129], v[182:185], v[170:173], v[126:129]
	ds_read_b128 v[182:185], v237 offset:53248
	v_add_f32_e32 v250, v106, v250
	v_add_f32_e32 v250, v107, v250
	s_waitcnt lgkmcnt(3)
	v_mfma_f32_16x16x32_bf16 v[130:133], v[186:189], v[154:157], v[130:133]
	v_add_f32_e32 v250, v108, v250
	ds_read_b64_tr_b16 v[202:203], v238 offset:32768
	ds_read_b64_tr_b16 v[204:205], v238 offset:36864
	v_mfma_f32_16x16x32_bf16 v[134:137], v[186:189], v[170:173], v[134:137]
	ds_read_b128 v[186:189], v237 offset:57344
	v_add_f32_e32 v250, v109, v250
	v_cvt_pk_bf16_f32 v98, v98, v99
	s_waitcnt lgkmcnt(5)
	v_mfma_f32_16x16x32_bf16 v[138:141], v[190:193], v[154:157], v[138:141]
	v_cvt_pk_bf16_f32 v99, v100, v101
	ds_read_b64_tr_b16 v[206:207], v239 offset:32768
	ds_read_b64_tr_b16 v[208:209], v239 offset:36864
	v_mfma_f32_16x16x32_bf16 v[142:145], v[190:193], v[170:173], v[142:145]
	ds_read_b128 v[190:193], v237 offset:61440
	v_cvt_pk_bf16_f32 v100, v106, v107
	v_cvt_pk_bf16_f32 v101, v108, v109
	s_waitcnt lgkmcnt(7)
	v_mfma_f32_16x16x32_bf16 v[114:117], v[178:181], v[158:161], v[114:117]
	v_add_f32_e32 v251, v102, v251
	ds_read_b64_tr_b16 v[210:211], v240 offset:32768
	ds_read_b64_tr_b16 v[212:213], v240 offset:36864
	v_mfma_f32_16x16x32_bf16 v[118:121], v[178:181], v[174:177], v[118:121]
	v_add_f32_e32 v251, v103, v251
	v_add_f32_e32 v251, v104, v251
	s_waitcnt lgkmcnt(8)
	v_mfma_f32_16x16x32_bf16 v[122:125], v[182:185], v[158:161], v[122:125]
	v_add_f32_e32 v251, v105, v251
	ds_read_b64_tr_b16 v[214:215], v241 offset:32768
	ds_read_b64_tr_b16 v[216:217], v241 offset:36864
	v_mfma_f32_16x16x32_bf16 v[126:129], v[182:185], v[174:177], v[126:129]
	v_add_f32_e32 v251, v110, v251
	v_add_f32_e32 v251, v111, v251
	s_waitcnt lgkmcnt(7)
	v_mfma_f32_16x16x32_bf16 v[130:133], v[186:189], v[158:161], v[130:133]
	v_add_f32_e32 v251, v112, v251
	ds_read_b64_tr_b16 v[218:219], v242 offset:32768
	ds_read_b64_tr_b16 v[220:221], v242 offset:36864
	v_mfma_f32_16x16x32_bf16 v[134:137], v[186:189], v[174:177], v[134:137]
	v_add_f32_e32 v251, v113, v251
	v_cvt_pk_bf16_f32 v102, v102, v103
	s_waitcnt lgkmcnt(6)
; #define SBAR() __builtin_amdgcn_sched_barrier(0)
; #define SLOAD(i, k0) do { sr_[i].vs0 = St::ld8(&Vh[(long)((k0) + sr) * LDK + sc]); sr_[i].vs1 = St::ld8(&Vh[(long)((k0) + 32 + sr) * LDK + sc]); \
;     sr_[i].ks0 = St::ld8(&Kh[(long)((k0) + sr) * LDK + sc]); sr_[i].ks1 = St::ld8(&Kh[(long)((k0) + 32 + sr) * LDK + sc]); } while (0)
; #define SWAIT() do { if constexpr (SDEPTH == 2) asm volatile("s_waitcnt vmcnt(4)" ::: "memory"); else asm volatile("s_waitcnt vmcnt(0)" ::: "memory"); } while (0)
; template <typename TQ> ...
;     ...
;   for (int j = 1; j + 1 < NT; j += 2) {
;     SBAR(); SLOAD(SO, (j + SDEPTH) * KVBLK); SBAR();
;     qkt(pB0, pB1, (bf16*)((char*)K_lds + SHM_K), qr, r32, hi, negm);
;     finishSM(pA0, pA1, l_reg, pa0, pa1, pa2, pa3); SBAR();
;     pv_d0(o, vb0, pa0, pa1, pa2, pa3); partialSM(pB0, pB1, mC);
;     __syncthreads(); SWAIT(); SWRITE(0, SE);
;     __syncthreads();
;     SBAR(); if (SDEPTH == 1 || j + 3 < NT) SLOAD(SE, (j + 1 + SDEPTH) * KVBLK); SBAR();
;     qkt(pA0, pA1, K_lds, qr, r32, hi, negm);
;     finishSM(pB0, pB1, l_reg, pa0, pa1, pa2, pa3); SBAR();
;     pv_d0(o, vb0 + (int)SHM_V, pa0, pa1, pa2, pa3); partialSM(pA0, pA1, mC);
;     __syncthreads(); SWAIT(); SWRITE(1, SO);
;     __syncthreads();
	v_mfma_f32_16x16x32_bf16 v[138:141], v[190:193], v[158:161], v[138:141]
	v_cvt_pk_bf16_f32 v103, v104, v105
	ds_read_b64_tr_b16 v[222:223], v243 offset:32768
	ds_read_b64_tr_b16 v[224:225], v243 offset:36864
	v_mfma_f32_16x16x32_bf16 v[142:145], v[190:193], v[174:177], v[142:145]
	v_cvt_pk_bf16_f32 v104, v110, v111
	v_cvt_pk_bf16_f32 v105, v112, v113
	v_mfma_f32_16x16x32_bf16 v[18:21], v[202:205], v[82:85], v[18:21]
	v_exp_f32_e32 v114, v114
	v_mfma_f32_16x16x32_bf16 v[22:25], v[202:205], v[86:89], v[22:25]
	ds_read_b64_tr_b16 v[202:203], v244 offset:32768
	ds_read_b64_tr_b16 v[204:205], v244 offset:36864
	v_exp_f32_e32 v115, v115
	v_mfma_f32_16x16x32_bf16 v[26:29], v[206:209], v[82:85], v[26:29]
	v_exp_f32_e32 v116, v116
	v_mfma_f32_16x16x32_bf16 v[30:33], v[206:209], v[86:89], v[30:33]
	ds_read_b64_tr_b16 v[206:207], v245 offset:32768
	ds_read_b64_tr_b16 v[208:209], v245 offset:36864
	v_exp_f32_e32 v117, v117
	s_waitcnt lgkmcnt(10)
	v_mfma_f32_16x16x32_bf16 v[34:37], v[210:213], v[82:85], v[34:37]
	v_exp_f32_e32 v118, v118
	v_mfma_f32_16x16x32_bf16 v[38:41], v[210:213], v[86:89], v[38:41]
	ds_read_b64_tr_b16 v[210:211], v238 offset:40960
	ds_read_b64_tr_b16 v[212:213], v238 offset:45056
	v_exp_f32_e32 v119, v119
	s_waitcnt lgkmcnt(10)
	v_mfma_f32_16x16x32_bf16 v[42:45], v[214:217], v[82:85], v[42:45]
	v_exp_f32_e32 v120, v120
	v_mfma_f32_16x16x32_bf16 v[46:49], v[214:217], v[86:89], v[46:49]
	ds_read_b64_tr_b16 v[214:215], v239 offset:40960
	ds_read_b64_tr_b16 v[216:217], v239 offset:45056
	v_exp_f32_e32 v121, v121
	s_waitcnt lgkmcnt(10)
	v_mfma_f32_16x16x32_bf16 v[50:53], v[218:221], v[82:85], v[50:53]
	v_exp_f32_e32 v122, v122
	v_mfma_f32_16x16x32_bf16 v[54:57], v[218:221], v[86:89], v[54:57]
	ds_read_b64_tr_b16 v[218:219], v240 offset:40960
	ds_read_b64_tr_b16 v[220:221], v240 offset:45056
	v_exp_f32_e32 v123, v123
	s_waitcnt lgkmcnt(10)
	v_mfma_f32_16x16x32_bf16 v[58:61], v[222:225], v[82:85], v[58:61]
	v_exp_f32_e32 v124, v124
	v_mfma_f32_16x16x32_bf16 v[62:65], v[222:225], v[86:89], v[62:65]
	ds_read_b64_tr_b16 v[222:223], v241 offset:40960
	ds_read_b64_tr_b16 v[224:225], v241 offset:45056
	v_exp_f32_e32 v125, v125
	s_waitcnt lgkmcnt(10)
	v_mfma_f32_16x16x32_bf16 v[66:69], v[202:205], v[82:85], v[66:69]
	v_exp_f32_e32 v126, v126
	v_mfma_f32_16x16x32_bf16 v[70:73], v[202:205], v[86:89], v[70:73]
	ds_read_b64_tr_b16 v[202:203], v242 offset:40960
	ds_read_b64_tr_b16 v[204:205], v242 offset:45056
	v_exp_f32_e32 v127, v127
	s_waitcnt lgkmcnt(10)
	v_mfma_f32_16x16x32_bf16 v[74:77], v[206:209], v[82:85], v[74:77]
	v_exp_f32_e32 v128, v128
	v_mfma_f32_16x16x32_bf16 v[78:81], v[206:209], v[86:89], v[78:81]
	ds_read_b64_tr_b16 v[206:207], v243 offset:40960
	ds_read_b64_tr_b16 v[208:209], v243 offset:45056
	v_exp_f32_e32 v129, v129
	s_waitcnt lgkmcnt(10)
	v_mfma_f32_16x16x32_bf16 v[18:21], v[210:213], v[98:101], v[18:21]
	v_exp_f32_e32 v130, v130
	v_mfma_f32_16x16x32_bf16 v[22:25], v[210:213], v[102:105], v[22:25]
	ds_read_b64_tr_b16 v[210:211], v244 offset:40960
	ds_read_b64_tr_b16 v[212:213], v244 offset:45056
	v_exp_f32_e32 v131, v131
	s_waitcnt lgkmcnt(10)
	v_mfma_f32_16x16x32_bf16 v[26:29], v[214:217], v[98:101], v[26:29]
	v_exp_f32_e32 v132, v132
	v_mfma_f32_16x16x32_bf16 v[30:33], v[214:217], v[102:105], v[30:33]
	ds_read_b64_tr_b16 v[214:215], v245 offset:40960
	ds_read_b64_tr_b16 v[216:217], v245 offset:45056
	v_exp_f32_e32 v133, v133
	s_waitcnt lgkmcnt(10)
	v_mfma_f32_16x16x32_bf16 v[34:37], v[218:221], v[98:101], v[34:37]
	v_exp_f32_e32 v134, v134
	v_mfma_f32_16x16x32_bf16 v[38:41], v[218:221], v[102:105], v[38:41]
	v_exp_f32_e32 v135, v135
	s_waitcnt lgkmcnt(8)
	v_mfma_f32_16x16x32_bf16 v[42:45], v[222:225], v[98:101], v[42:45]
	v_exp_f32_e32 v136, v136
	v_mfma_f32_16x16x32_bf16 v[46:49], v[222:225], v[102:105], v[46:49]
	v_exp_f32_e32 v137, v137
	s_waitcnt lgkmcnt(6)
	v_mfma_f32_16x16x32_bf16 v[50:53], v[202:205], v[98:101], v[50:53]
	v_exp_f32_e32 v138, v138
	ds_read_b128 v[178:181], v234 offset:0
	v_mfma_f32_16x16x32_bf16 v[54:57], v[202:205], v[102:105], v[54:57]
	v_exp_f32_e32 v139, v139
	s_waitcnt lgkmcnt(5)
	v_mfma_f32_16x16x32_bf16 v[58:61], v[206:209], v[98:101], v[58:61]
	v_exp_f32_e32 v140, v140
	ds_read_b128 v[182:185], v234 offset:4096
	v_mfma_f32_16x16x32_bf16 v[62:65], v[206:209], v[102:105], v[62:65]
	v_exp_f32_e32 v141, v141
	s_waitcnt lgkmcnt(4)
	v_mfma_f32_16x16x32_bf16 v[66:69], v[210:213], v[98:101], v[66:69]
	v_exp_f32_e32 v142, v142
	ds_read_b128 v[186:189], v234 offset:8192
	v_mfma_f32_16x16x32_bf16 v[70:73], v[210:213], v[102:105], v[70:73]
	v_exp_f32_e32 v143, v143
	s_waitcnt lgkmcnt(3)
	v_mfma_f32_16x16x32_bf16 v[74:77], v[214:217], v[98:101], v[74:77]
	v_exp_f32_e32 v144, v144
	ds_read_b128 v[190:193], v234 offset:12288
	v_mfma_f32_16x16x32_bf16 v[78:81], v[214:217], v[102:105], v[78:81]
	v_exp_f32_e32 v145, v145
	s_waitcnt vmcnt(4)
	s_barrier
; #define SBAR() __builtin_amdgcn_sched_barrier(0)
; #define SLOAD(i, k0) do { sr_[i].vs0 = St::ld8(&Vh[(long)((k0) + sr) * LDK + sc]); sr_[i].vs1 = St::ld8(&Vh[(long)((k0) + 32 + sr) * LDK + sc]); \
;     sr_[i].ks0 = St::ld8(&Kh[(long)((k0) + sr) * LDK + sc]); sr_[i].ks1 = St::ld8(&Kh[(long)((k0) + 32 + sr) * LDK + sc]); } while (0)
; #define SWAIT() do { if constexpr (SDEPTH == 2) asm volatile("s_waitcnt vmcnt(4)" ::: "memory"); else asm volatile("s_waitcnt vmcnt(0)" ::: "memory"); } while (0)
; template <typename TQ> ...
;     ...
;   for (int j = 1; j + 1 < NT; j += 2) {
;     SBAR(); SLOAD(SO, (j + SDEPTH) * KVBLK); SBAR();
;     qkt(pB0, pB1, (bf16*)((char*)K_lds + SHM_K), qr, r32, hi, negm);
;     finishSM(pA0, pA1, l_reg, pa0, pa1, pa2, pa3); SBAR();
;     pv_d0(o, vb0, pa0, pa1, pa2, pa3); partialSM(pB0, pB1, mC);
;     __syncthreads(); SWAIT(); SWRITE(0, SE);
;     __syncthreads();
;     SBAR(); if (SDEPTH == 1 || j + 3 < NT) SLOAD(SE, (j + 1 + SDEPTH) * KVBLK); SBAR();
;     qkt(pA0, pA1, K_lds, qr, r32, hi, negm);
;     finishSM(pB0, pB1, l_reg, pa0, pa1, pa2, pa3); SBAR();
;     pv_d0(o, vb0 + (int)SHM_V, pa0, pa1, pa2, pa3); partialSM(pA0, pA1, mC);
;     __syncthreads(); SWAIT(); SWRITE(1, SO);
;     __syncthreads();
	s_waitcnt lgkmcnt(3)
	v_mfma_f32_16x16x32_bf16 v[82:85], v[178:181], v[146:149], v[2:5]
	v_add_f32_e32 v250, v114, v250
	s_add_u32 s98, s98, 0x8000
	s_addc_u32 s99, s99, 0
	s_add_u32 s100, s100, 0x8000
	s_addc_u32 s101, s101, 0
	v_mfma_f32_16x16x32_bf16 v[86:89], v[178:181], v[162:165], v[2:5]
	ds_read_b128 v[178:181], v235 offset:0
	v_add_f32_e32 v250, v115, v250
	v_add_f32_e32 v250, v116, v250
	s_waitcnt lgkmcnt(3)
	v_mfma_f32_16x16x32_bf16 v[90:93], v[182:185], v[146:149], v[2:5]
	v_add_f32_e32 v250, v117, v250
	s_add_u32 m0, s79, 49152
	s_nop 0
	global_load_lds_dwordx4 v246, s[98:99]
	v_mfma_f32_16x16x32_bf16 v[94:97], v[182:185], v[162:165], v[2:5]
	ds_read_b128 v[182:185], v235 offset:4096
	v_add_f32_e32 v250, v122, v250
	v_add_f32_e32 v250, v123, v250
	s_waitcnt lgkmcnt(3)
	v_mfma_f32_16x16x32_bf16 v[98:101], v[186:189], v[146:149], v[2:5]
	v_add_f32_e32 v250, v124, v250
	v_mfma_f32_16x16x32_bf16 v[102:105], v[186:189], v[162:165], v[2:5]
	ds_read_b128 v[186:189], v235 offset:8192
	v_add_f32_e32 v250, v125, v250
	v_cvt_pk_bf16_f32 v114, v114, v115
	s_waitcnt lgkmcnt(3)
	v_mfma_f32_16x16x32_bf16 v[106:109], v[190:193], v[146:149], v[2:5]
	v_cvt_pk_bf16_f32 v115, v116, v117
	s_add_u32 m0, s79, 50176
	s_nop 0
	global_load_lds_dwordx4 v247, s[98:99]
	v_mfma_f32_16x16x32_bf16 v[110:113], v[190:193], v[162:165], v[2:5]
	ds_read_b128 v[190:193], v235 offset:12288
	v_cvt_pk_bf16_f32 v116, v122, v123
	v_cvt_pk_bf16_f32 v117, v124, v125
	s_waitcnt lgkmcnt(3)
	v_mfma_f32_16x16x32_bf16 v[82:85], v[178:181], v[150:153], v[82:85]
	v_add_f32_e32 v251, v118, v251
	v_mfma_f32_16x16x32_bf16 v[86:89], v[178:181], v[166:169], v[86:89]
	ds_read_b128 v[178:181], v236 offset:0
	v_add_f32_e32 v251, v119, v251
	v_add_f32_e32 v251, v120, v251
	s_waitcnt lgkmcnt(3)
	v_mfma_f32_16x16x32_bf16 v[90:93], v[182:185], v[150:153], v[90:93]
	v_add_f32_e32 v251, v121, v251
	s_add_u32 m0, s80, 16384
	s_nop 0
	global_load_lds_dwordx4 v248, s[100:101]
	v_mfma_f32_16x16x32_bf16 v[94:97], v[182:185], v[166:169], v[94:97]
	ds_read_b128 v[182:185], v236 offset:4096
	v_add_f32_e32 v251, v126, v251
	v_add_f32_e32 v251, v127, v251
	s_waitcnt lgkmcnt(3)
	v_mfma_f32_16x16x32_bf16 v[98:101], v[186:189], v[150:153], v[98:101]
	v_add_f32_e32 v251, v128, v251
	v_mfma_f32_16x16x32_bf16 v[102:105], v[186:189], v[166:169], v[102:105]
	ds_read_b128 v[186:189], v236 offset:8192
	v_add_f32_e32 v251, v129, v251
	v_cvt_pk_bf16_f32 v118, v118, v119
	s_waitcnt lgkmcnt(3)
	v_mfma_f32_16x16x32_bf16 v[106:109], v[190:193], v[150:153], v[106:109]
	v_cvt_pk_bf16_f32 v119, v120, v121
	s_add_u32 m0, s80, 17408
	s_nop 0
	global_load_lds_dwordx4 v249, s[100:101]
	v_mfma_f32_16x16x32_bf16 v[110:113], v[190:193], v[166:169], v[110:113]
	ds_read_b128 v[190:193], v236 offset:12288
	v_cvt_pk_bf16_f32 v120, v126, v127
	v_cvt_pk_bf16_f32 v121, v128, v129
	s_waitcnt lgkmcnt(3)
	v_mfma_f32_16x16x32_bf16 v[82:85], v[178:181], v[154:157], v[82:85]
	v_add_f32_e32 v250, v130, v250
	v_mfma_f32_16x16x32_bf16 v[86:89], v[178:181], v[170:173], v[86:89]
	ds_read_b128 v[178:181], v237 offset:0
	v_add_f32_e32 v250, v131, v250
	v_add_f32_e32 v250, v132, v250
	s_waitcnt lgkmcnt(3)
	v_mfma_f32_16x16x32_bf16 v[90:93], v[182:185], v[154:157], v[90:93]
	v_add_f32_e32 v250, v133, v250
	v_mfma_f32_16x16x32_bf16 v[94:97], v[182:185], v[170:173], v[94:97]
	ds_read_b128 v[182:185], v237 offset:4096
	v_add_f32_e32 v250, v138, v250
	v_add_f32_e32 v250, v139, v250
	s_waitcnt lgkmcnt(3)
	v_mfma_f32_16x16x32_bf16 v[98:101], v[186:189], v[154:157], v[98:101]
	v_add_f32_e32 v250, v140, v250
	ds_read_b64_tr_b16 v[202:203], v238 offset:49152
	ds_read_b64_tr_b16 v[204:205], v238 offset:53248
	v_mfma_f32_16x16x32_bf16 v[102:105], v[186:189], v[170:173], v[102:105]
	ds_read_b128 v[186:189], v237 offset:8192
	v_add_f32_e32 v250, v141, v250
	v_cvt_pk_bf16_f32 v130, v130, v131
	s_waitcnt lgkmcnt(5)
	v_mfma_f32_16x16x32_bf16 v[106:109], v[190:193], v[154:157], v[106:109]
	v_cvt_pk_bf16_f32 v131, v132, v133
	ds_read_b64_tr_b16 v[206:207], v239 offset:49152
	ds_read_b64_tr_b16 v[208:209], v239 offset:53248
	v_mfma_f32_16x16x32_bf16 v[110:113], v[190:193], v[170:173], v[110:113]
	ds_read_b128 v[190:193], v237 offset:12288
	v_cvt_pk_bf16_f32 v132, v138, v139
	v_cvt_pk_bf16_f32 v133, v140, v141
	s_waitcnt lgkmcnt(7)
	v_mfma_f32_16x16x32_bf16 v[82:85], v[178:181], v[158:161], v[82:85]
	v_add_f32_e32 v251, v134, v251
	ds_read_b64_tr_b16 v[210:211], v240 offset:49152
	ds_read_b64_tr_b16 v[212:213], v240 offset:53248
	v_mfma_f32_16x16x32_bf16 v[86:89], v[178:181], v[174:177], v[86:89]
	v_add_f32_e32 v251, v135, v251
	v_add_f32_e32 v251, v136, v251
	s_waitcnt lgkmcnt(8)
	v_mfma_f32_16x16x32_bf16 v[90:93], v[182:185], v[158:161], v[90:93]
	v_add_f32_e32 v251, v137, v251
	ds_read_b64_tr_b16 v[214:215], v241 offset:49152
	ds_read_b64_tr_b16 v[216:217], v241 offset:53248
	v_mfma_f32_16x16x32_bf16 v[94:97], v[182:185], v[174:177], v[94:97]
	v_add_f32_e32 v251, v142, v251
	v_add_f32_e32 v251, v143, v251
	s_waitcnt lgkmcnt(7)
	v_mfma_f32_16x16x32_bf16 v[98:101], v[186:189], v[158:161], v[98:101]
	v_add_f32_e32 v251, v144, v251
	ds_read_b64_tr_b16 v[218:219], v242 offset:49152
	ds_read_b64_tr_b16 v[220:221], v242 offset:53248
	v_mfma_f32_16x16x32_bf16 v[102:105], v[186:189], v[174:177], v[102:105]
	v_add_f32_e32 v251, v145, v251
	v_cvt_pk_bf16_f32 v134, v134, v135
	s_waitcnt lgkmcnt(6)
; #define SBAR() __builtin_amdgcn_sched_barrier(0)
; #define SLOAD(i, k0) do { sr_[i].vs0 = St::ld8(&Vh[(long)((k0) + sr) * LDK + sc]); sr_[i].vs1 = St::ld8(&Vh[(long)((k0) + 32 + sr) * LDK + sc]); \
;     sr_[i].ks0 = St::ld8(&Kh[(long)((k0) + sr) * LDK + sc]); sr_[i].ks1 = St::ld8(&Kh[(long)((k0) + 32 + sr) * LDK + sc]); } while (0)
; #define SWAIT() do { if constexpr (SDEPTH == 2) asm volatile("s_waitcnt vmcnt(4)" ::: "memory"); else asm volatile("s_waitcnt vmcnt(0)" ::: "memory"); } while (0)
; template <typename TQ> ...
;     ...
;   for (int j = 1; j + 1 < NT; j += 2) {
;     SBAR(); SLOAD(SO, (j + SDEPTH) * KVBLK); SBAR();
;     qkt(pB0, pB1, (bf16*)((char*)K_lds + SHM_K), qr, r32, hi, negm);
;     finishSM(pA0, pA1, l_reg, pa0, pa1, pa2, pa3); SBAR();
;     pv_d0(o, vb0, pa0, pa1, pa2, pa3); partialSM(pB0, pB1, mC);
;     __syncthreads(); SWAIT(); SWRITE(0, SE);
;     __syncthreads();
;     SBAR(); if (SDEPTH == 1 || j + 3 < NT) SLOAD(SE, (j + 1 + SDEPTH) * KVBLK); SBAR();
;     qkt(pA0, pA1, K_lds, qr, r32, hi, negm);
;     finishSM(pB0, pB1, l_reg, pa0, pa1, pa2, pa3); SBAR();
;     pv_d0(o, vb0 + (int)SHM_V, pa0, pa1, pa2, pa3); partialSM(pA0, pA1, mC);
;     __syncthreads(); SWAIT(); SWRITE(1, SO);
;     __syncthreads();
	v_mfma_f32_16x16x32_bf16 v[106:109], v[190:193], v[158:161], v[106:109]
	v_cvt_pk_bf16_f32 v135, v136, v137
	ds_read_b64_tr_b16 v[222:223], v243 offset:49152
	ds_read_b64_tr_b16 v[224:225], v243 offset:53248
	v_mfma_f32_16x16x32_bf16 v[110:113], v[190:193], v[174:177], v[110:113]
	v_cvt_pk_bf16_f32 v136, v142, v143
	v_cvt_pk_bf16_f32 v137, v144, v145
	v_mfma_f32_16x16x32_bf16 v[18:21], v[202:205], v[114:117], v[18:21]
	v_exp_f32_e32 v82, v82
	v_mfma_f32_16x16x32_bf16 v[22:25], v[202:205], v[118:121], v[22:25]
	ds_read_b64_tr_b16 v[202:203], v244 offset:49152
	ds_read_b64_tr_b16 v[204:205], v244 offset:53248
	v_exp_f32_e32 v83, v83
	v_mfma_f32_16x16x32_bf16 v[26:29], v[206:209], v[114:117], v[26:29]
	v_exp_f32_e32 v84, v84
	v_mfma_f32_16x16x32_bf16 v[30:33], v[206:209], v[118:121], v[30:33]
	ds_read_b64_tr_b16 v[206:207], v245 offset:49152
	ds_read_b64_tr_b16 v[208:209], v245 offset:53248
	v_exp_f32_e32 v85, v85
	s_waitcnt lgkmcnt(10)
	v_mfma_f32_16x16x32_bf16 v[34:37], v[210:213], v[114:117], v[34:37]
	v_exp_f32_e32 v86, v86
	v_mfma_f32_16x16x32_bf16 v[38:41], v[210:213], v[118:121], v[38:41]
	ds_read_b64_tr_b16 v[210:211], v238 offset:57344
	ds_read_b64_tr_b16 v[212:213], v238 offset:61440
	v_exp_f32_e32 v87, v87
	s_waitcnt lgkmcnt(10)
	v_mfma_f32_16x16x32_bf16 v[42:45], v[214:217], v[114:117], v[42:45]
	v_exp_f32_e32 v88, v88
	v_mfma_f32_16x16x32_bf16 v[46:49], v[214:217], v[118:121], v[46:49]
	ds_read_b64_tr_b16 v[214:215], v239 offset:57344
	ds_read_b64_tr_b16 v[216:217], v239 offset:61440
	v_exp_f32_e32 v89, v89
	s_waitcnt lgkmcnt(10)
	v_mfma_f32_16x16x32_bf16 v[50:53], v[218:221], v[114:117], v[50:53]
	v_exp_f32_e32 v90, v90
	v_mfma_f32_16x16x32_bf16 v[54:57], v[218:221], v[118:121], v[54:57]
	ds_read_b64_tr_b16 v[218:219], v240 offset:57344
	ds_read_b64_tr_b16 v[220:221], v240 offset:61440
	v_exp_f32_e32 v91, v91
	s_waitcnt lgkmcnt(10)
	v_mfma_f32_16x16x32_bf16 v[58:61], v[222:225], v[114:117], v[58:61]
	v_exp_f32_e32 v92, v92
	v_mfma_f32_16x16x32_bf16 v[62:65], v[222:225], v[118:121], v[62:65]
	ds_read_b64_tr_b16 v[222:223], v241 offset:57344
	ds_read_b64_tr_b16 v[224:225], v241 offset:61440
	v_exp_f32_e32 v93, v93
	s_waitcnt lgkmcnt(10)
	v_mfma_f32_16x16x32_bf16 v[66:69], v[202:205], v[114:117], v[66:69]
	v_exp_f32_e32 v94, v94
	v_mfma_f32_16x16x32_bf16 v[70:73], v[202:205], v[118:121], v[70:73]
	ds_read_b64_tr_b16 v[202:203], v242 offset:57344
	ds_read_b64_tr_b16 v[204:205], v242 offset:61440
	v_exp_f32_e32 v95, v95
	s_waitcnt lgkmcnt(10)
	v_mfma_f32_16x16x32_bf16 v[74:77], v[206:209], v[114:117], v[74:77]
	v_exp_f32_e32 v96, v96
	v_mfma_f32_16x16x32_bf16 v[78:81], v[206:209], v[118:121], v[78:81]
	ds_read_b64_tr_b16 v[206:207], v243 offset:57344
	ds_read_b64_tr_b16 v[208:209], v243 offset:61440
	v_exp_f32_e32 v97, v97
	s_waitcnt lgkmcnt(10)
	v_mfma_f32_16x16x32_bf16 v[18:21], v[210:213], v[130:133], v[18:21]
	v_exp_f32_e32 v98, v98
	v_mfma_f32_16x16x32_bf16 v[22:25], v[210:213], v[134:137], v[22:25]
	ds_read_b64_tr_b16 v[210:211], v244 offset:57344
	ds_read_b64_tr_b16 v[212:213], v244 offset:61440
	v_exp_f32_e32 v99, v99
	s_waitcnt lgkmcnt(10)
	v_mfma_f32_16x16x32_bf16 v[26:29], v[214:217], v[130:133], v[26:29]
	v_exp_f32_e32 v100, v100
	v_mfma_f32_16x16x32_bf16 v[30:33], v[214:217], v[134:137], v[30:33]
	ds_read_b64_tr_b16 v[214:215], v245 offset:57344
	ds_read_b64_tr_b16 v[216:217], v245 offset:61440
	v_exp_f32_e32 v101, v101
	s_waitcnt lgkmcnt(10)
	v_mfma_f32_16x16x32_bf16 v[34:37], v[218:221], v[130:133], v[34:37]
	v_exp_f32_e32 v102, v102
	v_mfma_f32_16x16x32_bf16 v[38:41], v[218:221], v[134:137], v[38:41]
	v_exp_f32_e32 v103, v103
	s_waitcnt lgkmcnt(8)
	v_mfma_f32_16x16x32_bf16 v[42:45], v[222:225], v[130:133], v[42:45]
	v_exp_f32_e32 v104, v104
	v_mfma_f32_16x16x32_bf16 v[46:49], v[222:225], v[134:137], v[46:49]
	v_exp_f32_e32 v105, v105
	s_waitcnt lgkmcnt(6)
	v_mfma_f32_16x16x32_bf16 v[50:53], v[202:205], v[130:133], v[50:53]
	v_exp_f32_e32 v106, v106
	ds_read_b128 v[178:181], v234 offset:16384
	v_mfma_f32_16x16x32_bf16 v[54:57], v[202:205], v[134:137], v[54:57]
	v_exp_f32_e32 v107, v107
	s_waitcnt lgkmcnt(5)
	v_mfma_f32_16x16x32_bf16 v[58:61], v[206:209], v[130:133], v[58:61]
	v_exp_f32_e32 v108, v108
	ds_read_b128 v[182:185], v234 offset:20480
	v_mfma_f32_16x16x32_bf16 v[62:65], v[206:209], v[134:137], v[62:65]
	v_exp_f32_e32 v109, v109
	s_waitcnt lgkmcnt(4)
	v_mfma_f32_16x16x32_bf16 v[66:69], v[210:213], v[130:133], v[66:69]
	v_exp_f32_e32 v110, v110
	ds_read_b128 v[186:189], v234 offset:24576
	v_mfma_f32_16x16x32_bf16 v[70:73], v[210:213], v[134:137], v[70:73]
	v_exp_f32_e32 v111, v111
	s_waitcnt lgkmcnt(3)
	v_mfma_f32_16x16x32_bf16 v[74:77], v[214:217], v[130:133], v[74:77]
	v_exp_f32_e32 v112, v112
	ds_read_b128 v[190:193], v234 offset:28672
	v_mfma_f32_16x16x32_bf16 v[78:81], v[214:217], v[134:137], v[78:81]
	v_exp_f32_e32 v113, v113
	s_waitcnt vmcnt(4)
	s_add_i32 s15, s15, 1
	s_cmp_lt_u32 s15, 32
	s_cbranch_scc1 .Lattn_loop1
	s_barrier
; #define SBAR() __builtin_amdgcn_sched_barrier(0)
; template <typename TQ> ...
;     ...
;   SBAR(); qkt(pB0, pB1, (bf16*)((char*)K_lds + SHM_K), qr, r32, hi, negm);
;   finishSM(pA0, pA1, l_reg, pa0, pa1, pa2, pa3); SBAR();
;   pv_d0(o, vb0, pa0, pa1, pa2, pa3); partialSM(pB0, pB1, mC);
;   __syncthreads();
;   finishSM(pB0, pB1, l_reg, pa0, pa1, pa2, pa3); SBAR();
;   pv_d0(o, vb0 + (int)SHM_V, pa0, pa1, pa2, pa3);
	s_waitcnt lgkmcnt(3)
	v_mfma_f32_16x16x32_bf16 v[114:117], v[178:181], v[146:149], v[2:5]
	v_add_f32_e32 v250, v82, v250
	s_add_u32 s98, s98, 0x8000
	s_addc_u32 s99, s99, 0
	s_add_u32 s100, s100, 0x8000
	s_addc_u32 s101, s101, 0
	v_mfma_f32_16x16x32_bf16 v[118:121], v[178:181], v[162:165], v[2:5]
	ds_read_b128 v[178:181], v235 offset:16384
	v_add_f32_e32 v250, v83, v250
	v_add_f32_e32 v250, v84, v250
	s_waitcnt lgkmcnt(3)
	v_mfma_f32_16x16x32_bf16 v[122:125], v[182:185], v[146:149], v[2:5]
	v_add_f32_e32 v250, v85, v250
	s_add_u32 m0, s80, 32768
	s_nop 0
	global_load_lds_dwordx4 v248, s[100:101]
	v_mfma_f32_16x16x32_bf16 v[126:129], v[182:185], v[162:165], v[2:5]
	ds_read_b128 v[182:185], v235 offset:20480
	v_add_f32_e32 v250, v90, v250
	v_add_f32_e32 v250, v91, v250
	s_waitcnt lgkmcnt(3)
	v_mfma_f32_16x16x32_bf16 v[130:133], v[186:189], v[146:149], v[2:5]
	v_add_f32_e32 v250, v92, v250
	v_mfma_f32_16x16x32_bf16 v[134:137], v[186:189], v[162:165], v[2:5]
	ds_read_b128 v[186:189], v235 offset:24576
	v_add_f32_e32 v250, v93, v250
	v_cvt_pk_bf16_f32 v82, v82, v83
	s_waitcnt lgkmcnt(3)
	v_mfma_f32_16x16x32_bf16 v[138:141], v[190:193], v[146:149], v[2:5]
	v_cvt_pk_bf16_f32 v83, v84, v85
	s_add_u32 m0, s80, 33792
	s_nop 0
	global_load_lds_dwordx4 v249, s[100:101]
	v_mfma_f32_16x16x32_bf16 v[142:145], v[190:193], v[162:165], v[2:5]
	ds_read_b128 v[190:193], v235 offset:28672
	v_cvt_pk_bf16_f32 v84, v90, v91
	v_cvt_pk_bf16_f32 v85, v92, v93
	s_waitcnt lgkmcnt(3)
	v_mfma_f32_16x16x32_bf16 v[114:117], v[178:181], v[150:153], v[114:117]
	v_add_f32_e32 v251, v86, v251
	v_mfma_f32_16x16x32_bf16 v[118:121], v[178:181], v[166:169], v[118:121]
	ds_read_b128 v[178:181], v236 offset:16384
	v_add_f32_e32 v251, v87, v251
	v_add_f32_e32 v251, v88, v251
	s_waitcnt lgkmcnt(3)
	v_mfma_f32_16x16x32_bf16 v[122:125], v[182:185], v[150:153], v[122:125]
	v_add_f32_e32 v251, v89, v251
	v_mfma_f32_16x16x32_bf16 v[126:129], v[182:185], v[166:169], v[126:129]
	ds_read_b128 v[182:185], v236 offset:20480
	v_add_f32_e32 v251, v94, v251
	v_add_f32_e32 v251, v95, v251
	s_waitcnt lgkmcnt(3)
	v_mfma_f32_16x16x32_bf16 v[130:133], v[186:189], v[150:153], v[130:133]
	v_add_f32_e32 v251, v96, v251
	v_mfma_f32_16x16x32_bf16 v[134:137], v[186:189], v[166:169], v[134:137]
	ds_read_b128 v[186:189], v236 offset:24576
	v_add_f32_e32 v251, v97, v251
	v_cvt_pk_bf16_f32 v86, v86, v87
	s_waitcnt lgkmcnt(3)
	v_mfma_f32_16x16x32_bf16 v[138:141], v[190:193], v[150:153], v[138:141]
	v_cvt_pk_bf16_f32 v87, v88, v89
	v_mfma_f32_16x16x32_bf16 v[142:145], v[190:193], v[166:169], v[142:145]
	ds_read_b128 v[190:193], v236 offset:28672
	v_cvt_pk_bf16_f32 v88, v94, v95
	v_cvt_pk_bf16_f32 v89, v96, v97
	s_waitcnt lgkmcnt(3)
	v_mfma_f32_16x16x32_bf16 v[114:117], v[178:181], v[154:157], v[114:117]
	v_add_f32_e32 v250, v98, v250
	v_mfma_f32_16x16x32_bf16 v[118:121], v[178:181], v[170:173], v[118:121]
	ds_read_b128 v[178:181], v237 offset:16384
	v_add_f32_e32 v250, v99, v250
	v_add_f32_e32 v250, v100, v250
	s_waitcnt lgkmcnt(3)
	v_mfma_f32_16x16x32_bf16 v[122:125], v[182:185], v[154:157], v[122:125]
	v_add_f32_e32 v250, v101, v250
	v_mfma_f32_16x16x32_bf16 v[126:129], v[182:185], v[170:173], v[126:129]
	ds_read_b128 v[182:185], v237 offset:20480
	v_add_f32_e32 v250, v106, v250
	v_add_f32_e32 v250, v107, v250
	s_waitcnt lgkmcnt(3)
	v_mfma_f32_16x16x32_bf16 v[130:133], v[186:189], v[154:157], v[130:133]
	v_add_f32_e32 v250, v108, v250
	ds_read_b64_tr_b16 v[202:203], v238 offset:0
	ds_read_b64_tr_b16 v[204:205], v238 offset:4096
	v_mfma_f32_16x16x32_bf16 v[134:137], v[186:189], v[170:173], v[134:137]
	ds_read_b128 v[186:189], v237 offset:24576
	v_add_f32_e32 v250, v109, v250
	v_cvt_pk_bf16_f32 v98, v98, v99
	s_waitcnt lgkmcnt(5)
	v_mfma_f32_16x16x32_bf16 v[138:141], v[190:193], v[154:157], v[138:141]
	v_cvt_pk_bf16_f32 v99, v100, v101
	ds_read_b64_tr_b16 v[206:207], v239 offset:0
	ds_read_b64_tr_b16 v[208:209], v239 offset:4096
	v_mfma_f32_16x16x32_bf16 v[142:145], v[190:193], v[170:173], v[142:145]
	ds_read_b128 v[190:193], v237 offset:28672
	v_cvt_pk_bf16_f32 v100, v106, v107
	v_cvt_pk_bf16_f32 v101, v108, v109
	s_waitcnt lgkmcnt(7)
	v_mfma_f32_16x16x32_bf16 v[114:117], v[178:181], v[158:161], v[114:117]
	v_add_f32_e32 v251, v102, v251
	ds_read_b64_tr_b16 v[210:211], v240 offset:0
	ds_read_b64_tr_b16 v[212:213], v240 offset:4096
	v_mfma_f32_16x16x32_bf16 v[118:121], v[178:181], v[174:177], v[118:121]
	v_add_f32_e32 v251, v103, v251
	v_add_f32_e32 v251, v104, v251
	s_waitcnt lgkmcnt(8)
	v_mfma_f32_16x16x32_bf16 v[122:125], v[182:185], v[158:161], v[122:125]
	v_add_f32_e32 v251, v105, v251
	ds_read_b64_tr_b16 v[214:215], v241 offset:0
	ds_read_b64_tr_b16 v[216:217], v241 offset:4096
	v_mfma_f32_16x16x32_bf16 v[126:129], v[182:185], v[174:177], v[126:129]
	v_add_f32_e32 v251, v110, v251
	v_add_f32_e32 v251, v111, v251
	s_waitcnt lgkmcnt(7)
	v_mfma_f32_16x16x32_bf16 v[130:133], v[186:189], v[158:161], v[130:133]
	v_add_f32_e32 v251, v112, v251
	ds_read_b64_tr_b16 v[218:219], v242 offset:0
	ds_read_b64_tr_b16 v[220:221], v242 offset:4096
	v_mfma_f32_16x16x32_bf16 v[134:137], v[186:189], v[174:177], v[134:137]
	v_add_f32_e32 v251, v113, v251
	v_cvt_pk_bf16_f32 v102, v102, v103
	s_waitcnt lgkmcnt(6)
; #define SBAR() __builtin_amdgcn_sched_barrier(0)
; template <typename TQ> ...
;     ...
;   SBAR(); qkt(pB0, pB1, (bf16*)((char*)K_lds + SHM_K), qr, r32, hi, negm);
;   finishSM(pA0, pA1, l_reg, pa0, pa1, pa2, pa3); SBAR();
;   pv_d0(o, vb0, pa0, pa1, pa2, pa3); partialSM(pB0, pB1, mC);
;   __syncthreads();
;   finishSM(pB0, pB1, l_reg, pa0, pa1, pa2, pa3); SBAR();
;   pv_d0(o, vb0 + (int)SHM_V, pa0, pa1, pa2, pa3);
	v_mfma_f32_16x16x32_bf16 v[138:141], v[190:193], v[158:161], v[138:141]
	v_cvt_pk_bf16_f32 v103, v104, v105
	ds_read_b64_tr_b16 v[222:223], v243 offset:0
	ds_read_b64_tr_b16 v[224:225], v243 offset:4096
	v_mfma_f32_16x16x32_bf16 v[142:145], v[190:193], v[174:177], v[142:145]
	v_cvt_pk_bf16_f32 v104, v110, v111
	v_cvt_pk_bf16_f32 v105, v112, v113
	v_mfma_f32_16x16x32_bf16 v[18:21], v[202:205], v[82:85], v[18:21]
	v_exp_f32_e32 v114, v114
	v_mfma_f32_16x16x32_bf16 v[22:25], v[202:205], v[86:89], v[22:25]
	ds_read_b64_tr_b16 v[202:203], v244 offset:0
	ds_read_b64_tr_b16 v[204:205], v244 offset:4096
	v_exp_f32_e32 v115, v115
	v_mfma_f32_16x16x32_bf16 v[26:29], v[206:209], v[82:85], v[26:29]
	v_exp_f32_e32 v116, v116
	v_mfma_f32_16x16x32_bf16 v[30:33], v[206:209], v[86:89], v[30:33]
	ds_read_b64_tr_b16 v[206:207], v245 offset:0
	ds_read_b64_tr_b16 v[208:209], v245 offset:4096
	v_exp_f32_e32 v117, v117
	s_waitcnt lgkmcnt(10)
	v_mfma_f32_16x16x32_bf16 v[34:37], v[210:213], v[82:85], v[34:37]
	v_exp_f32_e32 v118, v118
	v_mfma_f32_16x16x32_bf16 v[38:41], v[210:213], v[86:89], v[38:41]
	ds_read_b64_tr_b16 v[210:211], v238 offset:8192
	ds_read_b64_tr_b16 v[212:213], v238 offset:12288
	v_exp_f32_e32 v119, v119
	s_waitcnt lgkmcnt(10)
	v_mfma_f32_16x16x32_bf16 v[42:45], v[214:217], v[82:85], v[42:45]
	v_exp_f32_e32 v120, v120
	v_mfma_f32_16x16x32_bf16 v[46:49], v[214:217], v[86:89], v[46:49]
	ds_read_b64_tr_b16 v[214:215], v239 offset:8192
	ds_read_b64_tr_b16 v[216:217], v239 offset:12288
	v_exp_f32_e32 v121, v121
	s_waitcnt lgkmcnt(10)
	v_mfma_f32_16x16x32_bf16 v[50:53], v[218:221], v[82:85], v[50:53]
	v_exp_f32_e32 v122, v122
	v_mfma_f32_16x16x32_bf16 v[54:57], v[218:221], v[86:89], v[54:57]
	ds_read_b64_tr_b16 v[218:219], v240 offset:8192
	ds_read_b64_tr_b16 v[220:221], v240 offset:12288
	v_exp_f32_e32 v123, v123
	s_waitcnt lgkmcnt(10)
	v_mfma_f32_16x16x32_bf16 v[58:61], v[222:225], v[82:85], v[58:61]
	v_exp_f32_e32 v124, v124
	v_mfma_f32_16x16x32_bf16 v[62:65], v[222:225], v[86:89], v[62:65]
	ds_read_b64_tr_b16 v[222:223], v241 offset:8192
	ds_read_b64_tr_b16 v[224:225], v241 offset:12288
	v_exp_f32_e32 v125, v125
	s_waitcnt lgkmcnt(10)
	v_mfma_f32_16x16x32_bf16 v[66:69], v[202:205], v[82:85], v[66:69]
	v_exp_f32_e32 v126, v126
	v_mfma_f32_16x16x32_bf16 v[70:73], v[202:205], v[86:89], v[70:73]
	ds_read_b64_tr_b16 v[202:203], v242 offset:8192
	ds_read_b64_tr_b16 v[204:205], v242 offset:12288
	v_exp_f32_e32 v127, v127
	s_waitcnt lgkmcnt(10)
	v_mfma_f32_16x16x32_bf16 v[74:77], v[206:209], v[82:85], v[74:77]
	v_exp_f32_e32 v128, v128
	v_mfma_f32_16x16x32_bf16 v[78:81], v[206:209], v[86:89], v[78:81]
	ds_read_b64_tr_b16 v[206:207], v243 offset:8192
	ds_read_b64_tr_b16 v[208:209], v243 offset:12288
	v_exp_f32_e32 v129, v129
	s_waitcnt lgkmcnt(10)
	v_mfma_f32_16x16x32_bf16 v[18:21], v[210:213], v[98:101], v[18:21]
	v_exp_f32_e32 v130, v130
	v_mfma_f32_16x16x32_bf16 v[22:25], v[210:213], v[102:105], v[22:25]
	ds_read_b64_tr_b16 v[210:211], v244 offset:8192
	ds_read_b64_tr_b16 v[212:213], v244 offset:12288
	v_exp_f32_e32 v131, v131
	s_waitcnt lgkmcnt(10)
	v_mfma_f32_16x16x32_bf16 v[26:29], v[214:217], v[98:101], v[26:29]
	v_exp_f32_e32 v132, v132
	v_mfma_f32_16x16x32_bf16 v[30:33], v[214:217], v[102:105], v[30:33]
	ds_read_b64_tr_b16 v[214:215], v245 offset:8192
	ds_read_b64_tr_b16 v[216:217], v245 offset:12288
	v_exp_f32_e32 v133, v133
	s_waitcnt lgkmcnt(10)
	v_mfma_f32_16x16x32_bf16 v[34:37], v[218:221], v[98:101], v[34:37]
	v_exp_f32_e32 v134, v134
	v_mfma_f32_16x16x32_bf16 v[38:41], v[218:221], v[102:105], v[38:41]
	v_exp_f32_e32 v135, v135
	s_waitcnt lgkmcnt(8)
	v_mfma_f32_16x16x32_bf16 v[42:45], v[222:225], v[98:101], v[42:45]
	v_exp_f32_e32 v136, v136
	v_mfma_f32_16x16x32_bf16 v[46:49], v[222:225], v[102:105], v[46:49]
	v_exp_f32_e32 v137, v137
	s_waitcnt lgkmcnt(6)
	v_mfma_f32_16x16x32_bf16 v[50:53], v[202:205], v[98:101], v[50:53]
	v_exp_f32_e32 v138, v138
	ds_read_b128 v[178:181], v234 offset:32768
	v_mfma_f32_16x16x32_bf16 v[54:57], v[202:205], v[102:105], v[54:57]
	v_exp_f32_e32 v139, v139
	s_waitcnt lgkmcnt(5)
	v_mfma_f32_16x16x32_bf16 v[58:61], v[206:209], v[98:101], v[58:61]
	v_exp_f32_e32 v140, v140
	ds_read_b128 v[182:185], v234 offset:36864
	v_mfma_f32_16x16x32_bf16 v[62:65], v[206:209], v[102:105], v[62:65]
	v_exp_f32_e32 v141, v141
	s_waitcnt lgkmcnt(4)
	v_mfma_f32_16x16x32_bf16 v[66:69], v[210:213], v[98:101], v[66:69]
	v_exp_f32_e32 v142, v142
	ds_read_b128 v[186:189], v234 offset:40960
	v_mfma_f32_16x16x32_bf16 v[70:73], v[210:213], v[102:105], v[70:73]
	v_exp_f32_e32 v143, v143
	s_waitcnt lgkmcnt(3)
	v_mfma_f32_16x16x32_bf16 v[74:77], v[214:217], v[98:101], v[74:77]
	v_exp_f32_e32 v144, v144
	ds_read_b128 v[190:193], v234 offset:45056
	v_mfma_f32_16x16x32_bf16 v[78:81], v[214:217], v[102:105], v[78:81]
	v_exp_f32_e32 v145, v145
	s_waitcnt vmcnt(2)
	s_barrier
; #define SBAR() __builtin_amdgcn_sched_barrier(0)
; template <typename TQ> ...
;     ...
;   SBAR(); qkt(pB0, pB1, (bf16*)((char*)K_lds + SHM_K), qr, r32, hi, negm);
;   finishSM(pA0, pA1, l_reg, pa0, pa1, pa2, pa3); SBAR();
;   pv_d0(o, vb0, pa0, pa1, pa2, pa3); partialSM(pB0, pB1, mC);
;   __syncthreads();
;   finishSM(pB0, pB1, l_reg, pa0, pa1, pa2, pa3); SBAR();
;   pv_d0(o, vb0 + (int)SHM_V, pa0, pa1, pa2, pa3);
	s_waitcnt lgkmcnt(3)
	v_mfma_f32_16x16x32_bf16 v[82:85], v[178:181], v[146:149], v[2:5]
	v_add_f32_e32 v250, v114, v250
	s_add_u32 s98, s98, 0x8000
	s_addc_u32 s99, s99, 0
	s_add_u32 s100, s100, 0x8000
	s_addc_u32 s101, s101, 0
	v_mfma_f32_16x16x32_bf16 v[86:89], v[178:181], v[162:165], v[2:5]
	ds_read_b128 v[178:181], v235 offset:32768
	v_add_f32_e32 v250, v115, v250
	v_add_f32_e32 v250, v116, v250
	s_waitcnt lgkmcnt(3)
	v_mfma_f32_16x16x32_bf16 v[90:93], v[182:185], v[146:149], v[2:5]
	v_add_f32_e32 v250, v117, v250
	s_add_u32 m0, s80, 49152
	s_nop 0
	global_load_lds_dwordx4 v248, s[100:101]
	v_mfma_f32_16x16x32_bf16 v[94:97], v[182:185], v[162:165], v[2:5]
	ds_read_b128 v[182:185], v235 offset:36864
	v_add_f32_e32 v250, v122, v250
	v_add_f32_e32 v250, v123, v250
	s_waitcnt lgkmcnt(3)
	v_mfma_f32_16x16x32_bf16 v[98:101], v[186:189], v[146:149], v[2:5]
	v_add_f32_e32 v250, v124, v250
	v_mfma_f32_16x16x32_bf16 v[102:105], v[186:189], v[162:165], v[2:5]
	ds_read_b128 v[186:189], v235 offset:40960
	v_add_f32_e32 v250, v125, v250
	v_cvt_pk_bf16_f32 v114, v114, v115
	s_waitcnt lgkmcnt(3)
	v_mfma_f32_16x16x32_bf16 v[106:109], v[190:193], v[146:149], v[2:5]
	v_cvt_pk_bf16_f32 v115, v116, v117
	s_add_u32 m0, s80, 50176
	s_nop 0
	global_load_lds_dwordx4 v249, s[100:101]
	v_mfma_f32_16x16x32_bf16 v[110:113], v[190:193], v[162:165], v[2:5]
	ds_read_b128 v[190:193], v235 offset:45056
	v_cvt_pk_bf16_f32 v116, v122, v123
	v_cvt_pk_bf16_f32 v117, v124, v125
	s_waitcnt lgkmcnt(3)
	v_mfma_f32_16x16x32_bf16 v[82:85], v[178:181], v[150:153], v[82:85]
	v_add_f32_e32 v251, v118, v251
	v_mfma_f32_16x16x32_bf16 v[86:89], v[178:181], v[166:169], v[86:89]
	ds_read_b128 v[178:181], v236 offset:32768
	v_add_f32_e32 v251, v119, v251
	v_add_f32_e32 v251, v120, v251
	s_waitcnt lgkmcnt(3)
	v_mfma_f32_16x16x32_bf16 v[90:93], v[182:185], v[150:153], v[90:93]
	v_add_f32_e32 v251, v121, v251
	v_mfma_f32_16x16x32_bf16 v[94:97], v[182:185], v[166:169], v[94:97]
	ds_read_b128 v[182:185], v236 offset:36864
	v_add_f32_e32 v251, v126, v251
	v_add_f32_e32 v251, v127, v251
	s_waitcnt lgkmcnt(3)
	v_mfma_f32_16x16x32_bf16 v[98:101], v[186:189], v[150:153], v[98:101]
	v_add_f32_e32 v251, v128, v251
	v_mfma_f32_16x16x32_bf16 v[102:105], v[186:189], v[166:169], v[102:105]
	ds_read_b128 v[186:189], v236 offset:40960
	v_add_f32_e32 v251, v129, v251
	v_cvt_pk_bf16_f32 v118, v118, v119
	s_waitcnt lgkmcnt(3)
	v_mfma_f32_16x16x32_bf16 v[106:109], v[190:193], v[150:153], v[106:109]
	v_cvt_pk_bf16_f32 v119, v120, v121
	v_mfma_f32_16x16x32_bf16 v[110:113], v[190:193], v[166:169], v[110:113]
	ds_read_b128 v[190:193], v236 offset:45056
	v_cvt_pk_bf16_f32 v120, v126, v127
	v_cvt_pk_bf16_f32 v121, v128, v129
	s_waitcnt lgkmcnt(3)
	v_mfma_f32_16x16x32_bf16 v[82:85], v[178:181], v[154:157], v[82:85]
	v_add_f32_e32 v250, v130, v250
	v_mfma_f32_16x16x32_bf16 v[86:89], v[178:181], v[170:173], v[86:89]
	ds_read_b128 v[178:181], v237 offset:32768
	v_add_f32_e32 v250, v131, v250
	v_add_f32_e32 v250, v132, v250
	s_waitcnt lgkmcnt(3)
	v_mfma_f32_16x16x32_bf16 v[90:93], v[182:185], v[154:157], v[90:93]
	v_add_f32_e32 v250, v133, v250
	v_mfma_f32_16x16x32_bf16 v[94:97], v[182:185], v[170:173], v[94:97]
	ds_read_b128 v[182:185], v237 offset:36864
	v_add_f32_e32 v250, v138, v250
	v_add_f32_e32 v250, v139, v250
	s_waitcnt lgkmcnt(3)
	v_mfma_f32_16x16x32_bf16 v[98:101], v[186:189], v[154:157], v[98:101]
	v_add_f32_e32 v250, v140, v250
	ds_read_b64_tr_b16 v[202:203], v238 offset:16384
	ds_read_b64_tr_b16 v[204:205], v238 offset:20480
	v_mfma_f32_16x16x32_bf16 v[102:105], v[186:189], v[170:173], v[102:105]
	ds_read_b128 v[186:189], v237 offset:40960
	v_add_f32_e32 v250, v141, v250
	v_cvt_pk_bf16_f32 v130, v130, v131
	s_waitcnt lgkmcnt(5)
	v_mfma_f32_16x16x32_bf16 v[106:109], v[190:193], v[154:157], v[106:109]
	v_cvt_pk_bf16_f32 v131, v132, v133
	ds_read_b64_tr_b16 v[206:207], v239 offset:16384
	ds_read_b64_tr_b16 v[208:209], v239 offset:20480
	v_mfma_f32_16x16x32_bf16 v[110:113], v[190:193], v[170:173], v[110:113]
	ds_read_b128 v[190:193], v237 offset:45056
	v_cvt_pk_bf16_f32 v132, v138, v139
	v_cvt_pk_bf16_f32 v133, v140, v141
	s_waitcnt lgkmcnt(7)
	v_mfma_f32_16x16x32_bf16 v[82:85], v[178:181], v[158:161], v[82:85]
	v_add_f32_e32 v251, v134, v251
	ds_read_b64_tr_b16 v[210:211], v240 offset:16384
	ds_read_b64_tr_b16 v[212:213], v240 offset:20480
	v_mfma_f32_16x16x32_bf16 v[86:89], v[178:181], v[174:177], v[86:89]
	v_add_f32_e32 v251, v135, v251
	v_add_f32_e32 v251, v136, v251
	s_waitcnt lgkmcnt(8)
	v_mfma_f32_16x16x32_bf16 v[90:93], v[182:185], v[158:161], v[90:93]
	v_add_f32_e32 v251, v137, v251
	ds_read_b64_tr_b16 v[214:215], v241 offset:16384
	ds_read_b64_tr_b16 v[216:217], v241 offset:20480
	v_mfma_f32_16x16x32_bf16 v[94:97], v[182:185], v[174:177], v[94:97]
	v_add_f32_e32 v251, v142, v251
	v_add_f32_e32 v251, v143, v251
	s_waitcnt lgkmcnt(7)
	v_mfma_f32_16x16x32_bf16 v[98:101], v[186:189], v[158:161], v[98:101]
	v_add_f32_e32 v251, v144, v251
	ds_read_b64_tr_b16 v[218:219], v242 offset:16384
	ds_read_b64_tr_b16 v[220:221], v242 offset:20480
	v_mfma_f32_16x16x32_bf16 v[102:105], v[186:189], v[174:177], v[102:105]
	v_add_f32_e32 v251, v145, v251
	v_cvt_pk_bf16_f32 v134, v134, v135
	s_waitcnt lgkmcnt(6)
; #define SBAR() __builtin_amdgcn_sched_barrier(0)
; template <typename TQ> ...
;     ...
;   SBAR(); qkt(pB0, pB1, (bf16*)((char*)K_lds + SHM_K), qr, r32, hi, negm);
;   finishSM(pA0, pA1, l_reg, pa0, pa1, pa2, pa3); SBAR();
;   pv_d0(o, vb0, pa0, pa1, pa2, pa3); partialSM(pB0, pB1, mC);
;   __syncthreads();
;   finishSM(pB0, pB1, l_reg, pa0, pa1, pa2, pa3); SBAR();
;   pv_d0(o, vb0 + (int)SHM_V, pa0, pa1, pa2, pa3);
	v_mfma_f32_16x16x32_bf16 v[106:109], v[190:193], v[158:161], v[106:109]
	v_cvt_pk_bf16_f32 v135, v136, v137
	ds_read_b64_tr_b16 v[222:223], v243 offset:16384
	ds_read_b64_tr_b16 v[224:225], v243 offset:20480
	v_mfma_f32_16x16x32_bf16 v[110:113], v[190:193], v[174:177], v[110:113]
	v_cvt_pk_bf16_f32 v136, v142, v143
	v_cvt_pk_bf16_f32 v137, v144, v145
	v_mfma_f32_16x16x32_bf16 v[18:21], v[202:205], v[114:117], v[18:21]
	v_exp_f32_e32 v82, v82
	v_mfma_f32_16x16x32_bf16 v[22:25], v[202:205], v[118:121], v[22:25]
	ds_read_b64_tr_b16 v[202:203], v244 offset:16384
	ds_read_b64_tr_b16 v[204:205], v244 offset:20480
	v_exp_f32_e32 v83, v83
	v_mfma_f32_16x16x32_bf16 v[26:29], v[206:209], v[114:117], v[26:29]
	v_exp_f32_e32 v84, v84
	v_mfma_f32_16x16x32_bf16 v[30:33], v[206:209], v[118:121], v[30:33]
	ds_read_b64_tr_b16 v[206:207], v245 offset:16384
	ds_read_b64_tr_b16 v[208:209], v245 offset:20480
	v_exp_f32_e32 v85, v85
	s_waitcnt lgkmcnt(10)
	v_mfma_f32_16x16x32_bf16 v[34:37], v[210:213], v[114:117], v[34:37]
	v_exp_f32_e32 v86, v86
	v_mfma_f32_16x16x32_bf16 v[38:41], v[210:213], v[118:121], v[38:41]
	ds_read_b64_tr_b16 v[210:211], v238 offset:24576
	ds_read_b64_tr_b16 v[212:213], v238 offset:28672
	v_exp_f32_e32 v87, v87
	s_waitcnt lgkmcnt(10)
	v_mfma_f32_16x16x32_bf16 v[42:45], v[214:217], v[114:117], v[42:45]
	v_exp_f32_e32 v88, v88
	v_mfma_f32_16x16x32_bf16 v[46:49], v[214:217], v[118:121], v[46:49]
	ds_read_b64_tr_b16 v[214:215], v239 offset:24576
	ds_read_b64_tr_b16 v[216:217], v239 offset:28672
	v_exp_f32_e32 v89, v89
	s_waitcnt lgkmcnt(10)
	v_mfma_f32_16x16x32_bf16 v[50:53], v[218:221], v[114:117], v[50:53]
	v_exp_f32_e32 v90, v90
	v_mfma_f32_16x16x32_bf16 v[54:57], v[218:221], v[118:121], v[54:57]
	ds_read_b64_tr_b16 v[218:219], v240 offset:24576
	ds_read_b64_tr_b16 v[220:221], v240 offset:28672
	v_exp_f32_e32 v91, v91
	s_waitcnt lgkmcnt(10)
	v_mfma_f32_16x16x32_bf16 v[58:61], v[222:225], v[114:117], v[58:61]
	v_exp_f32_e32 v92, v92
	v_mfma_f32_16x16x32_bf16 v[62:65], v[222:225], v[118:121], v[62:65]
	ds_read_b64_tr_b16 v[222:223], v241 offset:24576
	ds_read_b64_tr_b16 v[224:225], v241 offset:28672
	v_exp_f32_e32 v93, v93
	s_waitcnt lgkmcnt(10)
	v_mfma_f32_16x16x32_bf16 v[66:69], v[202:205], v[114:117], v[66:69]
	v_exp_f32_e32 v94, v94
	v_mfma_f32_16x16x32_bf16 v[70:73], v[202:205], v[118:121], v[70:73]
	ds_read_b64_tr_b16 v[202:203], v242 offset:24576
	ds_read_b64_tr_b16 v[204:205], v242 offset:28672
	v_exp_f32_e32 v95, v95
	s_waitcnt lgkmcnt(10)
	v_mfma_f32_16x16x32_bf16 v[74:77], v[206:209], v[114:117], v[74:77]
	v_exp_f32_e32 v96, v96
	v_mfma_f32_16x16x32_bf16 v[78:81], v[206:209], v[118:121], v[78:81]
	ds_read_b64_tr_b16 v[206:207], v243 offset:24576
	ds_read_b64_tr_b16 v[208:209], v243 offset:28672
	v_exp_f32_e32 v97, v97
	s_waitcnt lgkmcnt(10)
	v_mfma_f32_16x16x32_bf16 v[18:21], v[210:213], v[130:133], v[18:21]
	v_exp_f32_e32 v98, v98
	v_mfma_f32_16x16x32_bf16 v[22:25], v[210:213], v[134:137], v[22:25]
	ds_read_b64_tr_b16 v[210:211], v244 offset:24576
	ds_read_b64_tr_b16 v[212:213], v244 offset:28672
	v_exp_f32_e32 v99, v99
	s_waitcnt lgkmcnt(10)
	v_mfma_f32_16x16x32_bf16 v[26:29], v[214:217], v[130:133], v[26:29]
	v_exp_f32_e32 v100, v100
	v_mfma_f32_16x16x32_bf16 v[30:33], v[214:217], v[134:137], v[30:33]
	ds_read_b64_tr_b16 v[214:215], v245 offset:24576
	ds_read_b64_tr_b16 v[216:217], v245 offset:28672
	v_exp_f32_e32 v101, v101
	s_waitcnt lgkmcnt(10)
	v_mfma_f32_16x16x32_bf16 v[34:37], v[218:221], v[130:133], v[34:37]
	v_exp_f32_e32 v102, v102
	v_mfma_f32_16x16x32_bf16 v[38:41], v[218:221], v[134:137], v[38:41]
	v_exp_f32_e32 v103, v103
	s_waitcnt lgkmcnt(8)
	v_mfma_f32_16x16x32_bf16 v[42:45], v[222:225], v[130:133], v[42:45]
	v_exp_f32_e32 v104, v104
	v_mfma_f32_16x16x32_bf16 v[46:49], v[222:225], v[134:137], v[46:49]
	v_exp_f32_e32 v105, v105
	s_waitcnt lgkmcnt(6)
	v_mfma_f32_16x16x32_bf16 v[50:53], v[202:205], v[130:133], v[50:53]
	v_exp_f32_e32 v106, v106
	ds_read_b128 v[178:181], v234 offset:49152
	v_mfma_f32_16x16x32_bf16 v[54:57], v[202:205], v[134:137], v[54:57]
	v_exp_f32_e32 v107, v107
	s_waitcnt lgkmcnt(5)
	v_mfma_f32_16x16x32_bf16 v[58:61], v[206:209], v[130:133], v[58:61]
	v_exp_f32_e32 v108, v108
	ds_read_b128 v[182:185], v234 offset:53248
	v_mfma_f32_16x16x32_bf16 v[62:65], v[206:209], v[134:137], v[62:65]
	v_exp_f32_e32 v109, v109
	s_waitcnt lgkmcnt(4)
	v_mfma_f32_16x16x32_bf16 v[66:69], v[210:213], v[130:133], v[66:69]
	v_exp_f32_e32 v110, v110
	ds_read_b128 v[186:189], v234 offset:57344
	v_mfma_f32_16x16x32_bf16 v[70:73], v[210:213], v[134:137], v[70:73]
	v_exp_f32_e32 v111, v111
	s_waitcnt lgkmcnt(3)
	v_mfma_f32_16x16x32_bf16 v[74:77], v[214:217], v[130:133], v[74:77]
	v_exp_f32_e32 v112, v112
	ds_read_b128 v[190:193], v234 offset:61440
	v_mfma_f32_16x16x32_bf16 v[78:81], v[214:217], v[134:137], v[78:81]
	v_exp_f32_e32 v113, v113
	s_waitcnt vmcnt(2)
	s_barrier
; #define SBAR() __builtin_amdgcn_sched_barrier(0)
; template <typename TQ> ...
;     ...
;   SBAR(); qkt(pB0, pB1, (bf16*)((char*)K_lds + SHM_K), qr, r32, hi, negm);
;   finishSM(pA0, pA1, l_reg, pa0, pa1, pa2, pa3); SBAR();
;   pv_d0(o, vb0, pa0, pa1, pa2, pa3); partialSM(pB0, pB1, mC);
;   __syncthreads();
;   finishSM(pB0, pB1, l_reg, pa0, pa1, pa2, pa3); SBAR();
;   pv_d0(o, vb0 + (int)SHM_V, pa0, pa1, pa2, pa3);
	s_waitcnt lgkmcnt(3)
	v_mfma_f32_16x16x32_bf16 v[114:117], v[178:181], v[146:149], v[2:5]
	v_add_f32_e32 v250, v82, v250
	v_mfma_f32_16x16x32_bf16 v[118:121], v[178:181], v[162:165], v[2:5]
	ds_read_b128 v[178:181], v235 offset:49152
	v_add_f32_e32 v250, v83, v250
	v_add_f32_e32 v250, v84, v250
	s_waitcnt lgkmcnt(3)
	v_mfma_f32_16x16x32_bf16 v[122:125], v[182:185], v[146:149], v[2:5]
	v_add_f32_e32 v250, v85, v250
	v_mfma_f32_16x16x32_bf16 v[126:129], v[182:185], v[162:165], v[2:5]
	ds_read_b128 v[182:185], v235 offset:53248
	v_add_f32_e32 v250, v90, v250
	v_add_f32_e32 v250, v91, v250
	s_waitcnt lgkmcnt(3)
	v_mfma_f32_16x16x32_bf16 v[130:133], v[186:189], v[146:149], v[2:5]
	v_add_f32_e32 v250, v92, v250
	v_mfma_f32_16x16x32_bf16 v[134:137], v[186:189], v[162:165], v[2:5]
	ds_read_b128 v[186:189], v235 offset:57344
	v_add_f32_e32 v250, v93, v250
	v_cvt_pk_bf16_f32 v82, v82, v83
	s_waitcnt lgkmcnt(3)
	v_mfma_f32_16x16x32_bf16 v[138:141], v[190:193], v[146:149], v[2:5]
	v_cvt_pk_bf16_f32 v83, v84, v85
	v_mfma_f32_16x16x32_bf16 v[142:145], v[190:193], v[162:165], v[2:5]
	ds_read_b128 v[190:193], v235 offset:61440
	v_cvt_pk_bf16_f32 v84, v90, v91
	v_cvt_pk_bf16_f32 v85, v92, v93
	s_waitcnt lgkmcnt(3)
	v_mfma_f32_16x16x32_bf16 v[114:117], v[178:181], v[150:153], v[114:117]
	v_add_f32_e32 v251, v86, v251
	v_mfma_f32_16x16x32_bf16 v[118:121], v[178:181], v[166:169], v[118:121]
	ds_read_b128 v[178:181], v236 offset:49152
	v_add_f32_e32 v251, v87, v251
	v_add_f32_e32 v251, v88, v251
	s_waitcnt lgkmcnt(3)
	v_mfma_f32_16x16x32_bf16 v[122:125], v[182:185], v[150:153], v[122:125]
	v_add_f32_e32 v251, v89, v251
	v_mfma_f32_16x16x32_bf16 v[126:129], v[182:185], v[166:169], v[126:129]
	ds_read_b128 v[182:185], v236 offset:53248
	v_add_f32_e32 v251, v94, v251
	v_add_f32_e32 v251, v95, v251
	s_waitcnt lgkmcnt(3)
	v_mfma_f32_16x16x32_bf16 v[130:133], v[186:189], v[150:153], v[130:133]
	v_add_f32_e32 v251, v96, v251
	v_mfma_f32_16x16x32_bf16 v[134:137], v[186:189], v[166:169], v[134:137]
	ds_read_b128 v[186:189], v236 offset:57344
	v_add_f32_e32 v251, v97, v251
	v_cvt_pk_bf16_f32 v86, v86, v87
	s_waitcnt lgkmcnt(3)
	v_mfma_f32_16x16x32_bf16 v[138:141], v[190:193], v[150:153], v[138:141]
	v_cvt_pk_bf16_f32 v87, v88, v89
	v_mfma_f32_16x16x32_bf16 v[142:145], v[190:193], v[166:169], v[142:145]
	ds_read_b128 v[190:193], v236 offset:61440
	v_cvt_pk_bf16_f32 v88, v94, v95
	v_cvt_pk_bf16_f32 v89, v96, v97
	s_waitcnt lgkmcnt(3)
	v_mfma_f32_16x16x32_bf16 v[114:117], v[178:181], v[154:157], v[114:117]
	v_add_f32_e32 v250, v98, v250
	v_mfma_f32_16x16x32_bf16 v[118:121], v[178:181], v[170:173], v[118:121]
	ds_read_b128 v[178:181], v237 offset:49152
	v_add_f32_e32 v250, v99, v250
	v_add_f32_e32 v250, v100, v250
	s_waitcnt lgkmcnt(3)
	v_mfma_f32_16x16x32_bf16 v[122:125], v[182:185], v[154:157], v[122:125]
	v_add_f32_e32 v250, v101, v250
	v_mfma_f32_16x16x32_bf16 v[126:129], v[182:185], v[170:173], v[126:129]
	ds_read_b128 v[182:185], v237 offset:53248
	v_add_f32_e32 v250, v106, v250
	v_add_f32_e32 v250, v107, v250
	s_waitcnt lgkmcnt(3)
	v_mfma_f32_16x16x32_bf16 v[130:133], v[186:189], v[154:157], v[130:133]
	v_add_f32_e32 v250, v108, v250
	ds_read_b64_tr_b16 v[202:203], v238 offset:32768
	ds_read_b64_tr_b16 v[204:205], v238 offset:36864
	v_mfma_f32_16x16x32_bf16 v[134:137], v[186:189], v[170:173], v[134:137]
	ds_read_b128 v[186:189], v237 offset:57344
	v_add_f32_e32 v250, v109, v250
	v_cvt_pk_bf16_f32 v98, v98, v99
	s_waitcnt lgkmcnt(5)
	v_mfma_f32_16x16x32_bf16 v[138:141], v[190:193], v[154:157], v[138:141]
	v_cvt_pk_bf16_f32 v99, v100, v101
	ds_read_b64_tr_b16 v[206:207], v239 offset:32768
	ds_read_b64_tr_b16 v[208:209], v239 offset:36864
	v_mfma_f32_16x16x32_bf16 v[142:145], v[190:193], v[170:173], v[142:145]
	ds_read_b128 v[190:193], v237 offset:61440
	v_cvt_pk_bf16_f32 v100, v106, v107
	v_cvt_pk_bf16_f32 v101, v108, v109
	s_waitcnt lgkmcnt(7)
	v_mfma_f32_16x16x32_bf16 v[114:117], v[178:181], v[158:161], v[114:117]
	v_add_f32_e32 v251, v102, v251
	ds_read_b64_tr_b16 v[210:211], v240 offset:32768
	ds_read_b64_tr_b16 v[212:213], v240 offset:36864
	v_mfma_f32_16x16x32_bf16 v[118:121], v[178:181], v[174:177], v[118:121]
	v_add_f32_e32 v251, v103, v251
	v_add_f32_e32 v251, v104, v251
	s_waitcnt lgkmcnt(8)
	v_mfma_f32_16x16x32_bf16 v[122:125], v[182:185], v[158:161], v[122:125]
	v_add_f32_e32 v251, v105, v251
	ds_read_b64_tr_b16 v[214:215], v241 offset:32768
	ds_read_b64_tr_b16 v[216:217], v241 offset:36864
	v_mfma_f32_16x16x32_bf16 v[126:129], v[182:185], v[174:177], v[126:129]
	v_add_f32_e32 v251, v110, v251
	v_add_f32_e32 v251, v111, v251
	s_waitcnt lgkmcnt(7)
	v_mfma_f32_16x16x32_bf16 v[130:133], v[186:189], v[158:161], v[130:133]
	v_add_f32_e32 v251, v112, v251
	ds_read_b64_tr_b16 v[218:219], v242 offset:32768
	ds_read_b64_tr_b16 v[220:221], v242 offset:36864
	v_mfma_f32_16x16x32_bf16 v[134:137], v[186:189], v[174:177], v[134:137]
	v_add_f32_e32 v251, v113, v251
	v_cvt_pk_bf16_f32 v102, v102, v103
	s_waitcnt lgkmcnt(6)
	v_mfma_f32_16x16x32_bf16 v[138:141], v[190:193], v[158:161], v[138:141]
	v_cvt_pk_bf16_f32 v103, v104, v105
	ds_read_b64_tr_b16 v[222:223], v243 offset:32768
	ds_read_b64_tr_b16 v[224:225], v243 offset:36864
	v_mfma_f32_16x16x32_bf16 v[142:145], v[190:193], v[174:177], v[142:145]
	v_cvt_pk_bf16_f32 v104, v110, v111
	v_cvt_pk_bf16_f32 v105, v112, v113
	v_mfma_f32_16x16x32_bf16 v[18:21], v[202:205], v[82:85], v[18:21]
	v_exp_f32_e32 v114, v114
	v_mfma_f32_16x16x32_bf16 v[22:25], v[202:205], v[86:89], v[22:25]
	ds_read_b64_tr_b16 v[202:203], v244 offset:32768
	ds_read_b64_tr_b16 v[204:205], v244 offset:36864
	v_exp_f32_e32 v115, v115
	v_mfma_f32_16x16x32_bf16 v[26:29], v[206:209], v[82:85], v[26:29]
	v_exp_f32_e32 v116, v116
	v_mfma_f32_16x16x32_bf16 v[30:33], v[206:209], v[86:89], v[30:33]
	ds_read_b64_tr_b16 v[206:207], v245 offset:32768
	ds_read_b64_tr_b16 v[208:209], v245 offset:36864
	v_exp_f32_e32 v117, v117
	s_waitcnt lgkmcnt(10)
; #define SBAR() __builtin_amdgcn_sched_barrier(0)
; #define SLOAD(i, k0) do { sr_[i].vs0 = St::ld8(&Vh[(long)((k0) + sr) * LDK + sc]); sr_[i].vs1 = St::ld8(&Vh[(long)((k0) + 32 + sr) * LDK + sc]); \
;     sr_[i].ks0 = St::ld8(&Kh[(long)((k0) + sr) * LDK + sc]); sr_[i].ks1 = St::ld8(&Kh[(long)((k0) + 32 + sr) * LDK + sc]); } while (0)
; #define SWAIT() do { if constexpr (SDEPTH == 2) asm volatile("s_waitcnt vmcnt(4)" ::: "memory"); else asm volatile("s_waitcnt vmcnt(0)" ::: "memory"); } while (0)
; template <typename TQ> ...
;     ...
;   for (int j = 1; j + 1 < NT; j += 2) {
;     SBAR(); SLOAD(SO, (j + SDEPTH) * KVBLK); SBAR();
;     qkt(pB0, pB1, (bf16*)((char*)K_lds + SHM_K), qr, r32, hi, negm);
;     finishSM(pA0, pA1, l_reg, pa0, pa1, pa2, pa3); SBAR();
;     pv_d0(o, vb0, pa0, pa1, pa2, pa3); partialSM(pB0, pB1, mC);
;     __syncthreads(); SWAIT(); SWRITE(0, SE);
;     __syncthreads();
;     SBAR(); if (SDEPTH == 1 || j + 3 < NT) SLOAD(SE, (j + 1 + SDEPTH) * KVBLK); SBAR();
;     qkt(pA0, pA1, K_lds, qr, r32, hi, negm);
;     finishSM(pB0, pB1, l_reg, pa0, pa1, pa2, pa3); SBAR();
;     pv_d0(o, vb0 + (int)SHM_V, pa0, pa1, pa2, pa3); partialSM(pA0, pA1, mC);
;     ...
;   SBAR(); qkt(pB0, pB1, (bf16*)((char*)K_lds + SHM_K), qr, r32, hi, negm);
;   finishSM(pA0, pA1, l_reg, pa0, pa1, pa2, pa3); SBAR();
;   pv_d0(o, vb0, pa0, pa1, pa2, pa3); partialSM(pB0, pB1, mC);
;   __syncthreads();
;   finishSM(pB0, pB1, l_reg, pa0, pa1, pa2, pa3); SBAR();
;   pv_d0(o, vb0 + (int)SHM_V, pa0, pa1, pa2, pa3);
	v_mfma_f32_16x16x32_bf16 v[34:37], v[210:213], v[82:85], v[34:37]
	v_exp_f32_e32 v118, v118
	v_mfma_f32_16x16x32_bf16 v[38:41], v[210:213], v[86:89], v[38:41]
	ds_read_b64_tr_b16 v[210:211], v238 offset:40960
	ds_read_b64_tr_b16 v[212:213], v238 offset:45056
	v_exp_f32_e32 v119, v119
	s_waitcnt lgkmcnt(10)
	v_mfma_f32_16x16x32_bf16 v[42:45], v[214:217], v[82:85], v[42:45]
	v_exp_f32_e32 v120, v120
	v_mfma_f32_16x16x32_bf16 v[46:49], v[214:217], v[86:89], v[46:49]
	ds_read_b64_tr_b16 v[214:215], v239 offset:40960
	ds_read_b64_tr_b16 v[216:217], v239 offset:45056
	v_exp_f32_e32 v121, v121
	s_waitcnt lgkmcnt(10)
	v_mfma_f32_16x16x32_bf16 v[50:53], v[218:221], v[82:85], v[50:53]
	v_exp_f32_e32 v122, v122
	v_mfma_f32_16x16x32_bf16 v[54:57], v[218:221], v[86:89], v[54:57]
	ds_read_b64_tr_b16 v[218:219], v240 offset:40960
	ds_read_b64_tr_b16 v[220:221], v240 offset:45056
	v_exp_f32_e32 v123, v123
	s_waitcnt lgkmcnt(10)
	v_mfma_f32_16x16x32_bf16 v[58:61], v[222:225], v[82:85], v[58:61]
	v_exp_f32_e32 v124, v124
	v_mfma_f32_16x16x32_bf16 v[62:65], v[222:225], v[86:89], v[62:65]
	ds_read_b64_tr_b16 v[222:223], v241 offset:40960
	ds_read_b64_tr_b16 v[224:225], v241 offset:45056
	v_exp_f32_e32 v125, v125
	s_waitcnt lgkmcnt(10)
	v_mfma_f32_16x16x32_bf16 v[66:69], v[202:205], v[82:85], v[66:69]
	v_exp_f32_e32 v126, v126
	v_mfma_f32_16x16x32_bf16 v[70:73], v[202:205], v[86:89], v[70:73]
	ds_read_b64_tr_b16 v[202:203], v242 offset:40960
	ds_read_b64_tr_b16 v[204:205], v242 offset:45056
	v_exp_f32_e32 v127, v127
	s_waitcnt lgkmcnt(10)
	v_mfma_f32_16x16x32_bf16 v[74:77], v[206:209], v[82:85], v[74:77]
	v_exp_f32_e32 v128, v128
	v_mfma_f32_16x16x32_bf16 v[78:81], v[206:209], v[86:89], v[78:81]
	ds_read_b64_tr_b16 v[206:207], v243 offset:40960
	ds_read_b64_tr_b16 v[208:209], v243 offset:45056
	v_exp_f32_e32 v129, v129
	s_waitcnt lgkmcnt(10)
	v_mfma_f32_16x16x32_bf16 v[18:21], v[210:213], v[98:101], v[18:21]
	v_exp_f32_e32 v130, v130
	v_mfma_f32_16x16x32_bf16 v[22:25], v[210:213], v[102:105], v[22:25]
	ds_read_b64_tr_b16 v[210:211], v244 offset:40960
	ds_read_b64_tr_b16 v[212:213], v244 offset:45056
	v_exp_f32_e32 v131, v131
	s_waitcnt lgkmcnt(10)
	v_mfma_f32_16x16x32_bf16 v[26:29], v[214:217], v[98:101], v[26:29]
	v_exp_f32_e32 v132, v132
	v_mfma_f32_16x16x32_bf16 v[30:33], v[214:217], v[102:105], v[30:33]
	ds_read_b64_tr_b16 v[214:215], v245 offset:40960
	ds_read_b64_tr_b16 v[216:217], v245 offset:45056
	v_exp_f32_e32 v133, v133
	s_waitcnt lgkmcnt(10)
	v_mfma_f32_16x16x32_bf16 v[34:37], v[218:221], v[98:101], v[34:37]
	v_exp_f32_e32 v134, v134
	v_mfma_f32_16x16x32_bf16 v[38:41], v[218:221], v[102:105], v[38:41]
	v_exp_f32_e32 v135, v135
	s_waitcnt lgkmcnt(8)
	v_mfma_f32_16x16x32_bf16 v[42:45], v[222:225], v[98:101], v[42:45]
	v_exp_f32_e32 v136, v136
	v_mfma_f32_16x16x32_bf16 v[46:49], v[222:225], v[102:105], v[46:49]
	v_exp_f32_e32 v137, v137
	s_waitcnt lgkmcnt(6)
	v_mfma_f32_16x16x32_bf16 v[50:53], v[202:205], v[98:101], v[50:53]
	v_exp_f32_e32 v138, v138
	v_mfma_f32_16x16x32_bf16 v[54:57], v[202:205], v[102:105], v[54:57]
	v_exp_f32_e32 v139, v139
	s_waitcnt lgkmcnt(4)
	v_mfma_f32_16x16x32_bf16 v[58:61], v[206:209], v[98:101], v[58:61]
	v_exp_f32_e32 v140, v140
	v_mfma_f32_16x16x32_bf16 v[62:65], v[206:209], v[102:105], v[62:65]
	v_exp_f32_e32 v141, v141
	s_waitcnt lgkmcnt(2)
	v_mfma_f32_16x16x32_bf16 v[66:69], v[210:213], v[98:101], v[66:69]
	v_exp_f32_e32 v142, v142
	v_mfma_f32_16x16x32_bf16 v[70:73], v[210:213], v[102:105], v[70:73]
	v_exp_f32_e32 v143, v143
	s_waitcnt lgkmcnt(0)
	v_mfma_f32_16x16x32_bf16 v[74:77], v[214:217], v[98:101], v[74:77]
	v_exp_f32_e32 v144, v144
	v_mfma_f32_16x16x32_bf16 v[78:81], v[214:217], v[102:105], v[78:81]
	v_exp_f32_e32 v145, v145
	s_waitcnt vmcnt(0)
	s_branch .Lattn_fin
.Lattn_v2:
	s_setprio 1
	s_barrier
	s_waitcnt lgkmcnt(3)
	v_mfma_f32_16x16x32_bf16 v[114:117], v[178:181], v[146:149], v[2:5]
	v_add_f32_e32 v250, v82, v250
	s_add_u32 s98, s98, 0x8000
	s_addc_u32 s99, s99, 0
	s_add_u32 s100, s100, 0x8000
	s_addc_u32 s101, s101, 0
	v_mfma_f32_16x16x32_bf16 v[118:121], v[178:181], v[162:165], v[2:5]
	ds_read_b128 v[178:181], v235 offset:16384
	v_add_f32_e32 v250, v83, v250
	v_add_f32_e32 v250, v84, v250
	s_waitcnt lgkmcnt(3)
	v_mfma_f32_16x16x32_bf16 v[122:125], v[182:185], v[146:149], v[2:5]
	v_add_f32_e32 v250, v85, v250
	s_add_u32 m0, s79, 0
	s_nop 0
	global_load_lds_dwordx4 v246, s[98:99]
	v_mfma_f32_16x16x32_bf16 v[126:129], v[182:185], v[162:165], v[2:5]
	ds_read_b128 v[182:185], v235 offset:20480
	v_add_f32_e32 v250, v90, v250
	v_add_f32_e32 v250, v91, v250
	s_waitcnt lgkmcnt(3)
	v_mfma_f32_16x16x32_bf16 v[130:133], v[186:189], v[146:149], v[2:5]
	v_add_f32_e32 v250, v92, v250
	v_mfma_f32_16x16x32_bf16 v[134:137], v[186:189], v[162:165], v[2:5]
	ds_read_b128 v[186:189], v235 offset:24576
	v_add_f32_e32 v250, v93, v250
	v_cvt_pk_bf16_f32 v82, v82, v83
	s_waitcnt lgkmcnt(3)
	v_mfma_f32_16x16x32_bf16 v[138:141], v[190:193], v[146:149], v[2:5]
	v_cvt_pk_bf16_f32 v83, v84, v85
	s_add_u32 m0, s79, 1024
	s_nop 0
	global_load_lds_dwordx4 v247, s[98:99]
	v_mfma_f32_16x16x32_bf16 v[142:145], v[190:193], v[162:165], v[2:5]
	ds_read_b128 v[190:193], v235 offset:28672
	v_cvt_pk_bf16_f32 v84, v90, v91
	v_cvt_pk_bf16_f32 v85, v92, v93
	s_waitcnt lgkmcnt(3)
	v_mfma_f32_16x16x32_bf16 v[114:117], v[178:181], v[150:153], v[114:117]
	v_add_f32_e32 v251, v86, v251
	v_mfma_f32_16x16x32_bf16 v[118:121], v[178:181], v[166:169], v[118:121]
	ds_read_b128 v[178:181], v236 offset:16384
	v_add_f32_e32 v251, v87, v251
	v_add_f32_e32 v251, v88, v251
	s_waitcnt lgkmcnt(3)
; #define SBAR() __builtin_amdgcn_sched_barrier(0)
; #define SLOAD(i, k0) do { sr_[i].vs0 = St::ld8(&Vh[(long)((k0) + sr) * LDK + sc]); sr_[i].vs1 = St::ld8(&Vh[(long)((k0) + 32 + sr) * LDK + sc]); \
;     sr_[i].ks0 = St::ld8(&Kh[(long)((k0) + sr) * LDK + sc]); sr_[i].ks1 = St::ld8(&Kh[(long)((k0) + 32 + sr) * LDK + sc]); } while (0)
; #define SWAIT() do { if constexpr (SDEPTH == 2) asm volatile("s_waitcnt vmcnt(4)" ::: "memory"); else asm volatile("s_waitcnt vmcnt(0)" ::: "memory"); } while (0)
; template <typename TQ> ...
;     ...
;   for (int j = 1; j + 1 < NT; j += 2) {
;     SBAR(); SLOAD(SO, (j + SDEPTH) * KVBLK); SBAR();
;     qkt(pB0, pB1, (bf16*)((char*)K_lds + SHM_K), qr, r32, hi, negm);
;     finishSM(pA0, pA1, l_reg, pa0, pa1, pa2, pa3); SBAR();
;     pv_d0(o, vb0, pa0, pa1, pa2, pa3); partialSM(pB0, pB1, mC);
;     __syncthreads(); SWAIT(); SWRITE(0, SE);
;     __syncthreads();
;     SBAR(); if (SDEPTH == 1 || j + 3 < NT) SLOAD(SE, (j + 1 + SDEPTH) * KVBLK); SBAR();
;     qkt(pA0, pA1, K_lds, qr, r32, hi, negm);
;     finishSM(pB0, pB1, l_reg, pa0, pa1, pa2, pa3); SBAR();
;     pv_d0(o, vb0 + (int)SHM_V, pa0, pa1, pa2, pa3); partialSM(pA0, pA1, mC);
;     __syncthreads(); SWAIT(); SWRITE(1, SO);
;     __syncthreads();
	v_mfma_f32_16x16x32_bf16 v[122:125], v[182:185], v[150:153], v[122:125]
	v_add_f32_e32 v251, v89, v251
	s_add_u32 m0, s80, 32768
	s_nop 0
	global_load_lds_dwordx4 v248, s[100:101]
	v_mfma_f32_16x16x32_bf16 v[126:129], v[182:185], v[166:169], v[126:129]
	ds_read_b128 v[182:185], v236 offset:20480
	v_add_f32_e32 v251, v94, v251
	v_add_f32_e32 v251, v95, v251
	s_waitcnt lgkmcnt(3)
	v_mfma_f32_16x16x32_bf16 v[130:133], v[186:189], v[150:153], v[130:133]
	v_add_f32_e32 v251, v96, v251
	v_mfma_f32_16x16x32_bf16 v[134:137], v[186:189], v[166:169], v[134:137]
	ds_read_b128 v[186:189], v236 offset:24576
	v_add_f32_e32 v251, v97, v251
	v_cvt_pk_bf16_f32 v86, v86, v87
	s_waitcnt lgkmcnt(3)
	v_mfma_f32_16x16x32_bf16 v[138:141], v[190:193], v[150:153], v[138:141]
	v_cvt_pk_bf16_f32 v87, v88, v89
	s_add_u32 m0, s80, 33792
	s_nop 0
	global_load_lds_dwordx4 v249, s[100:101]
	v_mfma_f32_16x16x32_bf16 v[142:145], v[190:193], v[166:169], v[142:145]
	ds_read_b128 v[190:193], v236 offset:28672
	v_cvt_pk_bf16_f32 v88, v94, v95
	v_cvt_pk_bf16_f32 v89, v96, v97
	s_waitcnt lgkmcnt(3)
	v_mfma_f32_16x16x32_bf16 v[114:117], v[178:181], v[154:157], v[114:117]
	v_add_f32_e32 v250, v98, v250
	v_mfma_f32_16x16x32_bf16 v[118:121], v[178:181], v[170:173], v[118:121]
	ds_read_b128 v[178:181], v237 offset:16384
	v_add_f32_e32 v250, v99, v250
	v_add_f32_e32 v250, v100, v250
	s_waitcnt lgkmcnt(3)
	v_mfma_f32_16x16x32_bf16 v[122:125], v[182:185], v[154:157], v[122:125]
	v_add_f32_e32 v250, v101, v250
	v_mfma_f32_16x16x32_bf16 v[126:129], v[182:185], v[170:173], v[126:129]
	ds_read_b128 v[182:185], v237 offset:20480
	v_add_f32_e32 v250, v106, v250
	v_add_f32_e32 v250, v107, v250
	s_waitcnt lgkmcnt(3)
	v_mfma_f32_16x16x32_bf16 v[130:133], v[186:189], v[154:157], v[130:133]
	v_add_f32_e32 v250, v108, v250
	ds_read_b64_tr_b16 v[202:203], v238 offset:0
	ds_read_b64_tr_b16 v[204:205], v238 offset:4096
	v_mfma_f32_16x16x32_bf16 v[134:137], v[186:189], v[170:173], v[134:137]
	ds_read_b128 v[186:189], v237 offset:24576
	v_add_f32_e32 v250, v109, v250
	v_cvt_pk_bf16_f32 v98, v98, v99
	s_waitcnt lgkmcnt(5)
	v_mfma_f32_16x16x32_bf16 v[138:141], v[190:193], v[154:157], v[138:141]
	v_cvt_pk_bf16_f32 v99, v100, v101
	ds_read_b64_tr_b16 v[206:207], v239 offset:0
	ds_read_b64_tr_b16 v[208:209], v239 offset:4096
	v_mfma_f32_16x16x32_bf16 v[142:145], v[190:193], v[170:173], v[142:145]
	ds_read_b128 v[190:193], v237 offset:28672
	v_cvt_pk_bf16_f32 v100, v106, v107
	v_cvt_pk_bf16_f32 v101, v108, v109
	s_waitcnt lgkmcnt(7)
	v_mfma_f32_16x16x32_bf16 v[114:117], v[178:181], v[158:161], v[114:117]
	v_add_f32_e32 v251, v102, v251
	ds_read_b64_tr_b16 v[210:211], v240 offset:0
	ds_read_b64_tr_b16 v[212:213], v240 offset:4096
	v_mfma_f32_16x16x32_bf16 v[118:121], v[178:181], v[174:177], v[118:121]
	v_add_f32_e32 v251, v103, v251
	v_add_f32_e32 v251, v104, v251
	s_waitcnt lgkmcnt(8)
	v_mfma_f32_16x16x32_bf16 v[122:125], v[182:185], v[158:161], v[122:125]
	v_add_f32_e32 v251, v105, v251
	ds_read_b64_tr_b16 v[214:215], v241 offset:0
	ds_read_b64_tr_b16 v[216:217], v241 offset:4096
	v_mfma_f32_16x16x32_bf16 v[126:129], v[182:185], v[174:177], v[126:129]
	v_add_f32_e32 v251, v110, v251
	v_add_f32_e32 v251, v111, v251
	s_waitcnt lgkmcnt(7)
	v_mfma_f32_16x16x32_bf16 v[130:133], v[186:189], v[158:161], v[130:133]
	v_add_f32_e32 v251, v112, v251
	ds_read_b64_tr_b16 v[218:219], v242 offset:0
	ds_read_b64_tr_b16 v[220:221], v242 offset:4096
	v_mfma_f32_16x16x32_bf16 v[134:137], v[186:189], v[174:177], v[134:137]
	v_add_f32_e32 v251, v113, v251
	v_cvt_pk_bf16_f32 v102, v102, v103
	s_waitcnt lgkmcnt(6)
	v_mfma_f32_16x16x32_bf16 v[138:141], v[190:193], v[158:161], v[138:141]
	v_cvt_pk_bf16_f32 v103, v104, v105
	ds_read_b64_tr_b16 v[222:223], v243 offset:0
	ds_read_b64_tr_b16 v[224:225], v243 offset:4096
	v_mfma_f32_16x16x32_bf16 v[142:145], v[190:193], v[174:177], v[142:145]
	v_cvt_pk_bf16_f32 v104, v110, v111
	v_cvt_pk_bf16_f32 v105, v112, v113
	s_waitcnt vmcnt(4)
.Lattn_loop2:
	s_barrier
	v_mfma_f32_16x16x32_bf16 v[18:21], v[202:205], v[82:85], v[18:21]
	v_exp_f32_e32 v114, v114
	v_mfma_f32_16x16x32_bf16 v[22:25], v[202:205], v[86:89], v[22:25]
	ds_read_b64_tr_b16 v[202:203], v244 offset:0
	ds_read_b64_tr_b16 v[204:205], v244 offset:4096
	v_exp_f32_e32 v115, v115
	v_mfma_f32_16x16x32_bf16 v[26:29], v[206:209], v[82:85], v[26:29]
	v_exp_f32_e32 v116, v116
	v_mfma_f32_16x16x32_bf16 v[30:33], v[206:209], v[86:89], v[30:33]
	ds_read_b64_tr_b16 v[206:207], v245 offset:0
	ds_read_b64_tr_b16 v[208:209], v245 offset:4096
	v_exp_f32_e32 v117, v117
	s_waitcnt lgkmcnt(10)
	v_mfma_f32_16x16x32_bf16 v[34:37], v[210:213], v[82:85], v[34:37]
	v_exp_f32_e32 v118, v118
	v_mfma_f32_16x16x32_bf16 v[38:41], v[210:213], v[86:89], v[38:41]
	ds_read_b64_tr_b16 v[210:211], v238 offset:8192
	ds_read_b64_tr_b16 v[212:213], v238 offset:12288
	v_exp_f32_e32 v119, v119
	s_waitcnt lgkmcnt(10)
	v_mfma_f32_16x16x32_bf16 v[42:45], v[214:217], v[82:85], v[42:45]
	v_exp_f32_e32 v120, v120
	v_mfma_f32_16x16x32_bf16 v[46:49], v[214:217], v[86:89], v[46:49]
	ds_read_b64_tr_b16 v[214:215], v239 offset:8192
	ds_read_b64_tr_b16 v[216:217], v239 offset:12288
	v_exp_f32_e32 v121, v121
	s_waitcnt lgkmcnt(10)
	v_mfma_f32_16x16x32_bf16 v[50:53], v[218:221], v[82:85], v[50:53]
	v_exp_f32_e32 v122, v122
	v_mfma_f32_16x16x32_bf16 v[54:57], v[218:221], v[86:89], v[54:57]
	ds_read_b64_tr_b16 v[218:219], v240 offset:8192
	ds_read_b64_tr_b16 v[220:221], v240 offset:12288
	v_exp_f32_e32 v123, v123
	s_waitcnt lgkmcnt(10)
; #define SBAR() __builtin_amdgcn_sched_barrier(0)
; #define SLOAD(i, k0) do { sr_[i].vs0 = St::ld8(&Vh[(long)((k0) + sr) * LDK + sc]); sr_[i].vs1 = St::ld8(&Vh[(long)((k0) + 32 + sr) * LDK + sc]); \
;     sr_[i].ks0 = St::ld8(&Kh[(long)((k0) + sr) * LDK + sc]); sr_[i].ks1 = St::ld8(&Kh[(long)((k0) + 32 + sr) * LDK + sc]); } while (0)
; #define SWAIT() do { if constexpr (SDEPTH == 2) asm volatile("s_waitcnt vmcnt(4)" ::: "memory"); else asm volatile("s_waitcnt vmcnt(0)" ::: "memory"); } while (0)
; template <typename TQ> ...
;     ...
;   for (int j = 1; j + 1 < NT; j += 2) {
;     SBAR(); SLOAD(SO, (j + SDEPTH) * KVBLK); SBAR();
;     qkt(pB0, pB1, (bf16*)((char*)K_lds + SHM_K), qr, r32, hi, negm);
;     finishSM(pA0, pA1, l_reg, pa0, pa1, pa2, pa3); SBAR();
;     pv_d0(o, vb0, pa0, pa1, pa2, pa3); partialSM(pB0, pB1, mC);
;     __syncthreads(); SWAIT(); SWRITE(0, SE);
;     __syncthreads();
;     SBAR(); if (SDEPTH == 1 || j + 3 < NT) SLOAD(SE, (j + 1 + SDEPTH) * KVBLK); SBAR();
;     qkt(pA0, pA1, K_lds, qr, r32, hi, negm);
;     finishSM(pB0, pB1, l_reg, pa0, pa1, pa2, pa3); SBAR();
;     pv_d0(o, vb0 + (int)SHM_V, pa0, pa1, pa2, pa3); partialSM(pA0, pA1, mC);
;     __syncthreads(); SWAIT(); SWRITE(1, SO);
;     __syncthreads();
	v_mfma_f32_16x16x32_bf16 v[58:61], v[222:225], v[82:85], v[58:61]
	v_exp_f32_e32 v124, v124
	v_mfma_f32_16x16x32_bf16 v[62:65], v[222:225], v[86:89], v[62:65]
	ds_read_b64_tr_b16 v[222:223], v241 offset:8192
	ds_read_b64_tr_b16 v[224:225], v241 offset:12288
	v_exp_f32_e32 v125, v125
	s_waitcnt lgkmcnt(10)
	v_mfma_f32_16x16x32_bf16 v[66:69], v[202:205], v[82:85], v[66:69]
	v_exp_f32_e32 v126, v126
	v_mfma_f32_16x16x32_bf16 v[70:73], v[202:205], v[86:89], v[70:73]
	ds_read_b64_tr_b16 v[202:203], v242 offset:8192
	ds_read_b64_tr_b16 v[204:205], v242 offset:12288
	v_exp_f32_e32 v127, v127
	s_waitcnt lgkmcnt(10)
	v_mfma_f32_16x16x32_bf16 v[74:77], v[206:209], v[82:85], v[74:77]
	v_exp_f32_e32 v128, v128
	v_mfma_f32_16x16x32_bf16 v[78:81], v[206:209], v[86:89], v[78:81]
	ds_read_b64_tr_b16 v[206:207], v243 offset:8192
	ds_read_b64_tr_b16 v[208:209], v243 offset:12288
	v_exp_f32_e32 v129, v129
	s_waitcnt lgkmcnt(10)
	v_mfma_f32_16x16x32_bf16 v[18:21], v[210:213], v[98:101], v[18:21]
	v_exp_f32_e32 v130, v130
	v_mfma_f32_16x16x32_bf16 v[22:25], v[210:213], v[102:105], v[22:25]
	ds_read_b64_tr_b16 v[210:211], v244 offset:8192
	ds_read_b64_tr_b16 v[212:213], v244 offset:12288
	v_exp_f32_e32 v131, v131
	s_waitcnt lgkmcnt(10)
	v_mfma_f32_16x16x32_bf16 v[26:29], v[214:217], v[98:101], v[26:29]
	v_exp_f32_e32 v132, v132
	v_mfma_f32_16x16x32_bf16 v[30:33], v[214:217], v[102:105], v[30:33]
	ds_read_b64_tr_b16 v[214:215], v245 offset:8192
	ds_read_b64_tr_b16 v[216:217], v245 offset:12288
	v_exp_f32_e32 v133, v133
	s_waitcnt lgkmcnt(10)
	v_mfma_f32_16x16x32_bf16 v[34:37], v[218:221], v[98:101], v[34:37]
	v_exp_f32_e32 v134, v134
	v_mfma_f32_16x16x32_bf16 v[38:41], v[218:221], v[102:105], v[38:41]
	v_exp_f32_e32 v135, v135
	s_waitcnt lgkmcnt(8)
	v_mfma_f32_16x16x32_bf16 v[42:45], v[222:225], v[98:101], v[42:45]
	v_exp_f32_e32 v136, v136
	v_mfma_f32_16x16x32_bf16 v[46:49], v[222:225], v[102:105], v[46:49]
	v_exp_f32_e32 v137, v137
	s_waitcnt lgkmcnt(6)
	v_mfma_f32_16x16x32_bf16 v[50:53], v[202:205], v[98:101], v[50:53]
	v_exp_f32_e32 v138, v138
	ds_read_b128 v[178:181], v234 offset:32768
	v_mfma_f32_16x16x32_bf16 v[54:57], v[202:205], v[102:105], v[54:57]
	v_exp_f32_e32 v139, v139
	s_waitcnt lgkmcnt(5)
	v_mfma_f32_16x16x32_bf16 v[58:61], v[206:209], v[98:101], v[58:61]
	v_exp_f32_e32 v140, v140
	ds_read_b128 v[182:185], v234 offset:36864
	v_mfma_f32_16x16x32_bf16 v[62:65], v[206:209], v[102:105], v[62:65]
	v_exp_f32_e32 v141, v141
	s_waitcnt lgkmcnt(4)
	v_mfma_f32_16x16x32_bf16 v[66:69], v[210:213], v[98:101], v[66:69]
	v_exp_f32_e32 v142, v142
	ds_read_b128 v[186:189], v234 offset:40960
	v_mfma_f32_16x16x32_bf16 v[70:73], v[210:213], v[102:105], v[70:73]
	v_exp_f32_e32 v143, v143
	s_waitcnt lgkmcnt(3)
	v_mfma_f32_16x16x32_bf16 v[74:77], v[214:217], v[98:101], v[74:77]
	v_exp_f32_e32 v144, v144
	ds_read_b128 v[190:193], v234 offset:45056
	v_mfma_f32_16x16x32_bf16 v[78:81], v[214:217], v[102:105], v[78:81]
	v_exp_f32_e32 v145, v145
	s_waitcnt lgkmcnt(3)
	v_mfma_f32_16x16x32_bf16 v[82:85], v[178:181], v[146:149], v[2:5]
	v_add_f32_e32 v250, v114, v250
	s_add_u32 s98, s98, 0x8000
	s_addc_u32 s99, s99, 0
	s_add_u32 s100, s100, 0x8000
	s_addc_u32 s101, s101, 0
	v_mfma_f32_16x16x32_bf16 v[86:89], v[178:181], v[162:165], v[2:5]
	ds_read_b128 v[178:181], v235 offset:32768
	v_add_f32_e32 v250, v115, v250
	v_add_f32_e32 v250, v116, v250
	s_waitcnt lgkmcnt(3)
	v_mfma_f32_16x16x32_bf16 v[90:93], v[182:185], v[146:149], v[2:5]
	v_add_f32_e32 v250, v117, v250
	s_add_u32 m0, s79, 16384
	s_nop 0
	global_load_lds_dwordx4 v246, s[98:99]
	v_mfma_f32_16x16x32_bf16 v[94:97], v[182:185], v[162:165], v[2:5]
	ds_read_b128 v[182:185], v235 offset:36864
	v_add_f32_e32 v250, v122, v250
	v_add_f32_e32 v250, v123, v250
	s_waitcnt lgkmcnt(3)
	v_mfma_f32_16x16x32_bf16 v[98:101], v[186:189], v[146:149], v[2:5]
	v_add_f32_e32 v250, v124, v250
	v_mfma_f32_16x16x32_bf16 v[102:105], v[186:189], v[162:165], v[2:5]
	ds_read_b128 v[186:189], v235 offset:40960
	v_add_f32_e32 v250, v125, v250
	v_cvt_pk_bf16_f32 v114, v114, v115
	s_waitcnt lgkmcnt(3)
	v_mfma_f32_16x16x32_bf16 v[106:109], v[190:193], v[146:149], v[2:5]
	v_cvt_pk_bf16_f32 v115, v116, v117
	s_add_u32 m0, s79, 17408
	s_nop 0
	global_load_lds_dwordx4 v247, s[98:99]
	v_mfma_f32_16x16x32_bf16 v[110:113], v[190:193], v[162:165], v[2:5]
	ds_read_b128 v[190:193], v235 offset:45056
	v_cvt_pk_bf16_f32 v116, v122, v123
	v_cvt_pk_bf16_f32 v117, v124, v125
	s_waitcnt lgkmcnt(3)
	v_mfma_f32_16x16x32_bf16 v[82:85], v[178:181], v[150:153], v[82:85]
	v_add_f32_e32 v251, v118, v251
	v_mfma_f32_16x16x32_bf16 v[86:89], v[178:181], v[166:169], v[86:89]
	ds_read_b128 v[178:181], v236 offset:32768
	v_add_f32_e32 v251, v119, v251
	v_add_f32_e32 v251, v120, v251
	s_waitcnt lgkmcnt(3)
	v_mfma_f32_16x16x32_bf16 v[90:93], v[182:185], v[150:153], v[90:93]
	v_add_f32_e32 v251, v121, v251
	s_add_u32 m0, s80, 49152
	s_nop 0
	global_load_lds_dwordx4 v248, s[100:101]
	v_mfma_f32_16x16x32_bf16 v[94:97], v[182:185], v[166:169], v[94:97]
	ds_read_b128 v[182:185], v236 offset:36864
	v_add_f32_e32 v251, v126, v251
	v_add_f32_e32 v251, v127, v251
	s_waitcnt lgkmcnt(3)
	v_mfma_f32_16x16x32_bf16 v[98:101], v[186:189], v[150:153], v[98:101]
	v_add_f32_e32 v251, v128, v251
	v_mfma_f32_16x16x32_bf16 v[102:105], v[186:189], v[166:169], v[102:105]
	ds_read_b128 v[186:189], v236 offset:40960
	v_add_f32_e32 v251, v129, v251
	v_cvt_pk_bf16_f32 v118, v118, v119
	s_waitcnt lgkmcnt(3)
	v_mfma_f32_16x16x32_bf16 v[106:109], v[190:193], v[150:153], v[106:109]
	v_cvt_pk_bf16_f32 v119, v120, v121
	s_add_u32 m0, s80, 50176
	s_nop 0
	global_load_lds_dwordx4 v249, s[100:101]
	v_mfma_f32_16x16x32_bf16 v[110:113], v[190:193], v[166:169], v[110:113]
	ds_read_b128 v[190:193], v236 offset:45056
	v_cvt_pk_bf16_f32 v120, v126, v127
	v_cvt_pk_bf16_f32 v121, v128, v129
	s_waitcnt lgkmcnt(3)
; __device__ __forceinline__ void partialSM(f32x16& p0, f32x16& p1, float mC) {
;   (void)mC; (void)p1;
;   for (int r = 0; r < 16; ++r) p0[r] = __builtin_amdgcn_exp2f(p0[r]);
; }
; __device__ __forceinline__ void finishSM(f32x16& p0, f32x16& p1, float& l_reg, bf16x8& pa0, bf16x8& pa1, bf16x8& pa2, bf16x8& pa3) {
;   for (int r = 0; r < 16; ++r) p1[r] = __builtin_amdgcn_exp2f(p1[r]);
;   float ps = 0; for (int r = 0; r < 16; ++r) ps += p0[r]; for (int r = 0; r < 16; ++r) ps += p1[r];
;   { auto rr = __builtin_amdgcn_permlane32_swap(__float_as_uint(ps), __float_as_uint(ps), false, false);
;     ps = __uint_as_float(rr[0]) + __uint_as_float(rr[1]); }
;   l_reg += ps;
;     ...
;   PK4(p0, 0, pa0); PK4(p0, 8, pa1); PK4(p1, 0, pa2); PK4(p1, 8, pa3);
;     ...
; }
; __device__ __forceinline__ void qkt(f32x16& p0, f32x16& p1, const bf16* Ks, const bf16x8* qr, int r32, int hi, const f32x16& negm) {
; #pragma unroll
;   for (int d0 = 0; d0 < 8; ++d0) { int cb = (d0 * 16 + hi * 8) * 2;
;     bf16x8 b0 = *reinterpret_cast<const bf16x8*>((const char*)Ks + KSWZ(r32, cb));
;     bf16x8 b1 = *reinterpret_cast<const bf16x8*>((const char*)Ks + KSWZ(32 + r32, cb));
;     if (d0 == 0) { p0 = __builtin_amdgcn_mfma_f32_32x32x16_bf16(b0, qr[0], negm, 0, 0, 0); p1 = __builtin_amdgcn_mfma_f32_32x32x16_bf16(b1, qr[0], negm, 0, 0, 0); }
;     else { p0 = __builtin_amdgcn_mfma_f32_32x32x16_bf16(b0, qr[d0], p0, 0, 0, 0); p1 = __builtin_amdgcn_mfma_f32_32x32x16_bf16(b1, qr[d0], p1, 0, 0, 0); } }
; }
; __device__ __forceinline__ int v_st(int k, int c) { const int kk = (k & ~0xC) | ((k & 4) << 1) | ((k & 8) >> 1); return ((kk >> 3) * 4 + (c >> 5)) * 512 + ((kk & 7) * 32 + (c & 31)) * 2; }
; __device__ __forceinline__ int v_rd_base(int lane) { return ((lane & 3) << 3) | (((lane >> 2) & 3) << 6) | (((lane >> 4) & 1) << 5) | (((lane >> 5) & 1) << 8); }
; template <int OFF> __device__ __forceinline__ s16x4 tr_read(int vb) {
;   s16x4 r; asm volatile("ds_read_b64_tr_b16 %0, %1 offset:%2" : "=&v"(r) : "v"(vb), "i"(OFF) : "memory"); return r;
; }
; template <int D0> __device__ __forceinline__ void pv_one(f32x16& od, int vb, bf16x8 pa0, bf16x8 pa1, bf16x8 pa2, bf16x8 pa3) {
;   const s16x4 l0 = tr_read<v_rd_off(D0, 0, 0)>(vb), h0 = tr_read<v_rd_off(D0, 0, 1)>(vb), l1 = tr_read<v_rd_off(D0, 1, 0)>(vb), h1 = tr_read<v_rd_off(D0, 1, 1)>(vb);
	v_mfma_f32_16x16x32_bf16 v[82:85], v[178:181], v[154:157], v[82:85]
	v_add_f32_e32 v250, v130, v250
	v_mfma_f32_16x16x32_bf16 v[86:89], v[178:181], v[170:173], v[86:89]
	ds_read_b128 v[178:181], v237 offset:32768
	v_add_f32_e32 v250, v131, v250
	v_add_f32_e32 v250, v132, v250
	s_waitcnt lgkmcnt(3)
	v_mfma_f32_16x16x32_bf16 v[90:93], v[182:185], v[154:157], v[90:93]
	v_add_f32_e32 v250, v133, v250
	v_mfma_f32_16x16x32_bf16 v[94:97], v[182:185], v[170:173], v[94:97]
	ds_read_b128 v[182:185], v237 offset:36864
	v_add_f32_e32 v250, v138, v250
	v_add_f32_e32 v250, v139, v250
	s_waitcnt lgkmcnt(3)
	v_mfma_f32_16x16x32_bf16 v[98:101], v[186:189], v[154:157], v[98:101]
	v_add_f32_e32 v250, v140, v250
	ds_read_b64_tr_b16 v[202:203], v238 offset:16384
	ds_read_b64_tr_b16 v[204:205], v238 offset:20480
	v_mfma_f32_16x16x32_bf16 v[102:105], v[186:189], v[170:173], v[102:105]
	ds_read_b128 v[186:189], v237 offset:40960
	v_add_f32_e32 v250, v141, v250
	v_cvt_pk_bf16_f32 v130, v130, v131
	s_waitcnt lgkmcnt(5)
	v_mfma_f32_16x16x32_bf16 v[106:109], v[190:193], v[154:157], v[106:109]
	v_cvt_pk_bf16_f32 v131, v132, v133
	ds_read_b64_tr_b16 v[206:207], v239 offset:16384
	ds_read_b64_tr_b16 v[208:209], v239 offset:20480
	v_mfma_f32_16x16x32_bf16 v[110:113], v[190:193], v[170:173], v[110:113]
	ds_read_b128 v[190:193], v237 offset:45056
	v_cvt_pk_bf16_f32 v132, v138, v139
	v_cvt_pk_bf16_f32 v133, v140, v141
	s_waitcnt lgkmcnt(7)
	v_mfma_f32_16x16x32_bf16 v[82:85], v[178:181], v[158:161], v[82:85]
	v_add_f32_e32 v251, v134, v251
	ds_read_b64_tr_b16 v[210:211], v240 offset:16384
	ds_read_b64_tr_b16 v[212:213], v240 offset:20480
	v_mfma_f32_16x16x32_bf16 v[86:89], v[178:181], v[174:177], v[86:89]
	v_add_f32_e32 v251, v135, v251
	v_add_f32_e32 v251, v136, v251
	s_waitcnt lgkmcnt(8)
	v_mfma_f32_16x16x32_bf16 v[90:93], v[182:185], v[158:161], v[90:93]
	v_add_f32_e32 v251, v137, v251
	ds_read_b64_tr_b16 v[214:215], v241 offset:16384
	ds_read_b64_tr_b16 v[216:217], v241 offset:20480
	v_mfma_f32_16x16x32_bf16 v[94:97], v[182:185], v[174:177], v[94:97]
	v_add_f32_e32 v251, v142, v251
	v_add_f32_e32 v251, v143, v251
	s_waitcnt lgkmcnt(7)
	v_mfma_f32_16x16x32_bf16 v[98:101], v[186:189], v[158:161], v[98:101]
	v_add_f32_e32 v251, v144, v251
	ds_read_b64_tr_b16 v[218:219], v242 offset:16384
	ds_read_b64_tr_b16 v[220:221], v242 offset:20480
	v_mfma_f32_16x16x32_bf16 v[102:105], v[186:189], v[174:177], v[102:105]
	v_add_f32_e32 v251, v145, v251
	v_cvt_pk_bf16_f32 v134, v134, v135
	s_waitcnt lgkmcnt(6)
	v_mfma_f32_16x16x32_bf16 v[106:109], v[190:193], v[158:161], v[106:109]
	v_cvt_pk_bf16_f32 v135, v136, v137
	ds_read_b64_tr_b16 v[222:223], v243 offset:16384
	ds_read_b64_tr_b16 v[224:225], v243 offset:20480
	v_mfma_f32_16x16x32_bf16 v[110:113], v[190:193], v[174:177], v[110:113]
	v_cvt_pk_bf16_f32 v136, v142, v143
	v_cvt_pk_bf16_f32 v137, v144, v145
	s_waitcnt vmcnt(4)
	s_barrier
	v_mfma_f32_16x16x32_bf16 v[18:21], v[202:205], v[114:117], v[18:21]
	v_exp_f32_e32 v82, v82
	v_mfma_f32_16x16x32_bf16 v[22:25], v[202:205], v[118:121], v[22:25]
	ds_read_b64_tr_b16 v[202:203], v244 offset:16384
	ds_read_b64_tr_b16 v[204:205], v244 offset:20480
	v_exp_f32_e32 v83, v83
	v_mfma_f32_16x16x32_bf16 v[26:29], v[206:209], v[114:117], v[26:29]
	v_exp_f32_e32 v84, v84
	v_mfma_f32_16x16x32_bf16 v[30:33], v[206:209], v[118:121], v[30:33]
	ds_read_b64_tr_b16 v[206:207], v245 offset:16384
	ds_read_b64_tr_b16 v[208:209], v245 offset:20480
	v_exp_f32_e32 v85, v85
	s_waitcnt lgkmcnt(10)
	v_mfma_f32_16x16x32_bf16 v[34:37], v[210:213], v[114:117], v[34:37]
	v_exp_f32_e32 v86, v86
	v_mfma_f32_16x16x32_bf16 v[38:41], v[210:213], v[118:121], v[38:41]
	ds_read_b64_tr_b16 v[210:211], v238 offset:24576
	ds_read_b64_tr_b16 v[212:213], v238 offset:28672
	v_exp_f32_e32 v87, v87
	s_waitcnt lgkmcnt(10)
	v_mfma_f32_16x16x32_bf16 v[42:45], v[214:217], v[114:117], v[42:45]
	v_exp_f32_e32 v88, v88
	v_mfma_f32_16x16x32_bf16 v[46:49], v[214:217], v[118:121], v[46:49]
	ds_read_b64_tr_b16 v[214:215], v239 offset:24576
	ds_read_b64_tr_b16 v[216:217], v239 offset:28672
	v_exp_f32_e32 v89, v89
	s_waitcnt lgkmcnt(10)
	v_mfma_f32_16x16x32_bf16 v[50:53], v[218:221], v[114:117], v[50:53]
	v_exp_f32_e32 v90, v90
	v_mfma_f32_16x16x32_bf16 v[54:57], v[218:221], v[118:121], v[54:57]
	ds_read_b64_tr_b16 v[218:219], v240 offset:24576
	ds_read_b64_tr_b16 v[220:221], v240 offset:28672
	v_exp_f32_e32 v91, v91
	s_waitcnt lgkmcnt(10)
	v_mfma_f32_16x16x32_bf16 v[58:61], v[222:225], v[114:117], v[58:61]
	v_exp_f32_e32 v92, v92
	v_mfma_f32_16x16x32_bf16 v[62:65], v[222:225], v[118:121], v[62:65]
	ds_read_b64_tr_b16 v[222:223], v241 offset:24576
	ds_read_b64_tr_b16 v[224:225], v241 offset:28672
	v_exp_f32_e32 v93, v93
	s_waitcnt lgkmcnt(10)
	v_mfma_f32_16x16x32_bf16 v[66:69], v[202:205], v[114:117], v[66:69]
	v_exp_f32_e32 v94, v94
	v_mfma_f32_16x16x32_bf16 v[70:73], v[202:205], v[118:121], v[70:73]
	ds_read_b64_tr_b16 v[202:203], v242 offset:24576
	ds_read_b64_tr_b16 v[204:205], v242 offset:28672
	v_exp_f32_e32 v95, v95
	s_waitcnt lgkmcnt(10)
	v_mfma_f32_16x16x32_bf16 v[74:77], v[206:209], v[114:117], v[74:77]
	v_exp_f32_e32 v96, v96
	v_mfma_f32_16x16x32_bf16 v[78:81], v[206:209], v[118:121], v[78:81]
	ds_read_b64_tr_b16 v[206:207], v243 offset:24576
	ds_read_b64_tr_b16 v[208:209], v243 offset:28672
	v_exp_f32_e32 v97, v97
	s_waitcnt lgkmcnt(10)
	v_mfma_f32_16x16x32_bf16 v[18:21], v[210:213], v[130:133], v[18:21]
	v_exp_f32_e32 v98, v98
	v_mfma_f32_16x16x32_bf16 v[22:25], v[210:213], v[134:137], v[22:25]
	ds_read_b64_tr_b16 v[210:211], v244 offset:24576
	ds_read_b64_tr_b16 v[212:213], v244 offset:28672
	v_exp_f32_e32 v99, v99
	s_waitcnt lgkmcnt(10)
; __device__ __forceinline__ void partialSM(f32x16& p0, f32x16& p1, float mC) {
;   (void)mC; (void)p1;
;   for (int r = 0; r < 16; ++r) p0[r] = __builtin_amdgcn_exp2f(p0[r]);
; }
; __device__ __forceinline__ void finishSM(f32x16& p0, f32x16& p1, float& l_reg, bf16x8& pa0, bf16x8& pa1, bf16x8& pa2, bf16x8& pa3) {
;   for (int r = 0; r < 16; ++r) p1[r] = __builtin_amdgcn_exp2f(p1[r]);
;   float ps = 0; for (int r = 0; r < 16; ++r) ps += p0[r]; for (int r = 0; r < 16; ++r) ps += p1[r];
;   { auto rr = __builtin_amdgcn_permlane32_swap(__float_as_uint(ps), __float_as_uint(ps), false, false);
;     ps = __uint_as_float(rr[0]) + __uint_as_float(rr[1]); }
;   l_reg += ps;
;     ...
;   PK4(p0, 0, pa0); PK4(p0, 8, pa1); PK4(p1, 0, pa2); PK4(p1, 8, pa3);
;     ...
; }
; __device__ __forceinline__ void qkt(f32x16& p0, f32x16& p1, const bf16* Ks, const bf16x8* qr, int r32, int hi, const f32x16& negm) {
; #pragma unroll
;   for (int d0 = 0; d0 < 8; ++d0) { int cb = (d0 * 16 + hi * 8) * 2;
;     bf16x8 b0 = *reinterpret_cast<const bf16x8*>((const char*)Ks + KSWZ(r32, cb));
;     bf16x8 b1 = *reinterpret_cast<const bf16x8*>((const char*)Ks + KSWZ(32 + r32, cb));
;     if (d0 == 0) { p0 = __builtin_amdgcn_mfma_f32_32x32x16_bf16(b0, qr[0], negm, 0, 0, 0); p1 = __builtin_amdgcn_mfma_f32_32x32x16_bf16(b1, qr[0], negm, 0, 0, 0); }
;     else { p0 = __builtin_amdgcn_mfma_f32_32x32x16_bf16(b0, qr[d0], p0, 0, 0, 0); p1 = __builtin_amdgcn_mfma_f32_32x32x16_bf16(b1, qr[d0], p1, 0, 0, 0); } }
; }
; __device__ __forceinline__ int v_st(int k, int c) { const int kk = (k & ~0xC) | ((k & 4) << 1) | ((k & 8) >> 1); return ((kk >> 3) * 4 + (c >> 5)) * 512 + ((kk & 7) * 32 + (c & 31)) * 2; }
; __device__ __forceinline__ int v_rd_base(int lane) { return ((lane & 3) << 3) | (((lane >> 2) & 3) << 6) | (((lane >> 4) & 1) << 5) | (((lane >> 5) & 1) << 8); }
; template <int OFF> __device__ __forceinline__ s16x4 tr_read(int vb) {
;   s16x4 r; asm volatile("ds_read_b64_tr_b16 %0, %1 offset:%2" : "=&v"(r) : "v"(vb), "i"(OFF) : "memory"); return r;
; }
; template <int D0> __device__ __forceinline__ void pv_one(f32x16& od, int vb, bf16x8 pa0, bf16x8 pa1, bf16x8 pa2, bf16x8 pa3) {
;   const s16x4 l0 = tr_read<v_rd_off(D0, 0, 0)>(vb), h0 = tr_read<v_rd_off(D0, 0, 1)>(vb), l1 = tr_read<v_rd_off(D0, 1, 0)>(vb), h1 = tr_read<v_rd_off(D0, 1, 1)>(vb);
	v_mfma_f32_16x16x32_bf16 v[26:29], v[214:217], v[130:133], v[26:29]
	v_exp_f32_e32 v100, v100
	v_mfma_f32_16x16x32_bf16 v[30:33], v[214:217], v[134:137], v[30:33]
	ds_read_b64_tr_b16 v[214:215], v245 offset:24576
	ds_read_b64_tr_b16 v[216:217], v245 offset:28672
	v_exp_f32_e32 v101, v101
	s_waitcnt lgkmcnt(10)
	v_mfma_f32_16x16x32_bf16 v[34:37], v[218:221], v[130:133], v[34:37]
	v_exp_f32_e32 v102, v102
	v_mfma_f32_16x16x32_bf16 v[38:41], v[218:221], v[134:137], v[38:41]
	v_exp_f32_e32 v103, v103
	s_waitcnt lgkmcnt(8)
	v_mfma_f32_16x16x32_bf16 v[42:45], v[222:225], v[130:133], v[42:45]
	v_exp_f32_e32 v104, v104
	v_mfma_f32_16x16x32_bf16 v[46:49], v[222:225], v[134:137], v[46:49]
	v_exp_f32_e32 v105, v105
	s_waitcnt lgkmcnt(6)
	v_mfma_f32_16x16x32_bf16 v[50:53], v[202:205], v[130:133], v[50:53]
	v_exp_f32_e32 v106, v106
	ds_read_b128 v[178:181], v234 offset:49152
	v_mfma_f32_16x16x32_bf16 v[54:57], v[202:205], v[134:137], v[54:57]
	v_exp_f32_e32 v107, v107
	s_waitcnt lgkmcnt(5)
	v_mfma_f32_16x16x32_bf16 v[58:61], v[206:209], v[130:133], v[58:61]
	v_exp_f32_e32 v108, v108
	ds_read_b128 v[182:185], v234 offset:53248
	v_mfma_f32_16x16x32_bf16 v[62:65], v[206:209], v[134:137], v[62:65]
	v_exp_f32_e32 v109, v109
	s_waitcnt lgkmcnt(4)
	v_mfma_f32_16x16x32_bf16 v[66:69], v[210:213], v[130:133], v[66:69]
	v_exp_f32_e32 v110, v110
	ds_read_b128 v[186:189], v234 offset:57344
	v_mfma_f32_16x16x32_bf16 v[70:73], v[210:213], v[134:137], v[70:73]
	v_exp_f32_e32 v111, v111
	s_waitcnt lgkmcnt(3)
	v_mfma_f32_16x16x32_bf16 v[74:77], v[214:217], v[130:133], v[74:77]
	v_exp_f32_e32 v112, v112
	ds_read_b128 v[190:193], v234 offset:61440
	v_mfma_f32_16x16x32_bf16 v[78:81], v[214:217], v[134:137], v[78:81]
	v_exp_f32_e32 v113, v113
	s_waitcnt lgkmcnt(3)
	v_mfma_f32_16x16x32_bf16 v[114:117], v[178:181], v[146:149], v[2:5]
	v_add_f32_e32 v250, v82, v250
	s_add_u32 s98, s98, 0x8000
	s_addc_u32 s99, s99, 0
	s_add_u32 s100, s100, 0x8000
	s_addc_u32 s101, s101, 0
	v_mfma_f32_16x16x32_bf16 v[118:121], v[178:181], v[162:165], v[2:5]
	ds_read_b128 v[178:181], v235 offset:49152
	v_add_f32_e32 v250, v83, v250
	v_add_f32_e32 v250, v84, v250
	s_waitcnt lgkmcnt(3)
	v_mfma_f32_16x16x32_bf16 v[122:125], v[182:185], v[146:149], v[2:5]
	v_add_f32_e32 v250, v85, v250
	s_add_u32 m0, s79, 32768
	s_nop 0
	global_load_lds_dwordx4 v246, s[98:99]
	v_mfma_f32_16x16x32_bf16 v[126:129], v[182:185], v[162:165], v[2:5]
	ds_read_b128 v[182:185], v235 offset:53248
	v_add_f32_e32 v250, v90, v250
	v_add_f32_e32 v250, v91, v250
	s_waitcnt lgkmcnt(3)
	v_mfma_f32_16x16x32_bf16 v[130:133], v[186:189], v[146:149], v[2:5]
	v_add_f32_e32 v250, v92, v250
	v_mfma_f32_16x16x32_bf16 v[134:137], v[186:189], v[162:165], v[2:5]
	ds_read_b128 v[186:189], v235 offset:57344
	v_add_f32_e32 v250, v93, v250
	v_cvt_pk_bf16_f32 v82, v82, v83
	s_waitcnt lgkmcnt(3)
	v_mfma_f32_16x16x32_bf16 v[138:141], v[190:193], v[146:149], v[2:5]
	v_cvt_pk_bf16_f32 v83, v84, v85
	s_add_u32 m0, s79, 33792
	s_nop 0
	global_load_lds_dwordx4 v247, s[98:99]
	v_mfma_f32_16x16x32_bf16 v[142:145], v[190:193], v[162:165], v[2:5]
	ds_read_b128 v[190:193], v235 offset:61440
	v_cvt_pk_bf16_f32 v84, v90, v91
	v_cvt_pk_bf16_f32 v85, v92, v93
	s_waitcnt lgkmcnt(3)
	v_mfma_f32_16x16x32_bf16 v[114:117], v[178:181], v[150:153], v[114:117]
	v_add_f32_e32 v251, v86, v251
	v_mfma_f32_16x16x32_bf16 v[118:121], v[178:181], v[166:169], v[118:121]
	ds_read_b128 v[178:181], v236 offset:49152
	v_add_f32_e32 v251, v87, v251
	v_add_f32_e32 v251, v88, v251
	s_waitcnt lgkmcnt(3)
	v_mfma_f32_16x16x32_bf16 v[122:125], v[182:185], v[150:153], v[122:125]
	v_add_f32_e32 v251, v89, v251
	s_add_u32 m0, s80, 0
	s_nop 0
	global_load_lds_dwordx4 v248, s[100:101]
	v_mfma_f32_16x16x32_bf16 v[126:129], v[182:185], v[166:169], v[126:129]
	ds_read_b128 v[182:185], v236 offset:53248
	v_add_f32_e32 v251, v94, v251
	v_add_f32_e32 v251, v95, v251
	s_waitcnt lgkmcnt(3)
	v_mfma_f32_16x16x32_bf16 v[130:133], v[186:189], v[150:153], v[130:133]
	v_add_f32_e32 v251, v96, v251
	v_mfma_f32_16x16x32_bf16 v[134:137], v[186:189], v[166:169], v[134:137]
	ds_read_b128 v[186:189], v236 offset:57344
	v_add_f32_e32 v251, v97, v251
	v_cvt_pk_bf16_f32 v86, v86, v87
	s_waitcnt lgkmcnt(3)
	v_mfma_f32_16x16x32_bf16 v[138:141], v[190:193], v[150:153], v[138:141]
	v_cvt_pk_bf16_f32 v87, v88, v89
	s_add_u32 m0, s80, 1024
	s_nop 0
	global_load_lds_dwordx4 v249, s[100:101]
	v_mfma_f32_16x16x32_bf16 v[142:145], v[190:193], v[166:169], v[142:145]
	ds_read_b128 v[190:193], v236 offset:61440
	v_cvt_pk_bf16_f32 v88, v94, v95
	v_cvt_pk_bf16_f32 v89, v96, v97
	s_waitcnt lgkmcnt(3)
	v_mfma_f32_16x16x32_bf16 v[114:117], v[178:181], v[154:157], v[114:117]
	v_add_f32_e32 v250, v98, v250
	v_mfma_f32_16x16x32_bf16 v[118:121], v[178:181], v[170:173], v[118:121]
	ds_read_b128 v[178:181], v237 offset:49152
	v_add_f32_e32 v250, v99, v250
	v_add_f32_e32 v250, v100, v250
	s_waitcnt lgkmcnt(3)
	v_mfma_f32_16x16x32_bf16 v[122:125], v[182:185], v[154:157], v[122:125]
	v_add_f32_e32 v250, v101, v250
	v_mfma_f32_16x16x32_bf16 v[126:129], v[182:185], v[170:173], v[126:129]
	ds_read_b128 v[182:185], v237 offset:53248
	v_add_f32_e32 v250, v106, v250
	v_add_f32_e32 v250, v107, v250
	s_waitcnt lgkmcnt(3)
	v_mfma_f32_16x16x32_bf16 v[130:133], v[186:189], v[154:157], v[130:133]
	v_add_f32_e32 v250, v108, v250
	ds_read_b64_tr_b16 v[202:203], v238 offset:32768
	ds_read_b64_tr_b16 v[204:205], v238 offset:36864
	v_mfma_f32_16x16x32_bf16 v[134:137], v[186:189], v[170:173], v[134:137]
	ds_read_b128 v[186:189], v237 offset:57344
	v_add_f32_e32 v250, v109, v250
	v_cvt_pk_bf16_f32 v98, v98, v99
	s_waitcnt lgkmcnt(5)
; __device__ __forceinline__ void partialSM(f32x16& p0, f32x16& p1, float mC) {
;   (void)mC; (void)p1;
;   for (int r = 0; r < 16; ++r) p0[r] = __builtin_amdgcn_exp2f(p0[r]);
; }
; __device__ __forceinline__ void finishSM(f32x16& p0, f32x16& p1, float& l_reg, bf16x8& pa0, bf16x8& pa1, bf16x8& pa2, bf16x8& pa3) {
;   for (int r = 0; r < 16; ++r) p1[r] = __builtin_amdgcn_exp2f(p1[r]);
;   float ps = 0; for (int r = 0; r < 16; ++r) ps += p0[r]; for (int r = 0; r < 16; ++r) ps += p1[r];
;   { auto rr = __builtin_amdgcn_permlane32_swap(__float_as_uint(ps), __float_as_uint(ps), false, false);
;     ps = __uint_as_float(rr[0]) + __uint_as_float(rr[1]); }
;   l_reg += ps;
;     ...
;   PK4(p0, 0, pa0); PK4(p0, 8, pa1); PK4(p1, 0, pa2); PK4(p1, 8, pa3);
;     ...
; }
; __device__ __forceinline__ void qkt(f32x16& p0, f32x16& p1, const bf16* Ks, const bf16x8* qr, int r32, int hi, const f32x16& negm) {
; #pragma unroll
;   for (int d0 = 0; d0 < 8; ++d0) { int cb = (d0 * 16 + hi * 8) * 2;
;     bf16x8 b0 = *reinterpret_cast<const bf16x8*>((const char*)Ks + KSWZ(r32, cb));
;     bf16x8 b1 = *reinterpret_cast<const bf16x8*>((const char*)Ks + KSWZ(32 + r32, cb));
;     if (d0 == 0) { p0 = __builtin_amdgcn_mfma_f32_32x32x16_bf16(b0, qr[0], negm, 0, 0, 0); p1 = __builtin_amdgcn_mfma_f32_32x32x16_bf16(b1, qr[0], negm, 0, 0, 0); }
;     else { p0 = __builtin_amdgcn_mfma_f32_32x32x16_bf16(b0, qr[d0], p0, 0, 0, 0); p1 = __builtin_amdgcn_mfma_f32_32x32x16_bf16(b1, qr[d0], p1, 0, 0, 0); } }
; }
; __device__ __forceinline__ int v_st(int k, int c) { const int kk = (k & ~0xC) | ((k & 4) << 1) | ((k & 8) >> 1); return ((kk >> 3) * 4 + (c >> 5)) * 512 + ((kk & 7) * 32 + (c & 31)) * 2; }
; __device__ __forceinline__ int v_rd_base(int lane) { return ((lane & 3) << 3) | (((lane >> 2) & 3) << 6) | (((lane >> 4) & 1) << 5) | (((lane >> 5) & 1) << 8); }
; template <int OFF> __device__ __forceinline__ s16x4 tr_read(int vb) {
;   s16x4 r; asm volatile("ds_read_b64_tr_b16 %0, %1 offset:%2" : "=&v"(r) : "v"(vb), "i"(OFF) : "memory"); return r;
; }
; template <int D0> __device__ __forceinline__ void pv_one(f32x16& od, int vb, bf16x8 pa0, bf16x8 pa1, bf16x8 pa2, bf16x8 pa3) {
;   const s16x4 l0 = tr_read<v_rd_off(D0, 0, 0)>(vb), h0 = tr_read<v_rd_off(D0, 0, 1)>(vb), l1 = tr_read<v_rd_off(D0, 1, 0)>(vb), h1 = tr_read<v_rd_off(D0, 1, 1)>(vb);
	v_mfma_f32_16x16x32_bf16 v[138:141], v[190:193], v[154:157], v[138:141]
	v_cvt_pk_bf16_f32 v99, v100, v101
	ds_read_b64_tr_b16 v[206:207], v239 offset:32768
	ds_read_b64_tr_b16 v[208:209], v239 offset:36864
	v_mfma_f32_16x16x32_bf16 v[142:145], v[190:193], v[170:173], v[142:145]
	ds_read_b128 v[190:193], v237 offset:61440
	v_cvt_pk_bf16_f32 v100, v106, v107
	v_cvt_pk_bf16_f32 v101, v108, v109
	s_waitcnt lgkmcnt(7)
	v_mfma_f32_16x16x32_bf16 v[114:117], v[178:181], v[158:161], v[114:117]
	v_add_f32_e32 v251, v102, v251
	ds_read_b64_tr_b16 v[210:211], v240 offset:32768
	ds_read_b64_tr_b16 v[212:213], v240 offset:36864
	v_mfma_f32_16x16x32_bf16 v[118:121], v[178:181], v[174:177], v[118:121]
	v_add_f32_e32 v251, v103, v251
	v_add_f32_e32 v251, v104, v251
	s_waitcnt lgkmcnt(8)
	v_mfma_f32_16x16x32_bf16 v[122:125], v[182:185], v[158:161], v[122:125]
	v_add_f32_e32 v251, v105, v251
	ds_read_b64_tr_b16 v[214:215], v241 offset:32768
	ds_read_b64_tr_b16 v[216:217], v241 offset:36864
	v_mfma_f32_16x16x32_bf16 v[126:129], v[182:185], v[174:177], v[126:129]
	v_add_f32_e32 v251, v110, v251
	v_add_f32_e32 v251, v111, v251
	s_waitcnt lgkmcnt(7)
	v_mfma_f32_16x16x32_bf16 v[130:133], v[186:189], v[158:161], v[130:133]
	v_add_f32_e32 v251, v112, v251
	ds_read_b64_tr_b16 v[218:219], v242 offset:32768
	ds_read_b64_tr_b16 v[220:221], v242 offset:36864
	v_mfma_f32_16x16x32_bf16 v[134:137], v[186:189], v[174:177], v[134:137]
	v_add_f32_e32 v251, v113, v251
	v_cvt_pk_bf16_f32 v102, v102, v103
	s_waitcnt lgkmcnt(6)
	v_mfma_f32_16x16x32_bf16 v[138:141], v[190:193], v[158:161], v[138:141]
	v_cvt_pk_bf16_f32 v103, v104, v105
	ds_read_b64_tr_b16 v[222:223], v243 offset:32768
	ds_read_b64_tr_b16 v[224:225], v243 offset:36864
	v_mfma_f32_16x16x32_bf16 v[142:145], v[190:193], v[174:177], v[142:145]
	v_cvt_pk_bf16_f32 v104, v110, v111
	v_cvt_pk_bf16_f32 v105, v112, v113
	s_waitcnt vmcnt(4)
	s_barrier
	v_mfma_f32_16x16x32_bf16 v[18:21], v[202:205], v[82:85], v[18:21]
	v_exp_f32_e32 v114, v114
	v_mfma_f32_16x16x32_bf16 v[22:25], v[202:205], v[86:89], v[22:25]
	ds_read_b64_tr_b16 v[202:203], v244 offset:32768
	ds_read_b64_tr_b16 v[204:205], v244 offset:36864
	v_exp_f32_e32 v115, v115
	v_mfma_f32_16x16x32_bf16 v[26:29], v[206:209], v[82:85], v[26:29]
	v_exp_f32_e32 v116, v116
	v_mfma_f32_16x16x32_bf16 v[30:33], v[206:209], v[86:89], v[30:33]
	ds_read_b64_tr_b16 v[206:207], v245 offset:32768
	ds_read_b64_tr_b16 v[208:209], v245 offset:36864
	v_exp_f32_e32 v117, v117
	s_waitcnt lgkmcnt(10)
	v_mfma_f32_16x16x32_bf16 v[34:37], v[210:213], v[82:85], v[34:37]
	v_exp_f32_e32 v118, v118
	v_mfma_f32_16x16x32_bf16 v[38:41], v[210:213], v[86:89], v[38:41]
	ds_read_b64_tr_b16 v[210:211], v238 offset:40960
	ds_read_b64_tr_b16 v[212:213], v238 offset:45056
	v_exp_f32_e32 v119, v119
	s_waitcnt lgkmcnt(10)
	v_mfma_f32_16x16x32_bf16 v[42:45], v[214:217], v[82:85], v[42:45]
	v_exp_f32_e32 v120, v120
	v_mfma_f32_16x16x32_bf16 v[46:49], v[214:217], v[86:89], v[46:49]
	ds_read_b64_tr_b16 v[214:215], v239 offset:40960
	ds_read_b64_tr_b16 v[216:217], v239 offset:45056
	v_exp_f32_e32 v121, v121
	s_waitcnt lgkmcnt(10)
	v_mfma_f32_16x16x32_bf16 v[50:53], v[218:221], v[82:85], v[50:53]
	v_exp_f32_e32 v122, v122
	v_mfma_f32_16x16x32_bf16 v[54:57], v[218:221], v[86:89], v[54:57]
	ds_read_b64_tr_b16 v[218:219], v240 offset:40960
	ds_read_b64_tr_b16 v[220:221], v240 offset:45056
	v_exp_f32_e32 v123, v123
	s_waitcnt lgkmcnt(10)
	v_mfma_f32_16x16x32_bf16 v[58:61], v[222:225], v[82:85], v[58:61]
	v_exp_f32_e32 v124, v124
	v_mfma_f32_16x16x32_bf16 v[62:65], v[222:225], v[86:89], v[62:65]
	ds_read_b64_tr_b16 v[222:223], v241 offset:40960
	ds_read_b64_tr_b16 v[224:225], v241 offset:45056
	v_exp_f32_e32 v125, v125
	s_waitcnt lgkmcnt(10)
	v_mfma_f32_16x16x32_bf16 v[66:69], v[202:205], v[82:85], v[66:69]
	v_exp_f32_e32 v126, v126
	v_mfma_f32_16x16x32_bf16 v[70:73], v[202:205], v[86:89], v[70:73]
	ds_read_b64_tr_b16 v[202:203], v242 offset:40960
	ds_read_b64_tr_b16 v[204:205], v242 offset:45056
	v_exp_f32_e32 v127, v127
	s_waitcnt lgkmcnt(10)
	v_mfma_f32_16x16x32_bf16 v[74:77], v[206:209], v[82:85], v[74:77]
	v_exp_f32_e32 v128, v128
	v_mfma_f32_16x16x32_bf16 v[78:81], v[206:209], v[86:89], v[78:81]
	ds_read_b64_tr_b16 v[206:207], v243 offset:40960
	ds_read_b64_tr_b16 v[208:209], v243 offset:45056
	v_exp_f32_e32 v129, v129
	s_waitcnt lgkmcnt(10)
	v_mfma_f32_16x16x32_bf16 v[18:21], v[210:213], v[98:101], v[18:21]
	v_exp_f32_e32 v130, v130
	v_mfma_f32_16x16x32_bf16 v[22:25], v[210:213], v[102:105], v[22:25]
	ds_read_b64_tr_b16 v[210:211], v244 offset:40960
	ds_read_b64_tr_b16 v[212:213], v244 offset:45056
	v_exp_f32_e32 v131, v131
	s_waitcnt lgkmcnt(10)
	v_mfma_f32_16x16x32_bf16 v[26:29], v[214:217], v[98:101], v[26:29]
	v_exp_f32_e32 v132, v132
	v_mfma_f32_16x16x32_bf16 v[30:33], v[214:217], v[102:105], v[30:33]
	ds_read_b64_tr_b16 v[214:215], v245 offset:40960
	ds_read_b64_tr_b16 v[216:217], v245 offset:45056
	v_exp_f32_e32 v133, v133
	s_waitcnt lgkmcnt(10)
	v_mfma_f32_16x16x32_bf16 v[34:37], v[218:221], v[98:101], v[34:37]
	v_exp_f32_e32 v134, v134
	v_mfma_f32_16x16x32_bf16 v[38:41], v[218:221], v[102:105], v[38:41]
	v_exp_f32_e32 v135, v135
	s_waitcnt lgkmcnt(8)
	v_mfma_f32_16x16x32_bf16 v[42:45], v[222:225], v[98:101], v[42:45]
	v_exp_f32_e32 v136, v136
	v_mfma_f32_16x16x32_bf16 v[46:49], v[222:225], v[102:105], v[46:49]
	v_exp_f32_e32 v137, v137
	s_waitcnt lgkmcnt(6)
	v_mfma_f32_16x16x32_bf16 v[50:53], v[202:205], v[98:101], v[50:53]
	v_exp_f32_e32 v138, v138
	ds_read_b128 v[178:181], v234 offset:0
	v_mfma_f32_16x16x32_bf16 v[54:57], v[202:205], v[102:105], v[54:57]
	v_exp_f32_e32 v139, v139
	s_waitcnt lgkmcnt(5)
; __device__ __forceinline__ void partialSM(f32x16& p0, f32x16& p1, float mC) {
;   (void)mC; (void)p1;
;   for (int r = 0; r < 16; ++r) p0[r] = __builtin_amdgcn_exp2f(p0[r]);
; }
; __device__ __forceinline__ void finishSM(f32x16& p0, f32x16& p1, float& l_reg, bf16x8& pa0, bf16x8& pa1, bf16x8& pa2, bf16x8& pa3) {
;   for (int r = 0; r < 16; ++r) p1[r] = __builtin_amdgcn_exp2f(p1[r]);
;   float ps = 0; for (int r = 0; r < 16; ++r) ps += p0[r]; for (int r = 0; r < 16; ++r) ps += p1[r];
;   { auto rr = __builtin_amdgcn_permlane32_swap(__float_as_uint(ps), __float_as_uint(ps), false, false);
;     ps = __uint_as_float(rr[0]) + __uint_as_float(rr[1]); }
;   l_reg += ps;
;     ...
;   PK4(p0, 0, pa0); PK4(p0, 8, pa1); PK4(p1, 0, pa2); PK4(p1, 8, pa3);
;     ...
; }
; __device__ __forceinline__ void qkt(f32x16& p0, f32x16& p1, const bf16* Ks, const bf16x8* qr, int r32, int hi, const f32x16& negm) {
; #pragma unroll
;   for (int d0 = 0; d0 < 8; ++d0) { int cb = (d0 * 16 + hi * 8) * 2;
;     bf16x8 b0 = *reinterpret_cast<const bf16x8*>((const char*)Ks + KSWZ(r32, cb));
;     bf16x8 b1 = *reinterpret_cast<const bf16x8*>((const char*)Ks + KSWZ(32 + r32, cb));
;     if (d0 == 0) { p0 = __builtin_amdgcn_mfma_f32_32x32x16_bf16(b0, qr[0], negm, 0, 0, 0); p1 = __builtin_amdgcn_mfma_f32_32x32x16_bf16(b1, qr[0], negm, 0, 0, 0); }
;     else { p0 = __builtin_amdgcn_mfma_f32_32x32x16_bf16(b0, qr[d0], p0, 0, 0, 0); p1 = __builtin_amdgcn_mfma_f32_32x32x16_bf16(b1, qr[d0], p1, 0, 0, 0); } }
; }
; __device__ __forceinline__ int v_st(int k, int c) { const int kk = (k & ~0xC) | ((k & 4) << 1) | ((k & 8) >> 1); return ((kk >> 3) * 4 + (c >> 5)) * 512 + ((kk & 7) * 32 + (c & 31)) * 2; }
; __device__ __forceinline__ int v_rd_base(int lane) { return ((lane & 3) << 3) | (((lane >> 2) & 3) << 6) | (((lane >> 4) & 1) << 5) | (((lane >> 5) & 1) << 8); }
; template <int OFF> __device__ __forceinline__ s16x4 tr_read(int vb) {
;   s16x4 r; asm volatile("ds_read_b64_tr_b16 %0, %1 offset:%2" : "=&v"(r) : "v"(vb), "i"(OFF) : "memory"); return r;
; }
; template <int D0> __device__ __forceinline__ void pv_one(f32x16& od, int vb, bf16x8 pa0, bf16x8 pa1, bf16x8 pa2, bf16x8 pa3) {
;   const s16x4 l0 = tr_read<v_rd_off(D0, 0, 0)>(vb), h0 = tr_read<v_rd_off(D0, 0, 1)>(vb), l1 = tr_read<v_rd_off(D0, 1, 0)>(vb), h1 = tr_read<v_rd_off(D0, 1, 1)>(vb);
	v_mfma_f32_16x16x32_bf16 v[58:61], v[206:209], v[98:101], v[58:61]
	v_exp_f32_e32 v140, v140
	ds_read_b128 v[182:185], v234 offset:4096
	v_mfma_f32_16x16x32_bf16 v[62:65], v[206:209], v[102:105], v[62:65]
	v_exp_f32_e32 v141, v141
	s_waitcnt lgkmcnt(4)
	v_mfma_f32_16x16x32_bf16 v[66:69], v[210:213], v[98:101], v[66:69]
	v_exp_f32_e32 v142, v142
	ds_read_b128 v[186:189], v234 offset:8192
	v_mfma_f32_16x16x32_bf16 v[70:73], v[210:213], v[102:105], v[70:73]
	v_exp_f32_e32 v143, v143
	s_waitcnt lgkmcnt(3)
	v_mfma_f32_16x16x32_bf16 v[74:77], v[214:217], v[98:101], v[74:77]
	v_exp_f32_e32 v144, v144
	ds_read_b128 v[190:193], v234 offset:12288
	v_mfma_f32_16x16x32_bf16 v[78:81], v[214:217], v[102:105], v[78:81]
	v_exp_f32_e32 v145, v145
	s_waitcnt lgkmcnt(3)
	v_mfma_f32_16x16x32_bf16 v[82:85], v[178:181], v[146:149], v[2:5]
	v_add_f32_e32 v250, v114, v250
	s_add_u32 s98, s98, 0x8000
	s_addc_u32 s99, s99, 0
	s_add_u32 s100, s100, 0x8000
	s_addc_u32 s101, s101, 0
	v_mfma_f32_16x16x32_bf16 v[86:89], v[178:181], v[162:165], v[2:5]
	ds_read_b128 v[178:181], v235 offset:0
	v_add_f32_e32 v250, v115, v250
	v_add_f32_e32 v250, v116, v250
	s_waitcnt lgkmcnt(3)
	v_mfma_f32_16x16x32_bf16 v[90:93], v[182:185], v[146:149], v[2:5]
	v_add_f32_e32 v250, v117, v250
	s_add_u32 m0, s79, 49152
	s_nop 0
	global_load_lds_dwordx4 v246, s[98:99]
	v_mfma_f32_16x16x32_bf16 v[94:97], v[182:185], v[162:165], v[2:5]
	ds_read_b128 v[182:185], v235 offset:4096
	v_add_f32_e32 v250, v122, v250
	v_add_f32_e32 v250, v123, v250
	s_waitcnt lgkmcnt(3)
	v_mfma_f32_16x16x32_bf16 v[98:101], v[186:189], v[146:149], v[2:5]
	v_add_f32_e32 v250, v124, v250
	v_mfma_f32_16x16x32_bf16 v[102:105], v[186:189], v[162:165], v[2:5]
	ds_read_b128 v[186:189], v235 offset:8192
	v_add_f32_e32 v250, v125, v250
	v_cvt_pk_bf16_f32 v114, v114, v115
	s_waitcnt lgkmcnt(3)
	v_mfma_f32_16x16x32_bf16 v[106:109], v[190:193], v[146:149], v[2:5]
	v_cvt_pk_bf16_f32 v115, v116, v117
	s_add_u32 m0, s79, 50176
	s_nop 0
	global_load_lds_dwordx4 v247, s[98:99]
	v_mfma_f32_16x16x32_bf16 v[110:113], v[190:193], v[162:165], v[2:5]
	ds_read_b128 v[190:193], v235 offset:12288
	v_cvt_pk_bf16_f32 v116, v122, v123
	v_cvt_pk_bf16_f32 v117, v124, v125
	s_waitcnt lgkmcnt(3)
	v_mfma_f32_16x16x32_bf16 v[82:85], v[178:181], v[150:153], v[82:85]
	v_add_f32_e32 v251, v118, v251
	v_mfma_f32_16x16x32_bf16 v[86:89], v[178:181], v[166:169], v[86:89]
	ds_read_b128 v[178:181], v236 offset:0
	v_add_f32_e32 v251, v119, v251
	v_add_f32_e32 v251, v120, v251
	s_waitcnt lgkmcnt(3)
	v_mfma_f32_16x16x32_bf16 v[90:93], v[182:185], v[150:153], v[90:93]
	v_add_f32_e32 v251, v121, v251
	s_add_u32 m0, s80, 16384
	s_nop 0
	global_load_lds_dwordx4 v248, s[100:101]
	v_mfma_f32_16x16x32_bf16 v[94:97], v[182:185], v[166:169], v[94:97]
	ds_read_b128 v[182:185], v236 offset:4096
	v_add_f32_e32 v251, v126, v251
	v_add_f32_e32 v251, v127, v251
	s_waitcnt lgkmcnt(3)
	v_mfma_f32_16x16x32_bf16 v[98:101], v[186:189], v[150:153], v[98:101]
	v_add_f32_e32 v251, v128, v251
	v_mfma_f32_16x16x32_bf16 v[102:105], v[186:189], v[166:169], v[102:105]
	ds_read_b128 v[186:189], v236 offset:8192
	v_add_f32_e32 v251, v129, v251
	v_cvt_pk_bf16_f32 v118, v118, v119
	s_waitcnt lgkmcnt(3)
	v_mfma_f32_16x16x32_bf16 v[106:109], v[190:193], v[150:153], v[106:109]
	v_cvt_pk_bf16_f32 v119, v120, v121
	s_add_u32 m0, s80, 17408
	s_nop 0
	global_load_lds_dwordx4 v249, s[100:101]
	v_mfma_f32_16x16x32_bf16 v[110:113], v[190:193], v[166:169], v[110:113]
	ds_read_b128 v[190:193], v236 offset:12288
	v_cvt_pk_bf16_f32 v120, v126, v127
	v_cvt_pk_bf16_f32 v121, v128, v129
	s_waitcnt lgkmcnt(3)
	v_mfma_f32_16x16x32_bf16 v[82:85], v[178:181], v[154:157], v[82:85]
	v_add_f32_e32 v250, v130, v250
	v_mfma_f32_16x16x32_bf16 v[86:89], v[178:181], v[170:173], v[86:89]
	ds_read_b128 v[178:181], v237 offset:0
	v_add_f32_e32 v250, v131, v250
	v_add_f32_e32 v250, v132, v250
	s_waitcnt lgkmcnt(3)
	v_mfma_f32_16x16x32_bf16 v[90:93], v[182:185], v[154:157], v[90:93]
	v_add_f32_e32 v250, v133, v250
	v_mfma_f32_16x16x32_bf16 v[94:97], v[182:185], v[170:173], v[94:97]
	ds_read_b128 v[182:185], v237 offset:4096
	v_add_f32_e32 v250, v138, v250
	v_add_f32_e32 v250, v139, v250
	s_waitcnt lgkmcnt(3)
	v_mfma_f32_16x16x32_bf16 v[98:101], v[186:189], v[154:157], v[98:101]
	v_add_f32_e32 v250, v140, v250
	ds_read_b64_tr_b16 v[202:203], v238 offset:49152
	ds_read_b64_tr_b16 v[204:205], v238 offset:53248
	v_mfma_f32_16x16x32_bf16 v[102:105], v[186:189], v[170:173], v[102:105]
	ds_read_b128 v[186:189], v237 offset:8192
	v_add_f32_e32 v250, v141, v250
	v_cvt_pk_bf16_f32 v130, v130, v131
	s_waitcnt lgkmcnt(5)
	v_mfma_f32_16x16x32_bf16 v[106:109], v[190:193], v[154:157], v[106:109]
	v_cvt_pk_bf16_f32 v131, v132, v133
	ds_read_b64_tr_b16 v[206:207], v239 offset:49152
	ds_read_b64_tr_b16 v[208:209], v239 offset:53248
	v_mfma_f32_16x16x32_bf16 v[110:113], v[190:193], v[170:173], v[110:113]
	ds_read_b128 v[190:193], v237 offset:12288
	v_cvt_pk_bf16_f32 v132, v138, v139
	v_cvt_pk_bf16_f32 v133, v140, v141
	s_waitcnt lgkmcnt(7)
	v_mfma_f32_16x16x32_bf16 v[82:85], v[178:181], v[158:161], v[82:85]
	v_add_f32_e32 v251, v134, v251
	ds_read_b64_tr_b16 v[210:211], v240 offset:49152
	ds_read_b64_tr_b16 v[212:213], v240 offset:53248
	v_mfma_f32_16x16x32_bf16 v[86:89], v[178:181], v[174:177], v[86:89]
	v_add_f32_e32 v251, v135, v251
	v_add_f32_e32 v251, v136, v251
	s_waitcnt lgkmcnt(8)
	v_mfma_f32_16x16x32_bf16 v[90:93], v[182:185], v[158:161], v[90:93]
	v_add_f32_e32 v251, v137, v251
	ds_read_b64_tr_b16 v[214:215], v241 offset:49152
	ds_read_b64_tr_b16 v[216:217], v241 offset:53248
	v_mfma_f32_16x16x32_bf16 v[94:97], v[182:185], v[174:177], v[94:97]
	v_add_f32_e32 v251, v142, v251
	v_add_f32_e32 v251, v143, v251
	s_waitcnt lgkmcnt(7)
	v_mfma_f32_16x16x32_bf16 v[98:101], v[186:189], v[158:161], v[98:101]
	v_add_f32_e32 v251, v144, v251
	ds_read_b64_tr_b16 v[218:219], v242 offset:49152
	ds_read_b64_tr_b16 v[220:221], v242 offset:53248
	v_mfma_f32_16x16x32_bf16 v[102:105], v[186:189], v[174:177], v[102:105]
	v_add_f32_e32 v251, v145, v251
	v_cvt_pk_bf16_f32 v134, v134, v135
	s_waitcnt lgkmcnt(6)
	v_mfma_f32_16x16x32_bf16 v[106:109], v[190:193], v[158:161], v[106:109]
	v_cvt_pk_bf16_f32 v135, v136, v137
	ds_read_b64_tr_b16 v[222:223], v243 offset:49152
	ds_read_b64_tr_b16 v[224:225], v243 offset:53248
	v_mfma_f32_16x16x32_bf16 v[110:113], v[190:193], v[174:177], v[110:113]
	v_cvt_pk_bf16_f32 v136, v142, v143
	v_cvt_pk_bf16_f32 v137, v144, v145
	s_waitcnt vmcnt(4)
	s_barrier
; __device__ __forceinline__ void partialSM(f32x16& p0, f32x16& p1, float mC) {
;   (void)mC; (void)p1;
;   for (int r = 0; r < 16; ++r) p0[r] = __builtin_amdgcn_exp2f(p0[r]);
; }
; __device__ __forceinline__ void finishSM(f32x16& p0, f32x16& p1, float& l_reg, bf16x8& pa0, bf16x8& pa1, bf16x8& pa2, bf16x8& pa3) {
;   for (int r = 0; r < 16; ++r) p1[r] = __builtin_amdgcn_exp2f(p1[r]);
;   float ps = 0; for (int r = 0; r < 16; ++r) ps += p0[r]; for (int r = 0; r < 16; ++r) ps += p1[r];
;   { auto rr = __builtin_amdgcn_permlane32_swap(__float_as_uint(ps), __float_as_uint(ps), false, false);
;     ps = __uint_as_float(rr[0]) + __uint_as_float(rr[1]); }
;   l_reg += ps;
;     ...
;   PK4(p0, 0, pa0); PK4(p0, 8, pa1); PK4(p1, 0, pa2); PK4(p1, 8, pa3);
;     ...
; }
; __device__ __forceinline__ void qkt(f32x16& p0, f32x16& p1, const bf16* Ks, const bf16x8* qr, int r32, int hi, const f32x16& negm) {
; #pragma unroll
;   for (int d0 = 0; d0 < 8; ++d0) { int cb = (d0 * 16 + hi * 8) * 2;
;     bf16x8 b0 = *reinterpret_cast<const bf16x8*>((const char*)Ks + KSWZ(r32, cb));
;     bf16x8 b1 = *reinterpret_cast<const bf16x8*>((const char*)Ks + KSWZ(32 + r32, cb));
;     if (d0 == 0) { p0 = __builtin_amdgcn_mfma_f32_32x32x16_bf16(b0, qr[0], negm, 0, 0, 0); p1 = __builtin_amdgcn_mfma_f32_32x32x16_bf16(b1, qr[0], negm, 0, 0, 0); }
;     else { p0 = __builtin_amdgcn_mfma_f32_32x32x16_bf16(b0, qr[d0], p0, 0, 0, 0); p1 = __builtin_amdgcn_mfma_f32_32x32x16_bf16(b1, qr[d0], p1, 0, 0, 0); } }
; }
; __device__ __forceinline__ int v_st(int k, int c) { const int kk = (k & ~0xC) | ((k & 4) << 1) | ((k & 8) >> 1); return ((kk >> 3) * 4 + (c >> 5)) * 512 + ((kk & 7) * 32 + (c & 31)) * 2; }
; __device__ __forceinline__ int v_rd_base(int lane) { return ((lane & 3) << 3) | (((lane >> 2) & 3) << 6) | (((lane >> 4) & 1) << 5) | (((lane >> 5) & 1) << 8); }
; template <int OFF> __device__ __forceinline__ s16x4 tr_read(int vb) {
;   s16x4 r; asm volatile("ds_read_b64_tr_b16 %0, %1 offset:%2" : "=&v"(r) : "v"(vb), "i"(OFF) : "memory"); return r;
; }
; template <int D0> __device__ __forceinline__ void pv_one(f32x16& od, int vb, bf16x8 pa0, bf16x8 pa1, bf16x8 pa2, bf16x8 pa3) {
;   const s16x4 l0 = tr_read<v_rd_off(D0, 0, 0)>(vb), h0 = tr_read<v_rd_off(D0, 0, 1)>(vb), l1 = tr_read<v_rd_off(D0, 1, 0)>(vb), h1 = tr_read<v_rd_off(D0, 1, 1)>(vb);
	v_mfma_f32_16x16x32_bf16 v[18:21], v[202:205], v[114:117], v[18:21]
	v_exp_f32_e32 v82, v82
	v_mfma_f32_16x16x32_bf16 v[22:25], v[202:205], v[118:121], v[22:25]
	ds_read_b64_tr_b16 v[202:203], v244 offset:49152
	ds_read_b64_tr_b16 v[204:205], v244 offset:53248
	v_exp_f32_e32 v83, v83
	v_mfma_f32_16x16x32_bf16 v[26:29], v[206:209], v[114:117], v[26:29]
	v_exp_f32_e32 v84, v84
	v_mfma_f32_16x16x32_bf16 v[30:33], v[206:209], v[118:121], v[30:33]
	ds_read_b64_tr_b16 v[206:207], v245 offset:49152
	ds_read_b64_tr_b16 v[208:209], v245 offset:53248
	v_exp_f32_e32 v85, v85
	s_waitcnt lgkmcnt(10)
	v_mfma_f32_16x16x32_bf16 v[34:37], v[210:213], v[114:117], v[34:37]
	v_exp_f32_e32 v86, v86
	v_mfma_f32_16x16x32_bf16 v[38:41], v[210:213], v[118:121], v[38:41]
	ds_read_b64_tr_b16 v[210:211], v238 offset:57344
	ds_read_b64_tr_b16 v[212:213], v238 offset:61440
	v_exp_f32_e32 v87, v87
	s_waitcnt lgkmcnt(10)
	v_mfma_f32_16x16x32_bf16 v[42:45], v[214:217], v[114:117], v[42:45]
	v_exp_f32_e32 v88, v88
	v_mfma_f32_16x16x32_bf16 v[46:49], v[214:217], v[118:121], v[46:49]
	ds_read_b64_tr_b16 v[214:215], v239 offset:57344
	ds_read_b64_tr_b16 v[216:217], v239 offset:61440
	v_exp_f32_e32 v89, v89
	s_waitcnt lgkmcnt(10)
	v_mfma_f32_16x16x32_bf16 v[50:53], v[218:221], v[114:117], v[50:53]
	v_exp_f32_e32 v90, v90
	v_mfma_f32_16x16x32_bf16 v[54:57], v[218:221], v[118:121], v[54:57]
	ds_read_b64_tr_b16 v[218:219], v240 offset:57344
	ds_read_b64_tr_b16 v[220:221], v240 offset:61440
	v_exp_f32_e32 v91, v91
	s_waitcnt lgkmcnt(10)
	v_mfma_f32_16x16x32_bf16 v[58:61], v[222:225], v[114:117], v[58:61]
	v_exp_f32_e32 v92, v92
	v_mfma_f32_16x16x32_bf16 v[62:65], v[222:225], v[118:121], v[62:65]
	ds_read_b64_tr_b16 v[222:223], v241 offset:57344
	ds_read_b64_tr_b16 v[224:225], v241 offset:61440
	v_exp_f32_e32 v93, v93
	s_waitcnt lgkmcnt(10)
	v_mfma_f32_16x16x32_bf16 v[66:69], v[202:205], v[114:117], v[66:69]
	v_exp_f32_e32 v94, v94
	v_mfma_f32_16x16x32_bf16 v[70:73], v[202:205], v[118:121], v[70:73]
	ds_read_b64_tr_b16 v[202:203], v242 offset:57344
	ds_read_b64_tr_b16 v[204:205], v242 offset:61440
	v_exp_f32_e32 v95, v95
	s_waitcnt lgkmcnt(10)
	v_mfma_f32_16x16x32_bf16 v[74:77], v[206:209], v[114:117], v[74:77]
	v_exp_f32_e32 v96, v96
	v_mfma_f32_16x16x32_bf16 v[78:81], v[206:209], v[118:121], v[78:81]
	ds_read_b64_tr_b16 v[206:207], v243 offset:57344
	ds_read_b64_tr_b16 v[208:209], v243 offset:61440
	v_exp_f32_e32 v97, v97
	s_waitcnt lgkmcnt(10)
	v_mfma_f32_16x16x32_bf16 v[18:21], v[210:213], v[130:133], v[18:21]
	v_exp_f32_e32 v98, v98
	v_mfma_f32_16x16x32_bf16 v[22:25], v[210:213], v[134:137], v[22:25]
	ds_read_b64_tr_b16 v[210:211], v244 offset:57344
	ds_read_b64_tr_b16 v[212:213], v244 offset:61440
	v_exp_f32_e32 v99, v99
	s_waitcnt lgkmcnt(10)
	v_mfma_f32_16x16x32_bf16 v[26:29], v[214:217], v[130:133], v[26:29]
	v_exp_f32_e32 v100, v100
	v_mfma_f32_16x16x32_bf16 v[30:33], v[214:217], v[134:137], v[30:33]
	ds_read_b64_tr_b16 v[214:215], v245 offset:57344
	ds_read_b64_tr_b16 v[216:217], v245 offset:61440
	v_exp_f32_e32 v101, v101
	s_waitcnt lgkmcnt(10)
	v_mfma_f32_16x16x32_bf16 v[34:37], v[218:221], v[130:133], v[34:37]
	v_exp_f32_e32 v102, v102
	v_mfma_f32_16x16x32_bf16 v[38:41], v[218:221], v[134:137], v[38:41]
	v_exp_f32_e32 v103, v103
	s_waitcnt lgkmcnt(8)
	v_mfma_f32_16x16x32_bf16 v[42:45], v[222:225], v[130:133], v[42:45]
	v_exp_f32_e32 v104, v104
	v_mfma_f32_16x16x32_bf16 v[46:49], v[222:225], v[134:137], v[46:49]
	v_exp_f32_e32 v105, v105
	s_waitcnt lgkmcnt(6)
	v_mfma_f32_16x16x32_bf16 v[50:53], v[202:205], v[130:133], v[50:53]
	v_exp_f32_e32 v106, v106
	ds_read_b128 v[178:181], v234 offset:16384
	v_mfma_f32_16x16x32_bf16 v[54:57], v[202:205], v[134:137], v[54:57]
	v_exp_f32_e32 v107, v107
	s_waitcnt lgkmcnt(5)
	v_mfma_f32_16x16x32_bf16 v[58:61], v[206:209], v[130:133], v[58:61]
	v_exp_f32_e32 v108, v108
	ds_read_b128 v[182:185], v234 offset:20480
	v_mfma_f32_16x16x32_bf16 v[62:65], v[206:209], v[134:137], v[62:65]
	v_exp_f32_e32 v109, v109
	s_waitcnt lgkmcnt(4)
	v_mfma_f32_16x16x32_bf16 v[66:69], v[210:213], v[130:133], v[66:69]
	v_exp_f32_e32 v110, v110
	ds_read_b128 v[186:189], v234 offset:24576
	v_mfma_f32_16x16x32_bf16 v[70:73], v[210:213], v[134:137], v[70:73]
	v_exp_f32_e32 v111, v111
	s_waitcnt lgkmcnt(3)
	v_mfma_f32_16x16x32_bf16 v[74:77], v[214:217], v[130:133], v[74:77]
	v_exp_f32_e32 v112, v112
	ds_read_b128 v[190:193], v234 offset:28672
	v_mfma_f32_16x16x32_bf16 v[78:81], v[214:217], v[134:137], v[78:81]
	v_exp_f32_e32 v113, v113
	s_waitcnt lgkmcnt(3)
	v_mfma_f32_16x16x32_bf16 v[114:117], v[178:181], v[146:149], v[2:5]
	v_add_f32_e32 v250, v82, v250
	s_add_u32 s98, s98, 0x8000
	s_addc_u32 s99, s99, 0
	s_add_u32 s100, s100, 0x8000
	s_addc_u32 s101, s101, 0
	v_mfma_f32_16x16x32_bf16 v[118:121], v[178:181], v[162:165], v[2:5]
	ds_read_b128 v[178:181], v235 offset:16384
	v_add_f32_e32 v250, v83, v250
	v_add_f32_e32 v250, v84, v250
	s_waitcnt lgkmcnt(3)
	v_mfma_f32_16x16x32_bf16 v[122:125], v[182:185], v[146:149], v[2:5]
	v_add_f32_e32 v250, v85, v250
	s_add_u32 m0, s79, 0
	s_nop 0
	global_load_lds_dwordx4 v246, s[98:99]
	v_mfma_f32_16x16x32_bf16 v[126:129], v[182:185], v[162:165], v[2:5]
	ds_read_b128 v[182:185], v235 offset:20480
	v_add_f32_e32 v250, v90, v250
	v_add_f32_e32 v250, v91, v250
	s_waitcnt lgkmcnt(3)
	v_mfma_f32_16x16x32_bf16 v[130:133], v[186:189], v[146:149], v[2:5]
	v_add_f32_e32 v250, v92, v250
	v_mfma_f32_16x16x32_bf16 v[134:137], v[186:189], v[162:165], v[2:5]
	ds_read_b128 v[186:189], v235 offset:24576
	v_add_f32_e32 v250, v93, v250
	v_cvt_pk_bf16_f32 v82, v82, v83
	s_waitcnt lgkmcnt(3)
; __device__ __forceinline__ void partialSM(f32x16& p0, f32x16& p1, float mC) {
;   (void)mC; (void)p1;
;   for (int r = 0; r < 16; ++r) p0[r] = __builtin_amdgcn_exp2f(p0[r]);
; }
; __device__ __forceinline__ void finishSM(f32x16& p0, f32x16& p1, float& l_reg, bf16x8& pa0, bf16x8& pa1, bf16x8& pa2, bf16x8& pa3) {
;   for (int r = 0; r < 16; ++r) p1[r] = __builtin_amdgcn_exp2f(p1[r]);
;   float ps = 0; for (int r = 0; r < 16; ++r) ps += p0[r]; for (int r = 0; r < 16; ++r) ps += p1[r];
;   { auto rr = __builtin_amdgcn_permlane32_swap(__float_as_uint(ps), __float_as_uint(ps), false, false);
;     ps = __uint_as_float(rr[0]) + __uint_as_float(rr[1]); }
;   l_reg += ps;
;     ...
;   PK4(p0, 0, pa0); PK4(p0, 8, pa1); PK4(p1, 0, pa2); PK4(p1, 8, pa3);
;     ...
; }
; __device__ __forceinline__ void qkt(f32x16& p0, f32x16& p1, const bf16* Ks, const bf16x8* qr, int r32, int hi, const f32x16& negm) {
; #pragma unroll
;   for (int d0 = 0; d0 < 8; ++d0) { int cb = (d0 * 16 + hi * 8) * 2;
;     bf16x8 b0 = *reinterpret_cast<const bf16x8*>((const char*)Ks + KSWZ(r32, cb));
;     bf16x8 b1 = *reinterpret_cast<const bf16x8*>((const char*)Ks + KSWZ(32 + r32, cb));
;     if (d0 == 0) { p0 = __builtin_amdgcn_mfma_f32_32x32x16_bf16(b0, qr[0], negm, 0, 0, 0); p1 = __builtin_amdgcn_mfma_f32_32x32x16_bf16(b1, qr[0], negm, 0, 0, 0); }
;     else { p0 = __builtin_amdgcn_mfma_f32_32x32x16_bf16(b0, qr[d0], p0, 0, 0, 0); p1 = __builtin_amdgcn_mfma_f32_32x32x16_bf16(b1, qr[d0], p1, 0, 0, 0); } }
; }
; __device__ __forceinline__ int v_st(int k, int c) { const int kk = (k & ~0xC) | ((k & 4) << 1) | ((k & 8) >> 1); return ((kk >> 3) * 4 + (c >> 5)) * 512 + ((kk & 7) * 32 + (c & 31)) * 2; }
; __device__ __forceinline__ int v_rd_base(int lane) { return ((lane & 3) << 3) | (((lane >> 2) & 3) << 6) | (((lane >> 4) & 1) << 5) | (((lane >> 5) & 1) << 8); }
; template <int OFF> __device__ __forceinline__ s16x4 tr_read(int vb) {
;   s16x4 r; asm volatile("ds_read_b64_tr_b16 %0, %1 offset:%2" : "=&v"(r) : "v"(vb), "i"(OFF) : "memory"); return r;
; }
; template <int D0> __device__ __forceinline__ void pv_one(f32x16& od, int vb, bf16x8 pa0, bf16x8 pa1, bf16x8 pa2, bf16x8 pa3) {
;   const s16x4 l0 = tr_read<v_rd_off(D0, 0, 0)>(vb), h0 = tr_read<v_rd_off(D0, 0, 1)>(vb), l1 = tr_read<v_rd_off(D0, 1, 0)>(vb), h1 = tr_read<v_rd_off(D0, 1, 1)>(vb);
	v_mfma_f32_16x16x32_bf16 v[138:141], v[190:193], v[146:149], v[2:5]
	v_cvt_pk_bf16_f32 v83, v84, v85
	s_add_u32 m0, s79, 1024
	s_nop 0
	global_load_lds_dwordx4 v247, s[98:99]
	v_mfma_f32_16x16x32_bf16 v[142:145], v[190:193], v[162:165], v[2:5]
	ds_read_b128 v[190:193], v235 offset:28672
	v_cvt_pk_bf16_f32 v84, v90, v91
	v_cvt_pk_bf16_f32 v85, v92, v93
	s_waitcnt lgkmcnt(3)
	v_mfma_f32_16x16x32_bf16 v[114:117], v[178:181], v[150:153], v[114:117]
	v_add_f32_e32 v251, v86, v251
	v_mfma_f32_16x16x32_bf16 v[118:121], v[178:181], v[166:169], v[118:121]
	ds_read_b128 v[178:181], v236 offset:16384
	v_add_f32_e32 v251, v87, v251
	v_add_f32_e32 v251, v88, v251
	s_waitcnt lgkmcnt(3)
	v_mfma_f32_16x16x32_bf16 v[122:125], v[182:185], v[150:153], v[122:125]
	v_add_f32_e32 v251, v89, v251
	s_add_u32 m0, s80, 32768
	s_nop 0
	global_load_lds_dwordx4 v248, s[100:101]
	v_mfma_f32_16x16x32_bf16 v[126:129], v[182:185], v[166:169], v[126:129]
	ds_read_b128 v[182:185], v236 offset:20480
	v_add_f32_e32 v251, v94, v251
	v_add_f32_e32 v251, v95, v251
	s_waitcnt lgkmcnt(3)
	v_mfma_f32_16x16x32_bf16 v[130:133], v[186:189], v[150:153], v[130:133]
	v_add_f32_e32 v251, v96, v251
	v_mfma_f32_16x16x32_bf16 v[134:137], v[186:189], v[166:169], v[134:137]
	ds_read_b128 v[186:189], v236 offset:24576
	v_add_f32_e32 v251, v97, v251
	v_cvt_pk_bf16_f32 v86, v86, v87
	s_waitcnt lgkmcnt(3)
	v_mfma_f32_16x16x32_bf16 v[138:141], v[190:193], v[150:153], v[138:141]
	v_cvt_pk_bf16_f32 v87, v88, v89
	s_add_u32 m0, s80, 33792
	s_nop 0
	global_load_lds_dwordx4 v249, s[100:101]
	v_mfma_f32_16x16x32_bf16 v[142:145], v[190:193], v[166:169], v[142:145]
	ds_read_b128 v[190:193], v236 offset:28672
	v_cvt_pk_bf16_f32 v88, v94, v95
	v_cvt_pk_bf16_f32 v89, v96, v97
	s_waitcnt lgkmcnt(3)
	v_mfma_f32_16x16x32_bf16 v[114:117], v[178:181], v[154:157], v[114:117]
	v_add_f32_e32 v250, v98, v250
	v_mfma_f32_16x16x32_bf16 v[118:121], v[178:181], v[170:173], v[118:121]
	ds_read_b128 v[178:181], v237 offset:16384
	v_add_f32_e32 v250, v99, v250
	v_add_f32_e32 v250, v100, v250
	s_waitcnt lgkmcnt(3)
	v_mfma_f32_16x16x32_bf16 v[122:125], v[182:185], v[154:157], v[122:125]
	v_add_f32_e32 v250, v101, v250
	v_mfma_f32_16x16x32_bf16 v[126:129], v[182:185], v[170:173], v[126:129]
	ds_read_b128 v[182:185], v237 offset:20480
	v_add_f32_e32 v250, v106, v250
	v_add_f32_e32 v250, v107, v250
	s_waitcnt lgkmcnt(3)
	v_mfma_f32_16x16x32_bf16 v[130:133], v[186:189], v[154:157], v[130:133]
	v_add_f32_e32 v250, v108, v250
	ds_read_b64_tr_b16 v[202:203], v238 offset:0
	ds_read_b64_tr_b16 v[204:205], v238 offset:4096
	v_mfma_f32_16x16x32_bf16 v[134:137], v[186:189], v[170:173], v[134:137]
	ds_read_b128 v[186:189], v237 offset:24576
	v_add_f32_e32 v250, v109, v250
	v_cvt_pk_bf16_f32 v98, v98, v99
	s_waitcnt lgkmcnt(5)
	v_mfma_f32_16x16x32_bf16 v[138:141], v[190:193], v[154:157], v[138:141]
	v_cvt_pk_bf16_f32 v99, v100, v101
	ds_read_b64_tr_b16 v[206:207], v239 offset:0
	ds_read_b64_tr_b16 v[208:209], v239 offset:4096
	v_mfma_f32_16x16x32_bf16 v[142:145], v[190:193], v[170:173], v[142:145]
	ds_read_b128 v[190:193], v237 offset:28672
	v_cvt_pk_bf16_f32 v100, v106, v107
	v_cvt_pk_bf16_f32 v101, v108, v109
	s_waitcnt lgkmcnt(7)
	v_mfma_f32_16x16x32_bf16 v[114:117], v[178:181], v[158:161], v[114:117]
	v_add_f32_e32 v251, v102, v251
	ds_read_b64_tr_b16 v[210:211], v240 offset:0
	ds_read_b64_tr_b16 v[212:213], v240 offset:4096
	v_mfma_f32_16x16x32_bf16 v[118:121], v[178:181], v[174:177], v[118:121]
	v_add_f32_e32 v251, v103, v251
	v_add_f32_e32 v251, v104, v251
	s_waitcnt lgkmcnt(8)
	v_mfma_f32_16x16x32_bf16 v[122:125], v[182:185], v[158:161], v[122:125]
	v_add_f32_e32 v251, v105, v251
	ds_read_b64_tr_b16 v[214:215], v241 offset:0
	ds_read_b64_tr_b16 v[216:217], v241 offset:4096
	v_mfma_f32_16x16x32_bf16 v[126:129], v[182:185], v[174:177], v[126:129]
	v_add_f32_e32 v251, v110, v251
	v_add_f32_e32 v251, v111, v251
	s_waitcnt lgkmcnt(7)
	v_mfma_f32_16x16x32_bf16 v[130:133], v[186:189], v[158:161], v[130:133]
	v_add_f32_e32 v251, v112, v251
	ds_read_b64_tr_b16 v[218:219], v242 offset:0
	ds_read_b64_tr_b16 v[220:221], v242 offset:4096
	v_mfma_f32_16x16x32_bf16 v[134:137], v[186:189], v[174:177], v[134:137]
	v_add_f32_e32 v251, v113, v251
	v_cvt_pk_bf16_f32 v102, v102, v103
	s_waitcnt lgkmcnt(6)
	v_mfma_f32_16x16x32_bf16 v[138:141], v[190:193], v[158:161], v[138:141]
	v_cvt_pk_bf16_f32 v103, v104, v105
	ds_read_b64_tr_b16 v[222:223], v243 offset:0
	ds_read_b64_tr_b16 v[224:225], v243 offset:4096
	v_mfma_f32_16x16x32_bf16 v[142:145], v[190:193], v[174:177], v[142:145]
	v_cvt_pk_bf16_f32 v104, v110, v111
	v_cvt_pk_bf16_f32 v105, v112, v113
	s_waitcnt vmcnt(4)
	s_add_i32 s15, s15, 1
	s_cmp_lt_u32 s15, 31
	s_cbranch_scc1 .Lattn_loop2
	s_barrier
; __device__ __forceinline__ void partialSM(f32x16& p0, f32x16& p1, float mC) {
;   (void)mC; (void)p1;
;   for (int r = 0; r < 16; ++r) p0[r] = __builtin_amdgcn_exp2f(p0[r]);
; }
; __device__ __forceinline__ void finishSM(f32x16& p0, f32x16& p1, float& l_reg, bf16x8& pa0, bf16x8& pa1, bf16x8& pa2, bf16x8& pa3) {
;   for (int r = 0; r < 16; ++r) p1[r] = __builtin_amdgcn_exp2f(p1[r]);
;   float ps = 0; for (int r = 0; r < 16; ++r) ps += p0[r]; for (int r = 0; r < 16; ++r) ps += p1[r];
;   { auto rr = __builtin_amdgcn_permlane32_swap(__float_as_uint(ps), __float_as_uint(ps), false, false);
;     ps = __uint_as_float(rr[0]) + __uint_as_float(rr[1]); }
;   l_reg += ps;
;     ...
;   PK4(p0, 0, pa0); PK4(p0, 8, pa1); PK4(p1, 0, pa2); PK4(p1, 8, pa3);
;     ...
; }
; __device__ __forceinline__ void qkt(f32x16& p0, f32x16& p1, const bf16* Ks, const bf16x8* qr, int r32, int hi, const f32x16& negm) {
; #pragma unroll
;   for (int d0 = 0; d0 < 8; ++d0) { int cb = (d0 * 16 + hi * 8) * 2;
;     bf16x8 b0 = *reinterpret_cast<const bf16x8*>((const char*)Ks + KSWZ(r32, cb));
;     bf16x8 b1 = *reinterpret_cast<const bf16x8*>((const char*)Ks + KSWZ(32 + r32, cb));
;     if (d0 == 0) { p0 = __builtin_amdgcn_mfma_f32_32x32x16_bf16(b0, qr[0], negm, 0, 0, 0); p1 = __builtin_amdgcn_mfma_f32_32x32x16_bf16(b1, qr[0], negm, 0, 0, 0); }
;     else { p0 = __builtin_amdgcn_mfma_f32_32x32x16_bf16(b0, qr[d0], p0, 0, 0, 0); p1 = __builtin_amdgcn_mfma_f32_32x32x16_bf16(b1, qr[d0], p1, 0, 0, 0); } }
; }
; __device__ __forceinline__ int v_st(int k, int c) { const int kk = (k & ~0xC) | ((k & 4) << 1) | ((k & 8) >> 1); return ((kk >> 3) * 4 + (c >> 5)) * 512 + ((kk & 7) * 32 + (c & 31)) * 2; }
; __device__ __forceinline__ int v_rd_base(int lane) { return ((lane & 3) << 3) | (((lane >> 2) & 3) << 6) | (((lane >> 4) & 1) << 5) | (((lane >> 5) & 1) << 8); }
; template <int OFF> __device__ __forceinline__ s16x4 tr_read(int vb) {
;   s16x4 r; asm volatile("ds_read_b64_tr_b16 %0, %1 offset:%2" : "=&v"(r) : "v"(vb), "i"(OFF) : "memory"); return r;
; }
; template <int D0> __device__ __forceinline__ void pv_one(f32x16& od, int vb, bf16x8 pa0, bf16x8 pa1, bf16x8 pa2, bf16x8 pa3) {
;   const s16x4 l0 = tr_read<v_rd_off(D0, 0, 0)>(vb), h0 = tr_read<v_rd_off(D0, 0, 1)>(vb), l1 = tr_read<v_rd_off(D0, 1, 0)>(vb), h1 = tr_read<v_rd_off(D0, 1, 1)>(vb);
	v_mfma_f32_16x16x32_bf16 v[18:21], v[202:205], v[82:85], v[18:21]
	v_exp_f32_e32 v114, v114
	v_mfma_f32_16x16x32_bf16 v[22:25], v[202:205], v[86:89], v[22:25]
	ds_read_b64_tr_b16 v[202:203], v244 offset:0
	ds_read_b64_tr_b16 v[204:205], v244 offset:4096
	v_exp_f32_e32 v115, v115
	v_mfma_f32_16x16x32_bf16 v[26:29], v[206:209], v[82:85], v[26:29]
	v_exp_f32_e32 v116, v116
	v_mfma_f32_16x16x32_bf16 v[30:33], v[206:209], v[86:89], v[30:33]
	ds_read_b64_tr_b16 v[206:207], v245 offset:0
	ds_read_b64_tr_b16 v[208:209], v245 offset:4096
	v_exp_f32_e32 v117, v117
	s_waitcnt lgkmcnt(10)
	v_mfma_f32_16x16x32_bf16 v[34:37], v[210:213], v[82:85], v[34:37]
	v_exp_f32_e32 v118, v118
	v_mfma_f32_16x16x32_bf16 v[38:41], v[210:213], v[86:89], v[38:41]
	ds_read_b64_tr_b16 v[210:211], v238 offset:8192
	ds_read_b64_tr_b16 v[212:213], v238 offset:12288
	v_exp_f32_e32 v119, v119
	s_waitcnt lgkmcnt(10)
	v_mfma_f32_16x16x32_bf16 v[42:45], v[214:217], v[82:85], v[42:45]
	v_exp_f32_e32 v120, v120
	v_mfma_f32_16x16x32_bf16 v[46:49], v[214:217], v[86:89], v[46:49]
	ds_read_b64_tr_b16 v[214:215], v239 offset:8192
	ds_read_b64_tr_b16 v[216:217], v239 offset:12288
	v_exp_f32_e32 v121, v121
	s_waitcnt lgkmcnt(10)
	v_mfma_f32_16x16x32_bf16 v[50:53], v[218:221], v[82:85], v[50:53]
	v_exp_f32_e32 v122, v122
	v_mfma_f32_16x16x32_bf16 v[54:57], v[218:221], v[86:89], v[54:57]
	ds_read_b64_tr_b16 v[218:219], v240 offset:8192
	ds_read_b64_tr_b16 v[220:221], v240 offset:12288
	v_exp_f32_e32 v123, v123
	s_waitcnt lgkmcnt(10)
	v_mfma_f32_16x16x32_bf16 v[58:61], v[222:225], v[82:85], v[58:61]
	v_exp_f32_e32 v124, v124
	v_mfma_f32_16x16x32_bf16 v[62:65], v[222:225], v[86:89], v[62:65]
	ds_read_b64_tr_b16 v[222:223], v241 offset:8192
	ds_read_b64_tr_b16 v[224:225], v241 offset:12288
	v_exp_f32_e32 v125, v125
	s_waitcnt lgkmcnt(10)
	v_mfma_f32_16x16x32_bf16 v[66:69], v[202:205], v[82:85], v[66:69]
	v_exp_f32_e32 v126, v126
	v_mfma_f32_16x16x32_bf16 v[70:73], v[202:205], v[86:89], v[70:73]
	ds_read_b64_tr_b16 v[202:203], v242 offset:8192
	ds_read_b64_tr_b16 v[204:205], v242 offset:12288
	v_exp_f32_e32 v127, v127
	s_waitcnt lgkmcnt(10)
	v_mfma_f32_16x16x32_bf16 v[74:77], v[206:209], v[82:85], v[74:77]
	v_exp_f32_e32 v128, v128
	v_mfma_f32_16x16x32_bf16 v[78:81], v[206:209], v[86:89], v[78:81]
	ds_read_b64_tr_b16 v[206:207], v243 offset:8192
	ds_read_b64_tr_b16 v[208:209], v243 offset:12288
	v_exp_f32_e32 v129, v129
	s_waitcnt lgkmcnt(10)
	v_mfma_f32_16x16x32_bf16 v[18:21], v[210:213], v[98:101], v[18:21]
	v_exp_f32_e32 v130, v130
	v_mfma_f32_16x16x32_bf16 v[22:25], v[210:213], v[102:105], v[22:25]
	ds_read_b64_tr_b16 v[210:211], v244 offset:8192
	ds_read_b64_tr_b16 v[212:213], v244 offset:12288
	v_exp_f32_e32 v131, v131
	s_waitcnt lgkmcnt(10)
	v_mfma_f32_16x16x32_bf16 v[26:29], v[214:217], v[98:101], v[26:29]
	v_exp_f32_e32 v132, v132
	v_mfma_f32_16x16x32_bf16 v[30:33], v[214:217], v[102:105], v[30:33]
	ds_read_b64_tr_b16 v[214:215], v245 offset:8192
	ds_read_b64_tr_b16 v[216:217], v245 offset:12288
	v_exp_f32_e32 v133, v133
	s_waitcnt lgkmcnt(10)
	v_mfma_f32_16x16x32_bf16 v[34:37], v[218:221], v[98:101], v[34:37]
	v_exp_f32_e32 v134, v134
	v_mfma_f32_16x16x32_bf16 v[38:41], v[218:221], v[102:105], v[38:41]
	v_exp_f32_e32 v135, v135
	s_waitcnt lgkmcnt(8)
	v_mfma_f32_16x16x32_bf16 v[42:45], v[222:225], v[98:101], v[42:45]
	v_exp_f32_e32 v136, v136
	v_mfma_f32_16x16x32_bf16 v[46:49], v[222:225], v[102:105], v[46:49]
	v_exp_f32_e32 v137, v137
	s_waitcnt lgkmcnt(6)
	v_mfma_f32_16x16x32_bf16 v[50:53], v[202:205], v[98:101], v[50:53]
	v_exp_f32_e32 v138, v138
	ds_read_b128 v[178:181], v234 offset:32768
	v_mfma_f32_16x16x32_bf16 v[54:57], v[202:205], v[102:105], v[54:57]
	v_exp_f32_e32 v139, v139
	s_waitcnt lgkmcnt(5)
	v_mfma_f32_16x16x32_bf16 v[58:61], v[206:209], v[98:101], v[58:61]
	v_exp_f32_e32 v140, v140
	ds_read_b128 v[182:185], v234 offset:36864
	v_mfma_f32_16x16x32_bf16 v[62:65], v[206:209], v[102:105], v[62:65]
	v_exp_f32_e32 v141, v141
	s_waitcnt lgkmcnt(4)
	v_mfma_f32_16x16x32_bf16 v[66:69], v[210:213], v[98:101], v[66:69]
	v_exp_f32_e32 v142, v142
	ds_read_b128 v[186:189], v234 offset:40960
	v_mfma_f32_16x16x32_bf16 v[70:73], v[210:213], v[102:105], v[70:73]
	v_exp_f32_e32 v143, v143
	s_waitcnt lgkmcnt(3)
	v_mfma_f32_16x16x32_bf16 v[74:77], v[214:217], v[98:101], v[74:77]
	v_exp_f32_e32 v144, v144
	ds_read_b128 v[190:193], v234 offset:45056
	v_mfma_f32_16x16x32_bf16 v[78:81], v[214:217], v[102:105], v[78:81]
	v_exp_f32_e32 v145, v145
	s_waitcnt lgkmcnt(3)
	v_mfma_f32_16x16x32_bf16 v[82:85], v[178:181], v[146:149], v[2:5]
	v_add_f32_e32 v250, v114, v250
	s_add_u32 s98, s98, 0x8000
	s_addc_u32 s99, s99, 0
	s_add_u32 s100, s100, 0x8000
	s_addc_u32 s101, s101, 0
	v_mfma_f32_16x16x32_bf16 v[86:89], v[178:181], v[162:165], v[2:5]
	ds_read_b128 v[178:181], v235 offset:32768
	v_add_f32_e32 v250, v115, v250
	v_add_f32_e32 v250, v116, v250
	s_waitcnt lgkmcnt(3)
	v_mfma_f32_16x16x32_bf16 v[90:93], v[182:185], v[146:149], v[2:5]
	v_add_f32_e32 v250, v117, v250
	s_add_u32 m0, s79, 16384
	s_nop 0
	global_load_lds_dwordx4 v246, s[98:99]
	v_mfma_f32_16x16x32_bf16 v[94:97], v[182:185], v[162:165], v[2:5]
	ds_read_b128 v[182:185], v235 offset:36864
	v_add_f32_e32 v250, v122, v250
	v_add_f32_e32 v250, v123, v250
	s_waitcnt lgkmcnt(3)
	v_mfma_f32_16x16x32_bf16 v[98:101], v[186:189], v[146:149], v[2:5]
	v_add_f32_e32 v250, v124, v250
	v_mfma_f32_16x16x32_bf16 v[102:105], v[186:189], v[162:165], v[2:5]
	ds_read_b128 v[186:189], v235 offset:40960
	v_add_f32_e32 v250, v125, v250
	v_cvt_pk_bf16_f32 v114, v114, v115
	s_waitcnt lgkmcnt(3)
; __device__ __forceinline__ void partialSM(f32x16& p0, f32x16& p1, float mC) {
;   (void)mC; (void)p1;
;   for (int r = 0; r < 16; ++r) p0[r] = __builtin_amdgcn_exp2f(p0[r]);
; }
; __device__ __forceinline__ void finishSM(f32x16& p0, f32x16& p1, float& l_reg, bf16x8& pa0, bf16x8& pa1, bf16x8& pa2, bf16x8& pa3) {
;   for (int r = 0; r < 16; ++r) p1[r] = __builtin_amdgcn_exp2f(p1[r]);
;   float ps = 0; for (int r = 0; r < 16; ++r) ps += p0[r]; for (int r = 0; r < 16; ++r) ps += p1[r];
;   { auto rr = __builtin_amdgcn_permlane32_swap(__float_as_uint(ps), __float_as_uint(ps), false, false);
;     ps = __uint_as_float(rr[0]) + __uint_as_float(rr[1]); }
;   l_reg += ps;
;     ...
;   PK4(p0, 0, pa0); PK4(p0, 8, pa1); PK4(p1, 0, pa2); PK4(p1, 8, pa3);
;     ...
; }
; __device__ __forceinline__ void qkt(f32x16& p0, f32x16& p1, const bf16* Ks, const bf16x8* qr, int r32, int hi, const f32x16& negm) {
; #pragma unroll
;   for (int d0 = 0; d0 < 8; ++d0) { int cb = (d0 * 16 + hi * 8) * 2;
;     bf16x8 b0 = *reinterpret_cast<const bf16x8*>((const char*)Ks + KSWZ(r32, cb));
;     bf16x8 b1 = *reinterpret_cast<const bf16x8*>((const char*)Ks + KSWZ(32 + r32, cb));
;     if (d0 == 0) { p0 = __builtin_amdgcn_mfma_f32_32x32x16_bf16(b0, qr[0], negm, 0, 0, 0); p1 = __builtin_amdgcn_mfma_f32_32x32x16_bf16(b1, qr[0], negm, 0, 0, 0); }
;     else { p0 = __builtin_amdgcn_mfma_f32_32x32x16_bf16(b0, qr[d0], p0, 0, 0, 0); p1 = __builtin_amdgcn_mfma_f32_32x32x16_bf16(b1, qr[d0], p1, 0, 0, 0); } }
; }
; __device__ __forceinline__ int v_st(int k, int c) { const int kk = (k & ~0xC) | ((k & 4) << 1) | ((k & 8) >> 1); return ((kk >> 3) * 4 + (c >> 5)) * 512 + ((kk & 7) * 32 + (c & 31)) * 2; }
; __device__ __forceinline__ int v_rd_base(int lane) { return ((lane & 3) << 3) | (((lane >> 2) & 3) << 6) | (((lane >> 4) & 1) << 5) | (((lane >> 5) & 1) << 8); }
; template <int OFF> __device__ __forceinline__ s16x4 tr_read(int vb) {
;   s16x4 r; asm volatile("ds_read_b64_tr_b16 %0, %1 offset:%2" : "=&v"(r) : "v"(vb), "i"(OFF) : "memory"); return r;
; }
; template <int D0> __device__ __forceinline__ void pv_one(f32x16& od, int vb, bf16x8 pa0, bf16x8 pa1, bf16x8 pa2, bf16x8 pa3) {
;   const s16x4 l0 = tr_read<v_rd_off(D0, 0, 0)>(vb), h0 = tr_read<v_rd_off(D0, 0, 1)>(vb), l1 = tr_read<v_rd_off(D0, 1, 0)>(vb), h1 = tr_read<v_rd_off(D0, 1, 1)>(vb);
	v_mfma_f32_16x16x32_bf16 v[106:109], v[190:193], v[146:149], v[2:5]
	v_cvt_pk_bf16_f32 v115, v116, v117
	s_add_u32 m0, s79, 17408
	s_nop 0
	global_load_lds_dwordx4 v247, s[98:99]
	v_mfma_f32_16x16x32_bf16 v[110:113], v[190:193], v[162:165], v[2:5]
	ds_read_b128 v[190:193], v235 offset:45056
	v_cvt_pk_bf16_f32 v116, v122, v123
	v_cvt_pk_bf16_f32 v117, v124, v125
	s_waitcnt lgkmcnt(3)
	v_mfma_f32_16x16x32_bf16 v[82:85], v[178:181], v[150:153], v[82:85]
	v_add_f32_e32 v251, v118, v251
	v_mfma_f32_16x16x32_bf16 v[86:89], v[178:181], v[166:169], v[86:89]
	ds_read_b128 v[178:181], v236 offset:32768
	v_add_f32_e32 v251, v119, v251
	v_add_f32_e32 v251, v120, v251
	s_waitcnt lgkmcnt(3)
	v_mfma_f32_16x16x32_bf16 v[90:93], v[182:185], v[150:153], v[90:93]
	v_add_f32_e32 v251, v121, v251
	s_add_u32 m0, s80, 49152
	s_nop 0
	global_load_lds_dwordx4 v248, s[100:101]
	v_mfma_f32_16x16x32_bf16 v[94:97], v[182:185], v[166:169], v[94:97]
	ds_read_b128 v[182:185], v236 offset:36864
	v_add_f32_e32 v251, v126, v251
	v_add_f32_e32 v251, v127, v251
	s_waitcnt lgkmcnt(3)
	v_mfma_f32_16x16x32_bf16 v[98:101], v[186:189], v[150:153], v[98:101]
	v_add_f32_e32 v251, v128, v251
	v_mfma_f32_16x16x32_bf16 v[102:105], v[186:189], v[166:169], v[102:105]
	ds_read_b128 v[186:189], v236 offset:40960
	v_add_f32_e32 v251, v129, v251
	v_cvt_pk_bf16_f32 v118, v118, v119
	s_waitcnt lgkmcnt(3)
	v_mfma_f32_16x16x32_bf16 v[106:109], v[190:193], v[150:153], v[106:109]
	v_cvt_pk_bf16_f32 v119, v120, v121
	s_add_u32 m0, s80, 50176
	s_nop 0
	global_load_lds_dwordx4 v249, s[100:101]
	v_mfma_f32_16x16x32_bf16 v[110:113], v[190:193], v[166:169], v[110:113]
	ds_read_b128 v[190:193], v236 offset:45056
	v_cvt_pk_bf16_f32 v120, v126, v127
	v_cvt_pk_bf16_f32 v121, v128, v129
	s_waitcnt lgkmcnt(3)
	v_mfma_f32_16x16x32_bf16 v[82:85], v[178:181], v[154:157], v[82:85]
	v_add_f32_e32 v250, v130, v250
	v_mfma_f32_16x16x32_bf16 v[86:89], v[178:181], v[170:173], v[86:89]
	ds_read_b128 v[178:181], v237 offset:32768
	v_add_f32_e32 v250, v131, v250
	v_add_f32_e32 v250, v132, v250
	s_waitcnt lgkmcnt(3)
	v_mfma_f32_16x16x32_bf16 v[90:93], v[182:185], v[154:157], v[90:93]
	v_add_f32_e32 v250, v133, v250
	v_mfma_f32_16x16x32_bf16 v[94:97], v[182:185], v[170:173], v[94:97]
	ds_read_b128 v[182:185], v237 offset:36864
	v_add_f32_e32 v250, v138, v250
	v_add_f32_e32 v250, v139, v250
	s_waitcnt lgkmcnt(3)
	v_mfma_f32_16x16x32_bf16 v[98:101], v[186:189], v[154:157], v[98:101]
	v_add_f32_e32 v250, v140, v250
	ds_read_b64_tr_b16 v[202:203], v238 offset:16384
	ds_read_b64_tr_b16 v[204:205], v238 offset:20480
	v_mfma_f32_16x16x32_bf16 v[102:105], v[186:189], v[170:173], v[102:105]
	ds_read_b128 v[186:189], v237 offset:40960
	v_add_f32_e32 v250, v141, v250
	v_cvt_pk_bf16_f32 v130, v130, v131
	s_waitcnt lgkmcnt(5)
	v_mfma_f32_16x16x32_bf16 v[106:109], v[190:193], v[154:157], v[106:109]
	v_cvt_pk_bf16_f32 v131, v132, v133
	ds_read_b64_tr_b16 v[206:207], v239 offset:16384
	ds_read_b64_tr_b16 v[208:209], v239 offset:20480
	v_mfma_f32_16x16x32_bf16 v[110:113], v[190:193], v[170:173], v[110:113]
	ds_read_b128 v[190:193], v237 offset:45056
	v_cvt_pk_bf16_f32 v132, v138, v139
	v_cvt_pk_bf16_f32 v133, v140, v141
	s_waitcnt lgkmcnt(7)
	v_mfma_f32_16x16x32_bf16 v[82:85], v[178:181], v[158:161], v[82:85]
	v_add_f32_e32 v251, v134, v251
	ds_read_b64_tr_b16 v[210:211], v240 offset:16384
	ds_read_b64_tr_b16 v[212:213], v240 offset:20480
	v_mfma_f32_16x16x32_bf16 v[86:89], v[178:181], v[174:177], v[86:89]
	v_add_f32_e32 v251, v135, v251
	v_add_f32_e32 v251, v136, v251
	s_waitcnt lgkmcnt(8)
	v_mfma_f32_16x16x32_bf16 v[90:93], v[182:185], v[158:161], v[90:93]
	v_add_f32_e32 v251, v137, v251
	ds_read_b64_tr_b16 v[214:215], v241 offset:16384
	ds_read_b64_tr_b16 v[216:217], v241 offset:20480
	v_mfma_f32_16x16x32_bf16 v[94:97], v[182:185], v[174:177], v[94:97]
	v_add_f32_e32 v251, v142, v251
	v_add_f32_e32 v251, v143, v251
	s_waitcnt lgkmcnt(7)
	v_mfma_f32_16x16x32_bf16 v[98:101], v[186:189], v[158:161], v[98:101]
	v_add_f32_e32 v251, v144, v251
	ds_read_b64_tr_b16 v[218:219], v242 offset:16384
	ds_read_b64_tr_b16 v[220:221], v242 offset:20480
	v_mfma_f32_16x16x32_bf16 v[102:105], v[186:189], v[174:177], v[102:105]
	v_add_f32_e32 v251, v145, v251
	v_cvt_pk_bf16_f32 v134, v134, v135
	s_waitcnt lgkmcnt(6)
	v_mfma_f32_16x16x32_bf16 v[106:109], v[190:193], v[158:161], v[106:109]
	v_cvt_pk_bf16_f32 v135, v136, v137
	ds_read_b64_tr_b16 v[222:223], v243 offset:16384
	ds_read_b64_tr_b16 v[224:225], v243 offset:20480
	v_mfma_f32_16x16x32_bf16 v[110:113], v[190:193], v[174:177], v[110:113]
	v_cvt_pk_bf16_f32 v136, v142, v143
	v_cvt_pk_bf16_f32 v137, v144, v145
	s_waitcnt vmcnt(4)
	s_barrier
; __device__ __forceinline__ void partialSM(f32x16& p0, f32x16& p1, float mC) {
;   (void)mC; (void)p1;
;   for (int r = 0; r < 16; ++r) p0[r] = __builtin_amdgcn_exp2f(p0[r]);
; }
; __device__ __forceinline__ void finishSM(f32x16& p0, f32x16& p1, float& l_reg, bf16x8& pa0, bf16x8& pa1, bf16x8& pa2, bf16x8& pa3) {
;   for (int r = 0; r < 16; ++r) p1[r] = __builtin_amdgcn_exp2f(p1[r]);
;   float ps = 0; for (int r = 0; r < 16; ++r) ps += p0[r]; for (int r = 0; r < 16; ++r) ps += p1[r];
;   { auto rr = __builtin_amdgcn_permlane32_swap(__float_as_uint(ps), __float_as_uint(ps), false, false);
;     ps = __uint_as_float(rr[0]) + __uint_as_float(rr[1]); }
;   l_reg += ps;
;     ...
;   PK4(p0, 0, pa0); PK4(p0, 8, pa1); PK4(p1, 0, pa2); PK4(p1, 8, pa3);
;     ...
; }
; __device__ __forceinline__ void qkt(f32x16& p0, f32x16& p1, const bf16* Ks, const bf16x8* qr, int r32, int hi, const f32x16& negm) {
; #pragma unroll
;   for (int d0 = 0; d0 < 8; ++d0) { int cb = (d0 * 16 + hi * 8) * 2;
;     bf16x8 b0 = *reinterpret_cast<const bf16x8*>((const char*)Ks + KSWZ(r32, cb));
;     bf16x8 b1 = *reinterpret_cast<const bf16x8*>((const char*)Ks + KSWZ(32 + r32, cb));
;     if (d0 == 0) { p0 = __builtin_amdgcn_mfma_f32_32x32x16_bf16(b0, qr[0], negm, 0, 0, 0); p1 = __builtin_amdgcn_mfma_f32_32x32x16_bf16(b1, qr[0], negm, 0, 0, 0); }
;     else { p0 = __builtin_amdgcn_mfma_f32_32x32x16_bf16(b0, qr[d0], p0, 0, 0, 0); p1 = __builtin_amdgcn_mfma_f32_32x32x16_bf16(b1, qr[d0], p1, 0, 0, 0); } }
; }
; __device__ __forceinline__ int v_st(int k, int c) { const int kk = (k & ~0xC) | ((k & 4) << 1) | ((k & 8) >> 1); return ((kk >> 3) * 4 + (c >> 5)) * 512 + ((kk & 7) * 32 + (c & 31)) * 2; }
; __device__ __forceinline__ int v_rd_base(int lane) { return ((lane & 3) << 3) | (((lane >> 2) & 3) << 6) | (((lane >> 4) & 1) << 5) | (((lane >> 5) & 1) << 8); }
; template <int OFF> __device__ __forceinline__ s16x4 tr_read(int vb) {
;   s16x4 r; asm volatile("ds_read_b64_tr_b16 %0, %1 offset:%2" : "=&v"(r) : "v"(vb), "i"(OFF) : "memory"); return r;
; }
; template <int D0> __device__ __forceinline__ void pv_one(f32x16& od, int vb, bf16x8 pa0, bf16x8 pa1, bf16x8 pa2, bf16x8 pa3) {
;   const s16x4 l0 = tr_read<v_rd_off(D0, 0, 0)>(vb), h0 = tr_read<v_rd_off(D0, 0, 1)>(vb), l1 = tr_read<v_rd_off(D0, 1, 0)>(vb), h1 = tr_read<v_rd_off(D0, 1, 1)>(vb);
	v_mfma_f32_16x16x32_bf16 v[18:21], v[202:205], v[114:117], v[18:21]
	v_exp_f32_e32 v82, v82
	v_mfma_f32_16x16x32_bf16 v[22:25], v[202:205], v[118:121], v[22:25]
	ds_read_b64_tr_b16 v[202:203], v244 offset:16384
	ds_read_b64_tr_b16 v[204:205], v244 offset:20480
	v_exp_f32_e32 v83, v83
	v_mfma_f32_16x16x32_bf16 v[26:29], v[206:209], v[114:117], v[26:29]
	v_exp_f32_e32 v84, v84
	v_mfma_f32_16x16x32_bf16 v[30:33], v[206:209], v[118:121], v[30:33]
	ds_read_b64_tr_b16 v[206:207], v245 offset:16384
	ds_read_b64_tr_b16 v[208:209], v245 offset:20480
	v_exp_f32_e32 v85, v85
	s_waitcnt lgkmcnt(10)
	v_mfma_f32_16x16x32_bf16 v[34:37], v[210:213], v[114:117], v[34:37]
	v_exp_f32_e32 v86, v86
	v_mfma_f32_16x16x32_bf16 v[38:41], v[210:213], v[118:121], v[38:41]
	ds_read_b64_tr_b16 v[210:211], v238 offset:24576
	ds_read_b64_tr_b16 v[212:213], v238 offset:28672
	v_exp_f32_e32 v87, v87
	s_waitcnt lgkmcnt(10)
	v_mfma_f32_16x16x32_bf16 v[42:45], v[214:217], v[114:117], v[42:45]
	v_exp_f32_e32 v88, v88
	v_mfma_f32_16x16x32_bf16 v[46:49], v[214:217], v[118:121], v[46:49]
	ds_read_b64_tr_b16 v[214:215], v239 offset:24576
	ds_read_b64_tr_b16 v[216:217], v239 offset:28672
	v_exp_f32_e32 v89, v89
	s_waitcnt lgkmcnt(10)
	v_mfma_f32_16x16x32_bf16 v[50:53], v[218:221], v[114:117], v[50:53]
	v_exp_f32_e32 v90, v90
	v_mfma_f32_16x16x32_bf16 v[54:57], v[218:221], v[118:121], v[54:57]
	ds_read_b64_tr_b16 v[218:219], v240 offset:24576
	ds_read_b64_tr_b16 v[220:221], v240 offset:28672
	v_exp_f32_e32 v91, v91
	s_waitcnt lgkmcnt(10)
	v_mfma_f32_16x16x32_bf16 v[58:61], v[222:225], v[114:117], v[58:61]
	v_exp_f32_e32 v92, v92
	v_mfma_f32_16x16x32_bf16 v[62:65], v[222:225], v[118:121], v[62:65]
	ds_read_b64_tr_b16 v[222:223], v241 offset:24576
	ds_read_b64_tr_b16 v[224:225], v241 offset:28672
	v_exp_f32_e32 v93, v93
	s_waitcnt lgkmcnt(10)
	v_mfma_f32_16x16x32_bf16 v[66:69], v[202:205], v[114:117], v[66:69]
	v_exp_f32_e32 v94, v94
	v_mfma_f32_16x16x32_bf16 v[70:73], v[202:205], v[118:121], v[70:73]
	ds_read_b64_tr_b16 v[202:203], v242 offset:24576
	ds_read_b64_tr_b16 v[204:205], v242 offset:28672
	v_exp_f32_e32 v95, v95
	s_waitcnt lgkmcnt(10)
	v_mfma_f32_16x16x32_bf16 v[74:77], v[206:209], v[114:117], v[74:77]
	v_exp_f32_e32 v96, v96
	v_mfma_f32_16x16x32_bf16 v[78:81], v[206:209], v[118:121], v[78:81]
	ds_read_b64_tr_b16 v[206:207], v243 offset:24576
	ds_read_b64_tr_b16 v[208:209], v243 offset:28672
	v_exp_f32_e32 v97, v97
	s_waitcnt lgkmcnt(10)
	v_mfma_f32_16x16x32_bf16 v[18:21], v[210:213], v[130:133], v[18:21]
	v_exp_f32_e32 v98, v98
	v_mfma_f32_16x16x32_bf16 v[22:25], v[210:213], v[134:137], v[22:25]
	ds_read_b64_tr_b16 v[210:211], v244 offset:24576
	ds_read_b64_tr_b16 v[212:213], v244 offset:28672
	v_exp_f32_e32 v99, v99
	s_waitcnt lgkmcnt(10)
	v_mfma_f32_16x16x32_bf16 v[26:29], v[214:217], v[130:133], v[26:29]
	v_exp_f32_e32 v100, v100
	v_mfma_f32_16x16x32_bf16 v[30:33], v[214:217], v[134:137], v[30:33]
	ds_read_b64_tr_b16 v[214:215], v245 offset:24576
	ds_read_b64_tr_b16 v[216:217], v245 offset:28672
	v_exp_f32_e32 v101, v101
	s_waitcnt lgkmcnt(10)
	v_mfma_f32_16x16x32_bf16 v[34:37], v[218:221], v[130:133], v[34:37]
	v_exp_f32_e32 v102, v102
	v_mfma_f32_16x16x32_bf16 v[38:41], v[218:221], v[134:137], v[38:41]
	v_exp_f32_e32 v103, v103
	s_waitcnt lgkmcnt(8)
	v_mfma_f32_16x16x32_bf16 v[42:45], v[222:225], v[130:133], v[42:45]
	v_exp_f32_e32 v104, v104
	v_mfma_f32_16x16x32_bf16 v[46:49], v[222:225], v[134:137], v[46:49]
	v_exp_f32_e32 v105, v105
	s_waitcnt lgkmcnt(6)
	v_mfma_f32_16x16x32_bf16 v[50:53], v[202:205], v[130:133], v[50:53]
	v_exp_f32_e32 v106, v106
	ds_read_b128 v[178:181], v234 offset:49152
	v_mfma_f32_16x16x32_bf16 v[54:57], v[202:205], v[134:137], v[54:57]
	v_exp_f32_e32 v107, v107
	s_waitcnt lgkmcnt(5)
	v_mfma_f32_16x16x32_bf16 v[58:61], v[206:209], v[130:133], v[58:61]
	v_exp_f32_e32 v108, v108
	ds_read_b128 v[182:185], v234 offset:53248
	v_mfma_f32_16x16x32_bf16 v[62:65], v[206:209], v[134:137], v[62:65]
	v_exp_f32_e32 v109, v109
	s_waitcnt lgkmcnt(4)
	v_mfma_f32_16x16x32_bf16 v[66:69], v[210:213], v[130:133], v[66:69]
	v_exp_f32_e32 v110, v110
	ds_read_b128 v[186:189], v234 offset:57344
	v_mfma_f32_16x16x32_bf16 v[70:73], v[210:213], v[134:137], v[70:73]
	v_exp_f32_e32 v111, v111
	s_waitcnt lgkmcnt(3)
	v_mfma_f32_16x16x32_bf16 v[74:77], v[214:217], v[130:133], v[74:77]
	v_exp_f32_e32 v112, v112
	ds_read_b128 v[190:193], v234 offset:61440
	v_mfma_f32_16x16x32_bf16 v[78:81], v[214:217], v[134:137], v[78:81]
	v_exp_f32_e32 v113, v113
	s_waitcnt lgkmcnt(3)
	v_mfma_f32_16x16x32_bf16 v[114:117], v[178:181], v[146:149], v[2:5]
	v_add_f32_e32 v250, v82, v250
	s_add_u32 s98, s98, 0x8000
	s_addc_u32 s99, s99, 0
	s_add_u32 s100, s100, 0x8000
	s_addc_u32 s101, s101, 0
	v_mfma_f32_16x16x32_bf16 v[118:121], v[178:181], v[162:165], v[2:5]
	ds_read_b128 v[178:181], v235 offset:49152
	v_add_f32_e32 v250, v83, v250
	v_add_f32_e32 v250, v84, v250
	s_waitcnt lgkmcnt(3)
	v_mfma_f32_16x16x32_bf16 v[122:125], v[182:185], v[146:149], v[2:5]
	v_add_f32_e32 v250, v85, v250
	s_add_u32 m0, s79, 32768
	s_nop 0
	global_load_lds_dwordx4 v246, s[98:99]
	v_mfma_f32_16x16x32_bf16 v[126:129], v[182:185], v[162:165], v[2:5]
	ds_read_b128 v[182:185], v235 offset:53248
	v_add_f32_e32 v250, v90, v250
	v_add_f32_e32 v250, v91, v250
	s_waitcnt lgkmcnt(3)
	v_mfma_f32_16x16x32_bf16 v[130:133], v[186:189], v[146:149], v[2:5]
	v_add_f32_e32 v250, v92, v250
	v_mfma_f32_16x16x32_bf16 v[134:137], v[186:189], v[162:165], v[2:5]
	ds_read_b128 v[186:189], v235 offset:57344
	v_add_f32_e32 v250, v93, v250
	v_cvt_pk_bf16_f32 v82, v82, v83
	s_waitcnt lgkmcnt(3)
; __device__ __forceinline__ void partialSM(f32x16& p0, f32x16& p1, float mC) {
;   (void)mC; (void)p1;
;   for (int r = 0; r < 16; ++r) p0[r] = __builtin_amdgcn_exp2f(p0[r]);
; }
; __device__ __forceinline__ void finishSM(f32x16& p0, f32x16& p1, float& l_reg, bf16x8& pa0, bf16x8& pa1, bf16x8& pa2, bf16x8& pa3) {
;   for (int r = 0; r < 16; ++r) p1[r] = __builtin_amdgcn_exp2f(p1[r]);
;   float ps = 0; for (int r = 0; r < 16; ++r) ps += p0[r]; for (int r = 0; r < 16; ++r) ps += p1[r];
;   { auto rr = __builtin_amdgcn_permlane32_swap(__float_as_uint(ps), __float_as_uint(ps), false, false);
;     ps = __uint_as_float(rr[0]) + __uint_as_float(rr[1]); }
;   l_reg += ps;
;     ...
;   PK4(p0, 0, pa0); PK4(p0, 8, pa1); PK4(p1, 0, pa2); PK4(p1, 8, pa3);
;     ...
; }
; __device__ __forceinline__ void qkt(f32x16& p0, f32x16& p1, const bf16* Ks, const bf16x8* qr, int r32, int hi, const f32x16& negm) {
; #pragma unroll
;   for (int d0 = 0; d0 < 8; ++d0) { int cb = (d0 * 16 + hi * 8) * 2;
;     bf16x8 b0 = *reinterpret_cast<const bf16x8*>((const char*)Ks + KSWZ(r32, cb));
;     bf16x8 b1 = *reinterpret_cast<const bf16x8*>((const char*)Ks + KSWZ(32 + r32, cb));
;     if (d0 == 0) { p0 = __builtin_amdgcn_mfma_f32_32x32x16_bf16(b0, qr[0], negm, 0, 0, 0); p1 = __builtin_amdgcn_mfma_f32_32x32x16_bf16(b1, qr[0], negm, 0, 0, 0); }
;     else { p0 = __builtin_amdgcn_mfma_f32_32x32x16_bf16(b0, qr[d0], p0, 0, 0, 0); p1 = __builtin_amdgcn_mfma_f32_32x32x16_bf16(b1, qr[d0], p1, 0, 0, 0); } }
; }
; __device__ __forceinline__ int v_st(int k, int c) { const int kk = (k & ~0xC) | ((k & 4) << 1) | ((k & 8) >> 1); return ((kk >> 3) * 4 + (c >> 5)) * 512 + ((kk & 7) * 32 + (c & 31)) * 2; }
; __device__ __forceinline__ int v_rd_base(int lane) { return ((lane & 3) << 3) | (((lane >> 2) & 3) << 6) | (((lane >> 4) & 1) << 5) | (((lane >> 5) & 1) << 8); }
; template <int OFF> __device__ __forceinline__ s16x4 tr_read(int vb) {
;   s16x4 r; asm volatile("ds_read_b64_tr_b16 %0, %1 offset:%2" : "=&v"(r) : "v"(vb), "i"(OFF) : "memory"); return r;
; }
; template <int D0> __device__ __forceinline__ void pv_one(f32x16& od, int vb, bf16x8 pa0, bf16x8 pa1, bf16x8 pa2, bf16x8 pa3) {
;   const s16x4 l0 = tr_read<v_rd_off(D0, 0, 0)>(vb), h0 = tr_read<v_rd_off(D0, 0, 1)>(vb), l1 = tr_read<v_rd_off(D0, 1, 0)>(vb), h1 = tr_read<v_rd_off(D0, 1, 1)>(vb);
	v_mfma_f32_16x16x32_bf16 v[138:141], v[190:193], v[146:149], v[2:5]
	v_cvt_pk_bf16_f32 v83, v84, v85
	s_add_u32 m0, s79, 33792
	s_nop 0
	global_load_lds_dwordx4 v247, s[98:99]
	v_mfma_f32_16x16x32_bf16 v[142:145], v[190:193], v[162:165], v[2:5]
	ds_read_b128 v[190:193], v235 offset:61440
	v_cvt_pk_bf16_f32 v84, v90, v91
	v_cvt_pk_bf16_f32 v85, v92, v93
	s_waitcnt lgkmcnt(3)
	v_mfma_f32_16x16x32_bf16 v[114:117], v[178:181], v[150:153], v[114:117]
	v_add_f32_e32 v251, v86, v251
	v_mfma_f32_16x16x32_bf16 v[118:121], v[178:181], v[166:169], v[118:121]
	ds_read_b128 v[178:181], v236 offset:49152
	v_add_f32_e32 v251, v87, v251
	v_add_f32_e32 v251, v88, v251
	s_waitcnt lgkmcnt(3)
	v_mfma_f32_16x16x32_bf16 v[122:125], v[182:185], v[150:153], v[122:125]
	v_add_f32_e32 v251, v89, v251
	s_add_u32 m0, s80, 0
	s_nop 0
	global_load_lds_dwordx4 v248, s[100:101]
	v_mfma_f32_16x16x32_bf16 v[126:129], v[182:185], v[166:169], v[126:129]
	ds_read_b128 v[182:185], v236 offset:53248
	v_add_f32_e32 v251, v94, v251
	v_add_f32_e32 v251, v95, v251
	s_waitcnt lgkmcnt(3)
	v_mfma_f32_16x16x32_bf16 v[130:133], v[186:189], v[150:153], v[130:133]
	v_add_f32_e32 v251, v96, v251
	v_mfma_f32_16x16x32_bf16 v[134:137], v[186:189], v[166:169], v[134:137]
	ds_read_b128 v[186:189], v236 offset:57344
	v_add_f32_e32 v251, v97, v251
	v_cvt_pk_bf16_f32 v86, v86, v87
	s_waitcnt lgkmcnt(3)
	v_mfma_f32_16x16x32_bf16 v[138:141], v[190:193], v[150:153], v[138:141]
	v_cvt_pk_bf16_f32 v87, v88, v89
	s_add_u32 m0, s80, 1024
	s_nop 0
	global_load_lds_dwordx4 v249, s[100:101]
	v_mfma_f32_16x16x32_bf16 v[142:145], v[190:193], v[166:169], v[142:145]
	ds_read_b128 v[190:193], v236 offset:61440
	v_cvt_pk_bf16_f32 v88, v94, v95
	v_cvt_pk_bf16_f32 v89, v96, v97
	s_waitcnt lgkmcnt(3)
	v_mfma_f32_16x16x32_bf16 v[114:117], v[178:181], v[154:157], v[114:117]
	v_add_f32_e32 v250, v98, v250
	v_mfma_f32_16x16x32_bf16 v[118:121], v[178:181], v[170:173], v[118:121]
	ds_read_b128 v[178:181], v237 offset:49152
	v_add_f32_e32 v250, v99, v250
	v_add_f32_e32 v250, v100, v250
	s_waitcnt lgkmcnt(3)
	v_mfma_f32_16x16x32_bf16 v[122:125], v[182:185], v[154:157], v[122:125]
	v_add_f32_e32 v250, v101, v250
	v_mfma_f32_16x16x32_bf16 v[126:129], v[182:185], v[170:173], v[126:129]
	ds_read_b128 v[182:185], v237 offset:53248
	v_add_f32_e32 v250, v106, v250
	v_add_f32_e32 v250, v107, v250
	s_waitcnt lgkmcnt(3)
	v_mfma_f32_16x16x32_bf16 v[130:133], v[186:189], v[154:157], v[130:133]
	v_add_f32_e32 v250, v108, v250
	ds_read_b64_tr_b16 v[202:203], v238 offset:32768
	ds_read_b64_tr_b16 v[204:205], v238 offset:36864
	v_mfma_f32_16x16x32_bf16 v[134:137], v[186:189], v[170:173], v[134:137]
	ds_read_b128 v[186:189], v237 offset:57344
	v_add_f32_e32 v250, v109, v250
	v_cvt_pk_bf16_f32 v98, v98, v99
	s_waitcnt lgkmcnt(5)
	v_mfma_f32_16x16x32_bf16 v[138:141], v[190:193], v[154:157], v[138:141]
	v_cvt_pk_bf16_f32 v99, v100, v101
	ds_read_b64_tr_b16 v[206:207], v239 offset:32768
	ds_read_b64_tr_b16 v[208:209], v239 offset:36864
	v_mfma_f32_16x16x32_bf16 v[142:145], v[190:193], v[170:173], v[142:145]
	ds_read_b128 v[190:193], v237 offset:61440
	v_cvt_pk_bf16_f32 v100, v106, v107
	v_cvt_pk_bf16_f32 v101, v108, v109
	s_waitcnt lgkmcnt(7)
	v_mfma_f32_16x16x32_bf16 v[114:117], v[178:181], v[158:161], v[114:117]
	v_add_f32_e32 v251, v102, v251
	ds_read_b64_tr_b16 v[210:211], v240 offset:32768
	ds_read_b64_tr_b16 v[212:213], v240 offset:36864
	v_mfma_f32_16x16x32_bf16 v[118:121], v[178:181], v[174:177], v[118:121]
	v_add_f32_e32 v251, v103, v251
	v_add_f32_e32 v251, v104, v251
	s_waitcnt lgkmcnt(8)
	v_mfma_f32_16x16x32_bf16 v[122:125], v[182:185], v[158:161], v[122:125]
	v_add_f32_e32 v251, v105, v251
	ds_read_b64_tr_b16 v[214:215], v241 offset:32768
	ds_read_b64_tr_b16 v[216:217], v241 offset:36864
	v_mfma_f32_16x16x32_bf16 v[126:129], v[182:185], v[174:177], v[126:129]
	v_add_f32_e32 v251, v110, v251
	v_add_f32_e32 v251, v111, v251
	s_waitcnt lgkmcnt(7)
	v_mfma_f32_16x16x32_bf16 v[130:133], v[186:189], v[158:161], v[130:133]
	v_add_f32_e32 v251, v112, v251
	ds_read_b64_tr_b16 v[218:219], v242 offset:32768
	ds_read_b64_tr_b16 v[220:221], v242 offset:36864
	v_mfma_f32_16x16x32_bf16 v[134:137], v[186:189], v[174:177], v[134:137]
	v_add_f32_e32 v251, v113, v251
	v_cvt_pk_bf16_f32 v102, v102, v103
	s_waitcnt lgkmcnt(6)
	v_mfma_f32_16x16x32_bf16 v[138:141], v[190:193], v[158:161], v[138:141]
	v_cvt_pk_bf16_f32 v103, v104, v105
	ds_read_b64_tr_b16 v[222:223], v243 offset:32768
	ds_read_b64_tr_b16 v[224:225], v243 offset:36864
	v_mfma_f32_16x16x32_bf16 v[142:145], v[190:193], v[174:177], v[142:145]
	v_cvt_pk_bf16_f32 v104, v110, v111
	v_cvt_pk_bf16_f32 v105, v112, v113
	s_waitcnt vmcnt(4)
	s_barrier
; __device__ __forceinline__ void partialSM(f32x16& p0, f32x16& p1, float mC) {
;   (void)mC; (void)p1;
;   for (int r = 0; r < 16; ++r) p0[r] = __builtin_amdgcn_exp2f(p0[r]);
; }
; __device__ __forceinline__ void finishSM(f32x16& p0, f32x16& p1, float& l_reg, bf16x8& pa0, bf16x8& pa1, bf16x8& pa2, bf16x8& pa3) {
;   for (int r = 0; r < 16; ++r) p1[r] = __builtin_amdgcn_exp2f(p1[r]);
;   float ps = 0; for (int r = 0; r < 16; ++r) ps += p0[r]; for (int r = 0; r < 16; ++r) ps += p1[r];
;   { auto rr = __builtin_amdgcn_permlane32_swap(__float_as_uint(ps), __float_as_uint(ps), false, false);
;     ps = __uint_as_float(rr[0]) + __uint_as_float(rr[1]); }
;   l_reg += ps;
;     ...
;   PK4(p0, 0, pa0); PK4(p0, 8, pa1); PK4(p1, 0, pa2); PK4(p1, 8, pa3);
;     ...
; }
; __device__ __forceinline__ void qkt(f32x16& p0, f32x16& p1, const bf16* Ks, const bf16x8* qr, int r32, int hi, const f32x16& negm) {
; #pragma unroll
;   for (int d0 = 0; d0 < 8; ++d0) { int cb = (d0 * 16 + hi * 8) * 2;
;     bf16x8 b0 = *reinterpret_cast<const bf16x8*>((const char*)Ks + KSWZ(r32, cb));
;     bf16x8 b1 = *reinterpret_cast<const bf16x8*>((const char*)Ks + KSWZ(32 + r32, cb));
;     if (d0 == 0) { p0 = __builtin_amdgcn_mfma_f32_32x32x16_bf16(b0, qr[0], negm, 0, 0, 0); p1 = __builtin_amdgcn_mfma_f32_32x32x16_bf16(b1, qr[0], negm, 0, 0, 0); }
;     else { p0 = __builtin_amdgcn_mfma_f32_32x32x16_bf16(b0, qr[d0], p0, 0, 0, 0); p1 = __builtin_amdgcn_mfma_f32_32x32x16_bf16(b1, qr[d0], p1, 0, 0, 0); } }
; }
; __device__ __forceinline__ int v_st(int k, int c) { const int kk = (k & ~0xC) | ((k & 4) << 1) | ((k & 8) >> 1); return ((kk >> 3) * 4 + (c >> 5)) * 512 + ((kk & 7) * 32 + (c & 31)) * 2; }
; __device__ __forceinline__ int v_rd_base(int lane) { return ((lane & 3) << 3) | (((lane >> 2) & 3) << 6) | (((lane >> 4) & 1) << 5) | (((lane >> 5) & 1) << 8); }
; template <int OFF> __device__ __forceinline__ s16x4 tr_read(int vb) {
;   s16x4 r; asm volatile("ds_read_b64_tr_b16 %0, %1 offset:%2" : "=&v"(r) : "v"(vb), "i"(OFF) : "memory"); return r;
; }
; template <int D0> __device__ __forceinline__ void pv_one(f32x16& od, int vb, bf16x8 pa0, bf16x8 pa1, bf16x8 pa2, bf16x8 pa3) {
;   const s16x4 l0 = tr_read<v_rd_off(D0, 0, 0)>(vb), h0 = tr_read<v_rd_off(D0, 0, 1)>(vb), l1 = tr_read<v_rd_off(D0, 1, 0)>(vb), h1 = tr_read<v_rd_off(D0, 1, 1)>(vb);
	v_mfma_f32_16x16x32_bf16 v[18:21], v[202:205], v[82:85], v[18:21]
	v_exp_f32_e32 v114, v114
	v_mfma_f32_16x16x32_bf16 v[22:25], v[202:205], v[86:89], v[22:25]
	ds_read_b64_tr_b16 v[202:203], v244 offset:32768
	ds_read_b64_tr_b16 v[204:205], v244 offset:36864
	v_exp_f32_e32 v115, v115
	v_mfma_f32_16x16x32_bf16 v[26:29], v[206:209], v[82:85], v[26:29]
	v_exp_f32_e32 v116, v116
	v_mfma_f32_16x16x32_bf16 v[30:33], v[206:209], v[86:89], v[30:33]
	ds_read_b64_tr_b16 v[206:207], v245 offset:32768
	ds_read_b64_tr_b16 v[208:209], v245 offset:36864
	v_exp_f32_e32 v117, v117
	s_waitcnt lgkmcnt(10)
	v_mfma_f32_16x16x32_bf16 v[34:37], v[210:213], v[82:85], v[34:37]
	v_exp_f32_e32 v118, v118
	v_mfma_f32_16x16x32_bf16 v[38:41], v[210:213], v[86:89], v[38:41]
	ds_read_b64_tr_b16 v[210:211], v238 offset:40960
	ds_read_b64_tr_b16 v[212:213], v238 offset:45056
	v_exp_f32_e32 v119, v119
	s_waitcnt lgkmcnt(10)
	v_mfma_f32_16x16x32_bf16 v[42:45], v[214:217], v[82:85], v[42:45]
	v_exp_f32_e32 v120, v120
	v_mfma_f32_16x16x32_bf16 v[46:49], v[214:217], v[86:89], v[46:49]
	ds_read_b64_tr_b16 v[214:215], v239 offset:40960
	ds_read_b64_tr_b16 v[216:217], v239 offset:45056
	v_exp_f32_e32 v121, v121
	s_waitcnt lgkmcnt(10)
	v_mfma_f32_16x16x32_bf16 v[50:53], v[218:221], v[82:85], v[50:53]
	v_exp_f32_e32 v122, v122
	v_mfma_f32_16x16x32_bf16 v[54:57], v[218:221], v[86:89], v[54:57]
	ds_read_b64_tr_b16 v[218:219], v240 offset:40960
	ds_read_b64_tr_b16 v[220:221], v240 offset:45056
	v_exp_f32_e32 v123, v123
	s_waitcnt lgkmcnt(10)
	v_mfma_f32_16x16x32_bf16 v[58:61], v[222:225], v[82:85], v[58:61]
	v_exp_f32_e32 v124, v124
	v_mfma_f32_16x16x32_bf16 v[62:65], v[222:225], v[86:89], v[62:65]
	ds_read_b64_tr_b16 v[222:223], v241 offset:40960
	ds_read_b64_tr_b16 v[224:225], v241 offset:45056
	v_exp_f32_e32 v125, v125
	s_waitcnt lgkmcnt(10)
	v_mfma_f32_16x16x32_bf16 v[66:69], v[202:205], v[82:85], v[66:69]
	v_exp_f32_e32 v126, v126
	v_mfma_f32_16x16x32_bf16 v[70:73], v[202:205], v[86:89], v[70:73]
	ds_read_b64_tr_b16 v[202:203], v242 offset:40960
	ds_read_b64_tr_b16 v[204:205], v242 offset:45056
	v_exp_f32_e32 v127, v127
	s_waitcnt lgkmcnt(10)
	v_mfma_f32_16x16x32_bf16 v[74:77], v[206:209], v[82:85], v[74:77]
	v_exp_f32_e32 v128, v128
	v_mfma_f32_16x16x32_bf16 v[78:81], v[206:209], v[86:89], v[78:81]
	ds_read_b64_tr_b16 v[206:207], v243 offset:40960
	ds_read_b64_tr_b16 v[208:209], v243 offset:45056
	v_exp_f32_e32 v129, v129
	s_waitcnt lgkmcnt(10)
	v_mfma_f32_16x16x32_bf16 v[18:21], v[210:213], v[98:101], v[18:21]
	v_exp_f32_e32 v130, v130
	v_mfma_f32_16x16x32_bf16 v[22:25], v[210:213], v[102:105], v[22:25]
	ds_read_b64_tr_b16 v[210:211], v244 offset:40960
	ds_read_b64_tr_b16 v[212:213], v244 offset:45056
	v_exp_f32_e32 v131, v131
	s_waitcnt lgkmcnt(10)
	v_mfma_f32_16x16x32_bf16 v[26:29], v[214:217], v[98:101], v[26:29]
	v_exp_f32_e32 v132, v132
	v_mfma_f32_16x16x32_bf16 v[30:33], v[214:217], v[102:105], v[30:33]
	ds_read_b64_tr_b16 v[214:215], v245 offset:40960
	ds_read_b64_tr_b16 v[216:217], v245 offset:45056
	v_exp_f32_e32 v133, v133
	s_waitcnt lgkmcnt(10)
	v_mfma_f32_16x16x32_bf16 v[34:37], v[218:221], v[98:101], v[34:37]
	v_exp_f32_e32 v134, v134
	v_mfma_f32_16x16x32_bf16 v[38:41], v[218:221], v[102:105], v[38:41]
	v_exp_f32_e32 v135, v135
	s_waitcnt lgkmcnt(8)
	v_mfma_f32_16x16x32_bf16 v[42:45], v[222:225], v[98:101], v[42:45]
	v_exp_f32_e32 v136, v136
	v_mfma_f32_16x16x32_bf16 v[46:49], v[222:225], v[102:105], v[46:49]
	v_exp_f32_e32 v137, v137
	s_waitcnt lgkmcnt(6)
	v_mfma_f32_16x16x32_bf16 v[50:53], v[202:205], v[98:101], v[50:53]
	v_exp_f32_e32 v138, v138
	ds_read_b128 v[178:181], v234 offset:0
	v_mfma_f32_16x16x32_bf16 v[54:57], v[202:205], v[102:105], v[54:57]
	v_exp_f32_e32 v139, v139
	s_waitcnt lgkmcnt(5)
	v_mfma_f32_16x16x32_bf16 v[58:61], v[206:209], v[98:101], v[58:61]
	v_exp_f32_e32 v140, v140
	ds_read_b128 v[182:185], v234 offset:4096
	v_mfma_f32_16x16x32_bf16 v[62:65], v[206:209], v[102:105], v[62:65]
	v_exp_f32_e32 v141, v141
	s_waitcnt lgkmcnt(4)
	v_mfma_f32_16x16x32_bf16 v[66:69], v[210:213], v[98:101], v[66:69]
	v_exp_f32_e32 v142, v142
	ds_read_b128 v[186:189], v234 offset:8192
	v_mfma_f32_16x16x32_bf16 v[70:73], v[210:213], v[102:105], v[70:73]
	v_exp_f32_e32 v143, v143
	s_waitcnt lgkmcnt(3)
	v_mfma_f32_16x16x32_bf16 v[74:77], v[214:217], v[98:101], v[74:77]
	v_exp_f32_e32 v144, v144
	ds_read_b128 v[190:193], v234 offset:12288
	v_mfma_f32_16x16x32_bf16 v[78:81], v[214:217], v[102:105], v[78:81]
	v_exp_f32_e32 v145, v145
	s_waitcnt lgkmcnt(3)
	v_mfma_f32_16x16x32_bf16 v[82:85], v[178:181], v[146:149], v[2:5]
	v_add_f32_e32 v250, v114, v250
	s_add_u32 s98, s98, 0x8000
	s_addc_u32 s99, s99, 0
	s_add_u32 s100, s100, 0x8000
	s_addc_u32 s101, s101, 0
	v_mfma_f32_16x16x32_bf16 v[86:89], v[178:181], v[162:165], v[2:5]
	ds_read_b128 v[178:181], v235 offset:0
	v_add_f32_e32 v250, v115, v250
	v_add_f32_e32 v250, v116, v250
	s_waitcnt lgkmcnt(3)
	v_mfma_f32_16x16x32_bf16 v[90:93], v[182:185], v[146:149], v[2:5]
	v_add_f32_e32 v250, v117, v250
	s_add_u32 m0, s79, 49152
	s_nop 0
	global_load_lds_dwordx4 v246, s[98:99]
	v_mfma_f32_16x16x32_bf16 v[94:97], v[182:185], v[162:165], v[2:5]
	ds_read_b128 v[182:185], v235 offset:4096
	v_add_f32_e32 v250, v122, v250
	v_add_f32_e32 v250, v123, v250
	s_waitcnt lgkmcnt(3)
	v_mfma_f32_16x16x32_bf16 v[98:101], v[186:189], v[146:149], v[2:5]
	v_add_f32_e32 v250, v124, v250
	v_mfma_f32_16x16x32_bf16 v[102:105], v[186:189], v[162:165], v[2:5]
	ds_read_b128 v[186:189], v235 offset:8192
	v_add_f32_e32 v250, v125, v250
	v_cvt_pk_bf16_f32 v114, v114, v115
	s_waitcnt lgkmcnt(3)
; __device__ __forceinline__ void partialSM(f32x16& p0, f32x16& p1, float mC) {
;   (void)mC; (void)p1;
;   for (int r = 0; r < 16; ++r) p0[r] = __builtin_amdgcn_exp2f(p0[r]);
; }
; __device__ __forceinline__ void finishSM(f32x16& p0, f32x16& p1, float& l_reg, bf16x8& pa0, bf16x8& pa1, bf16x8& pa2, bf16x8& pa3) {
;   for (int r = 0; r < 16; ++r) p1[r] = __builtin_amdgcn_exp2f(p1[r]);
;   float ps = 0; for (int r = 0; r < 16; ++r) ps += p0[r]; for (int r = 0; r < 16; ++r) ps += p1[r];
;   { auto rr = __builtin_amdgcn_permlane32_swap(__float_as_uint(ps), __float_as_uint(ps), false, false);
;     ps = __uint_as_float(rr[0]) + __uint_as_float(rr[1]); }
;   l_reg += ps;
;     ...
;   PK4(p0, 0, pa0); PK4(p0, 8, pa1); PK4(p1, 0, pa2); PK4(p1, 8, pa3);
;     ...
; }
; __device__ __forceinline__ void qkt(f32x16& p0, f32x16& p1, const bf16* Ks, const bf16x8* qr, int r32, int hi, const f32x16& negm) {
; #pragma unroll
;   for (int d0 = 0; d0 < 8; ++d0) { int cb = (d0 * 16 + hi * 8) * 2;
;     bf16x8 b0 = *reinterpret_cast<const bf16x8*>((const char*)Ks + KSWZ(r32, cb));
;     bf16x8 b1 = *reinterpret_cast<const bf16x8*>((const char*)Ks + KSWZ(32 + r32, cb));
;     if (d0 == 0) { p0 = __builtin_amdgcn_mfma_f32_32x32x16_bf16(b0, qr[0], negm, 0, 0, 0); p1 = __builtin_amdgcn_mfma_f32_32x32x16_bf16(b1, qr[0], negm, 0, 0, 0); }
;     else { p0 = __builtin_amdgcn_mfma_f32_32x32x16_bf16(b0, qr[d0], p0, 0, 0, 0); p1 = __builtin_amdgcn_mfma_f32_32x32x16_bf16(b1, qr[d0], p1, 0, 0, 0); } }
; }
; __device__ __forceinline__ int v_st(int k, int c) { const int kk = (k & ~0xC) | ((k & 4) << 1) | ((k & 8) >> 1); return ((kk >> 3) * 4 + (c >> 5)) * 512 + ((kk & 7) * 32 + (c & 31)) * 2; }
; __device__ __forceinline__ int v_rd_base(int lane) { return ((lane & 3) << 3) | (((lane >> 2) & 3) << 6) | (((lane >> 4) & 1) << 5) | (((lane >> 5) & 1) << 8); }
; template <int OFF> __device__ __forceinline__ s16x4 tr_read(int vb) {
;   s16x4 r; asm volatile("ds_read_b64_tr_b16 %0, %1 offset:%2" : "=&v"(r) : "v"(vb), "i"(OFF) : "memory"); return r;
; }
; template <int D0> __device__ __forceinline__ void pv_one(f32x16& od, int vb, bf16x8 pa0, bf16x8 pa1, bf16x8 pa2, bf16x8 pa3) {
;   const s16x4 l0 = tr_read<v_rd_off(D0, 0, 0)>(vb), h0 = tr_read<v_rd_off(D0, 0, 1)>(vb), l1 = tr_read<v_rd_off(D0, 1, 0)>(vb), h1 = tr_read<v_rd_off(D0, 1, 1)>(vb);
	v_mfma_f32_16x16x32_bf16 v[106:109], v[190:193], v[146:149], v[2:5]
	v_cvt_pk_bf16_f32 v115, v116, v117
	s_add_u32 m0, s79, 50176
	s_nop 0
	global_load_lds_dwordx4 v247, s[98:99]
	v_mfma_f32_16x16x32_bf16 v[110:113], v[190:193], v[162:165], v[2:5]
	ds_read_b128 v[190:193], v235 offset:12288
	v_cvt_pk_bf16_f32 v116, v122, v123
	v_cvt_pk_bf16_f32 v117, v124, v125
	s_waitcnt lgkmcnt(3)
	v_mfma_f32_16x16x32_bf16 v[82:85], v[178:181], v[150:153], v[82:85]
	v_add_f32_e32 v251, v118, v251
	v_mfma_f32_16x16x32_bf16 v[86:89], v[178:181], v[166:169], v[86:89]
	ds_read_b128 v[178:181], v236 offset:0
	v_add_f32_e32 v251, v119, v251
	v_add_f32_e32 v251, v120, v251
	s_waitcnt lgkmcnt(3)
	v_mfma_f32_16x16x32_bf16 v[90:93], v[182:185], v[150:153], v[90:93]
	v_add_f32_e32 v251, v121, v251
	s_add_u32 m0, s80, 16384
	s_nop 0
	global_load_lds_dwordx4 v248, s[100:101]
	v_mfma_f32_16x16x32_bf16 v[94:97], v[182:185], v[166:169], v[94:97]
	ds_read_b128 v[182:185], v236 offset:4096
	v_add_f32_e32 v251, v126, v251
	v_add_f32_e32 v251, v127, v251
	s_waitcnt lgkmcnt(3)
	v_mfma_f32_16x16x32_bf16 v[98:101], v[186:189], v[150:153], v[98:101]
	v_add_f32_e32 v251, v128, v251
	v_mfma_f32_16x16x32_bf16 v[102:105], v[186:189], v[166:169], v[102:105]
	ds_read_b128 v[186:189], v236 offset:8192
	v_add_f32_e32 v251, v129, v251
	v_cvt_pk_bf16_f32 v118, v118, v119
	s_waitcnt lgkmcnt(3)
	v_mfma_f32_16x16x32_bf16 v[106:109], v[190:193], v[150:153], v[106:109]
	v_cvt_pk_bf16_f32 v119, v120, v121
	s_add_u32 m0, s80, 17408
	s_nop 0
	global_load_lds_dwordx4 v249, s[100:101]
	v_mfma_f32_16x16x32_bf16 v[110:113], v[190:193], v[166:169], v[110:113]
	ds_read_b128 v[190:193], v236 offset:12288
	v_cvt_pk_bf16_f32 v120, v126, v127
	v_cvt_pk_bf16_f32 v121, v128, v129
	s_waitcnt lgkmcnt(3)
	v_mfma_f32_16x16x32_bf16 v[82:85], v[178:181], v[154:157], v[82:85]
	v_add_f32_e32 v250, v130, v250
	v_mfma_f32_16x16x32_bf16 v[86:89], v[178:181], v[170:173], v[86:89]
	ds_read_b128 v[178:181], v237 offset:0
	v_add_f32_e32 v250, v131, v250
	v_add_f32_e32 v250, v132, v250
	s_waitcnt lgkmcnt(3)
	v_mfma_f32_16x16x32_bf16 v[90:93], v[182:185], v[154:157], v[90:93]
	v_add_f32_e32 v250, v133, v250
	v_mfma_f32_16x16x32_bf16 v[94:97], v[182:185], v[170:173], v[94:97]
	ds_read_b128 v[182:185], v237 offset:4096
	v_add_f32_e32 v250, v138, v250
	v_add_f32_e32 v250, v139, v250
	s_waitcnt lgkmcnt(3)
	v_mfma_f32_16x16x32_bf16 v[98:101], v[186:189], v[154:157], v[98:101]
	v_add_f32_e32 v250, v140, v250
	ds_read_b64_tr_b16 v[202:203], v238 offset:49152
	ds_read_b64_tr_b16 v[204:205], v238 offset:53248
	v_mfma_f32_16x16x32_bf16 v[102:105], v[186:189], v[170:173], v[102:105]
	ds_read_b128 v[186:189], v237 offset:8192
	v_add_f32_e32 v250, v141, v250
	v_cvt_pk_bf16_f32 v130, v130, v131
	s_waitcnt lgkmcnt(5)
	v_mfma_f32_16x16x32_bf16 v[106:109], v[190:193], v[154:157], v[106:109]
	v_cvt_pk_bf16_f32 v131, v132, v133
	ds_read_b64_tr_b16 v[206:207], v239 offset:49152
	ds_read_b64_tr_b16 v[208:209], v239 offset:53248
	v_mfma_f32_16x16x32_bf16 v[110:113], v[190:193], v[170:173], v[110:113]
	ds_read_b128 v[190:193], v237 offset:12288
	v_cvt_pk_bf16_f32 v132, v138, v139
	v_cvt_pk_bf16_f32 v133, v140, v141
	s_waitcnt lgkmcnt(7)
	v_mfma_f32_16x16x32_bf16 v[82:85], v[178:181], v[158:161], v[82:85]
	v_add_f32_e32 v251, v134, v251
	ds_read_b64_tr_b16 v[210:211], v240 offset:49152
	ds_read_b64_tr_b16 v[212:213], v240 offset:53248
	v_mfma_f32_16x16x32_bf16 v[86:89], v[178:181], v[174:177], v[86:89]
	v_add_f32_e32 v251, v135, v251
	v_add_f32_e32 v251, v136, v251
	s_waitcnt lgkmcnt(8)
	v_mfma_f32_16x16x32_bf16 v[90:93], v[182:185], v[158:161], v[90:93]
	v_add_f32_e32 v251, v137, v251
	ds_read_b64_tr_b16 v[214:215], v241 offset:49152
	ds_read_b64_tr_b16 v[216:217], v241 offset:53248
	v_mfma_f32_16x16x32_bf16 v[94:97], v[182:185], v[174:177], v[94:97]
	v_add_f32_e32 v251, v142, v251
	v_add_f32_e32 v251, v143, v251
	s_waitcnt lgkmcnt(7)
	v_mfma_f32_16x16x32_bf16 v[98:101], v[186:189], v[158:161], v[98:101]
	v_add_f32_e32 v251, v144, v251
	ds_read_b64_tr_b16 v[218:219], v242 offset:49152
	ds_read_b64_tr_b16 v[220:221], v242 offset:53248
	v_mfma_f32_16x16x32_bf16 v[102:105], v[186:189], v[174:177], v[102:105]
	v_add_f32_e32 v251, v145, v251
	v_cvt_pk_bf16_f32 v134, v134, v135
	s_waitcnt lgkmcnt(6)
	v_mfma_f32_16x16x32_bf16 v[106:109], v[190:193], v[158:161], v[106:109]
	v_cvt_pk_bf16_f32 v135, v136, v137
	ds_read_b64_tr_b16 v[222:223], v243 offset:49152
	ds_read_b64_tr_b16 v[224:225], v243 offset:53248
	v_mfma_f32_16x16x32_bf16 v[110:113], v[190:193], v[174:177], v[110:113]
	v_cvt_pk_bf16_f32 v136, v142, v143
	v_cvt_pk_bf16_f32 v137, v144, v145
	s_waitcnt vmcnt(4)
	s_barrier
; __device__ __forceinline__ void partialSM(f32x16& p0, f32x16& p1, float mC) {
;   (void)mC; (void)p1;
;   for (int r = 0; r < 16; ++r) p0[r] = __builtin_amdgcn_exp2f(p0[r]);
; }
; __device__ __forceinline__ void finishSM(f32x16& p0, f32x16& p1, float& l_reg, bf16x8& pa0, bf16x8& pa1, bf16x8& pa2, bf16x8& pa3) {
;   for (int r = 0; r < 16; ++r) p1[r] = __builtin_amdgcn_exp2f(p1[r]);
;   float ps = 0; for (int r = 0; r < 16; ++r) ps += p0[r]; for (int r = 0; r < 16; ++r) ps += p1[r];
;   { auto rr = __builtin_amdgcn_permlane32_swap(__float_as_uint(ps), __float_as_uint(ps), false, false);
;     ps = __uint_as_float(rr[0]) + __uint_as_float(rr[1]); }
;   l_reg += ps;
;     ...
;   PK4(p0, 0, pa0); PK4(p0, 8, pa1); PK4(p1, 0, pa2); PK4(p1, 8, pa3);
;     ...
; }
; __device__ __forceinline__ void qkt(f32x16& p0, f32x16& p1, const bf16* Ks, const bf16x8* qr, int r32, int hi, const f32x16& negm) {
; #pragma unroll
;   for (int d0 = 0; d0 < 8; ++d0) { int cb = (d0 * 16 + hi * 8) * 2;
;     bf16x8 b0 = *reinterpret_cast<const bf16x8*>((const char*)Ks + KSWZ(r32, cb));
;     bf16x8 b1 = *reinterpret_cast<const bf16x8*>((const char*)Ks + KSWZ(32 + r32, cb));
;     if (d0 == 0) { p0 = __builtin_amdgcn_mfma_f32_32x32x16_bf16(b0, qr[0], negm, 0, 0, 0); p1 = __builtin_amdgcn_mfma_f32_32x32x16_bf16(b1, qr[0], negm, 0, 0, 0); }
;     else { p0 = __builtin_amdgcn_mfma_f32_32x32x16_bf16(b0, qr[d0], p0, 0, 0, 0); p1 = __builtin_amdgcn_mfma_f32_32x32x16_bf16(b1, qr[d0], p1, 0, 0, 0); } }
; }
; __device__ __forceinline__ int v_st(int k, int c) { const int kk = (k & ~0xC) | ((k & 4) << 1) | ((k & 8) >> 1); return ((kk >> 3) * 4 + (c >> 5)) * 512 + ((kk & 7) * 32 + (c & 31)) * 2; }
; __device__ __forceinline__ int v_rd_base(int lane) { return ((lane & 3) << 3) | (((lane >> 2) & 3) << 6) | (((lane >> 4) & 1) << 5) | (((lane >> 5) & 1) << 8); }
; template <int OFF> __device__ __forceinline__ s16x4 tr_read(int vb) {
;   s16x4 r; asm volatile("ds_read_b64_tr_b16 %0, %1 offset:%2" : "=&v"(r) : "v"(vb), "i"(OFF) : "memory"); return r;
; }
; template <int D0> __device__ __forceinline__ void pv_one(f32x16& od, int vb, bf16x8 pa0, bf16x8 pa1, bf16x8 pa2, bf16x8 pa3) {
;   const s16x4 l0 = tr_read<v_rd_off(D0, 0, 0)>(vb), h0 = tr_read<v_rd_off(D0, 0, 1)>(vb), l1 = tr_read<v_rd_off(D0, 1, 0)>(vb), h1 = tr_read<v_rd_off(D0, 1, 1)>(vb);
	v_mfma_f32_16x16x32_bf16 v[18:21], v[202:205], v[114:117], v[18:21]
	v_exp_f32_e32 v82, v82
	v_mfma_f32_16x16x32_bf16 v[22:25], v[202:205], v[118:121], v[22:25]
	ds_read_b64_tr_b16 v[202:203], v244 offset:49152
	ds_read_b64_tr_b16 v[204:205], v244 offset:53248
	v_exp_f32_e32 v83, v83
	v_mfma_f32_16x16x32_bf16 v[26:29], v[206:209], v[114:117], v[26:29]
	v_exp_f32_e32 v84, v84
	v_mfma_f32_16x16x32_bf16 v[30:33], v[206:209], v[118:121], v[30:33]
	ds_read_b64_tr_b16 v[206:207], v245 offset:49152
	ds_read_b64_tr_b16 v[208:209], v245 offset:53248
	v_exp_f32_e32 v85, v85
	s_waitcnt lgkmcnt(10)
	v_mfma_f32_16x16x32_bf16 v[34:37], v[210:213], v[114:117], v[34:37]
	v_exp_f32_e32 v86, v86
	v_mfma_f32_16x16x32_bf16 v[38:41], v[210:213], v[118:121], v[38:41]
	ds_read_b64_tr_b16 v[210:211], v238 offset:57344
	ds_read_b64_tr_b16 v[212:213], v238 offset:61440
	v_exp_f32_e32 v87, v87
	s_waitcnt lgkmcnt(10)
	v_mfma_f32_16x16x32_bf16 v[42:45], v[214:217], v[114:117], v[42:45]
	v_exp_f32_e32 v88, v88
	v_mfma_f32_16x16x32_bf16 v[46:49], v[214:217], v[118:121], v[46:49]
	ds_read_b64_tr_b16 v[214:215], v239 offset:57344
	ds_read_b64_tr_b16 v[216:217], v239 offset:61440
	v_exp_f32_e32 v89, v89
	s_waitcnt lgkmcnt(10)
	v_mfma_f32_16x16x32_bf16 v[50:53], v[218:221], v[114:117], v[50:53]
	v_exp_f32_e32 v90, v90
	v_mfma_f32_16x16x32_bf16 v[54:57], v[218:221], v[118:121], v[54:57]
	ds_read_b64_tr_b16 v[218:219], v240 offset:57344
	ds_read_b64_tr_b16 v[220:221], v240 offset:61440
	v_exp_f32_e32 v91, v91
	s_waitcnt lgkmcnt(10)
	v_mfma_f32_16x16x32_bf16 v[58:61], v[222:225], v[114:117], v[58:61]
	v_exp_f32_e32 v92, v92
	v_mfma_f32_16x16x32_bf16 v[62:65], v[222:225], v[118:121], v[62:65]
	ds_read_b64_tr_b16 v[222:223], v241 offset:57344
	ds_read_b64_tr_b16 v[224:225], v241 offset:61440
	v_exp_f32_e32 v93, v93
	s_waitcnt lgkmcnt(10)
	v_mfma_f32_16x16x32_bf16 v[66:69], v[202:205], v[114:117], v[66:69]
	v_exp_f32_e32 v94, v94
	v_mfma_f32_16x16x32_bf16 v[70:73], v[202:205], v[118:121], v[70:73]
	ds_read_b64_tr_b16 v[202:203], v242 offset:57344
	ds_read_b64_tr_b16 v[204:205], v242 offset:61440
	v_exp_f32_e32 v95, v95
	s_waitcnt lgkmcnt(10)
	v_mfma_f32_16x16x32_bf16 v[74:77], v[206:209], v[114:117], v[74:77]
	v_exp_f32_e32 v96, v96
	v_mfma_f32_16x16x32_bf16 v[78:81], v[206:209], v[118:121], v[78:81]
	ds_read_b64_tr_b16 v[206:207], v243 offset:57344
	ds_read_b64_tr_b16 v[208:209], v243 offset:61440
	v_exp_f32_e32 v97, v97
	s_waitcnt lgkmcnt(10)
	v_mfma_f32_16x16x32_bf16 v[18:21], v[210:213], v[130:133], v[18:21]
	v_exp_f32_e32 v98, v98
	v_mfma_f32_16x16x32_bf16 v[22:25], v[210:213], v[134:137], v[22:25]
	ds_read_b64_tr_b16 v[210:211], v244 offset:57344
	ds_read_b64_tr_b16 v[212:213], v244 offset:61440
	v_exp_f32_e32 v99, v99
	s_waitcnt lgkmcnt(10)
	v_mfma_f32_16x16x32_bf16 v[26:29], v[214:217], v[130:133], v[26:29]
	v_exp_f32_e32 v100, v100
	v_mfma_f32_16x16x32_bf16 v[30:33], v[214:217], v[134:137], v[30:33]
	ds_read_b64_tr_b16 v[214:215], v245 offset:57344
	ds_read_b64_tr_b16 v[216:217], v245 offset:61440
	v_exp_f32_e32 v101, v101
	s_waitcnt lgkmcnt(10)
	v_mfma_f32_16x16x32_bf16 v[34:37], v[218:221], v[130:133], v[34:37]
	v_exp_f32_e32 v102, v102
	v_mfma_f32_16x16x32_bf16 v[38:41], v[218:221], v[134:137], v[38:41]
	v_exp_f32_e32 v103, v103
	s_waitcnt lgkmcnt(8)
	v_mfma_f32_16x16x32_bf16 v[42:45], v[222:225], v[130:133], v[42:45]
	v_exp_f32_e32 v104, v104
	v_mfma_f32_16x16x32_bf16 v[46:49], v[222:225], v[134:137], v[46:49]
	v_exp_f32_e32 v105, v105
	s_waitcnt lgkmcnt(6)
	v_mfma_f32_16x16x32_bf16 v[50:53], v[202:205], v[130:133], v[50:53]
	v_exp_f32_e32 v106, v106
	ds_read_b128 v[178:181], v234 offset:16384
	v_mfma_f32_16x16x32_bf16 v[54:57], v[202:205], v[134:137], v[54:57]
	v_exp_f32_e32 v107, v107
	s_waitcnt lgkmcnt(5)
	v_mfma_f32_16x16x32_bf16 v[58:61], v[206:209], v[130:133], v[58:61]
	v_exp_f32_e32 v108, v108
	ds_read_b128 v[182:185], v234 offset:20480
	v_mfma_f32_16x16x32_bf16 v[62:65], v[206:209], v[134:137], v[62:65]
	v_exp_f32_e32 v109, v109
	s_waitcnt lgkmcnt(4)
	v_mfma_f32_16x16x32_bf16 v[66:69], v[210:213], v[130:133], v[66:69]
	v_exp_f32_e32 v110, v110
	ds_read_b128 v[186:189], v234 offset:24576
	v_mfma_f32_16x16x32_bf16 v[70:73], v[210:213], v[134:137], v[70:73]
	v_exp_f32_e32 v111, v111
	s_waitcnt lgkmcnt(3)
	v_mfma_f32_16x16x32_bf16 v[74:77], v[214:217], v[130:133], v[74:77]
	v_exp_f32_e32 v112, v112
	ds_read_b128 v[190:193], v234 offset:28672
	v_mfma_f32_16x16x32_bf16 v[78:81], v[214:217], v[134:137], v[78:81]
	v_exp_f32_e32 v113, v113
	s_waitcnt lgkmcnt(3)
	v_mfma_f32_16x16x32_bf16 v[114:117], v[178:181], v[146:149], v[2:5]
	v_add_f32_e32 v250, v82, v250
	s_add_u32 s98, s98, 0x8000
	s_addc_u32 s99, s99, 0
	s_add_u32 s100, s100, 0x8000
	s_addc_u32 s101, s101, 0
	v_mfma_f32_16x16x32_bf16 v[118:121], v[178:181], v[162:165], v[2:5]
	ds_read_b128 v[178:181], v235 offset:16384
	v_add_f32_e32 v250, v83, v250
	v_add_f32_e32 v250, v84, v250
	s_waitcnt lgkmcnt(3)
	v_mfma_f32_16x16x32_bf16 v[122:125], v[182:185], v[146:149], v[2:5]
	v_add_f32_e32 v250, v85, v250
	s_add_u32 m0, s80, 32768
	s_nop 0
	global_load_lds_dwordx4 v248, s[100:101]
	v_mfma_f32_16x16x32_bf16 v[126:129], v[182:185], v[162:165], v[2:5]
	ds_read_b128 v[182:185], v235 offset:20480
	v_add_f32_e32 v250, v90, v250
	v_add_f32_e32 v250, v91, v250
	s_waitcnt lgkmcnt(3)
	v_mfma_f32_16x16x32_bf16 v[130:133], v[186:189], v[146:149], v[2:5]
	v_add_f32_e32 v250, v92, v250
	v_mfma_f32_16x16x32_bf16 v[134:137], v[186:189], v[162:165], v[2:5]
	ds_read_b128 v[186:189], v235 offset:24576
	v_add_f32_e32 v250, v93, v250
	v_cvt_pk_bf16_f32 v82, v82, v83
	s_waitcnt lgkmcnt(3)
; __device__ __forceinline__ void partialSM(f32x16& p0, f32x16& p1, float mC) {
;   (void)mC; (void)p1;
;   for (int r = 0; r < 16; ++r) p0[r] = __builtin_amdgcn_exp2f(p0[r]);
; }
; __device__ __forceinline__ void finishSM(f32x16& p0, f32x16& p1, float& l_reg, bf16x8& pa0, bf16x8& pa1, bf16x8& pa2, bf16x8& pa3) {
;   for (int r = 0; r < 16; ++r) p1[r] = __builtin_amdgcn_exp2f(p1[r]);
;   float ps = 0; for (int r = 0; r < 16; ++r) ps += p0[r]; for (int r = 0; r < 16; ++r) ps += p1[r];
;   { auto rr = __builtin_amdgcn_permlane32_swap(__float_as_uint(ps), __float_as_uint(ps), false, false);
;     ps = __uint_as_float(rr[0]) + __uint_as_float(rr[1]); }
;   l_reg += ps;
;     ...
;   PK4(p0, 0, pa0); PK4(p0, 8, pa1); PK4(p1, 0, pa2); PK4(p1, 8, pa3);
;     ...
; }
; __device__ __forceinline__ void qkt(f32x16& p0, f32x16& p1, const bf16* Ks, const bf16x8* qr, int r32, int hi, const f32x16& negm) {
; #pragma unroll
;   for (int d0 = 0; d0 < 8; ++d0) { int cb = (d0 * 16 + hi * 8) * 2;
;     bf16x8 b0 = *reinterpret_cast<const bf16x8*>((const char*)Ks + KSWZ(r32, cb));
;     bf16x8 b1 = *reinterpret_cast<const bf16x8*>((const char*)Ks + KSWZ(32 + r32, cb));
;     if (d0 == 0) { p0 = __builtin_amdgcn_mfma_f32_32x32x16_bf16(b0, qr[0], negm, 0, 0, 0); p1 = __builtin_amdgcn_mfma_f32_32x32x16_bf16(b1, qr[0], negm, 0, 0, 0); }
;     else { p0 = __builtin_amdgcn_mfma_f32_32x32x16_bf16(b0, qr[d0], p0, 0, 0, 0); p1 = __builtin_amdgcn_mfma_f32_32x32x16_bf16(b1, qr[d0], p1, 0, 0, 0); } }
; }
; __device__ __forceinline__ int v_st(int k, int c) { const int kk = (k & ~0xC) | ((k & 4) << 1) | ((k & 8) >> 1); return ((kk >> 3) * 4 + (c >> 5)) * 512 + ((kk & 7) * 32 + (c & 31)) * 2; }
; __device__ __forceinline__ int v_rd_base(int lane) { return ((lane & 3) << 3) | (((lane >> 2) & 3) << 6) | (((lane >> 4) & 1) << 5) | (((lane >> 5) & 1) << 8); }
; template <int OFF> __device__ __forceinline__ s16x4 tr_read(int vb) {
;   s16x4 r; asm volatile("ds_read_b64_tr_b16 %0, %1 offset:%2" : "=&v"(r) : "v"(vb), "i"(OFF) : "memory"); return r;
; }
; template <int D0> __device__ __forceinline__ void pv_one(f32x16& od, int vb, bf16x8 pa0, bf16x8 pa1, bf16x8 pa2, bf16x8 pa3) {
;   const s16x4 l0 = tr_read<v_rd_off(D0, 0, 0)>(vb), h0 = tr_read<v_rd_off(D0, 0, 1)>(vb), l1 = tr_read<v_rd_off(D0, 1, 0)>(vb), h1 = tr_read<v_rd_off(D0, 1, 1)>(vb);
	v_mfma_f32_16x16x32_bf16 v[138:141], v[190:193], v[146:149], v[2:5]
	v_cvt_pk_bf16_f32 v83, v84, v85
	s_add_u32 m0, s80, 33792
	s_nop 0
	global_load_lds_dwordx4 v249, s[100:101]
	v_mfma_f32_16x16x32_bf16 v[142:145], v[190:193], v[162:165], v[2:5]
	ds_read_b128 v[190:193], v235 offset:28672
	v_cvt_pk_bf16_f32 v84, v90, v91
	v_cvt_pk_bf16_f32 v85, v92, v93
	s_waitcnt lgkmcnt(3)
	v_mfma_f32_16x16x32_bf16 v[114:117], v[178:181], v[150:153], v[114:117]
	v_add_f32_e32 v251, v86, v251
	v_mfma_f32_16x16x32_bf16 v[118:121], v[178:181], v[166:169], v[118:121]
	ds_read_b128 v[178:181], v236 offset:16384
	v_add_f32_e32 v251, v87, v251
	v_add_f32_e32 v251, v88, v251
	s_waitcnt lgkmcnt(3)
	v_mfma_f32_16x16x32_bf16 v[122:125], v[182:185], v[150:153], v[122:125]
	v_add_f32_e32 v251, v89, v251
	v_mfma_f32_16x16x32_bf16 v[126:129], v[182:185], v[166:169], v[126:129]
	ds_read_b128 v[182:185], v236 offset:20480
	v_add_f32_e32 v251, v94, v251
	v_add_f32_e32 v251, v95, v251
	s_waitcnt lgkmcnt(3)
	v_mfma_f32_16x16x32_bf16 v[130:133], v[186:189], v[150:153], v[130:133]
	v_add_f32_e32 v251, v96, v251
	v_mfma_f32_16x16x32_bf16 v[134:137], v[186:189], v[166:169], v[134:137]
	ds_read_b128 v[186:189], v236 offset:24576
	v_add_f32_e32 v251, v97, v251
	v_cvt_pk_bf16_f32 v86, v86, v87
	s_waitcnt lgkmcnt(3)
	v_mfma_f32_16x16x32_bf16 v[138:141], v[190:193], v[150:153], v[138:141]
	v_cvt_pk_bf16_f32 v87, v88, v89
	v_mfma_f32_16x16x32_bf16 v[142:145], v[190:193], v[166:169], v[142:145]
	ds_read_b128 v[190:193], v236 offset:28672
	v_cvt_pk_bf16_f32 v88, v94, v95
	v_cvt_pk_bf16_f32 v89, v96, v97
	s_waitcnt lgkmcnt(3)
	v_mfma_f32_16x16x32_bf16 v[114:117], v[178:181], v[154:157], v[114:117]
	v_add_f32_e32 v250, v98, v250
	v_mfma_f32_16x16x32_bf16 v[118:121], v[178:181], v[170:173], v[118:121]
	ds_read_b128 v[178:181], v237 offset:16384
	v_add_f32_e32 v250, v99, v250
	v_add_f32_e32 v250, v100, v250
	s_waitcnt lgkmcnt(3)
	v_mfma_f32_16x16x32_bf16 v[122:125], v[182:185], v[154:157], v[122:125]
	v_add_f32_e32 v250, v101, v250
	v_mfma_f32_16x16x32_bf16 v[126:129], v[182:185], v[170:173], v[126:129]
	ds_read_b128 v[182:185], v237 offset:20480
	v_add_f32_e32 v250, v106, v250
	v_add_f32_e32 v250, v107, v250
	s_waitcnt lgkmcnt(3)
	v_mfma_f32_16x16x32_bf16 v[130:133], v[186:189], v[154:157], v[130:133]
	v_add_f32_e32 v250, v108, v250
	ds_read_b64_tr_b16 v[202:203], v238 offset:0
	ds_read_b64_tr_b16 v[204:205], v238 offset:4096
	v_mfma_f32_16x16x32_bf16 v[134:137], v[186:189], v[170:173], v[134:137]
	ds_read_b128 v[186:189], v237 offset:24576
	v_add_f32_e32 v250, v109, v250
	v_cvt_pk_bf16_f32 v98, v98, v99
	s_waitcnt lgkmcnt(5)
	v_mfma_f32_16x16x32_bf16 v[138:141], v[190:193], v[154:157], v[138:141]
	v_cvt_pk_bf16_f32 v99, v100, v101
	ds_read_b64_tr_b16 v[206:207], v239 offset:0
	ds_read_b64_tr_b16 v[208:209], v239 offset:4096
	v_mfma_f32_16x16x32_bf16 v[142:145], v[190:193], v[170:173], v[142:145]
	ds_read_b128 v[190:193], v237 offset:28672
	v_cvt_pk_bf16_f32 v100, v106, v107
	v_cvt_pk_bf16_f32 v101, v108, v109
	s_waitcnt lgkmcnt(7)
	v_mfma_f32_16x16x32_bf16 v[114:117], v[178:181], v[158:161], v[114:117]
	v_add_f32_e32 v251, v102, v251
	ds_read_b64_tr_b16 v[210:211], v240 offset:0
	ds_read_b64_tr_b16 v[212:213], v240 offset:4096
	v_mfma_f32_16x16x32_bf16 v[118:121], v[178:181], v[174:177], v[118:121]
	v_add_f32_e32 v251, v103, v251
	v_add_f32_e32 v251, v104, v251
	s_waitcnt lgkmcnt(8)
	v_mfma_f32_16x16x32_bf16 v[122:125], v[182:185], v[158:161], v[122:125]
	v_add_f32_e32 v251, v105, v251
	ds_read_b64_tr_b16 v[214:215], v241 offset:0
	ds_read_b64_tr_b16 v[216:217], v241 offset:4096
	v_mfma_f32_16x16x32_bf16 v[126:129], v[182:185], v[174:177], v[126:129]
	v_add_f32_e32 v251, v110, v251
	v_add_f32_e32 v251, v111, v251
	s_waitcnt lgkmcnt(7)
	v_mfma_f32_16x16x32_bf16 v[130:133], v[186:189], v[158:161], v[130:133]
	v_add_f32_e32 v251, v112, v251
	ds_read_b64_tr_b16 v[218:219], v242 offset:0
	ds_read_b64_tr_b16 v[220:221], v242 offset:4096
	v_mfma_f32_16x16x32_bf16 v[134:137], v[186:189], v[174:177], v[134:137]
	v_add_f32_e32 v251, v113, v251
	v_cvt_pk_bf16_f32 v102, v102, v103
	s_waitcnt lgkmcnt(6)
	v_mfma_f32_16x16x32_bf16 v[138:141], v[190:193], v[158:161], v[138:141]
	v_cvt_pk_bf16_f32 v103, v104, v105
	ds_read_b64_tr_b16 v[222:223], v243 offset:0
	ds_read_b64_tr_b16 v[224:225], v243 offset:4096
	v_mfma_f32_16x16x32_bf16 v[142:145], v[190:193], v[174:177], v[142:145]
	v_cvt_pk_bf16_f32 v104, v110, v111
	v_cvt_pk_bf16_f32 v105, v112, v113
	s_waitcnt vmcnt(2)
	s_barrier
; __device__ __forceinline__ void partialSM(f32x16& p0, f32x16& p1, float mC) {
;   (void)mC; (void)p1;
;   for (int r = 0; r < 16; ++r) p0[r] = __builtin_amdgcn_exp2f(p0[r]);
; }
; __device__ __forceinline__ void finishSM(f32x16& p0, f32x16& p1, float& l_reg, bf16x8& pa0, bf16x8& pa1, bf16x8& pa2, bf16x8& pa3) {
;   for (int r = 0; r < 16; ++r) p1[r] = __builtin_amdgcn_exp2f(p1[r]);
;   float ps = 0; for (int r = 0; r < 16; ++r) ps += p0[r]; for (int r = 0; r < 16; ++r) ps += p1[r];
;   { auto rr = __builtin_amdgcn_permlane32_swap(__float_as_uint(ps), __float_as_uint(ps), false, false);
;     ps = __uint_as_float(rr[0]) + __uint_as_float(rr[1]); }
;   l_reg += ps;
;     ...
;   PK4(p0, 0, pa0); PK4(p0, 8, pa1); PK4(p1, 0, pa2); PK4(p1, 8, pa3);
;     ...
; }
; __device__ __forceinline__ void qkt(f32x16& p0, f32x16& p1, const bf16* Ks, const bf16x8* qr, int r32, int hi, const f32x16& negm) {
; #pragma unroll
;   for (int d0 = 0; d0 < 8; ++d0) { int cb = (d0 * 16 + hi * 8) * 2;
;     bf16x8 b0 = *reinterpret_cast<const bf16x8*>((const char*)Ks + KSWZ(r32, cb));
;     bf16x8 b1 = *reinterpret_cast<const bf16x8*>((const char*)Ks + KSWZ(32 + r32, cb));
;     if (d0 == 0) { p0 = __builtin_amdgcn_mfma_f32_32x32x16_bf16(b0, qr[0], negm, 0, 0, 0); p1 = __builtin_amdgcn_mfma_f32_32x32x16_bf16(b1, qr[0], negm, 0, 0, 0); }
;     else { p0 = __builtin_amdgcn_mfma_f32_32x32x16_bf16(b0, qr[d0], p0, 0, 0, 0); p1 = __builtin_amdgcn_mfma_f32_32x32x16_bf16(b1, qr[d0], p1, 0, 0, 0); } }
; }
; __device__ __forceinline__ int v_st(int k, int c) { const int kk = (k & ~0xC) | ((k & 4) << 1) | ((k & 8) >> 1); return ((kk >> 3) * 4 + (c >> 5)) * 512 + ((kk & 7) * 32 + (c & 31)) * 2; }
; __device__ __forceinline__ int v_rd_base(int lane) { return ((lane & 3) << 3) | (((lane >> 2) & 3) << 6) | (((lane >> 4) & 1) << 5) | (((lane >> 5) & 1) << 8); }
; template <int OFF> __device__ __forceinline__ s16x4 tr_read(int vb) {
;   s16x4 r; asm volatile("ds_read_b64_tr_b16 %0, %1 offset:%2" : "=&v"(r) : "v"(vb), "i"(OFF) : "memory"); return r;
; }
; template <int D0> __device__ __forceinline__ void pv_one(f32x16& od, int vb, bf16x8 pa0, bf16x8 pa1, bf16x8 pa2, bf16x8 pa3) {
;   const s16x4 l0 = tr_read<v_rd_off(D0, 0, 0)>(vb), h0 = tr_read<v_rd_off(D0, 0, 1)>(vb), l1 = tr_read<v_rd_off(D0, 1, 0)>(vb), h1 = tr_read<v_rd_off(D0, 1, 1)>(vb);
	v_mfma_f32_16x16x32_bf16 v[18:21], v[202:205], v[82:85], v[18:21]
	v_exp_f32_e32 v114, v114
	v_mfma_f32_16x16x32_bf16 v[22:25], v[202:205], v[86:89], v[22:25]
	ds_read_b64_tr_b16 v[202:203], v244 offset:0
	ds_read_b64_tr_b16 v[204:205], v244 offset:4096
	v_exp_f32_e32 v115, v115
	v_mfma_f32_16x16x32_bf16 v[26:29], v[206:209], v[82:85], v[26:29]
	v_exp_f32_e32 v116, v116
	v_mfma_f32_16x16x32_bf16 v[30:33], v[206:209], v[86:89], v[30:33]
	ds_read_b64_tr_b16 v[206:207], v245 offset:0
	ds_read_b64_tr_b16 v[208:209], v245 offset:4096
	v_exp_f32_e32 v117, v117
	s_waitcnt lgkmcnt(10)
	v_mfma_f32_16x16x32_bf16 v[34:37], v[210:213], v[82:85], v[34:37]
	v_exp_f32_e32 v118, v118
	v_mfma_f32_16x16x32_bf16 v[38:41], v[210:213], v[86:89], v[38:41]
	ds_read_b64_tr_b16 v[210:211], v238 offset:8192
	ds_read_b64_tr_b16 v[212:213], v238 offset:12288
	v_exp_f32_e32 v119, v119
	s_waitcnt lgkmcnt(10)
	v_mfma_f32_16x16x32_bf16 v[42:45], v[214:217], v[82:85], v[42:45]
	v_exp_f32_e32 v120, v120
	v_mfma_f32_16x16x32_bf16 v[46:49], v[214:217], v[86:89], v[46:49]
	ds_read_b64_tr_b16 v[214:215], v239 offset:8192
	ds_read_b64_tr_b16 v[216:217], v239 offset:12288
	v_exp_f32_e32 v121, v121
	s_waitcnt lgkmcnt(10)
	v_mfma_f32_16x16x32_bf16 v[50:53], v[218:221], v[82:85], v[50:53]
	v_exp_f32_e32 v122, v122
	v_mfma_f32_16x16x32_bf16 v[54:57], v[218:221], v[86:89], v[54:57]
	ds_read_b64_tr_b16 v[218:219], v240 offset:8192
	ds_read_b64_tr_b16 v[220:221], v240 offset:12288
	v_exp_f32_e32 v123, v123
	s_waitcnt lgkmcnt(10)
	v_mfma_f32_16x16x32_bf16 v[58:61], v[222:225], v[82:85], v[58:61]
	v_exp_f32_e32 v124, v124
	v_mfma_f32_16x16x32_bf16 v[62:65], v[222:225], v[86:89], v[62:65]
	ds_read_b64_tr_b16 v[222:223], v241 offset:8192
	ds_read_b64_tr_b16 v[224:225], v241 offset:12288
	v_exp_f32_e32 v125, v125
	s_waitcnt lgkmcnt(10)
	v_mfma_f32_16x16x32_bf16 v[66:69], v[202:205], v[82:85], v[66:69]
	v_exp_f32_e32 v126, v126
	v_mfma_f32_16x16x32_bf16 v[70:73], v[202:205], v[86:89], v[70:73]
	ds_read_b64_tr_b16 v[202:203], v242 offset:8192
	ds_read_b64_tr_b16 v[204:205], v242 offset:12288
	v_exp_f32_e32 v127, v127
	s_waitcnt lgkmcnt(10)
	v_mfma_f32_16x16x32_bf16 v[74:77], v[206:209], v[82:85], v[74:77]
	v_exp_f32_e32 v128, v128
	v_mfma_f32_16x16x32_bf16 v[78:81], v[206:209], v[86:89], v[78:81]
	ds_read_b64_tr_b16 v[206:207], v243 offset:8192
	ds_read_b64_tr_b16 v[208:209], v243 offset:12288
	v_exp_f32_e32 v129, v129
	s_waitcnt lgkmcnt(10)
	v_mfma_f32_16x16x32_bf16 v[18:21], v[210:213], v[98:101], v[18:21]
	v_exp_f32_e32 v130, v130
	v_mfma_f32_16x16x32_bf16 v[22:25], v[210:213], v[102:105], v[22:25]
	ds_read_b64_tr_b16 v[210:211], v244 offset:8192
	ds_read_b64_tr_b16 v[212:213], v244 offset:12288
	v_exp_f32_e32 v131, v131
	s_waitcnt lgkmcnt(10)
	v_mfma_f32_16x16x32_bf16 v[26:29], v[214:217], v[98:101], v[26:29]
	v_exp_f32_e32 v132, v132
	v_mfma_f32_16x16x32_bf16 v[30:33], v[214:217], v[102:105], v[30:33]
	ds_read_b64_tr_b16 v[214:215], v245 offset:8192
	ds_read_b64_tr_b16 v[216:217], v245 offset:12288
	v_exp_f32_e32 v133, v133
	s_waitcnt lgkmcnt(10)
	v_mfma_f32_16x16x32_bf16 v[34:37], v[218:221], v[98:101], v[34:37]
	v_exp_f32_e32 v134, v134
	v_mfma_f32_16x16x32_bf16 v[38:41], v[218:221], v[102:105], v[38:41]
	v_exp_f32_e32 v135, v135
	s_waitcnt lgkmcnt(8)
	v_mfma_f32_16x16x32_bf16 v[42:45], v[222:225], v[98:101], v[42:45]
	v_exp_f32_e32 v136, v136
	v_mfma_f32_16x16x32_bf16 v[46:49], v[222:225], v[102:105], v[46:49]
	v_exp_f32_e32 v137, v137
	s_waitcnt lgkmcnt(6)
	v_mfma_f32_16x16x32_bf16 v[50:53], v[202:205], v[98:101], v[50:53]
	v_exp_f32_e32 v138, v138
	ds_read_b128 v[178:181], v234 offset:32768
	v_mfma_f32_16x16x32_bf16 v[54:57], v[202:205], v[102:105], v[54:57]
	v_exp_f32_e32 v139, v139
	s_waitcnt lgkmcnt(5)
	v_mfma_f32_16x16x32_bf16 v[58:61], v[206:209], v[98:101], v[58:61]
	v_exp_f32_e32 v140, v140
	ds_read_b128 v[182:185], v234 offset:36864
	v_mfma_f32_16x16x32_bf16 v[62:65], v[206:209], v[102:105], v[62:65]
	v_exp_f32_e32 v141, v141
	s_waitcnt lgkmcnt(4)
	v_mfma_f32_16x16x32_bf16 v[66:69], v[210:213], v[98:101], v[66:69]
	v_exp_f32_e32 v142, v142
	ds_read_b128 v[186:189], v234 offset:40960
	v_mfma_f32_16x16x32_bf16 v[70:73], v[210:213], v[102:105], v[70:73]
	v_exp_f32_e32 v143, v143
	s_waitcnt lgkmcnt(3)
	v_mfma_f32_16x16x32_bf16 v[74:77], v[214:217], v[98:101], v[74:77]
	v_exp_f32_e32 v144, v144
	ds_read_b128 v[190:193], v234 offset:45056
	v_mfma_f32_16x16x32_bf16 v[78:81], v[214:217], v[102:105], v[78:81]
	v_exp_f32_e32 v145, v145
	s_waitcnt lgkmcnt(3)
	v_mfma_f32_16x16x32_bf16 v[82:85], v[178:181], v[146:149], v[2:5]
	v_add_f32_e32 v250, v114, v250
	s_add_u32 s98, s98, 0x8000
	s_addc_u32 s99, s99, 0
	s_add_u32 s100, s100, 0x8000
	s_addc_u32 s101, s101, 0
	v_mfma_f32_16x16x32_bf16 v[86:89], v[178:181], v[162:165], v[2:5]
	ds_read_b128 v[178:181], v235 offset:32768
	v_add_f32_e32 v250, v115, v250
	v_add_f32_e32 v250, v116, v250
	s_waitcnt lgkmcnt(3)
	v_mfma_f32_16x16x32_bf16 v[90:93], v[182:185], v[146:149], v[2:5]
	v_add_f32_e32 v250, v117, v250
	s_add_u32 m0, s80, 49152
	s_nop 0
	global_load_lds_dwordx4 v248, s[100:101]
	v_mfma_f32_16x16x32_bf16 v[94:97], v[182:185], v[162:165], v[2:5]
	ds_read_b128 v[182:185], v235 offset:36864
	v_add_f32_e32 v250, v122, v250
	v_add_f32_e32 v250, v123, v250
	s_waitcnt lgkmcnt(3)
	v_mfma_f32_16x16x32_bf16 v[98:101], v[186:189], v[146:149], v[2:5]
	v_add_f32_e32 v250, v124, v250
	v_mfma_f32_16x16x32_bf16 v[102:105], v[186:189], v[162:165], v[2:5]
	ds_read_b128 v[186:189], v235 offset:40960
	v_add_f32_e32 v250, v125, v250
	v_cvt_pk_bf16_f32 v114, v114, v115
	s_waitcnt lgkmcnt(3)
; __device__ __forceinline__ void partialSM(f32x16& p0, f32x16& p1, float mC) {
;   (void)mC; (void)p1;
;   for (int r = 0; r < 16; ++r) p0[r] = __builtin_amdgcn_exp2f(p0[r]);
; }
; __device__ __forceinline__ void finishSM(f32x16& p0, f32x16& p1, float& l_reg, bf16x8& pa0, bf16x8& pa1, bf16x8& pa2, bf16x8& pa3) {
;   for (int r = 0; r < 16; ++r) p1[r] = __builtin_amdgcn_exp2f(p1[r]);
;   float ps = 0; for (int r = 0; r < 16; ++r) ps += p0[r]; for (int r = 0; r < 16; ++r) ps += p1[r];
;   { auto rr = __builtin_amdgcn_permlane32_swap(__float_as_uint(ps), __float_as_uint(ps), false, false);
;     ps = __uint_as_float(rr[0]) + __uint_as_float(rr[1]); }
;   l_reg += ps;
;     ...
;   PK4(p0, 0, pa0); PK4(p0, 8, pa1); PK4(p1, 0, pa2); PK4(p1, 8, pa3);
;     ...
; }
; __device__ __forceinline__ void qkt(f32x16& p0, f32x16& p1, const bf16* Ks, const bf16x8* qr, int r32, int hi, const f32x16& negm) {
; #pragma unroll
;   for (int d0 = 0; d0 < 8; ++d0) { int cb = (d0 * 16 + hi * 8) * 2;
;     bf16x8 b0 = *reinterpret_cast<const bf16x8*>((const char*)Ks + KSWZ(r32, cb));
;     bf16x8 b1 = *reinterpret_cast<const bf16x8*>((const char*)Ks + KSWZ(32 + r32, cb));
;     if (d0 == 0) { p0 = __builtin_amdgcn_mfma_f32_32x32x16_bf16(b0, qr[0], negm, 0, 0, 0); p1 = __builtin_amdgcn_mfma_f32_32x32x16_bf16(b1, qr[0], negm, 0, 0, 0); }
;     else { p0 = __builtin_amdgcn_mfma_f32_32x32x16_bf16(b0, qr[d0], p0, 0, 0, 0); p1 = __builtin_amdgcn_mfma_f32_32x32x16_bf16(b1, qr[d0], p1, 0, 0, 0); } }
; }
; __device__ __forceinline__ int v_st(int k, int c) { const int kk = (k & ~0xC) | ((k & 4) << 1) | ((k & 8) >> 1); return ((kk >> 3) * 4 + (c >> 5)) * 512 + ((kk & 7) * 32 + (c & 31)) * 2; }
; __device__ __forceinline__ int v_rd_base(int lane) { return ((lane & 3) << 3) | (((lane >> 2) & 3) << 6) | (((lane >> 4) & 1) << 5) | (((lane >> 5) & 1) << 8); }
; template <int OFF> __device__ __forceinline__ s16x4 tr_read(int vb) {
;   s16x4 r; asm volatile("ds_read_b64_tr_b16 %0, %1 offset:%2" : "=&v"(r) : "v"(vb), "i"(OFF) : "memory"); return r;
; }
; template <int D0> __device__ __forceinline__ void pv_one(f32x16& od, int vb, bf16x8 pa0, bf16x8 pa1, bf16x8 pa2, bf16x8 pa3) {
;   const s16x4 l0 = tr_read<v_rd_off(D0, 0, 0)>(vb), h0 = tr_read<v_rd_off(D0, 0, 1)>(vb), l1 = tr_read<v_rd_off(D0, 1, 0)>(vb), h1 = tr_read<v_rd_off(D0, 1, 1)>(vb);
	v_mfma_f32_16x16x32_bf16 v[106:109], v[190:193], v[146:149], v[2:5]
	v_cvt_pk_bf16_f32 v115, v116, v117
	s_add_u32 m0, s80, 50176
	s_nop 0
	global_load_lds_dwordx4 v249, s[100:101]
	v_mfma_f32_16x16x32_bf16 v[110:113], v[190:193], v[162:165], v[2:5]
	ds_read_b128 v[190:193], v235 offset:45056
	v_cvt_pk_bf16_f32 v116, v122, v123
	v_cvt_pk_bf16_f32 v117, v124, v125
	s_waitcnt lgkmcnt(3)
	v_mfma_f32_16x16x32_bf16 v[82:85], v[178:181], v[150:153], v[82:85]
	v_add_f32_e32 v251, v118, v251
	v_mfma_f32_16x16x32_bf16 v[86:89], v[178:181], v[166:169], v[86:89]
	ds_read_b128 v[178:181], v236 offset:32768
	v_add_f32_e32 v251, v119, v251
	v_add_f32_e32 v251, v120, v251
	s_waitcnt lgkmcnt(3)
	v_mfma_f32_16x16x32_bf16 v[90:93], v[182:185], v[150:153], v[90:93]
	v_add_f32_e32 v251, v121, v251
	v_mfma_f32_16x16x32_bf16 v[94:97], v[182:185], v[166:169], v[94:97]
	ds_read_b128 v[182:185], v236 offset:36864
	v_add_f32_e32 v251, v126, v251
	v_add_f32_e32 v251, v127, v251
	s_waitcnt lgkmcnt(3)
	v_mfma_f32_16x16x32_bf16 v[98:101], v[186:189], v[150:153], v[98:101]
	v_add_f32_e32 v251, v128, v251
	v_mfma_f32_16x16x32_bf16 v[102:105], v[186:189], v[166:169], v[102:105]
	ds_read_b128 v[186:189], v236 offset:40960
	v_add_f32_e32 v251, v129, v251
	v_cvt_pk_bf16_f32 v118, v118, v119
	s_waitcnt lgkmcnt(3)
	v_mfma_f32_16x16x32_bf16 v[106:109], v[190:193], v[150:153], v[106:109]
	v_cvt_pk_bf16_f32 v119, v120, v121
	v_mfma_f32_16x16x32_bf16 v[110:113], v[190:193], v[166:169], v[110:113]
	ds_read_b128 v[190:193], v236 offset:45056
	v_cvt_pk_bf16_f32 v120, v126, v127
	v_cvt_pk_bf16_f32 v121, v128, v129
	s_waitcnt lgkmcnt(3)
	v_mfma_f32_16x16x32_bf16 v[82:85], v[178:181], v[154:157], v[82:85]
	v_add_f32_e32 v250, v130, v250
	v_mfma_f32_16x16x32_bf16 v[86:89], v[178:181], v[170:173], v[86:89]
	ds_read_b128 v[178:181], v237 offset:32768
	v_add_f32_e32 v250, v131, v250
	v_add_f32_e32 v250, v132, v250
	s_waitcnt lgkmcnt(3)
	v_mfma_f32_16x16x32_bf16 v[90:93], v[182:185], v[154:157], v[90:93]
	v_add_f32_e32 v250, v133, v250
	v_mfma_f32_16x16x32_bf16 v[94:97], v[182:185], v[170:173], v[94:97]
	ds_read_b128 v[182:185], v237 offset:36864
	v_add_f32_e32 v250, v138, v250
	v_add_f32_e32 v250, v139, v250
	s_waitcnt lgkmcnt(3)
	v_mfma_f32_16x16x32_bf16 v[98:101], v[186:189], v[154:157], v[98:101]
	v_add_f32_e32 v250, v140, v250
	ds_read_b64_tr_b16 v[202:203], v238 offset:16384
	ds_read_b64_tr_b16 v[204:205], v238 offset:20480
	v_mfma_f32_16x16x32_bf16 v[102:105], v[186:189], v[170:173], v[102:105]
	ds_read_b128 v[186:189], v237 offset:40960
	v_add_f32_e32 v250, v141, v250
	v_cvt_pk_bf16_f32 v130, v130, v131
	s_waitcnt lgkmcnt(5)
	v_mfma_f32_16x16x32_bf16 v[106:109], v[190:193], v[154:157], v[106:109]
	v_cvt_pk_bf16_f32 v131, v132, v133
	ds_read_b64_tr_b16 v[206:207], v239 offset:16384
	ds_read_b64_tr_b16 v[208:209], v239 offset:20480
	v_mfma_f32_16x16x32_bf16 v[110:113], v[190:193], v[170:173], v[110:113]
	ds_read_b128 v[190:193], v237 offset:45056
	v_cvt_pk_bf16_f32 v132, v138, v139
	v_cvt_pk_bf16_f32 v133, v140, v141
	s_waitcnt lgkmcnt(7)
	v_mfma_f32_16x16x32_bf16 v[82:85], v[178:181], v[158:161], v[82:85]
	v_add_f32_e32 v251, v134, v251
	ds_read_b64_tr_b16 v[210:211], v240 offset:16384
	ds_read_b64_tr_b16 v[212:213], v240 offset:20480
	v_mfma_f32_16x16x32_bf16 v[86:89], v[178:181], v[174:177], v[86:89]
	v_add_f32_e32 v251, v135, v251
	v_add_f32_e32 v251, v136, v251
	s_waitcnt lgkmcnt(8)
	v_mfma_f32_16x16x32_bf16 v[90:93], v[182:185], v[158:161], v[90:93]
	v_add_f32_e32 v251, v137, v251
	ds_read_b64_tr_b16 v[214:215], v241 offset:16384
	ds_read_b64_tr_b16 v[216:217], v241 offset:20480
	v_mfma_f32_16x16x32_bf16 v[94:97], v[182:185], v[174:177], v[94:97]
	v_add_f32_e32 v251, v142, v251
	v_add_f32_e32 v251, v143, v251
	s_waitcnt lgkmcnt(7)
	v_mfma_f32_16x16x32_bf16 v[98:101], v[186:189], v[158:161], v[98:101]
	v_add_f32_e32 v251, v144, v251
	ds_read_b64_tr_b16 v[218:219], v242 offset:16384
	ds_read_b64_tr_b16 v[220:221], v242 offset:20480
	v_mfma_f32_16x16x32_bf16 v[102:105], v[186:189], v[174:177], v[102:105]
	v_add_f32_e32 v251, v145, v251
	v_cvt_pk_bf16_f32 v134, v134, v135
	s_waitcnt lgkmcnt(6)
	v_mfma_f32_16x16x32_bf16 v[106:109], v[190:193], v[158:161], v[106:109]
	v_cvt_pk_bf16_f32 v135, v136, v137
	ds_read_b64_tr_b16 v[222:223], v243 offset:16384
	ds_read_b64_tr_b16 v[224:225], v243 offset:20480
	v_mfma_f32_16x16x32_bf16 v[110:113], v[190:193], v[174:177], v[110:113]
	v_cvt_pk_bf16_f32 v136, v142, v143
	v_cvt_pk_bf16_f32 v137, v144, v145
	s_waitcnt vmcnt(2)
	s_barrier
; __device__ __forceinline__ void partialSM(f32x16& p0, f32x16& p1, float mC) {
;   (void)mC; (void)p1;
;   for (int r = 0; r < 16; ++r) p0[r] = __builtin_amdgcn_exp2f(p0[r]);
; }
; __device__ __forceinline__ void finishSM(f32x16& p0, f32x16& p1, float& l_reg, bf16x8& pa0, bf16x8& pa1, bf16x8& pa2, bf16x8& pa3) {
;   for (int r = 0; r < 16; ++r) p1[r] = __builtin_amdgcn_exp2f(p1[r]);
;   float ps = 0; for (int r = 0; r < 16; ++r) ps += p0[r]; for (int r = 0; r < 16; ++r) ps += p1[r];
;   { auto rr = __builtin_amdgcn_permlane32_swap(__float_as_uint(ps), __float_as_uint(ps), false, false);
;     ps = __uint_as_float(rr[0]) + __uint_as_float(rr[1]); }
;   l_reg += ps;
;     ...
;   PK4(p0, 0, pa0); PK4(p0, 8, pa1); PK4(p1, 0, pa2); PK4(p1, 8, pa3);
;     ...
; }
; __device__ __forceinline__ void qkt(f32x16& p0, f32x16& p1, const bf16* Ks, const bf16x8* qr, int r32, int hi, const f32x16& negm) {
; #pragma unroll
;   for (int d0 = 0; d0 < 8; ++d0) { int cb = (d0 * 16 + hi * 8) * 2;
;     bf16x8 b0 = *reinterpret_cast<const bf16x8*>((const char*)Ks + KSWZ(r32, cb));
;     bf16x8 b1 = *reinterpret_cast<const bf16x8*>((const char*)Ks + KSWZ(32 + r32, cb));
;     if (d0 == 0) { p0 = __builtin_amdgcn_mfma_f32_32x32x16_bf16(b0, qr[0], negm, 0, 0, 0); p1 = __builtin_amdgcn_mfma_f32_32x32x16_bf16(b1, qr[0], negm, 0, 0, 0); }
;     else { p0 = __builtin_amdgcn_mfma_f32_32x32x16_bf16(b0, qr[d0], p0, 0, 0, 0); p1 = __builtin_amdgcn_mfma_f32_32x32x16_bf16(b1, qr[d0], p1, 0, 0, 0); } }
; }
; __device__ __forceinline__ int v_st(int k, int c) { const int kk = (k & ~0xC) | ((k & 4) << 1) | ((k & 8) >> 1); return ((kk >> 3) * 4 + (c >> 5)) * 512 + ((kk & 7) * 32 + (c & 31)) * 2; }
; __device__ __forceinline__ int v_rd_base(int lane) { return ((lane & 3) << 3) | (((lane >> 2) & 3) << 6) | (((lane >> 4) & 1) << 5) | (((lane >> 5) & 1) << 8); }
; template <int OFF> __device__ __forceinline__ s16x4 tr_read(int vb) {
;   s16x4 r; asm volatile("ds_read_b64_tr_b16 %0, %1 offset:%2" : "=&v"(r) : "v"(vb), "i"(OFF) : "memory"); return r;
; }
; template <int D0> __device__ __forceinline__ void pv_one(f32x16& od, int vb, bf16x8 pa0, bf16x8 pa1, bf16x8 pa2, bf16x8 pa3) {
;   const s16x4 l0 = tr_read<v_rd_off(D0, 0, 0)>(vb), h0 = tr_read<v_rd_off(D0, 0, 1)>(vb), l1 = tr_read<v_rd_off(D0, 1, 0)>(vb), h1 = tr_read<v_rd_off(D0, 1, 1)>(vb);
	v_mfma_f32_16x16x32_bf16 v[18:21], v[202:205], v[114:117], v[18:21]
	v_exp_f32_e32 v82, v82
	v_mfma_f32_16x16x32_bf16 v[22:25], v[202:205], v[118:121], v[22:25]
	ds_read_b64_tr_b16 v[202:203], v244 offset:16384
	ds_read_b64_tr_b16 v[204:205], v244 offset:20480
	v_exp_f32_e32 v83, v83
	v_mfma_f32_16x16x32_bf16 v[26:29], v[206:209], v[114:117], v[26:29]
	v_exp_f32_e32 v84, v84
	v_mfma_f32_16x16x32_bf16 v[30:33], v[206:209], v[118:121], v[30:33]
	ds_read_b64_tr_b16 v[206:207], v245 offset:16384
	ds_read_b64_tr_b16 v[208:209], v245 offset:20480
	v_exp_f32_e32 v85, v85
	s_waitcnt lgkmcnt(10)
	v_mfma_f32_16x16x32_bf16 v[34:37], v[210:213], v[114:117], v[34:37]
	v_exp_f32_e32 v86, v86
	v_mfma_f32_16x16x32_bf16 v[38:41], v[210:213], v[118:121], v[38:41]
	ds_read_b64_tr_b16 v[210:211], v238 offset:24576
	ds_read_b64_tr_b16 v[212:213], v238 offset:28672
	v_exp_f32_e32 v87, v87
	s_waitcnt lgkmcnt(10)
	v_mfma_f32_16x16x32_bf16 v[42:45], v[214:217], v[114:117], v[42:45]
	v_exp_f32_e32 v88, v88
	v_mfma_f32_16x16x32_bf16 v[46:49], v[214:217], v[118:121], v[46:49]
	ds_read_b64_tr_b16 v[214:215], v239 offset:24576
	ds_read_b64_tr_b16 v[216:217], v239 offset:28672
	v_exp_f32_e32 v89, v89
	s_waitcnt lgkmcnt(10)
	v_mfma_f32_16x16x32_bf16 v[50:53], v[218:221], v[114:117], v[50:53]
	v_exp_f32_e32 v90, v90
	v_mfma_f32_16x16x32_bf16 v[54:57], v[218:221], v[118:121], v[54:57]
	ds_read_b64_tr_b16 v[218:219], v240 offset:24576
	ds_read_b64_tr_b16 v[220:221], v240 offset:28672
	v_exp_f32_e32 v91, v91
	s_waitcnt lgkmcnt(10)
	v_mfma_f32_16x16x32_bf16 v[58:61], v[222:225], v[114:117], v[58:61]
	v_exp_f32_e32 v92, v92
	v_mfma_f32_16x16x32_bf16 v[62:65], v[222:225], v[118:121], v[62:65]
	ds_read_b64_tr_b16 v[222:223], v241 offset:24576
	ds_read_b64_tr_b16 v[224:225], v241 offset:28672
	v_exp_f32_e32 v93, v93
	s_waitcnt lgkmcnt(10)
	v_mfma_f32_16x16x32_bf16 v[66:69], v[202:205], v[114:117], v[66:69]
	v_exp_f32_e32 v94, v94
	v_mfma_f32_16x16x32_bf16 v[70:73], v[202:205], v[118:121], v[70:73]
	ds_read_b64_tr_b16 v[202:203], v242 offset:24576
	ds_read_b64_tr_b16 v[204:205], v242 offset:28672
	v_exp_f32_e32 v95, v95
	s_waitcnt lgkmcnt(10)
	v_mfma_f32_16x16x32_bf16 v[74:77], v[206:209], v[114:117], v[74:77]
	v_exp_f32_e32 v96, v96
	v_mfma_f32_16x16x32_bf16 v[78:81], v[206:209], v[118:121], v[78:81]
	ds_read_b64_tr_b16 v[206:207], v243 offset:24576
	ds_read_b64_tr_b16 v[208:209], v243 offset:28672
	v_exp_f32_e32 v97, v97
	s_waitcnt lgkmcnt(10)
	v_mfma_f32_16x16x32_bf16 v[18:21], v[210:213], v[130:133], v[18:21]
	v_exp_f32_e32 v98, v98
	v_mfma_f32_16x16x32_bf16 v[22:25], v[210:213], v[134:137], v[22:25]
	ds_read_b64_tr_b16 v[210:211], v244 offset:24576
	ds_read_b64_tr_b16 v[212:213], v244 offset:28672
	v_exp_f32_e32 v99, v99
	s_waitcnt lgkmcnt(10)
	v_mfma_f32_16x16x32_bf16 v[26:29], v[214:217], v[130:133], v[26:29]
	v_exp_f32_e32 v100, v100
	v_mfma_f32_16x16x32_bf16 v[30:33], v[214:217], v[134:137], v[30:33]
	ds_read_b64_tr_b16 v[214:215], v245 offset:24576
	ds_read_b64_tr_b16 v[216:217], v245 offset:28672
	v_exp_f32_e32 v101, v101
	s_waitcnt lgkmcnt(10)
	v_mfma_f32_16x16x32_bf16 v[34:37], v[218:221], v[130:133], v[34:37]
	v_exp_f32_e32 v102, v102
	v_mfma_f32_16x16x32_bf16 v[38:41], v[218:221], v[134:137], v[38:41]
	v_exp_f32_e32 v103, v103
	s_waitcnt lgkmcnt(8)
	v_mfma_f32_16x16x32_bf16 v[42:45], v[222:225], v[130:133], v[42:45]
	v_exp_f32_e32 v104, v104
	v_mfma_f32_16x16x32_bf16 v[46:49], v[222:225], v[134:137], v[46:49]
	v_exp_f32_e32 v105, v105
	s_waitcnt lgkmcnt(6)
	v_mfma_f32_16x16x32_bf16 v[50:53], v[202:205], v[130:133], v[50:53]
	v_exp_f32_e32 v106, v106
	ds_read_b128 v[178:181], v234 offset:49152
	v_mfma_f32_16x16x32_bf16 v[54:57], v[202:205], v[134:137], v[54:57]
	v_exp_f32_e32 v107, v107
	s_waitcnt lgkmcnt(5)
	v_mfma_f32_16x16x32_bf16 v[58:61], v[206:209], v[130:133], v[58:61]
	v_exp_f32_e32 v108, v108
	ds_read_b128 v[182:185], v234 offset:53248
	v_mfma_f32_16x16x32_bf16 v[62:65], v[206:209], v[134:137], v[62:65]
	v_exp_f32_e32 v109, v109
	s_waitcnt lgkmcnt(4)
	v_mfma_f32_16x16x32_bf16 v[66:69], v[210:213], v[130:133], v[66:69]
	v_exp_f32_e32 v110, v110
	ds_read_b128 v[186:189], v234 offset:57344
	v_mfma_f32_16x16x32_bf16 v[70:73], v[210:213], v[134:137], v[70:73]
	v_exp_f32_e32 v111, v111
	s_waitcnt lgkmcnt(3)
	v_mfma_f32_16x16x32_bf16 v[74:77], v[214:217], v[130:133], v[74:77]
	v_exp_f32_e32 v112, v112
	ds_read_b128 v[190:193], v234 offset:61440
	v_mfma_f32_16x16x32_bf16 v[78:81], v[214:217], v[134:137], v[78:81]
	v_exp_f32_e32 v113, v113
	s_waitcnt lgkmcnt(3)
	v_mfma_f32_16x16x32_bf16 v[114:117], v[178:181], v[146:149], v[2:5]
	v_add_f32_e32 v250, v82, v250
	v_mfma_f32_16x16x32_bf16 v[118:121], v[178:181], v[162:165], v[2:5]
	ds_read_b128 v[178:181], v235 offset:49152
	v_add_f32_e32 v250, v83, v250
	v_add_f32_e32 v250, v84, v250
	s_waitcnt lgkmcnt(3)
	v_mfma_f32_16x16x32_bf16 v[122:125], v[182:185], v[146:149], v[2:5]
	v_add_f32_e32 v250, v85, v250
	v_mfma_f32_16x16x32_bf16 v[126:129], v[182:185], v[162:165], v[2:5]
	ds_read_b128 v[182:185], v235 offset:53248
	v_add_f32_e32 v250, v90, v250
	v_add_f32_e32 v250, v91, v250
	s_waitcnt lgkmcnt(3)
	v_mfma_f32_16x16x32_bf16 v[130:133], v[186:189], v[146:149], v[2:5]
	v_add_f32_e32 v250, v92, v250
	v_mfma_f32_16x16x32_bf16 v[134:137], v[186:189], v[162:165], v[2:5]
	ds_read_b128 v[186:189], v235 offset:57344
	v_add_f32_e32 v250, v93, v250
	v_cvt_pk_bf16_f32 v82, v82, v83
	s_waitcnt lgkmcnt(3)
	v_mfma_f32_16x16x32_bf16 v[138:141], v[190:193], v[146:149], v[2:5]
	v_cvt_pk_bf16_f32 v83, v84, v85
	v_mfma_f32_16x16x32_bf16 v[142:145], v[190:193], v[162:165], v[2:5]
	ds_read_b128 v[190:193], v235 offset:61440
	v_cvt_pk_bf16_f32 v84, v90, v91
	v_cvt_pk_bf16_f32 v85, v92, v93
	s_waitcnt lgkmcnt(3)
; __device__ __forceinline__ void partialSM(f32x16& p0, f32x16& p1, float mC) {
;   (void)mC; (void)p1;
;   for (int r = 0; r < 16; ++r) p0[r] = __builtin_amdgcn_exp2f(p0[r]);
; }
; __device__ __forceinline__ void finishSM(f32x16& p0, f32x16& p1, float& l_reg, bf16x8& pa0, bf16x8& pa1, bf16x8& pa2, bf16x8& pa3) {
;   for (int r = 0; r < 16; ++r) p1[r] = __builtin_amdgcn_exp2f(p1[r]);
;   float ps = 0; for (int r = 0; r < 16; ++r) ps += p0[r]; for (int r = 0; r < 16; ++r) ps += p1[r];
;   { auto rr = __builtin_amdgcn_permlane32_swap(__float_as_uint(ps), __float_as_uint(ps), false, false);
;     ps = __uint_as_float(rr[0]) + __uint_as_float(rr[1]); }
;   l_reg += ps;
;     ...
;   PK4(p0, 0, pa0); PK4(p0, 8, pa1); PK4(p1, 0, pa2); PK4(p1, 8, pa3);
;     ...
; }
; __device__ __forceinline__ void qkt(f32x16& p0, f32x16& p1, const bf16* Ks, const bf16x8* qr, int r32, int hi, const f32x16& negm) {
; #pragma unroll
;   for (int d0 = 0; d0 < 8; ++d0) { int cb = (d0 * 16 + hi * 8) * 2;
;     bf16x8 b0 = *reinterpret_cast<const bf16x8*>((const char*)Ks + KSWZ(r32, cb));
;     bf16x8 b1 = *reinterpret_cast<const bf16x8*>((const char*)Ks + KSWZ(32 + r32, cb));
;     if (d0 == 0) { p0 = __builtin_amdgcn_mfma_f32_32x32x16_bf16(b0, qr[0], negm, 0, 0, 0); p1 = __builtin_amdgcn_mfma_f32_32x32x16_bf16(b1, qr[0], negm, 0, 0, 0); }
;     else { p0 = __builtin_amdgcn_mfma_f32_32x32x16_bf16(b0, qr[d0], p0, 0, 0, 0); p1 = __builtin_amdgcn_mfma_f32_32x32x16_bf16(b1, qr[d0], p1, 0, 0, 0); } }
; }
; __device__ __forceinline__ int v_st(int k, int c) { const int kk = (k & ~0xC) | ((k & 4) << 1) | ((k & 8) >> 1); return ((kk >> 3) * 4 + (c >> 5)) * 512 + ((kk & 7) * 32 + (c & 31)) * 2; }
; __device__ __forceinline__ int v_rd_base(int lane) { return ((lane & 3) << 3) | (((lane >> 2) & 3) << 6) | (((lane >> 4) & 1) << 5) | (((lane >> 5) & 1) << 8); }
; template <int OFF> __device__ __forceinline__ s16x4 tr_read(int vb) {
;   s16x4 r; asm volatile("ds_read_b64_tr_b16 %0, %1 offset:%2" : "=&v"(r) : "v"(vb), "i"(OFF) : "memory"); return r;
; }
; template <int D0> __device__ __forceinline__ void pv_one(f32x16& od, int vb, bf16x8 pa0, bf16x8 pa1, bf16x8 pa2, bf16x8 pa3) {
;   const s16x4 l0 = tr_read<v_rd_off(D0, 0, 0)>(vb), h0 = tr_read<v_rd_off(D0, 0, 1)>(vb), l1 = tr_read<v_rd_off(D0, 1, 0)>(vb), h1 = tr_read<v_rd_off(D0, 1, 1)>(vb);
	v_mfma_f32_16x16x32_bf16 v[114:117], v[178:181], v[150:153], v[114:117]
	v_add_f32_e32 v251, v86, v251
	v_mfma_f32_16x16x32_bf16 v[118:121], v[178:181], v[166:169], v[118:121]
	ds_read_b128 v[178:181], v236 offset:49152
	v_add_f32_e32 v251, v87, v251
	v_add_f32_e32 v251, v88, v251
	s_waitcnt lgkmcnt(3)
	v_mfma_f32_16x16x32_bf16 v[122:125], v[182:185], v[150:153], v[122:125]
	v_add_f32_e32 v251, v89, v251
	v_mfma_f32_16x16x32_bf16 v[126:129], v[182:185], v[166:169], v[126:129]
	ds_read_b128 v[182:185], v236 offset:53248
	v_add_f32_e32 v251, v94, v251
	v_add_f32_e32 v251, v95, v251
	s_waitcnt lgkmcnt(3)
	v_mfma_f32_16x16x32_bf16 v[130:133], v[186:189], v[150:153], v[130:133]
	v_add_f32_e32 v251, v96, v251
	v_mfma_f32_16x16x32_bf16 v[134:137], v[186:189], v[166:169], v[134:137]
	ds_read_b128 v[186:189], v236 offset:57344
	v_add_f32_e32 v251, v97, v251
	v_cvt_pk_bf16_f32 v86, v86, v87
	s_waitcnt lgkmcnt(3)
	v_mfma_f32_16x16x32_bf16 v[138:141], v[190:193], v[150:153], v[138:141]
	v_cvt_pk_bf16_f32 v87, v88, v89
	v_mfma_f32_16x16x32_bf16 v[142:145], v[190:193], v[166:169], v[142:145]
	ds_read_b128 v[190:193], v236 offset:61440
	v_cvt_pk_bf16_f32 v88, v94, v95
	v_cvt_pk_bf16_f32 v89, v96, v97
	s_waitcnt lgkmcnt(3)
	v_mfma_f32_16x16x32_bf16 v[114:117], v[178:181], v[154:157], v[114:117]
	v_add_f32_e32 v250, v98, v250
	v_mfma_f32_16x16x32_bf16 v[118:121], v[178:181], v[170:173], v[118:121]
	ds_read_b128 v[178:181], v237 offset:49152
	v_add_f32_e32 v250, v99, v250
	v_add_f32_e32 v250, v100, v250
	s_waitcnt lgkmcnt(3)
	v_mfma_f32_16x16x32_bf16 v[122:125], v[182:185], v[154:157], v[122:125]
	v_add_f32_e32 v250, v101, v250
	v_mfma_f32_16x16x32_bf16 v[126:129], v[182:185], v[170:173], v[126:129]
	ds_read_b128 v[182:185], v237 offset:53248
	v_add_f32_e32 v250, v106, v250
	v_add_f32_e32 v250, v107, v250
	s_waitcnt lgkmcnt(3)
	v_mfma_f32_16x16x32_bf16 v[130:133], v[186:189], v[154:157], v[130:133]
	v_add_f32_e32 v250, v108, v250
	ds_read_b64_tr_b16 v[202:203], v238 offset:32768
	ds_read_b64_tr_b16 v[204:205], v238 offset:36864
	v_mfma_f32_16x16x32_bf16 v[134:137], v[186:189], v[170:173], v[134:137]
	ds_read_b128 v[186:189], v237 offset:57344
	v_add_f32_e32 v250, v109, v250
	v_cvt_pk_bf16_f32 v98, v98, v99
	s_waitcnt lgkmcnt(5)
	v_mfma_f32_16x16x32_bf16 v[138:141], v[190:193], v[154:157], v[138:141]
	v_cvt_pk_bf16_f32 v99, v100, v101
	ds_read_b64_tr_b16 v[206:207], v239 offset:32768
	ds_read_b64_tr_b16 v[208:209], v239 offset:36864
	v_mfma_f32_16x16x32_bf16 v[142:145], v[190:193], v[170:173], v[142:145]
	ds_read_b128 v[190:193], v237 offset:61440
	v_cvt_pk_bf16_f32 v100, v106, v107
	v_cvt_pk_bf16_f32 v101, v108, v109
	s_waitcnt lgkmcnt(7)
	v_mfma_f32_16x16x32_bf16 v[114:117], v[178:181], v[158:161], v[114:117]
	v_add_f32_e32 v251, v102, v251
	ds_read_b64_tr_b16 v[210:211], v240 offset:32768
	ds_read_b64_tr_b16 v[212:213], v240 offset:36864
	v_mfma_f32_16x16x32_bf16 v[118:121], v[178:181], v[174:177], v[118:121]
	v_add_f32_e32 v251, v103, v251
	v_add_f32_e32 v251, v104, v251
	s_waitcnt lgkmcnt(8)
	v_mfma_f32_16x16x32_bf16 v[122:125], v[182:185], v[158:161], v[122:125]
	v_add_f32_e32 v251, v105, v251
	ds_read_b64_tr_b16 v[214:215], v241 offset:32768
	ds_read_b64_tr_b16 v[216:217], v241 offset:36864
	v_mfma_f32_16x16x32_bf16 v[126:129], v[182:185], v[174:177], v[126:129]
	v_add_f32_e32 v251, v110, v251
	v_add_f32_e32 v251, v111, v251
	s_waitcnt lgkmcnt(7)
	v_mfma_f32_16x16x32_bf16 v[130:133], v[186:189], v[158:161], v[130:133]
	v_add_f32_e32 v251, v112, v251
	ds_read_b64_tr_b16 v[218:219], v242 offset:32768
	ds_read_b64_tr_b16 v[220:221], v242 offset:36864
	v_mfma_f32_16x16x32_bf16 v[134:137], v[186:189], v[174:177], v[134:137]
	v_add_f32_e32 v251, v113, v251
	v_cvt_pk_bf16_f32 v102, v102, v103
	s_waitcnt lgkmcnt(6)
	v_mfma_f32_16x16x32_bf16 v[138:141], v[190:193], v[158:161], v[138:141]
	v_cvt_pk_bf16_f32 v103, v104, v105
	ds_read_b64_tr_b16 v[222:223], v243 offset:32768
	ds_read_b64_tr_b16 v[224:225], v243 offset:36864
	v_mfma_f32_16x16x32_bf16 v[142:145], v[190:193], v[174:177], v[142:145]
	v_cvt_pk_bf16_f32 v104, v110, v111
	v_cvt_pk_bf16_f32 v105, v112, v113
	s_waitcnt vmcnt(0)
	v_mfma_f32_16x16x32_bf16 v[18:21], v[202:205], v[82:85], v[18:21]
	v_exp_f32_e32 v114, v114
	v_mfma_f32_16x16x32_bf16 v[22:25], v[202:205], v[86:89], v[22:25]
	ds_read_b64_tr_b16 v[202:203], v244 offset:32768
	ds_read_b64_tr_b16 v[204:205], v244 offset:36864
	v_exp_f32_e32 v115, v115
	v_mfma_f32_16x16x32_bf16 v[26:29], v[206:209], v[82:85], v[26:29]
	v_exp_f32_e32 v116, v116
	v_mfma_f32_16x16x32_bf16 v[30:33], v[206:209], v[86:89], v[30:33]
	ds_read_b64_tr_b16 v[206:207], v245 offset:32768
	ds_read_b64_tr_b16 v[208:209], v245 offset:36864
	v_exp_f32_e32 v117, v117
	s_waitcnt lgkmcnt(10)
	v_mfma_f32_16x16x32_bf16 v[34:37], v[210:213], v[82:85], v[34:37]
	v_exp_f32_e32 v118, v118
	v_mfma_f32_16x16x32_bf16 v[38:41], v[210:213], v[86:89], v[38:41]
	ds_read_b64_tr_b16 v[210:211], v238 offset:40960
	ds_read_b64_tr_b16 v[212:213], v238 offset:45056
	v_exp_f32_e32 v119, v119
	s_waitcnt lgkmcnt(10)
	v_mfma_f32_16x16x32_bf16 v[42:45], v[214:217], v[82:85], v[42:45]
	v_exp_f32_e32 v120, v120
	v_mfma_f32_16x16x32_bf16 v[46:49], v[214:217], v[86:89], v[46:49]
	ds_read_b64_tr_b16 v[214:215], v239 offset:40960
	ds_read_b64_tr_b16 v[216:217], v239 offset:45056
	v_exp_f32_e32 v121, v121
	s_waitcnt lgkmcnt(10)
	v_mfma_f32_16x16x32_bf16 v[50:53], v[218:221], v[82:85], v[50:53]
	v_exp_f32_e32 v122, v122
	v_mfma_f32_16x16x32_bf16 v[54:57], v[218:221], v[86:89], v[54:57]
	ds_read_b64_tr_b16 v[218:219], v240 offset:40960
	ds_read_b64_tr_b16 v[220:221], v240 offset:45056
	v_exp_f32_e32 v123, v123
	s_waitcnt lgkmcnt(10)
; __device__ __forceinline__ void partialSM(f32x16& p0, f32x16& p1, float mC) {
;   (void)mC; (void)p1;
;   for (int r = 0; r < 16; ++r) p0[r] = __builtin_amdgcn_exp2f(p0[r]);
; }
; __device__ __forceinline__ void finishSM(f32x16& p0, f32x16& p1, float& l_reg, bf16x8& pa0, bf16x8& pa1, bf16x8& pa2, bf16x8& pa3) {
;   for (int r = 0; r < 16; ++r) p1[r] = __builtin_amdgcn_exp2f(p1[r]);
;   float ps = 0; for (int r = 0; r < 16; ++r) ps += p0[r]; for (int r = 0; r < 16; ++r) ps += p1[r];
;   { auto rr = __builtin_amdgcn_permlane32_swap(__float_as_uint(ps), __float_as_uint(ps), false, false);
;     ps = __uint_as_float(rr[0]) + __uint_as_float(rr[1]); }
;   l_reg += ps;
;     ...
;   PK4(p0, 0, pa0); PK4(p0, 8, pa1); PK4(p1, 0, pa2); PK4(p1, 8, pa3);
;     ...
; }
; __device__ __forceinline__ void qkt(f32x16& p0, f32x16& p1, const bf16* Ks, const bf16x8* qr, int r32, int hi, const f32x16& negm) {
; #pragma unroll
;   for (int d0 = 0; d0 < 8; ++d0) { int cb = (d0 * 16 + hi * 8) * 2;
;     bf16x8 b0 = *reinterpret_cast<const bf16x8*>((const char*)Ks + KSWZ(r32, cb));
;     bf16x8 b1 = *reinterpret_cast<const bf16x8*>((const char*)Ks + KSWZ(32 + r32, cb));
;     if (d0 == 0) { p0 = __builtin_amdgcn_mfma_f32_32x32x16_bf16(b0, qr[0], negm, 0, 0, 0); p1 = __builtin_amdgcn_mfma_f32_32x32x16_bf16(b1, qr[0], negm, 0, 0, 0); }
;     else { p0 = __builtin_amdgcn_mfma_f32_32x32x16_bf16(b0, qr[d0], p0, 0, 0, 0); p1 = __builtin_amdgcn_mfma_f32_32x32x16_bf16(b1, qr[d0], p1, 0, 0, 0); } }
; }
; __device__ __forceinline__ int v_st(int k, int c) { const int kk = (k & ~0xC) | ((k & 4) << 1) | ((k & 8) >> 1); return ((kk >> 3) * 4 + (c >> 5)) * 512 + ((kk & 7) * 32 + (c & 31)) * 2; }
; __device__ __forceinline__ int v_rd_base(int lane) { return ((lane & 3) << 3) | (((lane >> 2) & 3) << 6) | (((lane >> 4) & 1) << 5) | (((lane >> 5) & 1) << 8); }
; template <int OFF> __device__ __forceinline__ s16x4 tr_read(int vb) {
;   s16x4 r; asm volatile("ds_read_b64_tr_b16 %0, %1 offset:%2" : "=&v"(r) : "v"(vb), "i"(OFF) : "memory"); return r;
; }
; template <int D0> __device__ __forceinline__ void pv_one(f32x16& od, int vb, bf16x8 pa0, bf16x8 pa1, bf16x8 pa2, bf16x8 pa3) {
;   const s16x4 l0 = tr_read<v_rd_off(D0, 0, 0)>(vb), h0 = tr_read<v_rd_off(D0, 0, 1)>(vb), l1 = tr_read<v_rd_off(D0, 1, 0)>(vb), h1 = tr_read<v_rd_off(D0, 1, 1)>(vb);
	v_mfma_f32_16x16x32_bf16 v[58:61], v[222:225], v[82:85], v[58:61]
	v_exp_f32_e32 v124, v124
	v_mfma_f32_16x16x32_bf16 v[62:65], v[222:225], v[86:89], v[62:65]
	ds_read_b64_tr_b16 v[222:223], v241 offset:40960
	ds_read_b64_tr_b16 v[224:225], v241 offset:45056
	v_exp_f32_e32 v125, v125
	s_waitcnt lgkmcnt(10)
	v_mfma_f32_16x16x32_bf16 v[66:69], v[202:205], v[82:85], v[66:69]
	v_exp_f32_e32 v126, v126
	v_mfma_f32_16x16x32_bf16 v[70:73], v[202:205], v[86:89], v[70:73]
	ds_read_b64_tr_b16 v[202:203], v242 offset:40960
	ds_read_b64_tr_b16 v[204:205], v242 offset:45056
	v_exp_f32_e32 v127, v127
	s_waitcnt lgkmcnt(10)
	v_mfma_f32_16x16x32_bf16 v[74:77], v[206:209], v[82:85], v[74:77]
	v_exp_f32_e32 v128, v128
	v_mfma_f32_16x16x32_bf16 v[78:81], v[206:209], v[86:89], v[78:81]
	ds_read_b64_tr_b16 v[206:207], v243 offset:40960
	ds_read_b64_tr_b16 v[208:209], v243 offset:45056
	v_exp_f32_e32 v129, v129
	s_waitcnt lgkmcnt(10)
	v_mfma_f32_16x16x32_bf16 v[18:21], v[210:213], v[98:101], v[18:21]
	v_exp_f32_e32 v130, v130
	v_mfma_f32_16x16x32_bf16 v[22:25], v[210:213], v[102:105], v[22:25]
	ds_read_b64_tr_b16 v[210:211], v244 offset:40960
	ds_read_b64_tr_b16 v[212:213], v244 offset:45056
	v_exp_f32_e32 v131, v131
	s_waitcnt lgkmcnt(10)
	v_mfma_f32_16x16x32_bf16 v[26:29], v[214:217], v[98:101], v[26:29]
	v_exp_f32_e32 v132, v132
	v_mfma_f32_16x16x32_bf16 v[30:33], v[214:217], v[102:105], v[30:33]
	ds_read_b64_tr_b16 v[214:215], v245 offset:40960
	ds_read_b64_tr_b16 v[216:217], v245 offset:45056
	v_exp_f32_e32 v133, v133
	s_waitcnt lgkmcnt(10)
	v_mfma_f32_16x16x32_bf16 v[34:37], v[218:221], v[98:101], v[34:37]
	v_exp_f32_e32 v134, v134
	v_mfma_f32_16x16x32_bf16 v[38:41], v[218:221], v[102:105], v[38:41]
	v_exp_f32_e32 v135, v135
	s_waitcnt lgkmcnt(8)
	v_mfma_f32_16x16x32_bf16 v[42:45], v[222:225], v[98:101], v[42:45]
	v_exp_f32_e32 v136, v136
	v_mfma_f32_16x16x32_bf16 v[46:49], v[222:225], v[102:105], v[46:49]
	v_exp_f32_e32 v137, v137
	s_waitcnt lgkmcnt(6)
	v_mfma_f32_16x16x32_bf16 v[50:53], v[202:205], v[98:101], v[50:53]
	v_exp_f32_e32 v138, v138
	v_mfma_f32_16x16x32_bf16 v[54:57], v[202:205], v[102:105], v[54:57]
	v_exp_f32_e32 v139, v139
	s_waitcnt lgkmcnt(4)
	v_mfma_f32_16x16x32_bf16 v[58:61], v[206:209], v[98:101], v[58:61]
	v_exp_f32_e32 v140, v140
	v_mfma_f32_16x16x32_bf16 v[62:65], v[206:209], v[102:105], v[62:65]
	v_exp_f32_e32 v141, v141
	s_waitcnt lgkmcnt(2)
	v_mfma_f32_16x16x32_bf16 v[66:69], v[210:213], v[98:101], v[66:69]
	v_exp_f32_e32 v142, v142
	v_mfma_f32_16x16x32_bf16 v[70:73], v[210:213], v[102:105], v[70:73]
	v_exp_f32_e32 v143, v143
	s_waitcnt lgkmcnt(0)
	v_mfma_f32_16x16x32_bf16 v[74:77], v[214:217], v[98:101], v[74:77]
	v_exp_f32_e32 v144, v144
	v_mfma_f32_16x16x32_bf16 v[78:81], v[214:217], v[102:105], v[78:81]
	v_exp_f32_e32 v145, v145
.Lattn_fin:
	s_barrier
	v_add_f32_e32 v250, v114, v250
	v_add_f32_e32 v250, v115, v250
	v_add_f32_e32 v250, v116, v250
	v_add_f32_e32 v250, v117, v250
	v_add_f32_e32 v250, v122, v250
	v_add_f32_e32 v250, v123, v250
	v_add_f32_e32 v250, v124, v250
	v_add_f32_e32 v250, v125, v250
	v_cvt_pk_bf16_f32 v114, v114, v115
	v_cvt_pk_bf16_f32 v115, v116, v117
	v_cvt_pk_bf16_f32 v116, v122, v123
	v_cvt_pk_bf16_f32 v117, v124, v125
	v_add_f32_e32 v251, v118, v251
	v_add_f32_e32 v251, v119, v251
	v_add_f32_e32 v251, v120, v251
	v_add_f32_e32 v251, v121, v251
	v_add_f32_e32 v251, v126, v251
	v_add_f32_e32 v251, v127, v251
	v_add_f32_e32 v251, v128, v251
	v_add_f32_e32 v251, v129, v251
	v_cvt_pk_bf16_f32 v118, v118, v119
	v_cvt_pk_bf16_f32 v119, v120, v121
	v_cvt_pk_bf16_f32 v120, v126, v127
	v_cvt_pk_bf16_f32 v121, v128, v129
	v_add_f32_e32 v250, v130, v250
	v_add_f32_e32 v250, v131, v250
	v_add_f32_e32 v250, v132, v250
	v_add_f32_e32 v250, v133, v250
	v_add_f32_e32 v250, v138, v250
	v_add_f32_e32 v250, v139, v250
	v_add_f32_e32 v250, v140, v250
	v_add_f32_e32 v250, v141, v250
	v_cvt_pk_bf16_f32 v130, v130, v131
	v_cvt_pk_bf16_f32 v131, v132, v133
	v_cvt_pk_bf16_f32 v132, v138, v139
	v_cvt_pk_bf16_f32 v133, v140, v141
	v_add_f32_e32 v251, v134, v251
	v_add_f32_e32 v251, v135, v251
	v_add_f32_e32 v251, v136, v251
	v_add_f32_e32 v251, v137, v251
	v_add_f32_e32 v251, v142, v251
	v_add_f32_e32 v251, v143, v251
	v_add_f32_e32 v251, v144, v251
	v_add_f32_e32 v251, v145, v251
	v_cvt_pk_bf16_f32 v134, v134, v135
	v_cvt_pk_bf16_f32 v135, v136, v137
	v_cvt_pk_bf16_f32 v136, v142, v143
	v_cvt_pk_bf16_f32 v137, v144, v145
	ds_read_b64_tr_b16 v[202:203], v238 offset:49152
	ds_read_b64_tr_b16 v[204:205], v238 offset:53248
	ds_read_b64_tr_b16 v[206:207], v239 offset:49152
	ds_read_b64_tr_b16 v[208:209], v239 offset:53248
	ds_read_b64_tr_b16 v[210:211], v240 offset:49152
	ds_read_b64_tr_b16 v[212:213], v240 offset:53248
	ds_read_b64_tr_b16 v[214:215], v241 offset:49152
	ds_read_b64_tr_b16 v[216:217], v241 offset:53248
	ds_read_b64_tr_b16 v[218:219], v242 offset:49152
	ds_read_b64_tr_b16 v[220:221], v242 offset:53248
	ds_read_b64_tr_b16 v[222:223], v243 offset:49152
	ds_read_b64_tr_b16 v[224:225], v243 offset:53248
	s_waitcnt lgkmcnt(10)
	v_mfma_f32_16x16x32_bf16 v[18:21], v[202:205], v[114:117], v[18:21]
	v_mfma_f32_16x16x32_bf16 v[22:25], v[202:205], v[118:121], v[22:25]
	ds_read_b64_tr_b16 v[202:203], v244 offset:49152
	ds_read_b64_tr_b16 v[204:205], v244 offset:53248
	s_waitcnt lgkmcnt(10)
	v_mfma_f32_16x16x32_bf16 v[26:29], v[206:209], v[114:117], v[26:29]
	v_mfma_f32_16x16x32_bf16 v[30:33], v[206:209], v[118:121], v[30:33]
	ds_read_b64_tr_b16 v[206:207], v245 offset:49152
	ds_read_b64_tr_b16 v[208:209], v245 offset:53248
	s_waitcnt lgkmcnt(10)
; #define SBAR() __builtin_amdgcn_sched_barrier(0)
; __device__ __forceinline__ int crow(int r, int hi) { return (r & 3) + 8 * (r >> 2) + 4 * hi; }
; template <int D0> __device__ __forceinline__ void pv_one(f32x16& od, int vb, bf16x8 pa0, bf16x8 pa1, bf16x8 pa2, bf16x8 pa3) {
;   const s16x4 l0 = tr_read<v_rd_off(D0, 0, 0)>(vb), h0 = tr_read<v_rd_off(D0, 0, 1)>(vb), l1 = tr_read<v_rd_off(D0, 1, 0)>(vb), h1 = tr_read<v_rd_off(D0, 1, 1)>(vb);
;   const s16x4 l2 = tr_read<v_rd_off(D0, 2, 0)>(vb), h2 = tr_read<v_rd_off(D0, 2, 1)>(vb), l3 = tr_read<v_rd_off(D0, 3, 0)>(vb), h3 = tr_read<v_rd_off(D0, 3, 1)>(vb);
;   asm volatile("s_waitcnt lgkmcnt(0)" ::: "memory"); SBAR();
;     ...
;   od = __builtin_amdgcn_mfma_f32_32x32x16_bf16(pa0, PK(l0, h0), od, 0, 0, 0);
;   od = __builtin_amdgcn_mfma_f32_32x32x16_bf16(pa1, PK(l1, h1), od, 0, 0, 0);
;   od = __builtin_amdgcn_mfma_f32_32x32x16_bf16(pa2, PK(l2, h2), od, 0, 0, 0);
;   od = __builtin_amdgcn_mfma_f32_32x32x16_bf16(pa3, PK(l3, h3), od, 0, 0, 0);
;     ...
; }
; template <typename TQ> ...
;     ...
;   finishSM(pB0, pB1, l_reg, pa0, pa1, pa2, pa3); SBAR();
;   pv_d0(o, vb0 + (int)SHM_V, pa0, pa1, pa2, pa3);
;   if (hi == 0) li_l[r32] = l_reg; asm volatile("s_waitcnt lgkmcnt(0)" ::: "memory");
;   float rli[16];
; #pragma unroll
;   for (int r = 0; r < 16; ++r) rli[r] = __builtin_amdgcn_rcpf(li_l[crow(r, hi)]);
	v_mfma_f32_16x16x32_bf16 v[34:37], v[210:213], v[114:117], v[34:37]
	v_mfma_f32_16x16x32_bf16 v[38:41], v[210:213], v[118:121], v[38:41]
	ds_read_b64_tr_b16 v[210:211], v238 offset:57344
	ds_read_b64_tr_b16 v[212:213], v238 offset:61440
	s_waitcnt lgkmcnt(10)
	v_mfma_f32_16x16x32_bf16 v[42:45], v[214:217], v[114:117], v[42:45]
	v_mfma_f32_16x16x32_bf16 v[46:49], v[214:217], v[118:121], v[46:49]
	ds_read_b64_tr_b16 v[214:215], v239 offset:57344
	ds_read_b64_tr_b16 v[216:217], v239 offset:61440
	s_waitcnt lgkmcnt(10)
	v_mfma_f32_16x16x32_bf16 v[50:53], v[218:221], v[114:117], v[50:53]
	v_mfma_f32_16x16x32_bf16 v[54:57], v[218:221], v[118:121], v[54:57]
	ds_read_b64_tr_b16 v[218:219], v240 offset:57344
	ds_read_b64_tr_b16 v[220:221], v240 offset:61440
	s_waitcnt lgkmcnt(10)
	v_mfma_f32_16x16x32_bf16 v[58:61], v[222:225], v[114:117], v[58:61]
	v_mfma_f32_16x16x32_bf16 v[62:65], v[222:225], v[118:121], v[62:65]
	ds_read_b64_tr_b16 v[222:223], v241 offset:57344
	ds_read_b64_tr_b16 v[224:225], v241 offset:61440
	s_waitcnt lgkmcnt(10)
	v_mfma_f32_16x16x32_bf16 v[66:69], v[202:205], v[114:117], v[66:69]
	v_mfma_f32_16x16x32_bf16 v[70:73], v[202:205], v[118:121], v[70:73]
	ds_read_b64_tr_b16 v[202:203], v242 offset:57344
	ds_read_b64_tr_b16 v[204:205], v242 offset:61440
	s_waitcnt lgkmcnt(10)
	v_mfma_f32_16x16x32_bf16 v[74:77], v[206:209], v[114:117], v[74:77]
	v_mfma_f32_16x16x32_bf16 v[78:81], v[206:209], v[118:121], v[78:81]
	ds_read_b64_tr_b16 v[206:207], v243 offset:57344
	ds_read_b64_tr_b16 v[208:209], v243 offset:61440
	s_waitcnt lgkmcnt(10)
	v_mfma_f32_16x16x32_bf16 v[18:21], v[210:213], v[130:133], v[18:21]
	v_mfma_f32_16x16x32_bf16 v[22:25], v[210:213], v[134:137], v[22:25]
	ds_read_b64_tr_b16 v[210:211], v244 offset:57344
	ds_read_b64_tr_b16 v[212:213], v244 offset:61440
	s_waitcnt lgkmcnt(10)
	v_mfma_f32_16x16x32_bf16 v[26:29], v[214:217], v[130:133], v[26:29]
	v_mfma_f32_16x16x32_bf16 v[30:33], v[214:217], v[134:137], v[30:33]
	ds_read_b64_tr_b16 v[214:215], v245 offset:57344
	ds_read_b64_tr_b16 v[216:217], v245 offset:61440
	s_waitcnt lgkmcnt(10)
	v_mfma_f32_16x16x32_bf16 v[34:37], v[218:221], v[130:133], v[34:37]
	v_mfma_f32_16x16x32_bf16 v[38:41], v[218:221], v[134:137], v[38:41]
	s_waitcnt lgkmcnt(8)
	v_mfma_f32_16x16x32_bf16 v[42:45], v[222:225], v[130:133], v[42:45]
	v_mfma_f32_16x16x32_bf16 v[46:49], v[222:225], v[134:137], v[46:49]
	s_waitcnt lgkmcnt(6)
	v_mfma_f32_16x16x32_bf16 v[50:53], v[202:205], v[130:133], v[50:53]
	v_mfma_f32_16x16x32_bf16 v[54:57], v[202:205], v[134:137], v[54:57]
	s_waitcnt lgkmcnt(4)
	v_mfma_f32_16x16x32_bf16 v[58:61], v[206:209], v[130:133], v[58:61]
	v_mfma_f32_16x16x32_bf16 v[62:65], v[206:209], v[134:137], v[62:65]
	s_waitcnt lgkmcnt(2)
	v_mfma_f32_16x16x32_bf16 v[66:69], v[210:213], v[130:133], v[66:69]
	v_mfma_f32_16x16x32_bf16 v[70:73], v[210:213], v[134:137], v[70:73]
	s_waitcnt lgkmcnt(0)
	v_mfma_f32_16x16x32_bf16 v[74:77], v[214:217], v[130:133], v[74:77]
	v_mfma_f32_16x16x32_bf16 v[78:81], v[214:217], v[134:137], v[78:81]
	s_setprio 0
	ds_swizzle_b32 v6, v250 offset:swizzle(SWAP,16)
	s_waitcnt lgkmcnt(0)
	v_add_f32_e32 v250, v250, v6
	v_mov_b32_e32 v6, v250
	s_nop 1
	v_permlane32_swap_b32_e32 v250, v6
	v_add_f32_e32 v250, v250, v6
	v_rcp_f32_e32 v250, v250
	ds_swizzle_b32 v6, v251 offset:swizzle(SWAP,16)
	s_waitcnt lgkmcnt(0)
; __device__ __forceinline__ int crow(int r, int hi) { return (r & 3) + 8 * (r >> 2) + 4 * hi; }
; template <typename TQ> ...
;     ...
;   for (int r = 0; r < 16; ++r) rli[r] = __builtin_amdgcn_rcpf(li_l[crow(r, hi)]);
;   int le = (int)(threadIdx.x & 63u); asm volatile("" : "+v"(le));
;   const int r32e = le & 31, hie = le >> 5;
;   bf16* Ow = Ob + (long)(wid * QBLK) * LDO;
; #pragma unroll
;   for (int r = 0; r < 16; ++r) { int orow = crow(r, hie);
;     for (int d0 = 0; d0 < 4; ++d0) Ow[(long)orow * LDO + d0 * 32 + r32e] = __float2bfloat16(o[d0][r] * rli[r]); }
	v_add_f32_e32 v251, v251, v6
	v_mov_b32_e32 v6, v251
	s_nop 1
	v_permlane32_swap_b32_e32 v251, v6
	v_add_f32_e32 v251, v251, v6
	v_rcp_f32_e32 v251, v251
	s_add_u32 s12, s71, s48
	s_addc_u32 s13, s72, s49
	v_add_u32_e32 v201, s52, v16
	v_lshlrev_b32_e32 v201, 11, v201
	v_lshl_or_b32 v7, v17, 3, v201
	v_add_u32_e32 v200, 0x8000, v7
	v_mul_f32_e32 v18, v18, v250
	v_mul_f32_e32 v19, v19, v250
	v_mul_f32_e32 v20, v20, v250
	v_mul_f32_e32 v21, v21, v250
	v_cvt_pk_bf16_f32 v18, v18, v19
	v_cvt_pk_bf16_f32 v19, v20, v21
	global_store_dwordx2 v7, v[18:19], s[12:13] offset:0
	v_mul_f32_e32 v22, v22, v251
	v_mul_f32_e32 v23, v23, v251
	v_mul_f32_e32 v24, v24, v251
	v_mul_f32_e32 v25, v25, v251
	v_cvt_pk_bf16_f32 v22, v22, v23
	v_cvt_pk_bf16_f32 v23, v24, v25
	global_store_dwordx2 v200, v[22:23], s[12:13] offset:0
	v_mul_f32_e32 v26, v26, v250
	v_mul_f32_e32 v27, v27, v250
	v_mul_f32_e32 v28, v28, v250
	v_mul_f32_e32 v29, v29, v250
	v_cvt_pk_bf16_f32 v26, v26, v27
	v_cvt_pk_bf16_f32 v27, v28, v29
	global_store_dwordx2 v7, v[26:27], s[12:13] offset:32
	v_mul_f32_e32 v30, v30, v251
	v_mul_f32_e32 v31, v31, v251
	v_mul_f32_e32 v32, v32, v251
	v_mul_f32_e32 v33, v33, v251
	v_cvt_pk_bf16_f32 v30, v30, v31
	v_cvt_pk_bf16_f32 v31, v32, v33
	global_store_dwordx2 v200, v[30:31], s[12:13] offset:32
	v_mul_f32_e32 v34, v34, v250
	v_mul_f32_e32 v35, v35, v250
	v_mul_f32_e32 v36, v36, v250
	v_mul_f32_e32 v37, v37, v250
	v_cvt_pk_bf16_f32 v34, v34, v35
	v_cvt_pk_bf16_f32 v35, v36, v37
	global_store_dwordx2 v7, v[34:35], s[12:13] offset:64
	v_mul_f32_e32 v38, v38, v251
	v_mul_f32_e32 v39, v39, v251
	v_mul_f32_e32 v40, v40, v251
	v_mul_f32_e32 v41, v41, v251
	v_cvt_pk_bf16_f32 v38, v38, v39
	v_cvt_pk_bf16_f32 v39, v40, v41
	global_store_dwordx2 v200, v[38:39], s[12:13] offset:64
	v_mul_f32_e32 v42, v42, v250
	v_mul_f32_e32 v43, v43, v250
	v_mul_f32_e32 v44, v44, v250
	v_mul_f32_e32 v45, v45, v250
	v_cvt_pk_bf16_f32 v42, v42, v43
	v_cvt_pk_bf16_f32 v43, v44, v45
	global_store_dwordx2 v7, v[42:43], s[12:13] offset:96
	v_mul_f32_e32 v46, v46, v251
	v_mul_f32_e32 v47, v47, v251
	v_mul_f32_e32 v48, v48, v251
	v_mul_f32_e32 v49, v49, v251
	v_cvt_pk_bf16_f32 v46, v46, v47
	v_cvt_pk_bf16_f32 v47, v48, v49
	global_store_dwordx2 v200, v[46:47], s[12:13] offset:96
	v_mul_f32_e32 v50, v50, v250
	v_mul_f32_e32 v51, v51, v250
	v_mul_f32_e32 v52, v52, v250
	v_mul_f32_e32 v53, v53, v250
	v_cvt_pk_bf16_f32 v50, v50, v51
	v_cvt_pk_bf16_f32 v51, v52, v53
	global_store_dwordx2 v7, v[50:51], s[12:13] offset:128
	v_mul_f32_e32 v54, v54, v251
	v_mul_f32_e32 v55, v55, v251
	v_mul_f32_e32 v56, v56, v251
	v_mul_f32_e32 v57, v57, v251
	v_cvt_pk_bf16_f32 v54, v54, v55
	v_cvt_pk_bf16_f32 v55, v56, v57
	global_store_dwordx2 v200, v[54:55], s[12:13] offset:128
	v_mul_f32_e32 v58, v58, v250
	v_mul_f32_e32 v59, v59, v250
	v_mul_f32_e32 v60, v60, v250
	v_mul_f32_e32 v61, v61, v250
	v_cvt_pk_bf16_f32 v58, v58, v59
	v_cvt_pk_bf16_f32 v59, v60, v61
	global_store_dwordx2 v7, v[58:59], s[12:13] offset:160
	v_mul_f32_e32 v62, v62, v251
	v_mul_f32_e32 v63, v63, v251
	v_mul_f32_e32 v64, v64, v251
	v_mul_f32_e32 v65, v65, v251
	v_cvt_pk_bf16_f32 v62, v62, v63
	v_cvt_pk_bf16_f32 v63, v64, v65
	global_store_dwordx2 v200, v[62:63], s[12:13] offset:160
	v_mul_f32_e32 v66, v66, v250
	v_mul_f32_e32 v67, v67, v250
	v_mul_f32_e32 v68, v68, v250
	v_mul_f32_e32 v69, v69, v250
	v_cvt_pk_bf16_f32 v66, v66, v67
	v_cvt_pk_bf16_f32 v67, v68, v69
	global_store_dwordx2 v7, v[66:67], s[12:13] offset:192
	v_mul_f32_e32 v70, v70, v251
	v_mul_f32_e32 v71, v71, v251
	v_mul_f32_e32 v72, v72, v251
	v_mul_f32_e32 v73, v73, v251
	v_cvt_pk_bf16_f32 v70, v70, v71
	v_cvt_pk_bf16_f32 v71, v72, v73
	global_store_dwordx2 v200, v[70:71], s[12:13] offset:192
	v_mul_f32_e32 v74, v74, v250
	v_mul_f32_e32 v75, v75, v250
	v_mul_f32_e32 v76, v76, v250
	v_mul_f32_e32 v77, v77, v250
	v_cvt_pk_bf16_f32 v74, v74, v75
	v_cvt_pk_bf16_f32 v75, v76, v77
	global_store_dwordx2 v7, v[74:75], s[12:13] offset:224
	v_mul_f32_e32 v78, v78, v251
	v_mul_f32_e32 v79, v79, v251
	v_mul_f32_e32 v80, v80, v251
	v_mul_f32_e32 v81, v81, v251
	v_cvt_pk_bf16_f32 v78, v78, v79
	v_cvt_pk_bf16_f32 v79, v80, v81
	global_store_dwordx2 v200, v[78:79], s[12:13] offset:224
	s_add_i32 s74, s74, 1
	s_add_i32 s94, s94, 1
	s_cmp_eq_u32 s74, s66
	s_cselect_b64 s[0:1], -1, 0
	s_barrier
	s_branch .LBB0_818
